# v020
# speedup vs baseline: 1.1018x; 1.0440x over previous
; __device__ __forceinline__ void convert_wt(const float* __restrict__ W, int K, int N, u16* __restrict__ Wt, int Npad, int mode, char* smem,
;                                            const float* __restrict__ gain = nullptr) {
;     ...
;       for (int p = 0; p < 2; ++p) {
;         const int k = p * 32 + kk;
;         float4 v = make_float4(0.f, 0.f, 0.f, 0.f);
;         if (valid && (sn0 + n4 * 4 + 3) < N) v = *(const float4*)(W + (size_t)(k0 + k) * N + sn0 + n4 * 4);
;         if (gain) { const float gk = gain[k0 + k]; v.x *= gk; v.y *= gk; v.z *= gk; v.w *= gk; }
;         tile[(n4 * 4 + 0) * 65 + k] = v.x; tile[(n4 * 4 + 1) * 65 + k] = v.y;
;         tile[(n4 * 4 + 2) * 65 + k] = v.z; tile[(n4 * 4 + 3) * 65 + k] = v.w;
;       }
;     }
;     __syncthreads();
;     {
;       const int nn = tid >> 3, kc = tid & 7;
;       bf16x8 o;
; #pragma unroll
;       for (int e = 0; e < 8; ++e) o[e] = (short)f2bf(tile[nn * 65 + kc * 8 + e]);
;       *(bf16x8*)(Wt + (size_t)(n0 + nn) * K + k0 + kc * 8) = o;
;     }
;     __syncthreads();
.LBB0_60:
	ds_write2_b32 v1, v16, v17 offset0:32 offset1:97
	ds_write2_b32 v1, v14, v15 offset0:162 offset1:227
	s_waitcnt lgkmcnt(0)
	s_barrier
	s_waitcnt vmcnt(0)
	ds_read2_b32 v[4:5], v19 offset1:7
	ds_read2_b32 v[2:3], v19 offset0:1 offset1:2
	ds_read2_b32 v[14:15], v19 offset0:3 offset1:4
	ds_read2_b32 v[16:17], v19 offset0:5 offset1:6
	v_mov_b32_e32 v13, v8
	s_waitcnt lgkmcnt(3)
	v_cvt_pk_bf16_f32 v4, v4, s0
	s_waitcnt lgkmcnt(2)
	v_cvt_pk_bf16_f32 v3, v2, v3
	v_perm_b32 v2, v3, v4, s22
	s_waitcnt lgkmcnt(1)
	v_cvt_pk_bf16_f32 v4, v14, v15
	v_add_u32_e32 v14, s14, v6
	v_ashrrev_i32_e32 v15, 31, v14
	v_lshlrev_b64 v[14:15], 11, v[14:15]
	v_lshl_add_u64 v[14:15], s[10:11], 0, v[14:15]
	s_waitcnt lgkmcnt(0)
	v_cvt_pk_bf16_f32 v9, v16, v17
	v_cvt_pk_bf16_f32 v5, v5, s0
	v_lshl_add_u64 v[14:15], s[6:7], 1, v[14:15]
	s_add_i32 s23, s23, s68
	s_add_i32 s18, s18, s19
	v_alignbit_b32 v3, v4, v3, 16
	v_alignbit_b32 v4, v9, v4, 16
	v_alignbit_b32 v5, v5, v9, 16
	v_lshl_add_u64 v[14:15], v[14:15], 0, v[12:13]
	s_cmpk_lt_i32 s23, 0x700
	v_lshlrev_b32_e32 v255, 1, v14
	v_bfi_b32 v255, s100, v255, v14
	v_lshrrev_b32_e32 v14, 5, v14
	v_bfi_b32 v14, 64, v14, v255
	global_store_dwordx4 v[14:15], v[2:5], off
	s_barrier
	s_cbranch_scc0 .LBB0_70

; __device__ __forceinline__ void convert_wt(const float* __restrict__ W, int K, int N, u16* __restrict__ Wt, int Npad, int mode, char* smem,
;                                            const float* __restrict__ gain = nullptr) {
;     ...
;       for (int p = 0; p < 2; ++p) {
;         const int k = p * 32 + kk;
;         float4 v = make_float4(0.f, 0.f, 0.f, 0.f);
;         if (valid && (sn0 + n4 * 4 + 3) < N) v = *(const float4*)(W + (size_t)(k0 + k) * N + sn0 + n4 * 4);
;         if (gain) { const float gk = gain[k0 + k]; v.x *= gk; v.y *= gk; v.z *= gk; v.w *= gk; }
;         tile[(n4 * 4 + 0) * 65 + k] = v.x; tile[(n4 * 4 + 1) * 65 + k] = v.y;
;         tile[(n4 * 4 + 2) * 65 + k] = v.z; tile[(n4 * 4 + 3) * 65 + k] = v.w;
;       }
;     }
;     __syncthreads();
;     {
;       const int nn = tid >> 3, kc = tid & 7;
;       bf16x8 o;
; #pragma unroll
;       for (int e = 0; e < 8; ++e) o[e] = (short)f2bf(tile[nn * 65 + kc * 8 + e]);
;       *(bf16x8*)(Wt + (size_t)(n0 + nn) * K + k0 + kc * 8) = o;
;     }
;     __syncthreads();
.LBB0_72:
	s_or_b64 exec, exec, s[12:13]
	s_waitcnt vmcnt(0)
	ds_write2_b32 v14, v2, v6 offset1:32
	ds_write2_b32 v14, v3, v7 offset0:65 offset1:97
	ds_write2_b32 v14, v4, v8 offset0:130 offset1:162
	ds_write2_b32 v14, v5, v9 offset0:195 offset1:227
	s_waitcnt lgkmcnt(0)
	s_barrier
	ds_read2_b32 v[4:5], v16 offset1:7
	ds_read2_b32 v[2:3], v16 offset0:1 offset1:2
	ds_read2_b32 v[6:7], v16 offset0:3 offset1:4
	ds_read2_b32 v[8:9], v16 offset0:5 offset1:6
	s_add_i32 s12, s14, s19
	s_waitcnt lgkmcnt(3)
	v_cvt_pk_bf16_f32 v4, v4, s0
	s_waitcnt lgkmcnt(2)
	v_cvt_pk_bf16_f32 v3, v2, v3
	v_perm_b32 v2, v3, v4, s17
	s_waitcnt lgkmcnt(1)
	v_cvt_pk_bf16_f32 v4, v6, v7
	s_waitcnt lgkmcnt(0)
	v_cvt_pk_bf16_f32 v6, v8, v9
	v_cvt_pk_bf16_f32 v5, v5, s0
	v_alignbit_b32 v3, v4, v3, 16
	v_alignbit_b32 v4, v6, v4, 16
	v_alignbit_b32 v5, v5, v6, 16
	v_add_u32_e32 v6, s10, v1
	v_ashrrev_i32_e32 v7, 31, v6
	v_lshlrev_b64 v[6:7], 11, v[6:7]
	v_lshl_add_u64 v[6:7], s[6:7], 0, v[6:7]
	s_ashr_i32 s13, s12, 31
	v_lshl_add_u64 v[6:7], s[12:13], 1, v[6:7]
	s_add_i32 s18, s18, s68
	s_add_i32 s14, s14, s15
	v_lshl_add_u64 v[6:7], v[6:7], 0, v[10:11]
	s_cmpk_lt_i32 s18, 0x200
	v_lshlrev_b32_e32 v255, 1, v6
	v_bfi_b32 v255, s100, v255, v6
	v_lshrrev_b32_e32 v6, 5, v6
	v_bfi_b32 v6, 64, v6, v255
	global_store_dwordx4 v[6:7], v[2:5], off
	s_barrier
	s_cbranch_scc0 .LBB0_75

; __device__ __forceinline__ void convert_wt(const float* __restrict__ W, int K, int N, u16* __restrict__ Wt, int Npad, int mode, char* smem,
;                                            const float* __restrict__ gain = nullptr) {
;     ...
;       for (int p = 0; p < 2; ++p) {
;         const int k = p * 32 + kk;
;         float4 v = make_float4(0.f, 0.f, 0.f, 0.f);
;         if (valid && (sn0 + n4 * 4 + 3) < N) v = *(const float4*)(W + (size_t)(k0 + k) * N + sn0 + n4 * 4);
;         if (gain) { const float gk = gain[k0 + k]; v.x *= gk; v.y *= gk; v.z *= gk; v.w *= gk; }
;         tile[(n4 * 4 + 0) * 65 + k] = v.x; tile[(n4 * 4 + 1) * 65 + k] = v.y;
;         tile[(n4 * 4 + 2) * 65 + k] = v.z; tile[(n4 * 4 + 3) * 65 + k] = v.w;
;       }
;     }
;     __syncthreads();
;     {
;       const int nn = tid >> 3, kc = tid & 7;
;       bf16x8 o;
; #pragma unroll
;       for (int e = 0; e < 8; ++e) o[e] = (short)f2bf(tile[nn * 65 + kc * 8 + e]);
;       *(bf16x8*)(Wt + (size_t)(n0 + nn) * K + k0 + kc * 8) = o;
;     }
;     __syncthreads();
.LBB0_77:
	s_or_b64 exec, exec, s[12:13]
	v_lshl_add_u64 v[10:11], v[12:13], 2, s[8:9]
	global_load_dword v12, v[10:11], off
	v_add_u32_e32 v10, s10, v1
	v_ashrrev_i32_e32 v11, 31, v10
	s_add_i32 s12, s16, s22
	v_lshlrev_b64 v[10:11], 11, v[10:11]
	s_ashr_i32 s13, s12, 31
	v_lshl_add_u64 v[10:11], s[6:7], 0, v[10:11]
	s_add_i32 s21, s21, s68
	s_add_i32 s16, s16, s17
	v_lshl_add_u64 v[10:11], s[12:13], 1, v[10:11]
	s_cmpk_lt_i32 s21, 0x840
	v_lshl_add_u64 v[10:11], v[10:11], 0, v[6:7]
	s_waitcnt vmcnt(0)
	v_mul_f32_e32 v2, v2, v12
	v_mul_f32_e32 v3, v3, v12
	v_mul_f32_e32 v4, v4, v12
	v_mul_f32_e32 v5, v5, v12
	ds_write2_b32 v14, v2, v3 offset0:32 offset1:97
	ds_write2_b32 v14, v4, v5 offset0:162 offset1:227
	s_waitcnt lgkmcnt(0)
	s_barrier
	ds_read2_b32 v[2:3], v16 offset1:7
	ds_read2_b32 v[4:5], v16 offset0:1 offset1:2
	ds_read2_b32 v[12:13], v16 offset0:3 offset1:4
	ds_read2_b32 v[18:19], v16 offset0:5 offset1:6
	s_waitcnt lgkmcnt(3)
	v_cvt_pk_bf16_f32 v2, v2, s0
	s_waitcnt lgkmcnt(2)
	v_cvt_pk_bf16_f32 v4, v4, v5
	s_waitcnt lgkmcnt(1)
	v_cvt_pk_bf16_f32 v5, v12, v13
	s_waitcnt lgkmcnt(0)
	v_cvt_pk_bf16_f32 v12, v18, v19
	v_cvt_pk_bf16_f32 v13, v3, s0
	v_perm_b32 v2, v4, v2, s20
	v_alignbit_b32 v3, v5, v4, 16
	v_alignbit_b32 v4, v12, v5, 16
	v_alignbit_b32 v5, v13, v12, 16
	v_lshlrev_b32_e32 v255, 1, v10
	v_bfi_b32 v255, s100, v255, v10
	v_lshrrev_b32_e32 v10, 5, v10
	v_bfi_b32 v10, 64, v10, v255
	global_store_dwordx4 v[10:11], v[2:5], off
	s_barrier
	s_cbranch_scc0 .LBB0_86

; __device__ __forceinline__ void convert_wt(const float* __restrict__ W, int K, int N, u16* __restrict__ Wt, int Npad, int mode, char* smem,
;                                            const float* __restrict__ gain = nullptr) {
;     ...
;       for (int p = 0; p < 2; ++p) {
;         const int k = p * 32 + kk;
;         float4 v = make_float4(0.f, 0.f, 0.f, 0.f);
;         if (valid && (sn0 + n4 * 4 + 3) < N) v = *(const float4*)(W + (size_t)(k0 + k) * N + sn0 + n4 * 4);
;         if (gain) { const float gk = gain[k0 + k]; v.x *= gk; v.y *= gk; v.z *= gk; v.w *= gk; }
;         tile[(n4 * 4 + 0) * 65 + k] = v.x; tile[(n4 * 4 + 1) * 65 + k] = v.y;
;         tile[(n4 * 4 + 2) * 65 + k] = v.z; tile[(n4 * 4 + 3) * 65 + k] = v.w;
;       }
;     }
;     __syncthreads();
;     {
;       const int nn = tid >> 3, kc = tid & 7;
;       bf16x8 o;
; #pragma unroll
;       for (int e = 0; e < 8; ++e) o[e] = (short)f2bf(tile[nn * 65 + kc * 8 + e]);
;       *(bf16x8*)(Wt + (size_t)(n0 + nn) * K + k0 + kc * 8) = o;
;     }
;     __syncthreads();
.LBB0_88:
	s_or_b64 exec, exec, s[8:9]
	s_waitcnt vmcnt(0)
	ds_write2_b32 v14, v2, v6 offset1:32
	ds_write2_b32 v14, v3, v7 offset0:65 offset1:97
	ds_write2_b32 v14, v4, v8 offset0:130 offset1:162
	ds_write2_b32 v14, v5, v9 offset0:195 offset1:227
	s_waitcnt lgkmcnt(0)
	s_barrier
	ds_read2_b32 v[4:5], v16 offset1:7
	ds_read2_b32 v[2:3], v16 offset0:1 offset1:2
	ds_read2_b32 v[6:7], v16 offset0:3 offset1:4
	ds_read2_b32 v[8:9], v16 offset0:5 offset1:6
	s_add_i32 s8, s10, s15
	s_waitcnt lgkmcnt(3)
	v_cvt_pk_bf16_f32 v4, v4, s0
	s_waitcnt lgkmcnt(2)
	v_cvt_pk_bf16_f32 v3, v2, v3
	v_perm_b32 v2, v3, v4, s13
	s_waitcnt lgkmcnt(1)
	v_cvt_pk_bf16_f32 v4, v6, v7
	s_waitcnt lgkmcnt(0)
	v_cvt_pk_bf16_f32 v6, v8, v9
	v_cvt_pk_bf16_f32 v5, v5, s0
	v_alignbit_b32 v3, v4, v3, 16
	v_alignbit_b32 v4, v6, v4, 16
	v_alignbit_b32 v5, v5, v6, 16
	v_add_u32_e32 v6, s6, v1
	v_ashrrev_i32_e32 v7, 31, v6
	v_lshlrev_b64 v[6:7], 11, v[6:7]
	v_lshl_add_u64 v[6:7], s[4:5], 0, v[6:7]
	s_ashr_i32 s9, s8, 31
	v_lshl_add_u64 v[6:7], s[8:9], 1, v[6:7]
	s_add_i32 s14, s14, s68
	s_add_i32 s10, s10, s11
	v_lshl_add_u64 v[6:7], v[6:7], 0, v[10:11]
	s_cmpk_lt_i32 s14, 0x200
	v_lshlrev_b32_e32 v255, 1, v6
	v_bfi_b32 v255, s100, v255, v6
	v_lshrrev_b32_e32 v6, 5, v6
	v_bfi_b32 v6, 64, v6, v255
	global_store_dwordx4 v[6:7], v[2:5], off
	s_barrier
	s_cbranch_scc0 .LBB0_91

; __device__ __forceinline__ int opaque_tid() { int t = threadIdx.x; asm volatile("" : "+v"(t)); return t; }
; template <int EPI, int MF>
; __device__ __forceinline__ void gemm_part(const u16* __restrict__ A, int lda, const u16* __restrict__ Bt, int K, int ntn, GemmEpi ep, char* smem,
;                                           int mbase, int mrows) {
;   const int tid = opaque_tid(), lane = tid & 63, wid = tid >> 6, wr = wid >> 1, wc = wid & 1, fr = lane & 15, fq = lane >> 4;
;   constexpr int BM = 32 * MF;
;   constexpr int STG = BM * 32 + 4096;
;   constexpr int NA = MF / 2;
;   u16* const sbase = (u16*)smem;
;   const int ntm = mrows / BM;
;   const int total = ntm * ntn;
;   const int nk = K / 32;
;   const int nbx = (MF == 2) ? (int)gridDim.x : (int)(gridDim.x >> 3);
;   const int xcd = (MF == 2) ? 0 : (int)(blockIdx.x & 7), li = (MF == 2) ? (int)blockIdx.x : (int)(blockIdx.x >> 3);
;   for (int q = xcd; q * nbx < total; q += (MF == 2) ? 1 : 8) {
;     const int L = q * nbx + li;
;     if (L >= total) continue;
;     const int g = L / (8 * ntn), rr = L % (8 * ntn);
;     const int rows = min(8, ntm - 8 * g);
;     const int tm = 8 * g + rr % rows, tn = rr / rows;
;     const int row0 = mbase + tm * BM, col0 = tn * 128;
;     f32x4 acc[MF][4];
; #pragma unroll
;     for (int m = 0; m < MF; ++m)
; #pragma unroll
;       for (int n = 0; n < 4; ++n) acc[m][n] = (f32x4){0.f, 0.f, 0.f, 0.f};
;     const u16* gA = A + (size_t)(row0 + (tid >> 2)) * lda + (tid & 3) * 8;
;     const u16* gB = Bt + (size_t)(col0 + (tid >> 2)) * K + (tid & 3) * 8;
;     ...
;     GEMM_ISSUE(0);
;     GEMM_ISSUE(1);
;     for (int kt = 0; kt < nk; ++kt) {
;       if (kt + 1 < nk) {
;         if (MF == 8) asm volatile("s_waitcnt vmcnt(6)" ::: "memory");
;         else asm volatile("s_waitcnt vmcnt(3)" ::: "memory");
;       } else asm volatile("s_waitcnt vmcnt(0)" ::: "memory");
;       asm volatile("s_waitcnt lgkmcnt(0)" ::: "memory");
;       __builtin_amdgcn_s_barrier();
;       const u16* a_ = sbase + (kt % 3) * STG;
;       const u16* b_ = a_ + BM * 32;
;       bf16x8 bfr[4], afc[2], afn[2];
;       const u16* ap_ = a_ + (wr * (16 * MF) + fr) * 32 + fq * 8;
; #pragma unroll
;       for (int n = 0; n < 4; ++n) bfr[n] = rd_std(b_ + (wc * 64 + n * 16 + fr) * 32 + fq * 8);
;       afc[0] = rd_std(ap_); afc[1] = rd_std(ap_ + 16 * 32);
.LBB0_129:
	v_writelane_b32 v254, s4, 63
	s_xor_b64 s[2:3], s[4:5], -1
	v_mov_b32_e32 v2, v140
	v_writelane_b32 v252, s5, 0
	v_writelane_b32 v252, s2, 1
	v_cmp_ne_u32_e64 s[4:5], 1, v203
	s_nop 0
	v_writelane_b32 v252, s3, 2
	s_lshl_b64 s[2:3], s[90:91], 3
	s_add_u32 s2, s96, s2
	s_addc_u32 s3, s97, s3
	v_writelane_b32 v252, s2, 3
	s_nop 1
	v_writelane_b32 v252, s3, 4
	s_load_dwordx2 s[2:3], s[2:3], 0xe0
	v_writelane_b32 v252, s4, 5
	s_nop 1
	v_writelane_b32 v252, s5, 6
	v_readlane_b32 s4, v253, 10
	v_readlane_b32 s5, v253, 11
	s_andn2_b64 vcc, exec, s[4:5]
	s_cbranch_vccnz .LBB0_152
	v_lshlrev_b32_e32 v7, 4, v2
	v_lshrrev_b32_e32 v100, 4, v140
	v_sub_u32_e32 v100, 0, v100
	v_xor_b32_e32 v100, v100, v140
	v_and_b32_e32 v100, 3, v100
	v_lshlrev_b32_e32 v4, 4, v100
	v_mov_b32_e32 v5, v0
	v_bfe_u32 v6, v2, 6, 1
	v_lshl_add_u64 v[130:131], s[44:45], 0, v[4:5]
	s_waitcnt lgkmcnt(0)
	v_lshl_add_u64 v[132:133], s[2:3], 0, v[4:5]
	v_lshlrev_b32_e32 v4, 5, v2
	v_bfe_u32 v3, v2, 4, 2
	v_and_b32_e32 v153, 0xfffff1e0, v4
	v_lshlrev_b32_e32 v4, 6, v6
	v_lshlrev_b32_e32 v134, 3, v3
	v_lshl_add_u64 v[4:5], s[46:47], 0, v[4:5]
	v_mov_b32_e32 v135, v0
	v_ashrrev_i32_e32 v1, 2, v2
	v_and_b32_e32 v154, 0xffffff8f, v2
	v_lshl_add_u64 v[136:137], v[4:5], 0, v[134:135]
	v_and_b32_e32 v8, 1, v140
	v_mul_u32_u24_e32 v8, 0x15c0, v8
	v_bfe_u32 v9, v140, 6, 1
	v_lshlrev_b32_e32 v9, 6, v9
	v_sub_u32_e32 v8, v9, v8
	v_ashrrev_i32_e32 v9, 31, v8
	v_lshl_add_u64 v[136:137], v[136:137], 0, v[8:9]
	v_lshlrev_b32_e32 v135, 12, v6
	v_lshlrev_b32_e32 v4, 6, v2
	v_lshrrev_b32_e32 v101, 2, v140
	v_sub_u32_e32 v101, 0, v101
	v_lshrrev_b32_e32 v3, 4, v140
	v_xor_b32_e32 v101, v101, v3
	v_and_b32_e32 v101, 3, v101
	v_lshlrev_b32_e32 v3, 4, v101
	v_and_b32_e32 v2, 3, v2
	v_add_u32_e32 v151, 0, v7
	v_and_b32_e32 v155, 0x3c0, v4
	v_lshl_add_u32 v156, v153, 1, v3
	v_add_u32_e32 v4, v3, v135
	v_lshlrev_b32_e32 v2, 4, v100
	v_mov_b32_e32 v3, v0
	v_lshl_add_u64 v[138:139], s[44:45], 0, v[2:3]
	v_add_u32_e32 v157, 0x1000, v151
	v_add_u32_e32 v158, 0x2000, v151
	v_add_u32_e32 v159, 0x3000, v151
	v_add_u32_e32 v160, 0x4000, v151
	v_add_u32_e32 v161, 0x5000, v151
	v_add_u32_e32 v162, 0x6000, v151
	v_add_u32_e32 v163, 0x7000, v151
	v_add_u32_e32 v164, 0x8000, v151
	v_add_u32_e32 v165, 0x9000, v151
	v_add_u32_e32 v166, 0xa000, v151
	v_add_u32_e32 v167, 0xb000, v151
	v_add_u32_e32 v168, v4, v155
	v_readlane_b32 s4, v253, 56
	v_readlane_b32 s10, v253, 9
	s_branch .LBB0_133

; #define MFMA(a, b, c) __builtin_amdgcn_mfma_f32_16x16x32_bf16((a), (b), (c), 0, 0, 0)
; template <int EPI, int MF>
; __device__ __forceinline__ void gemm_part(const u16* __restrict__ A, int lda, const u16* __restrict__ Bt, int K, int ntn, GemmEpi ep, char* smem,
;                                           int mbase, int mrows) {
;     ...
;     for (int kt = 0; kt < nk; ++kt) {
;       if (kt + 1 < nk) {
;         if (MF == 8) asm volatile("s_waitcnt vmcnt(6)" ::: "memory");
;         else asm volatile("s_waitcnt vmcnt(3)" ::: "memory");
;       } else asm volatile("s_waitcnt vmcnt(0)" ::: "memory");
;       asm volatile("s_waitcnt lgkmcnt(0)" ::: "memory");
;       __builtin_amdgcn_s_barrier();
;       const u16* a_ = sbase + (kt % 3) * STG;
;       const u16* b_ = a_ + BM * 32;
;       bf16x8 bfr[4], afc[2], afn[2];
;       const u16* ap_ = a_ + (wr * (16 * MF) + fr) * 32 + fq * 8;
; #pragma unroll
;       for (int n = 0; n < 4; ++n) bfr[n] = rd_std(b_ + (wc * 64 + n * 16 + fr) * 32 + fq * 8);
;       afc[0] = rd_std(ap_); afc[1] = rd_std(ap_ + 16 * 32);
;       __builtin_amdgcn_sched_barrier(0);
;       if (kt + 2 < nk) GEMM_ISSUE(kt + 2);
;       __builtin_amdgcn_sched_barrier(0);
; #pragma unroll
;       for (int mh = 0; mh < MF / 2; ++mh) {
;         if (mh + 1 < MF / 2) {
;           afn[0] = rd_std(ap_ + ((mh + 1) * 2) * 16 * 32);
;           afn[1] = rd_std(ap_ + ((mh + 1) * 2 + 1) * 16 * 32);
;         }
;         __builtin_amdgcn_sched_barrier(0);
; #pragma unroll
;         for (int m = 0; m < 2; ++m)
; #pragma unroll
;           for (int n = 0; n < 4; ++n) acc[mh * 2 + m][n] = MFMA(bfr[n], afc[m], acc[mh * 2 + m][n]);
;         __builtin_amdgcn_sched_barrier(0);
;         afc[0] = afn[0]; afc[1] = afn[1];
;       }
.LBB0_135:
	s_mul_i32 s12, s11, 0xab
	s_add_i32 s13, s12, 0xfeaa
	s_bfe_u32 s13, s13, 0x70009
	s_mul_i32 s13, s13, 3
	s_sub_i32 s13, s11, s13
	s_add_i32 s13, s13, 0xfffe
	s_and_b32 s13, s13, 0xff
	s_mulk_i32 s13, 0x6000
	s_add_i32 s13, s13, 0
	v_lshl_add_u32 v150, v134, 1, s13
	s_waitcnt vmcnt(6)
	v_add_u32_e32 v152, s13, v168
	s_waitcnt lgkmcnt(0)
	s_barrier
	ds_read_b128 v[170:173], v152 offset:16384
	ds_read_b128 v[174:177], v152 offset:17408
	ds_read_b128 v[178:181], v152 offset:18432
	ds_read_b128 v[182:185], v152 offset:19456
	v_add_u32_e32 v150, s13, v156
	ds_read_b128 v[186:189], v150
	ds_read_b128 v[190:193], v150 offset:1024
	s_bfe_u32 s12, s12, 0x70009
	s_mul_i32 s12, s12, 3
	s_sub_i32 s12, s11, s12
	s_and_b32 s12, s12, 0xff
	s_mulk_i32 s12, 0x6000
	v_add_u32_e32 v152, s12, v151
	v_lshl_add_u64 v[194:195], s[4:5], 1, v[148:149]
	v_readfirstlane_b32 s12, v152
	v_add_u32_e32 v169, 0x1000, v152
	v_lshl_add_u64 v[196:197], v[194:195], 0, s[74:75]
	s_mov_b32 m0, s12
	v_readfirstlane_b32 s12, v169
	v_add_u32_e32 v169, 0x2000, v152
	global_load_lds_dwordx4 v[196:197], off
	v_lshl_add_u64 v[196:197], v[194:195], 0, s[92:93]
	s_mov_b32 m0, s12
	v_readfirstlane_b32 s12, v169
	v_add_u32_e32 v169, 0x3000, v152
	global_load_lds_dwordx4 v[196:197], off
	v_lshl_add_u64 v[196:197], v[194:195], 0, s[88:89]
	s_mov_b32 m0, s12
	v_readfirstlane_b32 s12, v169
	global_load_lds_dwordx4 v[196:197], off
	v_lshl_add_u64 v[194:195], v[194:195], 0, s[6:7]
	s_mov_b32 m0, s12
	v_add_u32_e32 v169, 0x4000, v152
	global_load_lds_dwordx4 v[194:195], off
	v_lshl_add_u64 v[194:195], s[4:5], 1, v[146:147]
	v_readfirstlane_b32 s12, v169
	v_add_u32_e32 v152, 0x5000, v152
	v_lshl_add_u64 v[196:197], v[194:195], 0, s[74:75]
	s_mov_b32 m0, s12
	v_readfirstlane_b32 s12, v152
	global_load_lds_dwordx4 v[196:197], off
	v_lshl_add_u64 v[194:195], v[194:195], 0, s[92:93]
	s_mov_b32 m0, s12
	s_nop 0
	global_load_lds_dwordx4 v[194:195], off
	ds_read_b128 v[194:197], v150 offset:2048
	ds_read_b128 v[210:213], v150 offset:3072
	s_waitcnt lgkmcnt(2)
	v_mfma_f32_16x16x32_bf16 v[126:129], v[170:173], v[186:189], v[126:129]
	v_mfma_f32_16x16x32_bf16 v[122:125], v[174:177], v[186:189], v[122:125]
	v_mfma_f32_16x16x32_bf16 v[118:121], v[178:181], v[186:189], v[118:121]
	v_mfma_f32_16x16x32_bf16 v[114:117], v[182:185], v[186:189], v[114:117]
	v_mfma_f32_16x16x32_bf16 v[110:113], v[170:173], v[190:193], v[110:113]
	v_mfma_f32_16x16x32_bf16 v[106:109], v[174:177], v[190:193], v[106:109]
	v_mfma_f32_16x16x32_bf16 v[102:105], v[178:181], v[190:193], v[102:105]
	v_mfma_f32_16x16x32_bf16 v[98:101], v[182:185], v[190:193], v[98:101]
	ds_read_b128 v[186:189], v150 offset:4096
	ds_read_b128 v[190:193], v150 offset:5120
	s_waitcnt lgkmcnt(2)
	v_mfma_f32_16x16x32_bf16 v[94:97], v[170:173], v[194:197], v[94:97]
	v_mfma_f32_16x16x32_bf16 v[90:93], v[174:177], v[194:197], v[90:93]
	v_mfma_f32_16x16x32_bf16 v[86:89], v[178:181], v[194:197], v[86:89]
	v_mfma_f32_16x16x32_bf16 v[82:85], v[182:185], v[194:197], v[82:85]
	v_mfma_f32_16x16x32_bf16 v[78:81], v[170:173], v[210:213], v[78:81]
	v_mfma_f32_16x16x32_bf16 v[74:77], v[174:177], v[210:213], v[74:77]
	v_mfma_f32_16x16x32_bf16 v[70:73], v[178:181], v[210:213], v[70:73]
	v_mfma_f32_16x16x32_bf16 v[66:69], v[182:185], v[210:213], v[66:69]
	ds_read_b128 v[194:197], v150 offset:6144
	ds_read_b128 v[210:213], v150 offset:7168
	s_waitcnt lgkmcnt(2)
	v_mfma_f32_16x16x32_bf16 v[62:65], v[170:173], v[186:189], v[62:65]
	v_mfma_f32_16x16x32_bf16 v[58:61], v[174:177], v[186:189], v[58:61]
	v_mfma_f32_16x16x32_bf16 v[54:57], v[178:181], v[186:189], v[54:57]
	v_mfma_f32_16x16x32_bf16 v[50:53], v[182:185], v[186:189], v[50:53]
	v_mfma_f32_16x16x32_bf16 v[46:49], v[170:173], v[190:193], v[46:49]
	v_mfma_f32_16x16x32_bf16 v[42:45], v[174:177], v[190:193], v[42:45]
	v_mfma_f32_16x16x32_bf16 v[38:41], v[178:181], v[190:193], v[38:41]
	v_mfma_f32_16x16x32_bf16 v[34:37], v[182:185], v[190:193], v[34:37]
	s_waitcnt lgkmcnt(0)
	v_mfma_f32_16x16x32_bf16 v[30:33], v[170:173], v[194:197], v[30:33]
	v_mfma_f32_16x16x32_bf16 v[26:29], v[174:177], v[194:197], v[26:29]
	v_mfma_f32_16x16x32_bf16 v[22:25], v[178:181], v[194:197], v[22:25]
	v_mfma_f32_16x16x32_bf16 v[18:21], v[182:185], v[194:197], v[18:21]
	v_mfma_f32_16x16x32_bf16 v[14:17], v[170:173], v[210:213], v[14:17]
	v_mfma_f32_16x16x32_bf16 v[10:13], v[174:177], v[210:213], v[10:13]
	v_mfma_f32_16x16x32_bf16 v[6:9], v[178:181], v[210:213], v[6:9]
	v_mfma_f32_16x16x32_bf16 v[2:5], v[182:185], v[210:213], v[2:5]
	s_add_u32 s4, s4, 64
	s_addc_u32 s5, s5, 0
	s_add_i32 s11, s11, 1
	s_cmpk_eq_i32 s4, 0x780
	s_cbranch_scc0 .LBB0_135
	s_waitcnt vmcnt(6)
	s_waitcnt lgkmcnt(0)
	s_barrier
; #define MFMA(a, b, c) __builtin_amdgcn_mfma_f32_16x16x32_bf16((a), (b), (c), 0, 0, 0)
; template <int EPI, int MF>
; __device__ __forceinline__ void gemm_part(const u16* __restrict__ A, int lda, const u16* __restrict__ Bt, int K, int ntn, GemmEpi ep, char* smem,
;                                           int mbase, int mrows) {
;     ...
;     for (int kt = 0; kt < nk; ++kt) {
;       if (kt + 1 < nk) {
;         if (MF == 8) asm volatile("s_waitcnt vmcnt(6)" ::: "memory");
;         else asm volatile("s_waitcnt vmcnt(3)" ::: "memory");
;       } else asm volatile("s_waitcnt vmcnt(0)" ::: "memory");
;       asm volatile("s_waitcnt lgkmcnt(0)" ::: "memory");
;       __builtin_amdgcn_s_barrier();
;       const u16* a_ = sbase + (kt % 3) * STG;
;       const u16* b_ = a_ + BM * 32;
;       bf16x8 bfr[4], afc[2], afn[2];
;       const u16* ap_ = a_ + (wr * (16 * MF) + fr) * 32 + fq * 8;
; #pragma unroll
;       for (int n = 0; n < 4; ++n) bfr[n] = rd_std(b_ + (wc * 64 + n * 16 + fr) * 32 + fq * 8);
;       afc[0] = rd_std(ap_); afc[1] = rd_std(ap_ + 16 * 32);
;       __builtin_amdgcn_sched_barrier(0);
;       if (kt + 2 < nk) GEMM_ISSUE(kt + 2);
;       __builtin_amdgcn_sched_barrier(0);
; #pragma unroll
;       for (int mh = 0; mh < MF / 2; ++mh) {
;         if (mh + 1 < MF / 2) {
;           afn[0] = rd_std(ap_ + ((mh + 1) * 2) * 16 * 32);
;           afn[1] = rd_std(ap_ + ((mh + 1) * 2 + 1) * 16 * 32);
;         }
;         __builtin_amdgcn_sched_barrier(0);
; #pragma unroll
;         for (int m = 0; m < 2; ++m)
; #pragma unroll
;           for (int n = 0; n < 4; ++n) acc[mh * 2 + m][n] = MFMA(bfr[n], afc[m], acc[mh * 2 + m][n]);
;         __builtin_amdgcn_sched_barrier(0);
;         afc[0] = afn[0]; afc[1] = afn[1];
;       }
;     }
;     ...
;     __syncthreads();
; #pragma unroll
;     for (int m = 0; m < MF; ++m) {
;       if (EPI == EPI_SWIGLU || (m & 1) == 0) __builtin_amdgcn_sched_barrier(0);
;       const int row = row0 + wr * (16 * MF) + m * 16 + fr;
;       const int cb = col0 + wc * 64 + 4 * fq;
;       float rstd = 1.f;
;       if (EPI != EPI_RESID) { if (ep.rss_in) rstd = rsqrtf(ep.rss_in[row] * (1.f / DM) + 1e-6f); }
	ds_read_b128 v[146:149], v168 offset:16384
	ds_read_b128 v[170:173], v168 offset:17408
	ds_read_b128 v[174:177], v168 offset:18432
	ds_read_b128 v[178:181], v168 offset:19456
	ds_read_b128 v[182:185], v156
	ds_read_b128 v[186:189], v156 offset:1024
	ds_read_b128 v[190:193], v156 offset:2048
	ds_read_b128 v[194:197], v156 offset:3072
	s_waitcnt lgkmcnt(0)
	v_mfma_f32_16x16x32_bf16 v[126:129], v[146:149], v[182:185], v[126:129]
	v_mfma_f32_16x16x32_bf16 v[122:125], v[170:173], v[182:185], v[122:125]
	v_mfma_f32_16x16x32_bf16 v[114:117], v[178:181], v[182:185], v[114:117]
	v_mfma_f32_16x16x32_bf16 v[110:113], v[146:149], v[186:189], v[110:113]
	v_mfma_f32_16x16x32_bf16 v[106:109], v[170:173], v[186:189], v[106:109]
	v_mfma_f32_16x16x32_bf16 v[98:101], v[178:181], v[186:189], v[98:101]
	v_mfma_f32_16x16x32_bf16 v[210:213], v[174:177], v[182:185], v[118:121]
	v_mfma_f32_16x16x32_bf16 v[182:185], v[174:177], v[186:189], v[102:105]
	s_nop 2
	ds_read_b128 v[102:105], v156 offset:4096
	ds_read_b128 v[118:121], v156 offset:5120
	v_mfma_f32_16x16x32_bf16 v[94:97], v[146:149], v[190:193], v[94:97]
	v_mfma_f32_16x16x32_bf16 v[90:93], v[170:173], v[190:193], v[90:93]
	v_mfma_f32_16x16x32_bf16 v[82:85], v[178:181], v[190:193], v[82:85]
	v_mfma_f32_16x16x32_bf16 v[78:81], v[146:149], v[194:197], v[78:81]
	v_mfma_f32_16x16x32_bf16 v[74:77], v[170:173], v[194:197], v[74:77]
	v_mfma_f32_16x16x32_bf16 v[66:69], v[178:181], v[194:197], v[66:69]
	v_mfma_f32_16x16x32_bf16 v[186:189], v[174:177], v[190:193], v[86:89]
	v_mfma_f32_16x16x32_bf16 v[190:193], v[174:177], v[194:197], v[70:73]
	s_nop 2
	ds_read_b128 v[70:73], v156 offset:6144
	ds_read_b128 v[86:89], v156 offset:7168
	s_waitcnt lgkmcnt(0)
	v_mfma_f32_16x16x32_bf16 v[62:65], v[146:149], v[102:105], v[62:65]
	v_mfma_f32_16x16x32_bf16 v[58:61], v[170:173], v[102:105], v[58:61]
	v_mfma_f32_16x16x32_bf16 v[50:53], v[178:181], v[102:105], v[50:53]
	v_mfma_f32_16x16x32_bf16 v[46:49], v[146:149], v[118:121], v[46:49]
	v_mfma_f32_16x16x32_bf16 v[42:45], v[170:173], v[118:121], v[42:45]
	v_mfma_f32_16x16x32_bf16 v[34:37], v[178:181], v[118:121], v[34:37]
	v_mfma_f32_16x16x32_bf16 v[194:197], v[174:177], v[102:105], v[54:57]
	v_mfma_f32_16x16x32_bf16 v[214:217], v[174:177], v[118:121], v[38:41]
	v_mfma_f32_16x16x32_bf16 v[30:33], v[146:149], v[70:73], v[30:33]
	v_mfma_f32_16x16x32_bf16 v[26:29], v[170:173], v[70:73], v[26:29]
	v_mfma_f32_16x16x32_bf16 v[18:21], v[178:181], v[70:73], v[18:21]
	v_mfma_f32_16x16x32_bf16 v[14:17], v[146:149], v[86:89], v[14:17]
	v_mfma_f32_16x16x32_bf16 v[10:13], v[170:173], v[86:89], v[10:13]
	v_mfma_f32_16x16x32_bf16 v[146:149], v[174:177], v[86:89], v[6:9]
	v_mfma_f32_16x16x32_bf16 v[2:5], v[178:181], v[86:89], v[2:5]
	v_mfma_f32_16x16x32_bf16 v[218:221], v[174:177], v[70:73], v[22:25]
	s_waitcnt vmcnt(0)
	s_waitcnt lgkmcnt(0)
	s_barrier
	ds_read_b128 v[6:9], v168 offset:40960
	ds_read_b128 v[170:173], v168 offset:41984
	ds_read_b128 v[174:177], v168 offset:43008
	ds_read_b128 v[178:181], v168 offset:44032
	ds_read_b128 v[22:25], v156 offset:24576
	ds_read_b128 v[38:41], v156 offset:25600
	ds_read_b128 v[54:57], v156 offset:26624
	ds_read_b128 v[222:225], v156 offset:27648
	s_waitcnt lgkmcnt(0)
	v_mfma_f32_16x16x32_bf16 v[126:129], v[6:9], v[22:25], v[126:129]
	v_mfma_f32_16x16x32_bf16 v[118:121], v[170:173], v[22:25], v[122:125]
	v_mfma_f32_16x16x32_bf16 v[122:125], v[174:177], v[22:25], v[210:213]
	v_mfma_f32_16x16x32_bf16 v[114:117], v[178:181], v[22:25], v[114:117]
	v_mfma_f32_16x16x32_bf16 v[110:113], v[6:9], v[38:41], v[110:113]
	v_mfma_f32_16x16x32_bf16 v[102:105], v[170:173], v[38:41], v[106:109]
	v_mfma_f32_16x16x32_bf16 v[106:109], v[174:177], v[38:41], v[182:185]
	v_mfma_f32_16x16x32_bf16 v[98:101], v[178:181], v[38:41], v[98:101]
	ds_read_b128 v[22:25], v156 offset:28672
	s_nop 0
	ds_read_b128 v[182:185], v156 offset:29696
	v_mfma_f32_16x16x32_bf16 v[94:97], v[6:9], v[54:57], v[94:97]
	v_mfma_f32_16x16x32_bf16 v[86:89], v[170:173], v[54:57], v[90:93]
	v_mfma_f32_16x16x32_bf16 v[90:93], v[174:177], v[54:57], v[186:189]
	v_mfma_f32_16x16x32_bf16 v[82:85], v[178:181], v[54:57], v[82:85]
	v_mfma_f32_16x16x32_bf16 v[78:81], v[6:9], v[222:225], v[78:81]
	v_mfma_f32_16x16x32_bf16 v[70:73], v[170:173], v[222:225], v[74:77]
	v_mfma_f32_16x16x32_bf16 v[74:77], v[174:177], v[222:225], v[190:193]
	v_mfma_f32_16x16x32_bf16 v[66:69], v[178:181], v[222:225], v[66:69]
	ds_read_b128 v[186:189], v156 offset:30720
	s_nop 0
	ds_read_b128 v[190:193], v156 offset:31744
	s_waitcnt lgkmcnt(0)
	v_mfma_f32_16x16x32_bf16 v[62:65], v[6:9], v[22:25], v[62:65]
	v_mfma_f32_16x16x32_bf16 v[54:57], v[170:173], v[22:25], v[58:61]
	v_mfma_f32_16x16x32_bf16 v[58:61], v[174:177], v[22:25], v[194:197]
	v_mfma_f32_16x16x32_bf16 v[50:53], v[178:181], v[22:25], v[50:53]
	v_mfma_f32_16x16x32_bf16 v[46:49], v[6:9], v[182:185], v[46:49]
	v_mfma_f32_16x16x32_bf16 v[38:41], v[170:173], v[182:185], v[42:45]
	v_mfma_f32_16x16x32_bf16 v[42:45], v[174:177], v[182:185], v[214:217]
	v_mfma_f32_16x16x32_bf16 v[34:37], v[178:181], v[182:185], v[34:37]
	v_mfma_f32_16x16x32_bf16 v[30:33], v[6:9], v[186:189], v[30:33]
	v_mfma_f32_16x16x32_bf16 v[22:25], v[170:173], v[186:189], v[26:29]
	v_mfma_f32_16x16x32_bf16 v[26:29], v[174:177], v[186:189], v[218:221]
	v_mfma_f32_16x16x32_bf16 v[18:21], v[178:181], v[186:189], v[18:21]
	v_mfma_f32_16x16x32_bf16 v[14:17], v[6:9], v[190:193], v[14:17]
	v_mfma_f32_16x16x32_bf16 v[6:9], v[170:173], v[190:193], v[10:13]
	v_mfma_f32_16x16x32_bf16 v[10:13], v[174:177], v[190:193], v[146:149]
	v_mfma_f32_16x16x32_bf16 v[2:5], v[178:181], v[190:193], v[2:5]
	s_nop 1
	v_add_u32_e32 v146, s9, v154
	s_waitcnt vmcnt(0)
	s_barrier
	v_readlane_b32 s4, v252, 1
	v_readlane_b32 s5, v252, 2
	v_ashrrev_i32_e32 v147, 31, v146
	v_mov_b32_e32 v150, 1.0
	s_and_b64 vcc, exec, s[4:5]
	v_mov_b32_e32 v152, 1.0
	s_cbranch_vccz .LBB0_138
	v_lshl_add_u64 v[148:149], v[146:147], 2, s[14:15]
	global_load_dword v147, v[148:149], off
	s_waitcnt vmcnt(0)
	v_fmamk_f32 v147, v147, 0x3a800000, v142
	v_mul_f32_e32 v148, 0x4b800000, v147
	v_cmp_gt_f32_e32 vcc, s69, v147
	s_nop 1
	v_cndmask_b32_e32 v147, v147, v148, vcc
	v_rsq_f32_e32 v147, v147
	s_nop 0
	v_mul_f32_e32 v148, 0x45800000, v147
	v_cndmask_b32_e32 v152, v147, v148, vcc

; template <int EPI, int MF>
; __device__ __forceinline__ void gemm_part(const u16* __restrict__ A, int lda, const u16* __restrict__ Bt, int K, int ntn, GemmEpi ep, char* smem,
;                                           int mbase, int mrows) {
;   const int tid = opaque_tid(), lane = tid & 63, wid = tid >> 6, wr = wid >> 1, wc = wid & 1, fr = lane & 15, fq = lane >> 4;
;   constexpr int BM = 32 * MF;
;   constexpr int STG = BM * 32 + 4096;
;   constexpr int NA = MF / 2;
;   u16* const sbase = (u16*)smem;
;   const int ntm = mrows / BM;
;   const int total = ntm * ntn;
;   const int nk = K / 32;
;   const int nbx = (MF == 2) ? (int)gridDim.x : (int)(gridDim.x >> 3);
;   const int xcd = (MF == 2) ? 0 : (int)(blockIdx.x & 7), li = (MF == 2) ? (int)blockIdx.x : (int)(blockIdx.x >> 3);
;   for (int q = xcd; q * nbx < total; q += (MF == 2) ? 1 : 8) {
;     const int L = q * nbx + li;
;     if (L >= total) continue;
;     const int g = L / (8 * ntn), rr = L % (8 * ntn);
;     const int rows = min(8, ntm - 8 * g);
;     const int tm = 8 * g + rr % rows, tn = rr / rows;
;     const int row0 = mbase + tm * BM, col0 = tn * 128;
;     f32x4 acc[MF][4];
; #pragma unroll
;     for (int m = 0; m < MF; ++m)
; #pragma unroll
;       for (int n = 0; n < 4; ++n) acc[m][n] = (f32x4){0.f, 0.f, 0.f, 0.f};
;     const u16* gA = A + (size_t)(row0 + (tid >> 2)) * lda + (tid & 3) * 8;
;     const u16* gB = Bt + (size_t)(col0 + (tid >> 2)) * K + (tid & 3) * 8;
;     ...
;     GEMM_ISSUE(0);
;     GEMM_ISSUE(1);
;     for (int kt = 0; kt < nk; ++kt) {
;       if (kt + 1 < nk) {
;         if (MF == 8) asm volatile("s_waitcnt vmcnt(6)" ::: "memory");
;         else asm volatile("s_waitcnt vmcnt(3)" ::: "memory");
;       } else asm volatile("s_waitcnt vmcnt(0)" ::: "memory");
;       asm volatile("s_waitcnt lgkmcnt(0)" ::: "memory");
;       __builtin_amdgcn_s_barrier();
;       const u16* a_ = sbase + (kt % 3) * STG;
;       const u16* b_ = a_ + BM * 32;
;       bf16x8 bfr[4], afc[2], afn[2];
; __global__ void __launch_bounds__(256, 2) fwd_megakernel(Params p) {
;     ...
;     ep = GemmEpi{};
;     if (layer == 0) { ep.res0 = p.x_prompt; ep.res1 = p.x_sample; } else { ep.res0 = xbuf; ep.res1 = xbuf + (size_t)MP * DM; }
;     ep.outf = xbuf; ep.scale = 0.5f; ep.xcopy = p.xn; ep.rss_out = rss_mix;
;     gemm_phase<EPI_RESID>(p.big, FF, p.wt_ffn_out[layer * 2 + 0], FF, DM / 128, ep, smem);
.LBB0_199:
	s_or_b64 exec, exec, s[2:3]
	v_readlane_b32 s4, v254, 63
	v_readlane_b32 s5, v252, 0
	s_and_b64 s[2:3], s[4:5], exec
	s_cselect_b32 s2, 0, 0xc1800
	v_readlane_b32 s8, v253, 26
	v_readlane_b32 s9, v253, 27
	s_add_u32 s66, s8, s2
	s_addc_u32 s67, s9, 0
	s_and_b64 s[2:3], s[4:5], exec
	v_readlane_b32 s2, v252, 3
	v_readlane_b32 s3, v252, 4
	s_barrier
	s_load_dwordx2 s[20:21], s[2:3], 0x100
	v_readlane_b32 s2, v253, 22
	v_readlane_b32 s10, v253, 28
	v_readlane_b32 s11, v253, 29
	v_readlane_b32 s3, v253, 23
	v_readlane_b32 s8, v254, 21
	v_readlane_b32 s9, v254, 22
	v_cndmask_b32_e64 v1, 0, 1, s[2:3]
	v_readlane_b32 s10, v254, 23
	v_readlane_b32 s11, v254, 24
	v_cmp_ne_u32_e64 s[4:5], 1, v1
	s_cselect_b32 s9, s9, s27
	s_cselect_b32 s8, s8, s26
	s_cselect_b32 s19, s11, s73
	s_cselect_b32 s18, s10, s72
	v_mov_b32_e32 v2, v140
	v_writelane_b32 v252, s4, 7
	s_andn2_b64 vcc, exec, s[2:3]
	v_readlane_b32 s12, v254, 25
	v_readlane_b32 s13, v254, 26
	v_readlane_b32 s14, v254, 27
	v_readlane_b32 s15, v254, 28
	v_writelane_b32 v252, s5, 8
	s_cbranch_vccnz .LBB0_333
	v_lshlrev_b32_e32 v7, 4, v2
	v_bfe_u32 v3, v2, 4, 2
	v_lshrrev_b32_e32 v100, 4, v140
	v_sub_u32_e32 v100, 0, v100
	v_xor_b32_e32 v100, v100, v140
	v_and_b32_e32 v100, 3, v100
	v_lshlrev_b32_e32 v4, 4, v100
	v_mov_b32_e32 v5, v0
	v_bfe_u32 v6, v2, 6, 1
	v_lshl_add_u64 v[130:131], s[46:47], 0, v[4:5]
	s_waitcnt lgkmcnt(0)
	v_lshl_add_u64 v[132:133], s[20:21], 0, v[4:5]
	v_lshlrev_b32_e32 v4, 2, v3
	v_lshlrev_b32_e32 v155, 3, v3
	v_lshl_or_b32 v157, v6, 6, v4
	v_cmp_eq_u32_e64 s[12:13], 0, v3
	v_lshlrev_b32_e32 v158, 12, v6
	v_lshlrev_b32_e32 v4, 6, v2
	s_add_i32 s2, 0, 0x10000
	v_lshrrev_b32_e32 v101, 2, v140
	v_sub_u32_e32 v101, 0, v101
	v_lshrrev_b32_e32 v3, 4, v140
	v_xor_b32_e32 v101, v101, v3
	v_and_b32_e32 v101, 3, v101
	v_lshlrev_b32_e32 v3, 4, v101
	v_ashrrev_i32_e32 v1, 2, v2
	v_and_b32_e32 v156, 0xffffff8f, v2
	v_and_b32_e32 v159, 0x3c0, v4
	v_and_b32_e32 v160, 0xffffe3c0, v4
	v_add3_u32 v4, s2, v3, v158
	v_add_u32_e32 v161, 0, v3
	v_and_b32_e32 v2, 3, v2
	v_readlane_b32 s2, v254, 2
	v_add_u32_e32 v154, 0, v7
	v_add_u32_e32 v162, v161, v160
	v_lshlrev_b32_e32 v134, 4, v100
	v_mov_b32_e32 v135, v0
	v_add_u32_e32 v163, s2, v1
	v_or_b32_e32 v164, v158, v159
	v_add_u32_e32 v165, v4, v159
	v_readlane_b32 s4, v254, 1
	v_readlane_b32 s5, v254, 0
	v_readlane_b32 s2, v253, 56
	v_readlane_b32 s10, v253, 9
	s_branch .LBB0_203

; #define MFMA(a, b, c) __builtin_amdgcn_mfma_f32_16x16x32_bf16((a), (b), (c), 0, 0, 0)
; template <int EPI, int MF>
; __device__ __forceinline__ void gemm_part(const u16* __restrict__ A, int lda, const u16* __restrict__ Bt, int K, int ntn, GemmEpi ep, char* smem,
;                                           int mbase, int mrows) {
;     ...
;     for (int kt = 0; kt < nk; ++kt) {
;       if (kt + 1 < nk) {
;         if (MF == 8) asm volatile("s_waitcnt vmcnt(6)" ::: "memory");
;         else asm volatile("s_waitcnt vmcnt(3)" ::: "memory");
;       } else asm volatile("s_waitcnt vmcnt(0)" ::: "memory");
;       asm volatile("s_waitcnt lgkmcnt(0)" ::: "memory");
;       __builtin_amdgcn_s_barrier();
;       const u16* a_ = sbase + (kt % 3) * STG;
;       const u16* b_ = a_ + BM * 32;
;       bf16x8 bfr[4], afc[2], afn[2];
;       const u16* ap_ = a_ + (wr * (16 * MF) + fr) * 32 + fq * 8;
; #pragma unroll
;       for (int n = 0; n < 4; ++n) bfr[n] = rd_std(b_ + (wc * 64 + n * 16 + fr) * 32 + fq * 8);
;       afc[0] = rd_std(ap_); afc[1] = rd_std(ap_ + 16 * 32);
;       __builtin_amdgcn_sched_barrier(0);
;       if (kt + 2 < nk) GEMM_ISSUE(kt + 2);
;       __builtin_amdgcn_sched_barrier(0);
; #pragma unroll
;       for (int mh = 0; mh < MF / 2; ++mh) {
;         if (mh + 1 < MF / 2) {
;           afn[0] = rd_std(ap_ + ((mh + 1) * 2) * 16 * 32);
;           afn[1] = rd_std(ap_ + ((mh + 1) * 2 + 1) * 16 * 32);
;         }
;         __builtin_amdgcn_sched_barrier(0);
; #pragma unroll
;         for (int m = 0; m < 2; ++m)
; #pragma unroll
;           for (int n = 0; n < 4; ++n) acc[mh * 2 + m][n] = MFMA(bfr[n], afc[m], acc[mh * 2 + m][n]);
;         __builtin_amdgcn_sched_barrier(0);
;         afc[0] = afn[0]; afc[1] = afn[1];
;       }
.LBB0_205:
	s_mul_hi_u32 s17, s16, 0xaaaaaaab
	s_lshr_b32 s17, s17, 1
	s_mul_i32 s17, s17, 0x12000
	v_add_u32_e32 v146, s3, v161
	v_subrev_u32_e32 v147, s17, v164
	s_waitcnt vmcnt(6)
	v_subrev_u32_e32 v148, s17, v160
	v_add_u32_e32 v170, v146, v147
	s_waitcnt lgkmcnt(0)
	s_barrier
	v_add_u32_e32 v190, v146, v148
	ds_read_b128 v[146:149], v170 offset:16384
	ds_read_b128 v[150:153], v170 offset:17408
	ds_read_b128 v[166:169], v170 offset:18432
	ds_read_b128 v[170:173], v170 offset:19456
	ds_read_b128 v[174:177], v190
	ds_read_b128 v[178:181], v190 offset:1024
	s_mul_hi_u32 s17, s15, 0xaaaaaaab
	s_add_i32 s16, s16, 1
	s_lshr_b32 s17, s17, 1
	s_mul_i32 s17, s17, 0x12000
	s_sub_i32 s17, s3, s17
	s_add_i32 s22, s17, 0xc000
	v_add_u32_e32 v186, s22, v154
	v_lshl_add_u64 v[182:183], v[136:137], 0, v[134:135]
	v_readfirstlane_b32 s22, v186
	s_mov_b32 m0, s22
	s_add_i32 s22, s17, 0xd000
	v_add_u32_e32 v186, s22, v154
	v_lshl_add_u64 v[184:185], v[182:183], 0, s[74:75]
	v_readfirstlane_b32 s22, v186
	global_load_lds_dwordx4 v[184:185], off
	s_mov_b32 m0, s22
	s_add_i32 s22, s17, 0xe000
	v_add_u32_e32 v186, s22, v154
	v_lshl_add_u64 v[184:185], v[182:183], 0, s[56:57]
	v_readfirstlane_b32 s22, v186
	global_load_lds_dwordx4 v[184:185], off
	v_lshl_add_u64 v[184:185], v[182:183], 0, s[58:59]
	s_mov_b32 m0, s22
	s_add_i32 s22, s17, 0xf000
	global_load_lds_dwordx4 v[184:185], off
	v_add_u32_e32 v184, s22, v154
	v_lshl_add_u64 v[182:183], v[182:183], 0, s[86:87]
	v_readfirstlane_b32 s22, v184
	s_mov_b32 m0, s22
	s_add_i32 s22, s17, 0x10000
	v_add_u32_e32 v186, s22, v154
	global_load_lds_dwordx4 v[182:183], off
	v_lshl_add_u64 v[182:183], v[138:139], 0, v[134:135]
	v_readfirstlane_b32 s22, v186
	v_lshl_add_u64 v[184:185], v[182:183], 0, s[74:75]
	s_mov_b32 m0, s22
	s_add_i32 s17, s17, 0x11000
	global_load_lds_dwordx4 v[184:185], off
	v_add_u32_e32 v184, s17, v154
	v_lshl_add_u64 v[182:183], v[182:183], 0, s[56:57]
	v_readfirstlane_b32 s17, v184
	s_mov_b32 m0, s17
	s_nop 0
	global_load_lds_dwordx4 v[182:183], off
	ds_read_b128 v[182:185], v190 offset:3072
	ds_read_b128 v[186:189], v190 offset:2048
	s_waitcnt lgkmcnt(2)
	v_mfma_f32_16x16x32_bf16 v[126:129], v[146:149], v[174:177], v[126:129]
	v_mfma_f32_16x16x32_bf16 v[122:125], v[150:153], v[174:177], v[122:125]
	v_mfma_f32_16x16x32_bf16 v[118:121], v[166:169], v[174:177], v[118:121]
	v_mfma_f32_16x16x32_bf16 v[114:117], v[170:173], v[174:177], v[114:117]
	v_mfma_f32_16x16x32_bf16 v[110:113], v[146:149], v[178:181], v[110:113]
	v_mfma_f32_16x16x32_bf16 v[106:109], v[150:153], v[178:181], v[106:109]
	v_mfma_f32_16x16x32_bf16 v[102:105], v[166:169], v[178:181], v[102:105]
	v_mfma_f32_16x16x32_bf16 v[98:101], v[170:173], v[178:181], v[98:101]
	ds_read_b128 v[174:177], v190 offset:5120
	ds_read_b128 v[178:181], v190 offset:4096
	s_waitcnt lgkmcnt(2)
	v_mfma_f32_16x16x32_bf16 v[94:97], v[146:149], v[186:189], v[94:97]
	v_mfma_f32_16x16x32_bf16 v[90:93], v[150:153], v[186:189], v[90:93]
	v_mfma_f32_16x16x32_bf16 v[86:89], v[166:169], v[186:189], v[86:89]
	v_mfma_f32_16x16x32_bf16 v[82:85], v[170:173], v[186:189], v[82:85]
	v_mfma_f32_16x16x32_bf16 v[78:81], v[146:149], v[182:185], v[78:81]
	v_mfma_f32_16x16x32_bf16 v[74:77], v[150:153], v[182:185], v[74:77]
	v_mfma_f32_16x16x32_bf16 v[70:73], v[166:169], v[182:185], v[70:73]
	v_mfma_f32_16x16x32_bf16 v[66:69], v[170:173], v[182:185], v[66:69]
	ds_read_b128 v[182:185], v190 offset:7168
	ds_read_b128 v[186:189], v190 offset:6144
	s_waitcnt lgkmcnt(2)
	v_mfma_f32_16x16x32_bf16 v[62:65], v[146:149], v[178:181], v[62:65]
	v_mfma_f32_16x16x32_bf16 v[58:61], v[150:153], v[178:181], v[58:61]
	v_mfma_f32_16x16x32_bf16 v[54:57], v[166:169], v[178:181], v[54:57]
	v_mfma_f32_16x16x32_bf16 v[50:53], v[170:173], v[178:181], v[50:53]
	v_mfma_f32_16x16x32_bf16 v[46:49], v[146:149], v[174:177], v[46:49]
	v_mfma_f32_16x16x32_bf16 v[42:45], v[150:153], v[174:177], v[42:45]
	v_mfma_f32_16x16x32_bf16 v[38:41], v[166:169], v[174:177], v[38:41]
	v_mfma_f32_16x16x32_bf16 v[34:37], v[170:173], v[174:177], v[34:37]
	s_waitcnt lgkmcnt(0)
	v_mfma_f32_16x16x32_bf16 v[30:33], v[146:149], v[186:189], v[30:33]
	v_mfma_f32_16x16x32_bf16 v[26:29], v[150:153], v[186:189], v[26:29]
	v_mfma_f32_16x16x32_bf16 v[22:25], v[166:169], v[186:189], v[22:25]
	v_mfma_f32_16x16x32_bf16 v[18:21], v[170:173], v[186:189], v[18:21]
	v_mfma_f32_16x16x32_bf16 v[14:17], v[146:149], v[182:185], v[14:17]
	v_mfma_f32_16x16x32_bf16 v[10:13], v[150:153], v[182:185], v[10:13]
	v_mfma_f32_16x16x32_bf16 v[6:9], v[166:169], v[182:185], v[6:9]
	v_mfma_f32_16x16x32_bf16 v[2:5], v[170:173], v[182:185], v[2:5]
	s_addk_i32 s3, 0x6000
	s_add_i32 s14, s14, 1
	s_add_i32 s15, s15, 1
	v_lshl_add_u64 v[136:137], v[136:137], 0, 64
	v_lshl_add_u64 v[136:137], v[136:137], 0, 64
	s_cmp_eq_u32 s3, 0x204000
	v_lshl_add_u64 v[138:139], v[138:139], 0, 64
	v_lshl_add_u64 v[138:139], v[138:139], 0, 64
	s_cbranch_scc0 .LBB0_205
	s_waitcnt vmcnt(6)
	s_waitcnt lgkmcnt(0)
	s_barrier
; #define MFMA(a, b, c) __builtin_amdgcn_mfma_f32_16x16x32_bf16((a), (b), (c), 0, 0, 0)
; template <int EPI, int MF>
; __device__ __forceinline__ void gemm_part(const u16* __restrict__ A, int lda, const u16* __restrict__ Bt, int K, int ntn, GemmEpi ep, char* smem,
;                                           int mbase, int mrows) {
;     ...
;     for (int kt = 0; kt < nk; ++kt) {
;       if (kt + 1 < nk) {
;         if (MF == 8) asm volatile("s_waitcnt vmcnt(6)" ::: "memory");
;         else asm volatile("s_waitcnt vmcnt(3)" ::: "memory");
;       } else asm volatile("s_waitcnt vmcnt(0)" ::: "memory");
;       asm volatile("s_waitcnt lgkmcnt(0)" ::: "memory");
;       __builtin_amdgcn_s_barrier();
;       const u16* a_ = sbase + (kt % 3) * STG;
;       const u16* b_ = a_ + BM * 32;
;       bf16x8 bfr[4], afc[2], afn[2];
;       const u16* ap_ = a_ + (wr * (16 * MF) + fr) * 32 + fq * 8;
; #pragma unroll
;       for (int n = 0; n < 4; ++n) bfr[n] = rd_std(b_ + (wc * 64 + n * 16 + fr) * 32 + fq * 8);
;       afc[0] = rd_std(ap_); afc[1] = rd_std(ap_ + 16 * 32);
;       __builtin_amdgcn_sched_barrier(0);
;       if (kt + 2 < nk) GEMM_ISSUE(kt + 2);
;       __builtin_amdgcn_sched_barrier(0);
; #pragma unroll
;       for (int mh = 0; mh < MF / 2; ++mh) {
;         if (mh + 1 < MF / 2) {
;           afn[0] = rd_std(ap_ + ((mh + 1) * 2) * 16 * 32);
;           afn[1] = rd_std(ap_ + ((mh + 1) * 2 + 1) * 16 * 32);
;         }
;         __builtin_amdgcn_sched_barrier(0);
; #pragma unroll
;         for (int m = 0; m < 2; ++m)
; #pragma unroll
;           for (int n = 0; n < 4; ++n) acc[mh * 2 + m][n] = MFMA(bfr[n], afc[m], acc[mh * 2 + m][n]);
;         __builtin_amdgcn_sched_barrier(0);
;         afc[0] = afn[0]; afc[1] = afn[1];
;       }
	ds_read_b128 v[136:139], v165
	ds_read_b128 v[146:149], v165 offset:1024
	ds_read_b128 v[150:153], v165 offset:2048
	ds_read_b128 v[166:169], v165 offset:3072
	ds_read_b128 v[170:173], v162 offset:49152
	ds_read_b128 v[174:177], v162 offset:50176
	s_mul_hi_u32 s14, s14, 0xaaaaaaab
	s_lshr_b32 s14, s14, 1
	s_mul_i32 s14, s14, 0x12000
	s_sub_i32 s3, s3, s14
	s_add_i32 s3, s3, 0
	s_addk_i32 s3, 0x6000
	ds_read_b128 v[178:181], v162 offset:52224
	ds_read_b128 v[182:185], v162 offset:51200
	s_waitcnt lgkmcnt(0)
	v_mfma_f32_16x16x32_bf16 v[126:129], v[136:139], v[170:173], v[126:129]
	v_mfma_f32_16x16x32_bf16 v[122:125], v[146:149], v[170:173], v[122:125]
	v_mfma_f32_16x16x32_bf16 v[118:121], v[150:153], v[170:173], v[118:121]
	v_mfma_f32_16x16x32_bf16 v[114:117], v[166:169], v[170:173], v[114:117]
	v_mfma_f32_16x16x32_bf16 v[110:113], v[136:139], v[174:177], v[110:113]
	v_mfma_f32_16x16x32_bf16 v[106:109], v[146:149], v[174:177], v[106:109]
	v_mfma_f32_16x16x32_bf16 v[102:105], v[150:153], v[174:177], v[102:105]
	v_mfma_f32_16x16x32_bf16 v[98:101], v[166:169], v[174:177], v[98:101]
	ds_read_b128 v[170:173], v162 offset:54272
	ds_read_b128 v[174:177], v162 offset:53248
	v_mfma_f32_16x16x32_bf16 v[94:97], v[136:139], v[182:185], v[94:97]
	v_mfma_f32_16x16x32_bf16 v[90:93], v[146:149], v[182:185], v[90:93]
	v_mfma_f32_16x16x32_bf16 v[86:89], v[150:153], v[182:185], v[86:89]
	v_mfma_f32_16x16x32_bf16 v[82:85], v[166:169], v[182:185], v[82:85]
	v_mfma_f32_16x16x32_bf16 v[78:81], v[136:139], v[178:181], v[78:81]
	v_mfma_f32_16x16x32_bf16 v[74:77], v[146:149], v[178:181], v[74:77]
	v_mfma_f32_16x16x32_bf16 v[70:73], v[150:153], v[178:181], v[70:73]
	v_mfma_f32_16x16x32_bf16 v[66:69], v[166:169], v[178:181], v[66:69]
	ds_read_b128 v[178:181], v162 offset:56320
	ds_read_b128 v[182:185], v162 offset:55296
	s_waitcnt lgkmcnt(0)
	v_mfma_f32_16x16x32_bf16 v[62:65], v[136:139], v[174:177], v[62:65]
	v_mfma_f32_16x16x32_bf16 v[58:61], v[146:149], v[174:177], v[58:61]
	v_mfma_f32_16x16x32_bf16 v[54:57], v[150:153], v[174:177], v[54:57]
	v_mfma_f32_16x16x32_bf16 v[50:53], v[166:169], v[174:177], v[50:53]
	v_mfma_f32_16x16x32_bf16 v[46:49], v[136:139], v[170:173], v[46:49]
	v_mfma_f32_16x16x32_bf16 v[42:45], v[146:149], v[170:173], v[42:45]
	v_mfma_f32_16x16x32_bf16 v[38:41], v[150:153], v[170:173], v[38:41]
	v_mfma_f32_16x16x32_bf16 v[34:37], v[166:169], v[170:173], v[34:37]
	v_mfma_f32_16x16x32_bf16 v[30:33], v[136:139], v[182:185], v[30:33]
	v_mfma_f32_16x16x32_bf16 v[26:29], v[146:149], v[182:185], v[26:29]
	v_mfma_f32_16x16x32_bf16 v[22:25], v[150:153], v[182:185], v[22:25]
	v_mfma_f32_16x16x32_bf16 v[18:21], v[166:169], v[182:185], v[18:21]
	v_mfma_f32_16x16x32_bf16 v[14:17], v[136:139], v[178:181], v[14:17]
	v_mfma_f32_16x16x32_bf16 v[10:13], v[146:149], v[178:181], v[10:13]
	v_mfma_f32_16x16x32_bf16 v[6:9], v[150:153], v[178:181], v[6:9]
	v_mfma_f32_16x16x32_bf16 v[2:5], v[166:169], v[178:181], v[2:5]
	v_add_u32_e32 v136, s3, v161
	s_waitcnt vmcnt(0)
	v_add3_u32 v166, v136, v158, v159
	s_waitcnt lgkmcnt(0)
	s_barrier
	ds_read_b128 v[136:139], v166 offset:16384
	ds_read_b128 v[146:149], v166 offset:17408
	ds_read_b128 v[150:153], v166 offset:18432
	ds_read_b128 v[166:169], v166 offset:19456
	ds_read_b128 v[170:173], v162
	ds_read_b128 v[174:177], v162 offset:1024
	ds_read_b128 v[178:181], v162 offset:3072
	ds_read_b128 v[182:185], v162 offset:2048
	s_waitcnt lgkmcnt(0)
	v_mfma_f32_16x16x32_bf16 v[126:129], v[136:139], v[170:173], v[126:129]
	v_mfma_f32_16x16x32_bf16 v[122:125], v[146:149], v[170:173], v[122:125]
	v_mfma_f32_16x16x32_bf16 v[118:121], v[150:153], v[170:173], v[118:121]
	v_mfma_f32_16x16x32_bf16 v[114:117], v[166:169], v[170:173], v[114:117]
	v_mfma_f32_16x16x32_bf16 v[110:113], v[136:139], v[174:177], v[110:113]
	v_mfma_f32_16x16x32_bf16 v[106:109], v[146:149], v[174:177], v[106:109]
	v_mfma_f32_16x16x32_bf16 v[102:105], v[150:153], v[174:177], v[102:105]
	v_mfma_f32_16x16x32_bf16 v[98:101], v[166:169], v[174:177], v[98:101]
	ds_read_b128 v[170:173], v162 offset:5120
	ds_read_b128 v[174:177], v162 offset:4096
	v_mfma_f32_16x16x32_bf16 v[94:97], v[136:139], v[182:185], v[94:97]
	v_mfma_f32_16x16x32_bf16 v[90:93], v[146:149], v[182:185], v[90:93]
	v_mfma_f32_16x16x32_bf16 v[86:89], v[150:153], v[182:185], v[86:89]
	v_mfma_f32_16x16x32_bf16 v[82:85], v[166:169], v[182:185], v[82:85]
	v_mfma_f32_16x16x32_bf16 v[78:81], v[136:139], v[178:181], v[78:81]
	v_mfma_f32_16x16x32_bf16 v[74:77], v[146:149], v[178:181], v[74:77]
	v_mfma_f32_16x16x32_bf16 v[70:73], v[150:153], v[178:181], v[70:73]
	v_mfma_f32_16x16x32_bf16 v[66:69], v[166:169], v[178:181], v[66:69]
	ds_read_b128 v[178:181], v162 offset:7168
	ds_read_b128 v[182:185], v162 offset:6144
	s_waitcnt lgkmcnt(0)
	v_mfma_f32_16x16x32_bf16 v[62:65], v[136:139], v[174:177], v[62:65]
	v_mfma_f32_16x16x32_bf16 v[58:61], v[146:149], v[174:177], v[58:61]
	v_mfma_f32_16x16x32_bf16 v[54:57], v[150:153], v[174:177], v[54:57]
	v_mfma_f32_16x16x32_bf16 v[50:53], v[166:169], v[174:177], v[50:53]
	v_mfma_f32_16x16x32_bf16 v[46:49], v[136:139], v[170:173], v[46:49]
	v_mfma_f32_16x16x32_bf16 v[42:45], v[146:149], v[170:173], v[42:45]
	v_mfma_f32_16x16x32_bf16 v[38:41], v[150:153], v[170:173], v[38:41]
	v_mfma_f32_16x16x32_bf16 v[34:37], v[166:169], v[170:173], v[34:37]
	v_mfma_f32_16x16x32_bf16 v[30:33], v[136:139], v[182:185], v[30:33]
	v_mfma_f32_16x16x32_bf16 v[26:29], v[146:149], v[182:185], v[26:29]
	v_mfma_f32_16x16x32_bf16 v[22:25], v[150:153], v[182:185], v[22:25]
	v_mfma_f32_16x16x32_bf16 v[18:21], v[166:169], v[182:185], v[18:21]
	v_mfma_f32_16x16x32_bf16 v[14:17], v[136:139], v[178:181], v[14:17]
	v_mfma_f32_16x16x32_bf16 v[10:13], v[146:149], v[178:181], v[10:13]
	v_mfma_f32_16x16x32_bf16 v[6:9], v[150:153], v[178:181], v[6:9]
	v_mfma_f32_16x16x32_bf16 v[2:5], v[166:169], v[178:181], v[2:5]
	v_add_u32_e32 v138, s2, v156
	s_waitcnt vmcnt(0)
	s_barrier
; template <int EPI, int MF>
; __device__ __forceinline__ void gemm_part(const u16* __restrict__ A, int lda, const u16* __restrict__ Bt, int K, int ntn, GemmEpi ep, char* smem,
;                                           int mbase, int mrows) {
;     ...
;       } else if (EPI == EPI_RESID) {
;         const float* rp = (row < MP) ? ep.res0 + (size_t)row * DM : ep.res1 + (size_t)(row - MP) * DM;
;         float ssq = 0.f;
; #pragma unroll
;         for (int n = 0; n < 4; ++n) {
;           const int col = cb + n * 16;
;           const float4 r = *(const float4*)(rp + col);
;           float4 v;
;           v.x = r.x + ep.scale * acc[m][n][0]; v.y = r.y + ep.scale * acc[m][n][1];
;           v.z = r.z + ep.scale * acc[m][n][2]; v.w = r.w + ep.scale * acc[m][n][3];
;           *(float4*)(ep.outf + (size_t)row * DM + col) = v;
;           if (ep.xcopy) {
;             bf16x4 o;
;             o[0] = (short)f2bf(v.x); o[1] = (short)f2bf(v.y); o[2] = (short)f2bf(v.z); o[3] = (short)f2bf(v.w);
;             *(bf16x4*)(ep.xcopy + (size_t)row * DM + col) = o;
;           }
;           ssq += v.x * v.x + v.y * v.y + v.z * v.z + v.w * v.w;
;         }
	s_mov_b32 s2, 0xffff
	v_cmp_lt_i32_e32 vcc, s2, v138
	s_and_saveexec_b64 s[2:3], vcc
	s_xor_b64 s[2:3], exec, s[2:3]
	v_add_u32_e32 v136, 0xffff0000, v138
	v_mov_b32_e32 v137, v0
	v_lshlrev_b64 v[136:137], 12, v[136:137]
	v_lshl_add_u64 v[136:137], s[18:19], 0, v[136:137]
	v_mov_b32_e32 v139, v0
	s_andn2_saveexec_b64 s[2:3], s[2:3]
	v_ashrrev_i32_e32 v139, 31, v138
	v_lshlrev_b64 v[136:137], 12, v[138:139]
	v_lshl_add_u64 v[136:137], s[8:9], 0, v[136:137]
	s_or_b64 exec, exec, s[2:3]
	v_lshlrev_b64 v[146:147], 12, v[138:139]
	v_or_b32_e32 v170, s11, v157
	v_lshl_add_u64 v[150:151], s[26:27], 0, v[146:147]
	v_lshlrev_b64 v[146:147], 11, v[138:139]
	v_lshl_add_u64 v[148:149], s[44:45], 0, v[146:147]
	v_lshlrev_b32_e32 v146, 2, v170
	v_mov_b32_e32 v147, v0
	v_lshl_add_u64 v[152:153], v[136:137], 0, v[146:147]
	global_load_dwordx4 v[166:169], v[152:153], off
	global_load_dwordx4 v[172:175], v[152:153], off offset:64
	global_load_dwordx4 v[176:179], v[152:153], off offset:128
	global_load_dwordx4 v[180:183], v[152:153], off offset:192
	v_readlane_b32 s2, v253, 24
	v_readlane_b32 s3, v253, 25
	v_lshl_add_u64 v[150:151], v[150:151], 0, v[146:147]
	s_andn2_b64 vcc, exec, s[2:3]
	v_cndmask_b32_e64 v136, 0, 1, s[2:3]
	v_cmp_ne_u32_e64 s[14:15], 1, v136
	v_lshlrev_b32_e32 v136, 1, v170
	s_waitcnt vmcnt(0)
	v_pk_fma_f32 v[126:127], v[126:127], 0.5, v[166:167] op_sel_hi:[1,0,1]
	v_pk_fma_f32 v[128:129], v[128:129], 0.5, v[168:169] op_sel_hi:[1,0,1]
	global_store_dwordx4 v[150:151], v[126:129], off
	s_cbranch_vccnz .LBB0_212
	v_mov_b32_e32 v137, v0
	v_cvt_pk_bf16_f32 v166, v126, v127
	v_cvt_pk_bf16_f32 v167, v128, v129
	v_lshl_add_u64 v[168:169], v[148:149], 0, v[136:137]
	v_lshlrev_b32_e32 v184, 1, v168
	v_bfi_b32 v184, s100, v184, v168
	v_lshrrev_b32_e32 v185, 5, v168
	v_bfi_b32 v184, 64, v185, v184
	v_mov_b32_e32 v185, v169
	global_store_dwordx2 v[184:185], v[166:167], off
.LBB0_212:
	s_nop 0
	s_and_b64 vcc, exec, s[14:15]
	s_nop 0
	v_pk_fma_f32 v[122:123], v[122:123], 0.5, v[172:173] op_sel_hi:[1,0,1]
	v_pk_fma_f32 v[124:125], v[124:125], 0.5, v[174:175] op_sel_hi:[1,0,1]
	global_store_dwordx4 v[150:151], v[122:125], off offset:64
	s_cbranch_vccnz .LBB0_214
	v_mov_b32_e32 v137, v0
	v_cvt_pk_bf16_f32 v166, v122, v123
	v_cvt_pk_bf16_f32 v167, v124, v125
	v_lshl_add_u64 v[168:169], v[148:149], 0, v[136:137]
	v_lshlrev_b32_e32 v184, 1, v168
	v_bfi_b32 v184, s100, v184, v168
	v_lshrrev_b32_e32 v185, 5, v168
	v_bfi_b32 v184, 64, v185, v184
	v_mov_b32_e32 v185, v169
	global_store_dwordx2 v[184:185], v[166:167], off offset:32
.LBB0_214:
	s_nop 0
	s_and_b64 vcc, exec, s[14:15]
	s_nop 0
	v_pk_fma_f32 v[118:119], v[118:119], 0.5, v[176:177] op_sel_hi:[1,0,1]
	v_pk_fma_f32 v[120:121], v[120:121], 0.5, v[178:179] op_sel_hi:[1,0,1]
	global_store_dwordx4 v[150:151], v[118:121], off offset:128
	s_cbranch_vccnz .LBB0_216
	v_mov_b32_e32 v137, v0
	v_cvt_pk_bf16_f32 v166, v118, v119
	v_cvt_pk_bf16_f32 v167, v120, v121
	v_lshl_add_u64 v[168:169], v[148:149], 0, v[136:137]
	v_lshlrev_b32_e32 v184, 1, v168
	v_bfi_b32 v184, s100, v184, v168
	v_lshrrev_b32_e32 v185, 5, v168
	v_bfi_b32 v184, 64, v185, v184
	v_mov_b32_e32 v185, v169
	global_store_dwordx2 v[184:185], v[166:167], off offset:128
.LBB0_216:
	s_nop 0
	s_and_b64 vcc, exec, s[14:15]
	s_nop 0
	v_pk_fma_f32 v[114:115], v[114:115], 0.5, v[180:181] op_sel_hi:[1,0,1]
	v_pk_fma_f32 v[116:117], v[116:117], 0.5, v[182:183] op_sel_hi:[1,0,1]
	global_store_dwordx4 v[150:151], v[114:117], off offset:192
	s_cbranch_vccnz .LBB0_218
	v_mov_b32_e32 v137, v0
	v_cvt_pk_bf16_f32 v150, v114, v115
	v_cvt_pk_bf16_f32 v151, v116, v117
	v_lshl_add_u64 v[148:149], v[148:149], 0, v[136:137]
	v_lshlrev_b32_e32 v184, 1, v148
	v_bfi_b32 v184, s100, v184, v148
	v_lshrrev_b32_e32 v185, 5, v148
	v_bfi_b32 v184, 64, v185, v184
	v_mov_b32_e32 v185, v149
	global_store_dwordx2 v[184:185], v[150:151], off offset:160

; template <int EPI, int MF>
; __device__ __forceinline__ void gemm_part(const u16* __restrict__ A, int lda, const u16* __restrict__ Bt, int K, int ntn, GemmEpi ep, char* smem,
;                                           int mbase, int mrows) {
;     ...
;       } else if (EPI == EPI_RESID) {
;         const float* rp = (row < MP) ? ep.res0 + (size_t)row * DM : ep.res1 + (size_t)(row - MP) * DM;
;         float ssq = 0.f;
; #pragma unroll
;         for (int n = 0; n < 4; ++n) {
;           const int col = cb + n * 16;
;           const float4 r = *(const float4*)(rp + col);
;           float4 v;
;           v.x = r.x + ep.scale * acc[m][n][0]; v.y = r.y + ep.scale * acc[m][n][1];
;           v.z = r.z + ep.scale * acc[m][n][2]; v.w = r.w + ep.scale * acc[m][n][3];
;           *(float4*)(ep.outf + (size_t)row * DM + col) = v;
;           if (ep.xcopy) {
;             bf16x4 o;
;             o[0] = (short)f2bf(v.x); o[1] = (short)f2bf(v.y); o[2] = (short)f2bf(v.z); o[3] = (short)f2bf(v.w);
;             *(bf16x4*)(ep.xcopy + (size_t)row * DM + col) = o;
;           }
;           ssq += v.x * v.x + v.y * v.y + v.z * v.z + v.w * v.w;
;         }
.LBB0_222:
	s_waitcnt lgkmcnt(0)
	v_or_b32_e32 v114, 16, v138
	s_mov_b32 s2, 0xffff
	v_cmp_lt_i32_e32 vcc, s2, v114
	s_and_saveexec_b64 s[2:3], vcc
	s_xor_b64 s[2:3], exec, s[2:3]
	v_add_u32_e32 v116, 0xffff0010, v138
	v_mov_b32_e32 v117, v0
	v_lshlrev_b64 v[116:117], 12, v[116:117]
	v_lshl_add_u64 v[116:117], s[18:19], 0, v[116:117]
	v_mov_b32_e32 v115, v0
	s_andn2_saveexec_b64 s[2:3], s[2:3]
	v_ashrrev_i32_e32 v115, 31, v114
	v_lshlrev_b64 v[116:117], 12, v[114:115]
	v_lshl_add_u64 v[116:117], s[8:9], 0, v[116:117]
	s_or_b64 exec, exec, s[2:3]
	v_mov_b32_e32 v147, v0
	v_lshl_add_u64 v[120:121], v[116:117], 0, v[146:147]
	global_load_dwordx4 v[122:125], v[120:121], off
	global_load_dwordx4 v[172:175], v[120:121], off offset:64
	global_load_dwordx4 v[176:179], v[120:121], off offset:128
	global_load_dwordx4 v[180:183], v[120:121], off offset:192
	v_lshlrev_b64 v[116:117], 12, v[114:115]
	v_lshlrev_b64 v[118:119], 11, v[114:115]
	v_lshl_add_u64 v[126:127], s[26:27], 0, v[116:117]
	v_lshl_add_u64 v[116:117], s[44:45], 0, v[118:119]
	v_lshl_add_u64 v[118:119], v[126:127], 0, v[146:147]
	s_and_b64 vcc, exec, s[14:15]
	s_waitcnt vmcnt(0)
	v_pk_fma_f32 v[110:111], v[110:111], 0.5, v[122:123] op_sel_hi:[1,0,1]
	v_pk_fma_f32 v[112:113], v[112:113], 0.5, v[124:125] op_sel_hi:[1,0,1]
	global_store_dwordx4 v[118:119], v[110:113], off
	s_cbranch_vccnz .LBB0_228
	v_mov_b32_e32 v137, v0
	v_cvt_pk_bf16_f32 v122, v110, v111
	v_cvt_pk_bf16_f32 v123, v112, v113
	v_lshl_add_u64 v[124:125], v[116:117], 0, v[136:137]
	v_lshlrev_b32_e32 v184, 1, v124
	v_bfi_b32 v184, s100, v184, v124
	v_lshrrev_b32_e32 v185, 5, v124
	v_bfi_b32 v184, 64, v185, v184
	v_mov_b32_e32 v185, v125
	global_store_dwordx2 v[184:185], v[122:123], off
.LBB0_228:
	s_nop 0
	s_and_b64 vcc, exec, s[14:15]
	s_nop 0
	v_pk_fma_f32 v[106:107], v[106:107], 0.5, v[172:173] op_sel_hi:[1,0,1]
	v_pk_fma_f32 v[108:109], v[108:109], 0.5, v[174:175] op_sel_hi:[1,0,1]
	global_store_dwordx4 v[118:119], v[106:109], off offset:64
	s_cbranch_vccnz .LBB0_230
	v_mov_b32_e32 v137, v0
	v_cvt_pk_bf16_f32 v122, v106, v107
	v_cvt_pk_bf16_f32 v123, v108, v109
	v_lshl_add_u64 v[124:125], v[116:117], 0, v[136:137]
	v_lshlrev_b32_e32 v184, 1, v124
	v_bfi_b32 v184, s100, v184, v124
	v_lshrrev_b32_e32 v185, 5, v124
	v_bfi_b32 v184, 64, v185, v184
	v_mov_b32_e32 v185, v125
	global_store_dwordx2 v[184:185], v[122:123], off offset:32
.LBB0_230:
	s_nop 0
	s_and_b64 vcc, exec, s[14:15]
	s_nop 0
	v_pk_fma_f32 v[102:103], v[102:103], 0.5, v[176:177] op_sel_hi:[1,0,1]
	v_pk_fma_f32 v[104:105], v[104:105], 0.5, v[178:179] op_sel_hi:[1,0,1]
	global_store_dwordx4 v[118:119], v[102:105], off offset:128
	s_cbranch_vccnz .LBB0_232
	v_mov_b32_e32 v137, v0
	v_cvt_pk_bf16_f32 v122, v102, v103
	v_cvt_pk_bf16_f32 v123, v104, v105
	v_lshl_add_u64 v[124:125], v[116:117], 0, v[136:137]
	v_lshlrev_b32_e32 v184, 1, v124
	v_bfi_b32 v184, s100, v184, v124
	v_lshrrev_b32_e32 v185, 5, v124
	v_bfi_b32 v184, 64, v185, v184
	v_mov_b32_e32 v185, v125
	global_store_dwordx2 v[184:185], v[122:123], off offset:128
.LBB0_232:
	s_nop 0
	s_and_b64 vcc, exec, s[14:15]
	s_nop 0
	v_pk_fma_f32 v[98:99], v[98:99], 0.5, v[180:181] op_sel_hi:[1,0,1]
	v_pk_fma_f32 v[100:101], v[100:101], 0.5, v[182:183] op_sel_hi:[1,0,1]
	global_store_dwordx4 v[118:119], v[98:101], off offset:192
	s_cbranch_vccnz .LBB0_234
	v_mov_b32_e32 v137, v0
	v_cvt_pk_bf16_f32 v118, v98, v99
	v_cvt_pk_bf16_f32 v119, v100, v101
	v_lshl_add_u64 v[116:117], v[116:117], 0, v[136:137]
	v_lshlrev_b32_e32 v184, 1, v116
	v_bfi_b32 v184, s100, v184, v116
	v_lshrrev_b32_e32 v185, 5, v116
	v_bfi_b32 v184, 64, v185, v184
	v_mov_b32_e32 v185, v117
	global_store_dwordx2 v[184:185], v[118:119], off offset:160

; template <int EPI, int MF>
; __device__ __forceinline__ void gemm_part(const u16* __restrict__ A, int lda, const u16* __restrict__ Bt, int K, int ntn, GemmEpi ep, char* smem,
;                                           int mbase, int mrows) {
;     ...
;       } else if (EPI == EPI_RESID) {
;         const float* rp = (row < MP) ? ep.res0 + (size_t)row * DM : ep.res1 + (size_t)(row - MP) * DM;
;         float ssq = 0.f;
; #pragma unroll
;         for (int n = 0; n < 4; ++n) {
;           const int col = cb + n * 16;
;           const float4 r = *(const float4*)(rp + col);
;           float4 v;
;           v.x = r.x + ep.scale * acc[m][n][0]; v.y = r.y + ep.scale * acc[m][n][1];
;           v.z = r.z + ep.scale * acc[m][n][2]; v.w = r.w + ep.scale * acc[m][n][3];
;           *(float4*)(ep.outf + (size_t)row * DM + col) = v;
;           if (ep.xcopy) {
;             bf16x4 o;
;             o[0] = (short)f2bf(v.x); o[1] = (short)f2bf(v.y); o[2] = (short)f2bf(v.z); o[3] = (short)f2bf(v.w);
;             *(bf16x4*)(ep.xcopy + (size_t)row * DM + col) = o;
;           }
;           ssq += v.x * v.x + v.y * v.y + v.z * v.z + v.w * v.w;
;         }
.LBB0_238:
	s_waitcnt lgkmcnt(0)
	v_or_b32_e32 v98, 32, v138
	s_mov_b32 s2, 0xffff
	v_cmp_lt_i32_e32 vcc, s2, v98
	s_and_saveexec_b64 s[2:3], vcc
	s_xor_b64 s[2:3], exec, s[2:3]
	v_add_u32_e32 v100, 0xffff0020, v138
	v_mov_b32_e32 v101, v0
	v_lshlrev_b64 v[100:101], 12, v[100:101]
	v_lshl_add_u64 v[100:101], s[18:19], 0, v[100:101]
	v_mov_b32_e32 v99, v0
	s_andn2_saveexec_b64 s[2:3], s[2:3]
	v_ashrrev_i32_e32 v99, 31, v98
	v_lshlrev_b64 v[100:101], 12, v[98:99]
	v_lshl_add_u64 v[100:101], s[8:9], 0, v[100:101]
	s_or_b64 exec, exec, s[2:3]
	v_mov_b32_e32 v147, v0
	v_lshl_add_u64 v[104:105], v[100:101], 0, v[146:147]
	global_load_dwordx4 v[106:109], v[104:105], off
	global_load_dwordx4 v[172:175], v[104:105], off offset:64
	global_load_dwordx4 v[176:179], v[104:105], off offset:128
	global_load_dwordx4 v[180:183], v[104:105], off offset:192
	v_lshlrev_b64 v[100:101], 12, v[98:99]
	v_lshlrev_b64 v[102:103], 11, v[98:99]
	v_lshl_add_u64 v[110:111], s[26:27], 0, v[100:101]
	v_lshl_add_u64 v[100:101], s[44:45], 0, v[102:103]
	v_lshl_add_u64 v[102:103], v[110:111], 0, v[146:147]
	s_and_b64 vcc, exec, s[14:15]
	s_waitcnt vmcnt(0)
	v_pk_fma_f32 v[94:95], v[94:95], 0.5, v[106:107] op_sel_hi:[1,0,1]
	v_pk_fma_f32 v[96:97], v[96:97], 0.5, v[108:109] op_sel_hi:[1,0,1]
	global_store_dwordx4 v[102:103], v[94:97], off
	s_cbranch_vccnz .LBB0_244
	v_mov_b32_e32 v137, v0
	v_cvt_pk_bf16_f32 v106, v94, v95
	v_cvt_pk_bf16_f32 v107, v96, v97
	v_lshl_add_u64 v[108:109], v[100:101], 0, v[136:137]
	v_lshlrev_b32_e32 v184, 1, v108
	v_bfi_b32 v184, s100, v184, v108
	v_lshrrev_b32_e32 v185, 5, v108
	v_bfi_b32 v184, 64, v185, v184
	v_mov_b32_e32 v185, v109
	global_store_dwordx2 v[184:185], v[106:107], off
.LBB0_244:
	s_nop 0
	s_and_b64 vcc, exec, s[14:15]
	s_nop 0
	v_pk_fma_f32 v[90:91], v[90:91], 0.5, v[172:173] op_sel_hi:[1,0,1]
	v_pk_fma_f32 v[92:93], v[92:93], 0.5, v[174:175] op_sel_hi:[1,0,1]
	global_store_dwordx4 v[102:103], v[90:93], off offset:64
	s_cbranch_vccnz .LBB0_246
	v_mov_b32_e32 v137, v0
	v_cvt_pk_bf16_f32 v106, v90, v91
	v_cvt_pk_bf16_f32 v107, v92, v93
	v_lshl_add_u64 v[108:109], v[100:101], 0, v[136:137]
	v_lshlrev_b32_e32 v184, 1, v108
	v_bfi_b32 v184, s100, v184, v108
	v_lshrrev_b32_e32 v185, 5, v108
	v_bfi_b32 v184, 64, v185, v184
	v_mov_b32_e32 v185, v109
	global_store_dwordx2 v[184:185], v[106:107], off offset:32
.LBB0_246:
	s_nop 0
	s_and_b64 vcc, exec, s[14:15]
	s_nop 0
	v_pk_fma_f32 v[86:87], v[86:87], 0.5, v[176:177] op_sel_hi:[1,0,1]
	v_pk_fma_f32 v[88:89], v[88:89], 0.5, v[178:179] op_sel_hi:[1,0,1]
	global_store_dwordx4 v[102:103], v[86:89], off offset:128
	s_cbranch_vccnz .LBB0_248
	v_mov_b32_e32 v137, v0
	v_cvt_pk_bf16_f32 v106, v86, v87
	v_cvt_pk_bf16_f32 v107, v88, v89
	v_lshl_add_u64 v[108:109], v[100:101], 0, v[136:137]
	v_lshlrev_b32_e32 v184, 1, v108
	v_bfi_b32 v184, s100, v184, v108
	v_lshrrev_b32_e32 v185, 5, v108
	v_bfi_b32 v184, 64, v185, v184
	v_mov_b32_e32 v185, v109
	global_store_dwordx2 v[184:185], v[106:107], off offset:128
.LBB0_248:
	s_nop 0
	s_and_b64 vcc, exec, s[14:15]
	s_nop 0
	v_pk_fma_f32 v[82:83], v[82:83], 0.5, v[180:181] op_sel_hi:[1,0,1]
	v_pk_fma_f32 v[84:85], v[84:85], 0.5, v[182:183] op_sel_hi:[1,0,1]
	global_store_dwordx4 v[102:103], v[82:85], off offset:192
	s_cbranch_vccnz .LBB0_250
	v_mov_b32_e32 v137, v0
	v_cvt_pk_bf16_f32 v102, v82, v83
	v_cvt_pk_bf16_f32 v103, v84, v85
	v_lshl_add_u64 v[100:101], v[100:101], 0, v[136:137]
	v_lshlrev_b32_e32 v184, 1, v100
	v_bfi_b32 v184, s100, v184, v100
	v_lshrrev_b32_e32 v185, 5, v100
	v_bfi_b32 v184, 64, v185, v184
	v_mov_b32_e32 v185, v101
	global_store_dwordx2 v[184:185], v[102:103], off offset:160

; template <int EPI, int MF>
; __device__ __forceinline__ void gemm_part(const u16* __restrict__ A, int lda, const u16* __restrict__ Bt, int K, int ntn, GemmEpi ep, char* smem,
;                                           int mbase, int mrows) {
;     ...
;       } else if (EPI == EPI_RESID) {
;         const float* rp = (row < MP) ? ep.res0 + (size_t)row * DM : ep.res1 + (size_t)(row - MP) * DM;
;         float ssq = 0.f;
; #pragma unroll
;         for (int n = 0; n < 4; ++n) {
;           const int col = cb + n * 16;
;           const float4 r = *(const float4*)(rp + col);
;           float4 v;
;           v.x = r.x + ep.scale * acc[m][n][0]; v.y = r.y + ep.scale * acc[m][n][1];
;           v.z = r.z + ep.scale * acc[m][n][2]; v.w = r.w + ep.scale * acc[m][n][3];
;           *(float4*)(ep.outf + (size_t)row * DM + col) = v;
;           if (ep.xcopy) {
;             bf16x4 o;
;             o[0] = (short)f2bf(v.x); o[1] = (short)f2bf(v.y); o[2] = (short)f2bf(v.z); o[3] = (short)f2bf(v.w);
;             *(bf16x4*)(ep.xcopy + (size_t)row * DM + col) = o;
;           }
;           ssq += v.x * v.x + v.y * v.y + v.z * v.z + v.w * v.w;
;         }
.LBB0_254:
	s_waitcnt lgkmcnt(0)
	v_or_b32_e32 v82, 48, v138
	s_mov_b32 s2, 0xffff
	v_cmp_lt_i32_e32 vcc, s2, v82
	s_and_saveexec_b64 s[2:3], vcc
	s_xor_b64 s[2:3], exec, s[2:3]
	v_add_u32_e32 v84, 0xffff0030, v138
	v_mov_b32_e32 v85, v0
	v_lshlrev_b64 v[84:85], 12, v[84:85]
	v_lshl_add_u64 v[84:85], s[18:19], 0, v[84:85]
	v_mov_b32_e32 v83, v0
	s_andn2_saveexec_b64 s[2:3], s[2:3]
	v_ashrrev_i32_e32 v83, 31, v82
	v_lshlrev_b64 v[84:85], 12, v[82:83]
	v_lshl_add_u64 v[84:85], s[8:9], 0, v[84:85]
	s_or_b64 exec, exec, s[2:3]
	v_mov_b32_e32 v147, v0
	v_lshl_add_u64 v[88:89], v[84:85], 0, v[146:147]
	global_load_dwordx4 v[90:93], v[88:89], off
	global_load_dwordx4 v[172:175], v[88:89], off offset:64
	global_load_dwordx4 v[176:179], v[88:89], off offset:128
	global_load_dwordx4 v[180:183], v[88:89], off offset:192
	v_lshlrev_b64 v[84:85], 12, v[82:83]
	v_lshlrev_b64 v[86:87], 11, v[82:83]
	v_lshl_add_u64 v[94:95], s[26:27], 0, v[84:85]
	v_lshl_add_u64 v[84:85], s[44:45], 0, v[86:87]
	v_lshl_add_u64 v[86:87], v[94:95], 0, v[146:147]
	s_and_b64 vcc, exec, s[14:15]
	s_waitcnt vmcnt(0)
	v_pk_fma_f32 v[78:79], v[78:79], 0.5, v[90:91] op_sel_hi:[1,0,1]
	v_pk_fma_f32 v[80:81], v[80:81], 0.5, v[92:93] op_sel_hi:[1,0,1]
	global_store_dwordx4 v[86:87], v[78:81], off
	s_cbranch_vccnz .LBB0_260
	v_mov_b32_e32 v137, v0
	v_cvt_pk_bf16_f32 v90, v78, v79
	v_cvt_pk_bf16_f32 v91, v80, v81
	v_lshl_add_u64 v[92:93], v[84:85], 0, v[136:137]
	v_lshlrev_b32_e32 v184, 1, v92
	v_bfi_b32 v184, s100, v184, v92
	v_lshrrev_b32_e32 v185, 5, v92
	v_bfi_b32 v184, 64, v185, v184
	v_mov_b32_e32 v185, v93
	global_store_dwordx2 v[184:185], v[90:91], off
.LBB0_260:
	s_nop 0
	s_and_b64 vcc, exec, s[14:15]
	s_nop 0
	v_pk_fma_f32 v[74:75], v[74:75], 0.5, v[172:173] op_sel_hi:[1,0,1]
	v_pk_fma_f32 v[76:77], v[76:77], 0.5, v[174:175] op_sel_hi:[1,0,1]
	global_store_dwordx4 v[86:87], v[74:77], off offset:64
	s_cbranch_vccnz .LBB0_262
	v_mov_b32_e32 v137, v0
	v_cvt_pk_bf16_f32 v90, v74, v75
	v_cvt_pk_bf16_f32 v91, v76, v77
	v_lshl_add_u64 v[92:93], v[84:85], 0, v[136:137]
	v_lshlrev_b32_e32 v184, 1, v92
	v_bfi_b32 v184, s100, v184, v92
	v_lshrrev_b32_e32 v185, 5, v92
	v_bfi_b32 v184, 64, v185, v184
	v_mov_b32_e32 v185, v93
	global_store_dwordx2 v[184:185], v[90:91], off offset:32
.LBB0_262:
	s_nop 0
	s_and_b64 vcc, exec, s[14:15]
	s_nop 0
	v_pk_fma_f32 v[70:71], v[70:71], 0.5, v[176:177] op_sel_hi:[1,0,1]
	v_pk_fma_f32 v[72:73], v[72:73], 0.5, v[178:179] op_sel_hi:[1,0,1]
	global_store_dwordx4 v[86:87], v[70:73], off offset:128
	s_cbranch_vccnz .LBB0_264
	v_mov_b32_e32 v137, v0
	v_cvt_pk_bf16_f32 v90, v70, v71
	v_cvt_pk_bf16_f32 v91, v72, v73
	v_lshl_add_u64 v[92:93], v[84:85], 0, v[136:137]
	v_lshlrev_b32_e32 v184, 1, v92
	v_bfi_b32 v184, s100, v184, v92
	v_lshrrev_b32_e32 v185, 5, v92
	v_bfi_b32 v184, 64, v185, v184
	v_mov_b32_e32 v185, v93
	global_store_dwordx2 v[184:185], v[90:91], off offset:128
.LBB0_264:
	s_nop 0
	s_and_b64 vcc, exec, s[14:15]
	s_nop 0
	v_pk_fma_f32 v[66:67], v[66:67], 0.5, v[180:181] op_sel_hi:[1,0,1]
	v_pk_fma_f32 v[68:69], v[68:69], 0.5, v[182:183] op_sel_hi:[1,0,1]
	global_store_dwordx4 v[86:87], v[66:69], off offset:192
	s_cbranch_vccnz .LBB0_266
	v_mov_b32_e32 v137, v0
	v_cvt_pk_bf16_f32 v86, v66, v67
	v_cvt_pk_bf16_f32 v87, v68, v69
	v_lshl_add_u64 v[84:85], v[84:85], 0, v[136:137]
	v_lshlrev_b32_e32 v184, 1, v84
	v_bfi_b32 v184, s100, v184, v84
	v_lshrrev_b32_e32 v185, 5, v84
	v_bfi_b32 v184, 64, v185, v184
	v_mov_b32_e32 v185, v85
	global_store_dwordx2 v[184:185], v[86:87], off offset:160

; template <int EPI, int MF>
; __device__ __forceinline__ void gemm_part(const u16* __restrict__ A, int lda, const u16* __restrict__ Bt, int K, int ntn, GemmEpi ep, char* smem,
;                                           int mbase, int mrows) {
;     ...
;       } else if (EPI == EPI_RESID) {
;         const float* rp = (row < MP) ? ep.res0 + (size_t)row * DM : ep.res1 + (size_t)(row - MP) * DM;
;         float ssq = 0.f;
; #pragma unroll
;         for (int n = 0; n < 4; ++n) {
;           const int col = cb + n * 16;
;           const float4 r = *(const float4*)(rp + col);
;           float4 v;
;           v.x = r.x + ep.scale * acc[m][n][0]; v.y = r.y + ep.scale * acc[m][n][1];
;           v.z = r.z + ep.scale * acc[m][n][2]; v.w = r.w + ep.scale * acc[m][n][3];
;           *(float4*)(ep.outf + (size_t)row * DM + col) = v;
;           if (ep.xcopy) {
;             bf16x4 o;
;             o[0] = (short)f2bf(v.x); o[1] = (short)f2bf(v.y); o[2] = (short)f2bf(v.z); o[3] = (short)f2bf(v.w);
;             *(bf16x4*)(ep.xcopy + (size_t)row * DM + col) = o;
;           }
;           ssq += v.x * v.x + v.y * v.y + v.z * v.z + v.w * v.w;
;         }
.LBB0_270:
	s_waitcnt lgkmcnt(0)
	v_or_b32_e32 v66, 64, v138
	s_mov_b32 s2, 0xffff
	v_cmp_lt_i32_e32 vcc, s2, v66
	s_and_saveexec_b64 s[2:3], vcc
	s_xor_b64 s[2:3], exec, s[2:3]
	v_add_u32_e32 v68, 0xffff0040, v138
	v_mov_b32_e32 v69, v0
	v_lshlrev_b64 v[68:69], 12, v[68:69]
	v_lshl_add_u64 v[68:69], s[18:19], 0, v[68:69]
	v_mov_b32_e32 v67, v0
	s_andn2_saveexec_b64 s[2:3], s[2:3]
	v_ashrrev_i32_e32 v67, 31, v66
	v_lshlrev_b64 v[68:69], 12, v[66:67]
	v_lshl_add_u64 v[68:69], s[8:9], 0, v[68:69]
	s_or_b64 exec, exec, s[2:3]
	v_mov_b32_e32 v147, v0
	v_lshl_add_u64 v[72:73], v[68:69], 0, v[146:147]
	global_load_dwordx4 v[74:77], v[72:73], off
	global_load_dwordx4 v[172:175], v[72:73], off offset:64
	global_load_dwordx4 v[176:179], v[72:73], off offset:128
	global_load_dwordx4 v[180:183], v[72:73], off offset:192
	v_lshlrev_b64 v[68:69], 12, v[66:67]
	v_lshlrev_b64 v[70:71], 11, v[66:67]
	v_lshl_add_u64 v[78:79], s[26:27], 0, v[68:69]
	v_lshl_add_u64 v[68:69], s[44:45], 0, v[70:71]
	v_lshl_add_u64 v[70:71], v[78:79], 0, v[146:147]
	s_and_b64 vcc, exec, s[14:15]
	s_waitcnt vmcnt(0)
	v_pk_fma_f32 v[62:63], v[62:63], 0.5, v[74:75] op_sel_hi:[1,0,1]
	v_pk_fma_f32 v[64:65], v[64:65], 0.5, v[76:77] op_sel_hi:[1,0,1]
	global_store_dwordx4 v[70:71], v[62:65], off
	s_cbranch_vccnz .LBB0_276
	v_mov_b32_e32 v137, v0
	v_cvt_pk_bf16_f32 v74, v62, v63
	v_cvt_pk_bf16_f32 v75, v64, v65
	v_lshl_add_u64 v[76:77], v[68:69], 0, v[136:137]
	v_lshlrev_b32_e32 v184, 1, v76
	v_bfi_b32 v184, s100, v184, v76
	v_lshrrev_b32_e32 v185, 5, v76
	v_bfi_b32 v184, 64, v185, v184
	v_mov_b32_e32 v185, v77
	global_store_dwordx2 v[184:185], v[74:75], off
.LBB0_276:
	s_nop 0
	s_and_b64 vcc, exec, s[14:15]
	s_nop 0
	v_pk_fma_f32 v[58:59], v[58:59], 0.5, v[172:173] op_sel_hi:[1,0,1]
	v_pk_fma_f32 v[60:61], v[60:61], 0.5, v[174:175] op_sel_hi:[1,0,1]
	global_store_dwordx4 v[70:71], v[58:61], off offset:64
	s_cbranch_vccnz .LBB0_278
	v_mov_b32_e32 v137, v0
	v_cvt_pk_bf16_f32 v74, v58, v59
	v_cvt_pk_bf16_f32 v75, v60, v61
	v_lshl_add_u64 v[76:77], v[68:69], 0, v[136:137]
	v_lshlrev_b32_e32 v184, 1, v76
	v_bfi_b32 v184, s100, v184, v76
	v_lshrrev_b32_e32 v185, 5, v76
	v_bfi_b32 v184, 64, v185, v184
	v_mov_b32_e32 v185, v77
	global_store_dwordx2 v[184:185], v[74:75], off offset:32
.LBB0_278:
	s_nop 0
	s_and_b64 vcc, exec, s[14:15]
	s_nop 0
	v_pk_fma_f32 v[54:55], v[54:55], 0.5, v[176:177] op_sel_hi:[1,0,1]
	v_pk_fma_f32 v[56:57], v[56:57], 0.5, v[178:179] op_sel_hi:[1,0,1]
	global_store_dwordx4 v[70:71], v[54:57], off offset:128
	s_cbranch_vccnz .LBB0_280
	v_mov_b32_e32 v137, v0
	v_cvt_pk_bf16_f32 v74, v54, v55
	v_cvt_pk_bf16_f32 v75, v56, v57
	v_lshl_add_u64 v[76:77], v[68:69], 0, v[136:137]
	v_lshlrev_b32_e32 v184, 1, v76
	v_bfi_b32 v184, s100, v184, v76
	v_lshrrev_b32_e32 v185, 5, v76
	v_bfi_b32 v184, 64, v185, v184
	v_mov_b32_e32 v185, v77
	global_store_dwordx2 v[184:185], v[74:75], off offset:128
.LBB0_280:
	s_nop 0
	s_and_b64 vcc, exec, s[14:15]
	s_nop 0
	v_pk_fma_f32 v[50:51], v[50:51], 0.5, v[180:181] op_sel_hi:[1,0,1]
	v_pk_fma_f32 v[52:53], v[52:53], 0.5, v[182:183] op_sel_hi:[1,0,1]
	global_store_dwordx4 v[70:71], v[50:53], off offset:192
	s_cbranch_vccnz .LBB0_282
	v_mov_b32_e32 v137, v0
	v_cvt_pk_bf16_f32 v70, v50, v51
	v_cvt_pk_bf16_f32 v71, v52, v53
	v_lshl_add_u64 v[68:69], v[68:69], 0, v[136:137]
	v_lshlrev_b32_e32 v184, 1, v68
	v_bfi_b32 v184, s100, v184, v68
	v_lshrrev_b32_e32 v185, 5, v68
	v_bfi_b32 v184, 64, v185, v184
	v_mov_b32_e32 v185, v69
	global_store_dwordx2 v[184:185], v[70:71], off offset:160

; template <int EPI, int MF>
; __device__ __forceinline__ void gemm_part(const u16* __restrict__ A, int lda, const u16* __restrict__ Bt, int K, int ntn, GemmEpi ep, char* smem,
;                                           int mbase, int mrows) {
;     ...
;       } else if (EPI == EPI_RESID) {
;         const float* rp = (row < MP) ? ep.res0 + (size_t)row * DM : ep.res1 + (size_t)(row - MP) * DM;
;         float ssq = 0.f;
; #pragma unroll
;         for (int n = 0; n < 4; ++n) {
;           const int col = cb + n * 16;
;           const float4 r = *(const float4*)(rp + col);
;           float4 v;
;           v.x = r.x + ep.scale * acc[m][n][0]; v.y = r.y + ep.scale * acc[m][n][1];
;           v.z = r.z + ep.scale * acc[m][n][2]; v.w = r.w + ep.scale * acc[m][n][3];
;           *(float4*)(ep.outf + (size_t)row * DM + col) = v;
;           if (ep.xcopy) {
;             bf16x4 o;
;             o[0] = (short)f2bf(v.x); o[1] = (short)f2bf(v.y); o[2] = (short)f2bf(v.z); o[3] = (short)f2bf(v.w);
;             *(bf16x4*)(ep.xcopy + (size_t)row * DM + col) = o;
;           }
;           ssq += v.x * v.x + v.y * v.y + v.z * v.z + v.w * v.w;
;         }
.LBB0_286:
	s_waitcnt lgkmcnt(0)
	v_or_b32_e32 v50, 0x50, v138
	s_mov_b32 s2, 0xffff
	v_cmp_lt_i32_e32 vcc, s2, v50
	s_and_saveexec_b64 s[2:3], vcc
	s_xor_b64 s[2:3], exec, s[2:3]
	v_add_u32_e32 v52, 0xffff0050, v138
	v_mov_b32_e32 v53, v0
	v_lshlrev_b64 v[52:53], 12, v[52:53]
	v_lshl_add_u64 v[52:53], s[18:19], 0, v[52:53]
	v_mov_b32_e32 v51, v0
	s_andn2_saveexec_b64 s[2:3], s[2:3]
	v_ashrrev_i32_e32 v51, 31, v50
	v_lshlrev_b64 v[52:53], 12, v[50:51]
	v_lshl_add_u64 v[52:53], s[8:9], 0, v[52:53]
	s_or_b64 exec, exec, s[2:3]
	v_mov_b32_e32 v147, v0
	v_lshl_add_u64 v[56:57], v[52:53], 0, v[146:147]
	global_load_dwordx4 v[58:61], v[56:57], off
	global_load_dwordx4 v[172:175], v[56:57], off offset:64
	global_load_dwordx4 v[176:179], v[56:57], off offset:128
	global_load_dwordx4 v[180:183], v[56:57], off offset:192
	v_lshlrev_b64 v[52:53], 12, v[50:51]
	v_lshlrev_b64 v[54:55], 11, v[50:51]
	v_lshl_add_u64 v[62:63], s[26:27], 0, v[52:53]
	v_lshl_add_u64 v[52:53], s[44:45], 0, v[54:55]
	v_lshl_add_u64 v[54:55], v[62:63], 0, v[146:147]
	s_and_b64 vcc, exec, s[14:15]
	s_waitcnt vmcnt(0)
	v_pk_fma_f32 v[46:47], v[46:47], 0.5, v[58:59] op_sel_hi:[1,0,1]
	v_pk_fma_f32 v[48:49], v[48:49], 0.5, v[60:61] op_sel_hi:[1,0,1]
	global_store_dwordx4 v[54:55], v[46:49], off
	s_cbranch_vccnz .LBB0_292
	v_mov_b32_e32 v137, v0
	v_cvt_pk_bf16_f32 v58, v46, v47
	v_cvt_pk_bf16_f32 v59, v48, v49
	v_lshl_add_u64 v[60:61], v[52:53], 0, v[136:137]
	v_lshlrev_b32_e32 v184, 1, v60
	v_bfi_b32 v184, s100, v184, v60
	v_lshrrev_b32_e32 v185, 5, v60
	v_bfi_b32 v184, 64, v185, v184
	v_mov_b32_e32 v185, v61
	global_store_dwordx2 v[184:185], v[58:59], off
.LBB0_292:
	s_nop 0
	s_and_b64 vcc, exec, s[14:15]
	s_nop 0
	v_pk_fma_f32 v[42:43], v[42:43], 0.5, v[172:173] op_sel_hi:[1,0,1]
	v_pk_fma_f32 v[44:45], v[44:45], 0.5, v[174:175] op_sel_hi:[1,0,1]
	global_store_dwordx4 v[54:55], v[42:45], off offset:64
	s_cbranch_vccnz .LBB0_294
	v_mov_b32_e32 v137, v0
	v_cvt_pk_bf16_f32 v58, v42, v43
	v_cvt_pk_bf16_f32 v59, v44, v45
	v_lshl_add_u64 v[60:61], v[52:53], 0, v[136:137]
	v_lshlrev_b32_e32 v184, 1, v60
	v_bfi_b32 v184, s100, v184, v60
	v_lshrrev_b32_e32 v185, 5, v60
	v_bfi_b32 v184, 64, v185, v184
	v_mov_b32_e32 v185, v61
	global_store_dwordx2 v[184:185], v[58:59], off offset:32
.LBB0_294:
	s_nop 0
	s_and_b64 vcc, exec, s[14:15]
	s_nop 0
	v_pk_fma_f32 v[38:39], v[38:39], 0.5, v[176:177] op_sel_hi:[1,0,1]
	v_pk_fma_f32 v[40:41], v[40:41], 0.5, v[178:179] op_sel_hi:[1,0,1]
	global_store_dwordx4 v[54:55], v[38:41], off offset:128
	s_cbranch_vccnz .LBB0_296
	v_mov_b32_e32 v137, v0
	v_cvt_pk_bf16_f32 v58, v38, v39
	v_cvt_pk_bf16_f32 v59, v40, v41
	v_lshl_add_u64 v[60:61], v[52:53], 0, v[136:137]
	v_lshlrev_b32_e32 v184, 1, v60
	v_bfi_b32 v184, s100, v184, v60
	v_lshrrev_b32_e32 v185, 5, v60
	v_bfi_b32 v184, 64, v185, v184
	v_mov_b32_e32 v185, v61
	global_store_dwordx2 v[184:185], v[58:59], off offset:128
.LBB0_296:
	s_nop 0
	s_and_b64 vcc, exec, s[14:15]
	s_nop 0
	v_pk_fma_f32 v[34:35], v[34:35], 0.5, v[180:181] op_sel_hi:[1,0,1]
	v_pk_fma_f32 v[36:37], v[36:37], 0.5, v[182:183] op_sel_hi:[1,0,1]
	global_store_dwordx4 v[54:55], v[34:37], off offset:192
	s_cbranch_vccnz .LBB0_298
	v_mov_b32_e32 v137, v0
	v_cvt_pk_bf16_f32 v54, v34, v35
	v_cvt_pk_bf16_f32 v55, v36, v37
	v_lshl_add_u64 v[52:53], v[52:53], 0, v[136:137]
	v_lshlrev_b32_e32 v184, 1, v52
	v_bfi_b32 v184, s100, v184, v52
	v_lshrrev_b32_e32 v185, 5, v52
	v_bfi_b32 v184, 64, v185, v184
	v_mov_b32_e32 v185, v53
	global_store_dwordx2 v[184:185], v[54:55], off offset:160

; template <int EPI, int MF>
; __device__ __forceinline__ void gemm_part(const u16* __restrict__ A, int lda, const u16* __restrict__ Bt, int K, int ntn, GemmEpi ep, char* smem,
;                                           int mbase, int mrows) {
;     ...
;       } else if (EPI == EPI_RESID) {
;         const float* rp = (row < MP) ? ep.res0 + (size_t)row * DM : ep.res1 + (size_t)(row - MP) * DM;
;         float ssq = 0.f;
; #pragma unroll
;         for (int n = 0; n < 4; ++n) {
;           const int col = cb + n * 16;
;           const float4 r = *(const float4*)(rp + col);
;           float4 v;
;           v.x = r.x + ep.scale * acc[m][n][0]; v.y = r.y + ep.scale * acc[m][n][1];
;           v.z = r.z + ep.scale * acc[m][n][2]; v.w = r.w + ep.scale * acc[m][n][3];
;           *(float4*)(ep.outf + (size_t)row * DM + col) = v;
;           if (ep.xcopy) {
;             bf16x4 o;
;             o[0] = (short)f2bf(v.x); o[1] = (short)f2bf(v.y); o[2] = (short)f2bf(v.z); o[3] = (short)f2bf(v.w);
;             *(bf16x4*)(ep.xcopy + (size_t)row * DM + col) = o;
;           }
;           ssq += v.x * v.x + v.y * v.y + v.z * v.z + v.w * v.w;
;         }
.LBB0_302:
	s_waitcnt lgkmcnt(0)
	v_or_b32_e32 v34, 0x60, v138
	s_mov_b32 s2, 0xffff
	v_cmp_lt_i32_e32 vcc, s2, v34
	s_and_saveexec_b64 s[2:3], vcc
	s_xor_b64 s[2:3], exec, s[2:3]
	v_add_u32_e32 v36, 0xffff0060, v138
	v_mov_b32_e32 v37, v0
	v_lshlrev_b64 v[36:37], 12, v[36:37]
	v_lshl_add_u64 v[36:37], s[18:19], 0, v[36:37]
	v_mov_b32_e32 v35, v0
	s_andn2_saveexec_b64 s[2:3], s[2:3]
	v_ashrrev_i32_e32 v35, 31, v34
	v_lshlrev_b64 v[36:37], 12, v[34:35]
	v_lshl_add_u64 v[36:37], s[8:9], 0, v[36:37]
	s_or_b64 exec, exec, s[2:3]
	v_mov_b32_e32 v147, v0
	v_lshl_add_u64 v[40:41], v[36:37], 0, v[146:147]
	global_load_dwordx4 v[42:45], v[40:41], off
	global_load_dwordx4 v[172:175], v[40:41], off offset:64
	global_load_dwordx4 v[176:179], v[40:41], off offset:128
	global_load_dwordx4 v[180:183], v[40:41], off offset:192
	v_lshlrev_b64 v[36:37], 12, v[34:35]
	v_lshlrev_b64 v[38:39], 11, v[34:35]
	v_lshl_add_u64 v[46:47], s[26:27], 0, v[36:37]
	v_lshl_add_u64 v[36:37], s[44:45], 0, v[38:39]
	v_lshl_add_u64 v[38:39], v[46:47], 0, v[146:147]
	s_and_b64 vcc, exec, s[14:15]
	s_waitcnt vmcnt(0)
	v_pk_fma_f32 v[30:31], v[30:31], 0.5, v[42:43] op_sel_hi:[1,0,1]
	v_pk_fma_f32 v[32:33], v[32:33], 0.5, v[44:45] op_sel_hi:[1,0,1]
	global_store_dwordx4 v[38:39], v[30:33], off
	s_cbranch_vccnz .LBB0_308
	v_mov_b32_e32 v137, v0
	v_cvt_pk_bf16_f32 v42, v30, v31
	v_cvt_pk_bf16_f32 v43, v32, v33
	v_lshl_add_u64 v[44:45], v[36:37], 0, v[136:137]
	v_lshlrev_b32_e32 v184, 1, v44
	v_bfi_b32 v184, s100, v184, v44
	v_lshrrev_b32_e32 v185, 5, v44
	v_bfi_b32 v184, 64, v185, v184
	v_mov_b32_e32 v185, v45
	global_store_dwordx2 v[184:185], v[42:43], off
.LBB0_308:
	s_nop 0
	s_and_b64 vcc, exec, s[14:15]
	s_nop 0
	v_pk_fma_f32 v[26:27], v[26:27], 0.5, v[172:173] op_sel_hi:[1,0,1]
	v_pk_fma_f32 v[28:29], v[28:29], 0.5, v[174:175] op_sel_hi:[1,0,1]
	global_store_dwordx4 v[38:39], v[26:29], off offset:64
	s_cbranch_vccnz .LBB0_310
	v_mov_b32_e32 v137, v0
	v_cvt_pk_bf16_f32 v42, v26, v27
	v_cvt_pk_bf16_f32 v43, v28, v29
	v_lshl_add_u64 v[44:45], v[36:37], 0, v[136:137]
	v_lshlrev_b32_e32 v184, 1, v44
	v_bfi_b32 v184, s100, v184, v44
	v_lshrrev_b32_e32 v185, 5, v44
	v_bfi_b32 v184, 64, v185, v184
	v_mov_b32_e32 v185, v45
	global_store_dwordx2 v[184:185], v[42:43], off offset:32
.LBB0_310:
	s_nop 0
	s_and_b64 vcc, exec, s[14:15]
	s_nop 0
	v_pk_fma_f32 v[22:23], v[22:23], 0.5, v[176:177] op_sel_hi:[1,0,1]
	v_pk_fma_f32 v[24:25], v[24:25], 0.5, v[178:179] op_sel_hi:[1,0,1]
	global_store_dwordx4 v[38:39], v[22:25], off offset:128
	s_cbranch_vccnz .LBB0_312
	v_mov_b32_e32 v137, v0
	v_cvt_pk_bf16_f32 v42, v22, v23
	v_cvt_pk_bf16_f32 v43, v24, v25
	v_lshl_add_u64 v[44:45], v[36:37], 0, v[136:137]
	v_lshlrev_b32_e32 v184, 1, v44
	v_bfi_b32 v184, s100, v184, v44
	v_lshrrev_b32_e32 v185, 5, v44
	v_bfi_b32 v184, 64, v185, v184
	v_mov_b32_e32 v185, v45
	global_store_dwordx2 v[184:185], v[42:43], off offset:128
.LBB0_312:
	s_nop 0
	s_and_b64 vcc, exec, s[14:15]
	s_nop 0
	v_pk_fma_f32 v[18:19], v[18:19], 0.5, v[180:181] op_sel_hi:[1,0,1]
	v_pk_fma_f32 v[20:21], v[20:21], 0.5, v[182:183] op_sel_hi:[1,0,1]
	global_store_dwordx4 v[38:39], v[18:21], off offset:192
	s_cbranch_vccnz .LBB0_314
	v_mov_b32_e32 v137, v0
	v_cvt_pk_bf16_f32 v38, v18, v19
	v_cvt_pk_bf16_f32 v39, v20, v21
	v_lshl_add_u64 v[36:37], v[36:37], 0, v[136:137]
	v_lshlrev_b32_e32 v184, 1, v36
	v_bfi_b32 v184, s100, v184, v36
	v_lshrrev_b32_e32 v185, 5, v36
	v_bfi_b32 v184, 64, v185, v184
	v_mov_b32_e32 v185, v37
	global_store_dwordx2 v[184:185], v[38:39], off offset:160

; template <int EPI, int MF>
; __device__ __forceinline__ void gemm_part(const u16* __restrict__ A, int lda, const u16* __restrict__ Bt, int K, int ntn, GemmEpi ep, char* smem,
;                                           int mbase, int mrows) {
;     ...
;       } else if (EPI == EPI_RESID) {
;         const float* rp = (row < MP) ? ep.res0 + (size_t)row * DM : ep.res1 + (size_t)(row - MP) * DM;
;         float ssq = 0.f;
; #pragma unroll
;         for (int n = 0; n < 4; ++n) {
;           const int col = cb + n * 16;
;           const float4 r = *(const float4*)(rp + col);
;           float4 v;
;           v.x = r.x + ep.scale * acc[m][n][0]; v.y = r.y + ep.scale * acc[m][n][1];
;           v.z = r.z + ep.scale * acc[m][n][2]; v.w = r.w + ep.scale * acc[m][n][3];
;           *(float4*)(ep.outf + (size_t)row * DM + col) = v;
;           if (ep.xcopy) {
;             bf16x4 o;
;             o[0] = (short)f2bf(v.x); o[1] = (short)f2bf(v.y); o[2] = (short)f2bf(v.z); o[3] = (short)f2bf(v.w);
;             *(bf16x4*)(ep.xcopy + (size_t)row * DM + col) = o;
;           }
;           ssq += v.x * v.x + v.y * v.y + v.z * v.z + v.w * v.w;
;         }
.LBB0_318:
	s_waitcnt lgkmcnt(0)
	v_or_b32_e32 v18, 0x70, v138
	s_mov_b32 s2, 0xffff
	v_cmp_lt_i32_e32 vcc, s2, v18
	s_and_saveexec_b64 s[2:3], vcc
	s_xor_b64 s[2:3], exec, s[2:3]
	v_add_u32_e32 v20, 0xffff0070, v138
	v_mov_b32_e32 v21, v0
	v_lshlrev_b64 v[20:21], 12, v[20:21]
	v_lshl_add_u64 v[20:21], s[18:19], 0, v[20:21]
	v_mov_b32_e32 v19, v0
	s_andn2_saveexec_b64 s[2:3], s[2:3]
	v_ashrrev_i32_e32 v19, 31, v18
	v_lshlrev_b64 v[20:21], 12, v[18:19]
	v_lshl_add_u64 v[20:21], s[8:9], 0, v[20:21]
	s_or_b64 exec, exec, s[2:3]
	v_mov_b32_e32 v147, v0
	v_lshl_add_u64 v[24:25], v[20:21], 0, v[146:147]
	global_load_dwordx4 v[26:29], v[24:25], off
	global_load_dwordx4 v[172:175], v[24:25], off offset:64
	global_load_dwordx4 v[176:179], v[24:25], off offset:128
	global_load_dwordx4 v[180:183], v[24:25], off offset:192
	v_lshlrev_b64 v[20:21], 12, v[18:19]
	v_lshlrev_b64 v[22:23], 11, v[18:19]
	v_lshl_add_u64 v[30:31], s[26:27], 0, v[20:21]
	v_lshl_add_u64 v[20:21], s[44:45], 0, v[22:23]
	v_lshl_add_u64 v[22:23], v[30:31], 0, v[146:147]
	s_and_b64 vcc, exec, s[14:15]
	s_waitcnt vmcnt(0)
	v_pk_fma_f32 v[14:15], v[14:15], 0.5, v[26:27] op_sel_hi:[1,0,1]
	v_pk_fma_f32 v[16:17], v[16:17], 0.5, v[28:29] op_sel_hi:[1,0,1]
	global_store_dwordx4 v[22:23], v[14:17], off
	s_cbranch_vccnz .LBB0_324
	v_mov_b32_e32 v137, v0
	v_cvt_pk_bf16_f32 v26, v14, v15
	v_cvt_pk_bf16_f32 v27, v16, v17
	v_lshl_add_u64 v[28:29], v[20:21], 0, v[136:137]
	v_lshlrev_b32_e32 v184, 1, v28
	v_bfi_b32 v184, s100, v184, v28
	v_lshrrev_b32_e32 v185, 5, v28
	v_bfi_b32 v184, 64, v185, v184
	v_mov_b32_e32 v185, v29
	global_store_dwordx2 v[184:185], v[26:27], off
.LBB0_324:
	s_nop 0
	s_and_b64 vcc, exec, s[14:15]
	s_nop 0
	v_pk_fma_f32 v[10:11], v[10:11], 0.5, v[172:173] op_sel_hi:[1,0,1]
	v_pk_fma_f32 v[12:13], v[12:13], 0.5, v[174:175] op_sel_hi:[1,0,1]
	global_store_dwordx4 v[22:23], v[10:13], off offset:64
	s_cbranch_vccnz .LBB0_326
	v_mov_b32_e32 v137, v0
	v_cvt_pk_bf16_f32 v26, v10, v11
	v_cvt_pk_bf16_f32 v27, v12, v13
	v_lshl_add_u64 v[28:29], v[20:21], 0, v[136:137]
	v_lshlrev_b32_e32 v184, 1, v28
	v_bfi_b32 v184, s100, v184, v28
	v_lshrrev_b32_e32 v185, 5, v28
	v_bfi_b32 v184, 64, v185, v184
	v_mov_b32_e32 v185, v29
	global_store_dwordx2 v[184:185], v[26:27], off offset:32
.LBB0_326:
	s_nop 0
	s_and_b64 vcc, exec, s[14:15]
	s_nop 0
	v_pk_fma_f32 v[6:7], v[6:7], 0.5, v[176:177] op_sel_hi:[1,0,1]
	v_pk_fma_f32 v[8:9], v[8:9], 0.5, v[178:179] op_sel_hi:[1,0,1]
	global_store_dwordx4 v[22:23], v[6:9], off offset:128
	s_cbranch_vccnz .LBB0_328
	v_mov_b32_e32 v137, v0
	v_cvt_pk_bf16_f32 v26, v6, v7
	v_cvt_pk_bf16_f32 v27, v8, v9
	v_lshl_add_u64 v[28:29], v[20:21], 0, v[136:137]
	v_lshlrev_b32_e32 v184, 1, v28
	v_bfi_b32 v184, s100, v184, v28
	v_lshrrev_b32_e32 v185, 5, v28
	v_bfi_b32 v184, 64, v185, v184
	v_mov_b32_e32 v185, v29
	global_store_dwordx2 v[184:185], v[26:27], off offset:128
.LBB0_328:
	s_nop 0
	s_and_b64 vcc, exec, s[14:15]
	s_nop 0
	v_pk_fma_f32 v[2:3], v[2:3], 0.5, v[180:181] op_sel_hi:[1,0,1]
	v_pk_fma_f32 v[4:5], v[4:5], 0.5, v[182:183] op_sel_hi:[1,0,1]
	global_store_dwordx4 v[22:23], v[2:5], off offset:192
	s_cbranch_vccnz .LBB0_330
	v_mov_b32_e32 v137, v0
	v_cvt_pk_bf16_f32 v22, v2, v3
	v_cvt_pk_bf16_f32 v23, v4, v5
	v_lshl_add_u64 v[20:21], v[20:21], 0, v[136:137]
	v_lshlrev_b32_e32 v184, 1, v20
	v_bfi_b32 v184, s100, v184, v20
	v_lshrrev_b32_e32 v185, 5, v20
	v_bfi_b32 v184, 64, v185, v184
	v_mov_b32_e32 v185, v21
	global_store_dwordx2 v[184:185], v[22:23], off offset:160

; #define MFMA(a, b, c) __builtin_amdgcn_mfma_f32_16x16x32_bf16((a), (b), (c), 0, 0, 0)
; template <int EPI, int MF>
; __device__ __forceinline__ void gemm_part(const u16* __restrict__ A, int lda, const u16* __restrict__ Bt, int K, int ntn, GemmEpi ep, char* smem,
;                                           int mbase, int mrows) {
;     ...
;     for (int kt = 0; kt < nk; ++kt) {
;       if (kt + 1 < nk) {
;         if (MF == 8) asm volatile("s_waitcnt vmcnt(6)" ::: "memory");
;         else asm volatile("s_waitcnt vmcnt(3)" ::: "memory");
;       } else asm volatile("s_waitcnt vmcnt(0)" ::: "memory");
;       asm volatile("s_waitcnt lgkmcnt(0)" ::: "memory");
;       __builtin_amdgcn_s_barrier();
;       const u16* a_ = sbase + (kt % 3) * STG;
;       const u16* b_ = a_ + BM * 32;
;       bf16x8 bfr[4], afc[2], afn[2];
;       const u16* ap_ = a_ + (wr * (16 * MF) + fr) * 32 + fq * 8;
; #pragma unroll
;       for (int n = 0; n < 4; ++n) bfr[n] = rd_std(b_ + (wc * 64 + n * 16 + fr) * 32 + fq * 8);
;       afc[0] = rd_std(ap_); afc[1] = rd_std(ap_ + 16 * 32);
;       __builtin_amdgcn_sched_barrier(0);
;       if (kt + 2 < nk) GEMM_ISSUE(kt + 2);
;       __builtin_amdgcn_sched_barrier(0);
; #pragma unroll
;       for (int mh = 0; mh < MF / 2; ++mh) {
;         if (mh + 1 < MF / 2) {
;           afn[0] = rd_std(ap_ + ((mh + 1) * 2) * 16 * 32);
;           afn[1] = rd_std(ap_ + ((mh + 1) * 2 + 1) * 16 * 32);
;         }
;         __builtin_amdgcn_sched_barrier(0);
; #pragma unroll
;         for (int m = 0; m < 2; ++m)
; #pragma unroll
;           for (int n = 0; n < 4; ++n) acc[mh * 2 + m][n] = MFMA(bfr[n], afc[m], acc[mh * 2 + m][n]);
;         __builtin_amdgcn_sched_barrier(0);
;         afc[0] = afn[0]; afc[1] = afn[1];
;       }
.LBB0_338:
	s_mul_hi_u32 s17, s15, 0xaaaaaaab
	s_lshr_b32 s17, s17, 1
	s_mul_i32 s17, s17, 0x9000
	s_mul_hi_u32 s16, s11, 0xaaaaaaab
	v_subrev_u32_e32 v44, s17, v60
	v_add_u32_e32 v97, s3, v58
	s_lshr_b32 s16, s16, 1
	s_waitcnt vmcnt(3)
	v_add_u32_e32 v74, v97, v44
	s_mul_i32 s16, s16, 0x9000
	v_subrev_u32_e32 v78, s17, v61
	s_waitcnt lgkmcnt(0)
	s_barrier
	ds_read_b128 v[44:47], v74 offset:4096
	ds_read_b128 v[48:51], v74 offset:5120
	ds_read_b128 v[70:73], v74 offset:6144
	ds_read_b128 v[74:77], v74 offset:7168
	v_subrev_u32_e32 v92, s16, v60
	v_subrev_u32_e32 v93, s16, v62
	s_mul_hi_u32 s16, s10, 0xaaaaaaab
	v_add_u32_e32 v82, v97, v78
	s_lshr_b32 s16, s16, 1
	ds_read_b128 v[78:81], v82
	ds_read_b128 v[82:85], v82 offset:1024
	s_mul_i32 s16, s16, 0x9000
	v_subrev_u32_e32 v94, s16, v63
	v_subrev_u32_e32 v95, s16, v64
	v_subrev_u32_e32 v96, s16, v65
	s_mul_hi_u32 s16, s14, 0xaaaaaaab
	s_lshr_b32 s16, s16, 1
	s_mul_i32 s16, s16, 0x9000
	s_waitcnt vmcnt(0)
	v_subrev_u32_e32 v90, s16, v66
	v_subrev_u32_e32 v98, s16, v67
	v_subrev_u32_e32 v99, s16, v68
	s_add_i32 s16, s3, 0
	v_add_u32_e32 v90, s16, v90
	v_lshl_add_u64 v[86:87], v[42:43], 0, v[38:39]
	v_readfirstlane_b32 s17, v90
	v_lshl_add_u64 v[88:89], v[86:87], 0, s[74:75]
	s_mov_b32 m0, s17
	v_add_u32_e32 v98, s16, v98
	global_load_lds_dwordx4 v[88:89], off
	v_lshl_add_u64 v[88:89], v[40:41], 0, v[38:39]
	v_readfirstlane_b32 s17, v98
	v_add_u32_e32 v98, s16, v99
	v_lshl_add_u64 v[90:91], v[88:89], 0, s[74:75]
	s_mov_b32 m0, s17
	v_readfirstlane_b32 s17, v98
	global_load_lds_dwordx4 v[90:91], off
	v_lshl_add_u64 v[90:91], v[88:89], 0, s[56:57]
	s_mov_b32 m0, s17
	s_add_i32 s15, s15, 2
	global_load_lds_dwordx4 v[90:91], off
	s_waitcnt lgkmcnt(0)
	v_mfma_f32_16x16x32_bf16 v[30:33], v[44:47], v[78:81], v[30:33]
	v_mfma_f32_16x16x32_bf16 v[26:29], v[48:51], v[78:81], v[26:29]
	v_mfma_f32_16x16x32_bf16 v[22:25], v[70:73], v[78:81], v[22:25]
	v_mfma_f32_16x16x32_bf16 v[18:21], v[74:77], v[78:81], v[18:21]
	v_mfma_f32_16x16x32_bf16 v[14:17], v[44:47], v[82:85], v[14:17]
	v_mfma_f32_16x16x32_bf16 v[10:13], v[48:51], v[82:85], v[10:13]
	v_mfma_f32_16x16x32_bf16 v[6:9], v[70:73], v[82:85], v[6:9]
	v_mfma_f32_16x16x32_bf16 v[2:5], v[74:77], v[82:85], v[2:5]
	s_waitcnt vmcnt(3)
	v_add_u32_e32 v74, v97, v92
	s_waitcnt lgkmcnt(0)
	s_barrier
	ds_read_b128 v[44:47], v74 offset:16384
	ds_read_b128 v[48:51], v74 offset:17408
	ds_read_b128 v[70:73], v74 offset:18432
	ds_read_b128 v[74:77], v74 offset:19456
	v_add_u32_e32 v82, v97, v93
	ds_read_b128 v[78:81], v82
	ds_read_b128 v[82:85], v82 offset:1024
	v_add_u32_e32 v90, s16, v96
	v_lshl_add_u64 v[86:87], v[86:87], 0, s[52:53]
	v_lshl_add_u64 v[86:87], v[86:87], 0, 64
	v_readfirstlane_b32 s17, v90
	v_add_u32_e32 v90, s16, v95
	s_mov_b32 m0, s17
	v_readfirstlane_b32 s17, v90
	global_load_lds_dwordx4 v[86:87], off
	v_lshl_add_u64 v[86:87], v[88:89], 0, s[52:53]
	v_lshl_add_u64 v[86:87], v[86:87], 0, 64
	s_mov_b32 m0, s17
	s_nop 0
	global_load_lds_dwordx4 v[86:87], off
	v_lshl_add_u64 v[86:87], v[88:89], 0, s[0:1]
	v_lshl_add_u64 v[86:87], v[86:87], 0, 64
	v_add_u32_e32 v88, s16, v94
	s_nop 0
	v_readfirstlane_b32 s16, v88
	s_mov_b32 m0, s16
	s_nop 0
	global_load_lds_dwordx4 v[86:87], off
	s_waitcnt lgkmcnt(0)
	v_mfma_f32_16x16x32_bf16 v[30:33], v[44:47], v[78:81], v[30:33]
	v_mfma_f32_16x16x32_bf16 v[26:29], v[48:51], v[78:81], v[26:29]
	v_mfma_f32_16x16x32_bf16 v[22:25], v[70:73], v[78:81], v[22:25]
	v_mfma_f32_16x16x32_bf16 v[18:21], v[74:77], v[78:81], v[18:21]
	v_mfma_f32_16x16x32_bf16 v[14:17], v[44:47], v[82:85], v[14:17]
	v_mfma_f32_16x16x32_bf16 v[10:13], v[48:51], v[82:85], v[10:13]
	v_mfma_f32_16x16x32_bf16 v[6:9], v[70:73], v[82:85], v[6:9]
	v_mfma_f32_16x16x32_bf16 v[2:5], v[74:77], v[82:85], v[2:5]
	s_addk_i32 s3, 0x6000
	s_add_i32 s11, s11, 2
	s_add_i32 s10, s10, 2
	s_add_i32 s14, s14, 2
	v_lshl_add_u64 v[40:41], v[40:41], 0, s[74:75]
	v_lshl_add_u64 v[40:41], v[40:41], 0, s[74:75]
	s_cmp_eq_u32 s3, 0x102000
	v_lshl_add_u64 v[42:43], v[42:43], 0, s[74:75]
	v_lshl_add_u64 v[42:43], v[42:43], 0, s[74:75]
	s_cbranch_scc0 .LBB0_338
	s_waitcnt vmcnt(3)
	s_waitcnt lgkmcnt(0)
	s_barrier
	ds_read_b128 v[40:43], v69 offset:28672
	ds_read_b128 v[44:47], v69 offset:29696
	ds_read_b128 v[48:51], v69 offset:30720
	ds_read_b128 v[70:73], v69 offset:31744
	ds_read_b128 v[74:77], v59 offset:24576
	ds_read_b128 v[78:81], v59 offset:25600
	s_mul_hi_u32 s10, s11, 0xaaaaaaab
	s_lshr_b32 s10, s10, 1
	s_mul_i32 s10, s10, 0x9000
	s_sub_i32 s3, s3, s10
	s_add_i32 s3, s3, 0
	s_addk_i32 s3, 0x3000
	s_waitcnt lgkmcnt(0)
	v_mfma_f32_16x16x32_bf16 v[30:33], v[40:43], v[74:77], v[30:33]
	v_mfma_f32_16x16x32_bf16 v[26:29], v[44:47], v[74:77], v[26:29]
	v_mfma_f32_16x16x32_bf16 v[22:25], v[48:51], v[74:77], v[22:25]
	v_mfma_f32_16x16x32_bf16 v[18:21], v[70:73], v[74:77], v[18:21]
	v_mfma_f32_16x16x32_bf16 v[14:17], v[40:43], v[78:81], v[14:17]
	v_mfma_f32_16x16x32_bf16 v[10:13], v[44:47], v[78:81], v[10:13]
	v_mfma_f32_16x16x32_bf16 v[6:9], v[48:51], v[78:81], v[6:9]
	v_mfma_f32_16x16x32_bf16 v[2:5], v[70:73], v[78:81], v[2:5]
	v_lshl_add_u32 v40, v54, 1, s3
	s_waitcnt vmcnt(0)
	v_add3_u32 v70, v40, v57, v53
	s_waitcnt lgkmcnt(0)
	s_barrier
; #define MFMA(a, b, c) __builtin_amdgcn_mfma_f32_16x16x32_bf16((a), (b), (c), 0, 0, 0)
; template <int EPI, int MF>
; __device__ __forceinline__ void gemm_part(const u16* __restrict__ A, int lda, const u16* __restrict__ Bt, int K, int ntn, GemmEpi ep, char* smem,
;                                           int mbase, int mrows) {
;     ...
;     for (int kt = 0; kt < nk; ++kt) {
;       if (kt + 1 < nk) {
;         if (MF == 8) asm volatile("s_waitcnt vmcnt(6)" ::: "memory");
;         else asm volatile("s_waitcnt vmcnt(3)" ::: "memory");
;       } else asm volatile("s_waitcnt vmcnt(0)" ::: "memory");
;       asm volatile("s_waitcnt lgkmcnt(0)" ::: "memory");
;       __builtin_amdgcn_s_barrier();
;       const u16* a_ = sbase + (kt % 3) * STG;
;       const u16* b_ = a_ + BM * 32;
;       bf16x8 bfr[4], afc[2], afn[2];
;       const u16* ap_ = a_ + (wr * (16 * MF) + fr) * 32 + fq * 8;
; #pragma unroll
;       for (int n = 0; n < 4; ++n) bfr[n] = rd_std(b_ + (wc * 64 + n * 16 + fr) * 32 + fq * 8);
;       afc[0] = rd_std(ap_); afc[1] = rd_std(ap_ + 16 * 32);
;       __builtin_amdgcn_sched_barrier(0);
;       if (kt + 2 < nk) GEMM_ISSUE(kt + 2);
;       __builtin_amdgcn_sched_barrier(0);
; #pragma unroll
;       for (int mh = 0; mh < MF / 2; ++mh) {
;         if (mh + 1 < MF / 2) {
;           afn[0] = rd_std(ap_ + ((mh + 1) * 2) * 16 * 32);
;           afn[1] = rd_std(ap_ + ((mh + 1) * 2 + 1) * 16 * 32);
;         }
;         __builtin_amdgcn_sched_barrier(0);
; #pragma unroll
;         for (int m = 0; m < 2; ++m)
; #pragma unroll
;           for (int n = 0; n < 4; ++n) acc[mh * 2 + m][n] = MFMA(bfr[n], afc[m], acc[mh * 2 + m][n]);
;         __builtin_amdgcn_sched_barrier(0);
;         afc[0] = afn[0]; afc[1] = afn[1];
;       }
;     ...
;       } else if (EPI == EPI_RESID) {
;         const float* rp = (row < MP) ? ep.res0 + (size_t)row * DM : ep.res1 + (size_t)(row - MP) * DM;
;         float ssq = 0.f;
; #pragma unroll
;         for (int n = 0; n < 4; ++n) {
;           const int col = cb + n * 16;
;           const float4 r = *(const float4*)(rp + col);
;           float4 v;
;           v.x = r.x + ep.scale * acc[m][n][0]; v.y = r.y + ep.scale * acc[m][n][1];
;           v.z = r.z + ep.scale * acc[m][n][2]; v.w = r.w + ep.scale * acc[m][n][3];
;           *(float4*)(ep.outf + (size_t)row * DM + col) = v;
;           if (ep.xcopy) {
;             bf16x4 o;
	ds_read_b128 v[40:43], v70 offset:4096
	ds_read_b128 v[44:47], v70 offset:5120
	ds_read_b128 v[48:51], v70 offset:6144
	ds_read_b128 v[70:73], v70 offset:7168
	ds_read_b128 v[74:77], v59
	ds_read_b128 v[78:81], v59 offset:1024
	s_waitcnt lgkmcnt(0)
	v_mfma_f32_16x16x32_bf16 v[30:33], v[40:43], v[74:77], v[30:33]
	v_mfma_f32_16x16x32_bf16 v[26:29], v[44:47], v[74:77], v[26:29]
	v_mfma_f32_16x16x32_bf16 v[22:25], v[48:51], v[74:77], v[22:25]
	v_mfma_f32_16x16x32_bf16 v[18:21], v[70:73], v[74:77], v[18:21]
	v_mfma_f32_16x16x32_bf16 v[14:17], v[40:43], v[78:81], v[14:17]
	v_mfma_f32_16x16x32_bf16 v[10:13], v[44:47], v[78:81], v[10:13]
	v_mfma_f32_16x16x32_bf16 v[6:9], v[48:51], v[78:81], v[6:9]
	v_mfma_f32_16x16x32_bf16 v[2:5], v[70:73], v[78:81], v[2:5]
	v_add_u32_e32 v42, s2, v55
	s_waitcnt vmcnt(0)
	s_barrier
	s_mov_b32 s2, 0xffff
	v_cmp_lt_i32_e32 vcc, s2, v42
	s_and_saveexec_b64 s[2:3], vcc
	s_xor_b64 s[2:3], exec, s[2:3]
	v_add_u32_e32 v40, 0xffff0000, v42
	v_mov_b32_e32 v41, v0
	v_lshlrev_b64 v[40:41], 12, v[40:41]
	v_lshl_add_u64 v[46:47], s[18:19], 0, v[40:41]
	v_mov_b32_e32 v43, v0
	s_andn2_saveexec_b64 s[2:3], s[2:3]
	v_ashrrev_i32_e32 v43, 31, v42
	v_lshlrev_b64 v[40:41], 12, v[42:43]
	v_lshl_add_u64 v[46:47], s[8:9], 0, v[40:41]
	s_or_b64 exec, exec, s[2:3]
	v_or_b32_e32 v40, s5, v56
	v_lshlrev_b64 v[44:45], 12, v[42:43]
	v_lshl_add_u64 v[50:51], s[26:27], 0, v[44:45]
	v_lshlrev_b64 v[44:45], 11, v[42:43]
	v_ashrrev_i32_e32 v41, 31, v40
	v_lshl_add_u64 v[74:75], s[44:45], 0, v[44:45]
	v_lshlrev_b64 v[44:45], 2, v[40:41]
	v_lshl_add_u64 v[48:49], v[46:47], 0, v[44:45]
	global_load_dwordx4 v[70:73], v[48:49], off
	v_readlane_b32 s2, v253, 24
	v_readlane_b32 s3, v253, 25
	v_lshl_add_u64 v[46:47], v[50:51], 0, v[44:45]
	s_andn2_b64 vcc, exec, s[2:3]
	v_cndmask_b32_e64 v50, 0, 1, s[2:3]
	v_cmp_ne_u32_e64 s[14:15], 1, v50
	v_lshl_add_u64 v[50:51], v[40:41], 1, v[74:75]
	s_waitcnt vmcnt(0)
	v_pk_fma_f32 v[30:31], v[30:31], 0.5, v[70:71] op_sel_hi:[1,0,1]
	v_pk_fma_f32 v[32:33], v[32:33], 0.5, v[72:73] op_sel_hi:[1,0,1]
	global_store_dwordx4 v[46:47], v[30:33], off
	s_cbranch_vccnz .LBB0_345
	v_cvt_pk_bf16_f32 v70, v30, v31
	v_cvt_pk_bf16_f32 v71, v32, v33
	v_lshlrev_b32_e32 v84, 1, v50
	v_bfi_b32 v84, s100, v84, v50
	v_lshrrev_b32_e32 v85, 5, v50
	v_bfi_b32 v84, 64, v85, v84
	v_mov_b32_e32 v85, v51
	global_store_dwordx2 v[84:85], v[70:71], off
.LBB0_345:
	global_load_dwordx4 v[70:73], v[48:49], off offset:64
	s_and_b64 vcc, exec, s[14:15]
	s_waitcnt vmcnt(0)
	v_pk_fma_f32 v[26:27], v[26:27], 0.5, v[70:71] op_sel_hi:[1,0,1]
	v_pk_fma_f32 v[28:29], v[28:29], 0.5, v[72:73] op_sel_hi:[1,0,1]
	global_store_dwordx4 v[46:47], v[26:29], off offset:64
	s_cbranch_vccnz .LBB0_347
	v_cvt_pk_bf16_f32 v70, v26, v27
	v_cvt_pk_bf16_f32 v71, v28, v29
	v_lshlrev_b32_e32 v84, 1, v50
	v_bfi_b32 v84, s100, v84, v50
	v_lshrrev_b32_e32 v85, 5, v50
	v_bfi_b32 v84, 64, v85, v84
	v_mov_b32_e32 v85, v51
	global_store_dwordx2 v[84:85], v[70:71], off offset:32
.LBB0_347:
	global_load_dwordx4 v[70:73], v[48:49], off offset:128
	s_and_b64 vcc, exec, s[14:15]
	s_waitcnt vmcnt(0)
	v_pk_fma_f32 v[22:23], v[22:23], 0.5, v[70:71] op_sel_hi:[1,0,1]
	v_pk_fma_f32 v[24:25], v[24:25], 0.5, v[72:73] op_sel_hi:[1,0,1]
	global_store_dwordx4 v[46:47], v[22:25], off offset:128
	s_cbranch_vccnz .LBB0_349
	v_cvt_pk_bf16_f32 v70, v22, v23
	v_cvt_pk_bf16_f32 v71, v24, v25
	v_lshlrev_b32_e32 v84, 1, v50
	v_bfi_b32 v84, s100, v84, v50
	v_lshrrev_b32_e32 v85, 5, v50
	v_bfi_b32 v84, 64, v85, v84
	v_mov_b32_e32 v85, v51
	global_store_dwordx2 v[84:85], v[70:71], off offset:128
.LBB0_349:
	global_load_dwordx4 v[70:73], v[48:49], off offset:192
	s_and_b64 vcc, exec, s[14:15]
	s_waitcnt vmcnt(0)
	v_pk_fma_f32 v[18:19], v[18:19], 0.5, v[70:71] op_sel_hi:[1,0,1]
	v_pk_fma_f32 v[20:21], v[20:21], 0.5, v[72:73] op_sel_hi:[1,0,1]
	global_store_dwordx4 v[46:47], v[18:21], off offset:192
	s_cbranch_vccnz .LBB0_351
	v_cvt_pk_bf16_f32 v46, v18, v19
	v_cvt_pk_bf16_f32 v47, v20, v21
	v_lshlrev_b32_e32 v84, 1, v50
	v_bfi_b32 v84, s100, v84, v50
	v_lshrrev_b32_e32 v85, 5, v50
	v_bfi_b32 v84, 64, v85, v84
	v_mov_b32_e32 v85, v51
	global_store_dwordx2 v[84:85], v[46:47], off offset:160

; template <int EPI, int MF>
; __device__ __forceinline__ void gemm_part(const u16* __restrict__ A, int lda, const u16* __restrict__ Bt, int K, int ntn, GemmEpi ep, char* smem,
;                                           int mbase, int mrows) {
;     ...
;       } else if (EPI == EPI_RESID) {
;         const float* rp = (row < MP) ? ep.res0 + (size_t)row * DM : ep.res1 + (size_t)(row - MP) * DM;
;         float ssq = 0.f;
; #pragma unroll
;         for (int n = 0; n < 4; ++n) {
;           const int col = cb + n * 16;
;           const float4 r = *(const float4*)(rp + col);
;           float4 v;
;           v.x = r.x + ep.scale * acc[m][n][0]; v.y = r.y + ep.scale * acc[m][n][1];
;           v.z = r.z + ep.scale * acc[m][n][2]; v.w = r.w + ep.scale * acc[m][n][3];
;           *(float4*)(ep.outf + (size_t)row * DM + col) = v;
;           if (ep.xcopy) {
;             bf16x4 o;
;             o[0] = (short)f2bf(v.x); o[1] = (short)f2bf(v.y); o[2] = (short)f2bf(v.z); o[3] = (short)f2bf(v.w);
;             *(bf16x4*)(ep.xcopy + (size_t)row * DM + col) = o;
;           }
;           ssq += v.x * v.x + v.y * v.y + v.z * v.z + v.w * v.w;
;         }
.LBB0_355:
	s_waitcnt lgkmcnt(0)
	v_or_b32_e32 v18, 16, v42
	s_mov_b32 s2, 0xffff
	v_cmp_lt_i32_e32 vcc, s2, v18
	s_and_saveexec_b64 s[2:3], vcc
	s_xor_b64 s[2:3], exec, s[2:3]
	v_add_u32_e32 v20, 0xffff0010, v42
	v_mov_b32_e32 v21, v0
	v_lshlrev_b64 v[20:21], 12, v[20:21]
	v_lshl_add_u64 v[20:21], s[18:19], 0, v[20:21]
	v_mov_b32_e32 v19, v0
	s_andn2_saveexec_b64 s[2:3], s[2:3]
	v_ashrrev_i32_e32 v19, 31, v18
	v_lshlrev_b64 v[20:21], 12, v[18:19]
	v_lshl_add_u64 v[20:21], s[8:9], 0, v[20:21]
	s_or_b64 exec, exec, s[2:3]
	v_lshl_add_u64 v[20:21], v[20:21], 0, v[44:45]
	global_load_dwordx4 v[26:29], v[20:21], off
	v_lshlrev_b64 v[22:23], 12, v[18:19]
	v_lshlrev_b64 v[24:25], 11, v[18:19]
	v_lshl_add_u64 v[22:23], s[26:27], 0, v[22:23]
	v_lshl_add_u64 v[30:31], s[44:45], 0, v[24:25]
	s_and_b64 vcc, exec, s[14:15]
	v_lshl_add_u64 v[24:25], v[22:23], 0, v[44:45]
	v_lshl_add_u64 v[22:23], v[40:41], 1, v[30:31]
	s_waitcnt vmcnt(0)
	v_pk_fma_f32 v[14:15], v[14:15], 0.5, v[26:27] op_sel_hi:[1,0,1]
	v_pk_fma_f32 v[16:17], v[16:17], 0.5, v[28:29] op_sel_hi:[1,0,1]
	global_store_dwordx4 v[24:25], v[14:17], off
	s_cbranch_vccnz .LBB0_361
	v_cvt_pk_bf16_f32 v26, v14, v15
	v_cvt_pk_bf16_f32 v27, v16, v17
	v_lshlrev_b32_e32 v84, 1, v22
	v_bfi_b32 v84, s100, v84, v22
	v_lshrrev_b32_e32 v85, 5, v22
	v_bfi_b32 v84, 64, v85, v84
	v_mov_b32_e32 v85, v23
	global_store_dwordx2 v[84:85], v[26:27], off
.LBB0_361:
	global_load_dwordx4 v[26:29], v[20:21], off offset:64
	s_and_b64 vcc, exec, s[14:15]
	s_waitcnt vmcnt(0)
	v_pk_fma_f32 v[10:11], v[10:11], 0.5, v[26:27] op_sel_hi:[1,0,1]
	v_pk_fma_f32 v[12:13], v[12:13], 0.5, v[28:29] op_sel_hi:[1,0,1]
	global_store_dwordx4 v[24:25], v[10:13], off offset:64
	s_cbranch_vccnz .LBB0_363
	v_cvt_pk_bf16_f32 v26, v10, v11
	v_cvt_pk_bf16_f32 v27, v12, v13
	v_lshlrev_b32_e32 v84, 1, v22
	v_bfi_b32 v84, s100, v84, v22
	v_lshrrev_b32_e32 v85, 5, v22
	v_bfi_b32 v84, 64, v85, v84
	v_mov_b32_e32 v85, v23
	global_store_dwordx2 v[84:85], v[26:27], off offset:32
.LBB0_363:
	global_load_dwordx4 v[26:29], v[20:21], off offset:128
	s_and_b64 vcc, exec, s[14:15]
	s_waitcnt vmcnt(0)
	v_pk_fma_f32 v[6:7], v[6:7], 0.5, v[26:27] op_sel_hi:[1,0,1]
	v_pk_fma_f32 v[8:9], v[8:9], 0.5, v[28:29] op_sel_hi:[1,0,1]
	global_store_dwordx4 v[24:25], v[6:9], off offset:128
	s_cbranch_vccnz .LBB0_365
	v_cvt_pk_bf16_f32 v26, v6, v7
	v_cvt_pk_bf16_f32 v27, v8, v9
	v_lshlrev_b32_e32 v84, 1, v22
	v_bfi_b32 v84, s100, v84, v22
	v_lshrrev_b32_e32 v85, 5, v22
	v_bfi_b32 v84, 64, v85, v84
	v_mov_b32_e32 v85, v23
	global_store_dwordx2 v[84:85], v[26:27], off offset:128
.LBB0_365:
	global_load_dwordx4 v[26:29], v[20:21], off offset:192
	s_and_b64 vcc, exec, s[14:15]
	s_waitcnt vmcnt(0)
	v_pk_fma_f32 v[2:3], v[2:3], 0.5, v[26:27] op_sel_hi:[1,0,1]
	v_pk_fma_f32 v[4:5], v[4:5], 0.5, v[28:29] op_sel_hi:[1,0,1]
	global_store_dwordx4 v[24:25], v[2:5], off offset:192
	s_cbranch_vccnz .LBB0_367
	v_cvt_pk_bf16_f32 v20, v2, v3
	v_cvt_pk_bf16_f32 v21, v4, v5
	v_lshlrev_b32_e32 v84, 1, v22
	v_bfi_b32 v84, s100, v84, v22
	v_lshrrev_b32_e32 v85, 5, v22
	v_bfi_b32 v84, 64, v85, v84
	v_mov_b32_e32 v85, v23
	global_store_dwordx2 v[84:85], v[20:21], off offset:160

; template <int EPI, int MF>
; __device__ __forceinline__ void gemm_part(const u16* __restrict__ A, int lda, const u16* __restrict__ Bt, int K, int ntn, GemmEpi ep, char* smem,
;                                           int mbase, int mrows) {
;   const int tid = opaque_tid(), lane = tid & 63, wid = tid >> 6, wr = wid >> 1, wc = wid & 1, fr = lane & 15, fq = lane >> 4;
;   constexpr int BM = 32 * MF;
;   constexpr int STG = BM * 32 + 4096;
;   constexpr int NA = MF / 2;
;   u16* const sbase = (u16*)smem;
;   const int ntm = mrows / BM;
;   const int total = ntm * ntn;
;   const int nk = K / 32;
;   const int nbx = (MF == 2) ? (int)gridDim.x : (int)(gridDim.x >> 3);
;   const int xcd = (MF == 2) ? 0 : (int)(blockIdx.x & 7), li = (MF == 2) ? (int)blockIdx.x : (int)(blockIdx.x >> 3);
;   for (int q = xcd; q * nbx < total; q += (MF == 2) ? 1 : 8) {
;     const int L = q * nbx + li;
;     if (L >= total) continue;
;     const int g = L / (8 * ntn), rr = L % (8 * ntn);
;     const int rows = min(8, ntm - 8 * g);
;     const int tm = 8 * g + rr % rows, tn = rr / rows;
;     const int row0 = mbase + tm * BM, col0 = tn * 128;
;     f32x4 acc[MF][4];
; #pragma unroll
;     for (int m = 0; m < MF; ++m)
; #pragma unroll
;       for (int n = 0; n < 4; ++n) acc[m][n] = (f32x4){0.f, 0.f, 0.f, 0.f};
;     const u16* gA = A + (size_t)(row0 + (tid >> 2)) * lda + (tid & 3) * 8;
;     const u16* gB = Bt + (size_t)(col0 + (tid >> 2)) * K + (tid & 3) * 8;
;     ...
;     GEMM_ISSUE(0);
;     GEMM_ISSUE(1);
;     for (int kt = 0; kt < nk; ++kt) {
;       if (kt + 1 < nk) {
;         if (MF == 8) asm volatile("s_waitcnt vmcnt(6)" ::: "memory");
;         else asm volatile("s_waitcnt vmcnt(3)" ::: "memory");
;       } else asm volatile("s_waitcnt vmcnt(0)" ::: "memory");
;       asm volatile("s_waitcnt lgkmcnt(0)" ::: "memory");
;       __builtin_amdgcn_s_barrier();
;       const u16* a_ = sbase + (kt % 3) * STG;
;       const u16* b_ = a_ + BM * 32;
;       bf16x8 bfr[4], afc[2], afn[2];
;       const u16* ap_ = a_ + (wr * (16 * MF) + fr) * 32 + fq * 8;
; #pragma unroll
;       for (int n = 0; n < 4; ++n) bfr[n] = rd_std(b_ + (wc * 64 + n * 16 + fr) * 32 + fq * 8);
; __global__ void __launch_bounds__(256, 2) fwd_megakernel(Params p) {
;     ...
;       ep = GemmEpi{}; ep.outb = p.big; ep.rss_in = rss_mix;
;       gemm_phase<EPI_PROJ_ODD>(p.xn, DM, p.wt_odd_in, DM, OPP / 128, ep, smem);
.LBB0_407:
	s_or_b64 exec, exec, s[2:3]
	v_readlane_b32 s2, v254, 63
	v_readlane_b32 s3, v252, 0
	s_and_b64 s[2:3], s[2:3], exec
	s_mov_b32 s2, 0x40800
	s_cselect_b32 s2, s2, 0x102000
	v_readlane_b32 s8, v253, 26
	v_readlane_b32 s9, v253, 27
	s_add_u32 s2, s8, s2
	s_addc_u32 s3, s9, 0
	v_writelane_b32 v252, s2, 9
	v_readlane_b32 s10, v253, 28
	v_readlane_b32 s11, v253, 29
	v_writelane_b32 v252, s3, 10
	s_mov_b64 s[2:3], -1
	v_readlane_b32 s4, v252, 1
	v_readlane_b32 s5, v252, 2
	s_and_b64 vcc, exec, s[4:5]
	s_barrier
	s_cbranch_vccz .LBB0_1196
	v_readlane_b32 s2, v253, 32
	v_readlane_b32 s3, v253, 33
	v_mov_b32_e32 v2, v140
	s_andn2_b64 vcc, exec, s[2:3]
	s_movk_i32 s22, 0x1010
	s_cbranch_vccnz .LBB0_503
	v_lshlrev_b32_e32 v7, 4, v2
	v_lshrrev_b32_e32 v100, 4, v140
	v_sub_u32_e32 v100, 0, v100
	v_xor_b32_e32 v100, v100, v140
	v_and_b32_e32 v100, 3, v100
	v_lshlrev_b32_e32 v4, 4, v100
	v_mov_b32_e32 v5, v0
	v_bfe_u32 v3, v2, 4, 2
	v_lshl_add_u64 v[130:131], s[44:45], 0, v[4:5]
	v_lshl_add_u64 v[132:133], s[40:41], 0, v[4:5]
	v_lshlrev_b32_e32 v4, 5, v2
	v_bfe_u32 v6, v2, 6, 1
	v_and_b32_e32 v152, 0xfffff1e0, v4
	v_lshlrev_b32_e32 v4, 2, v3
	v_ashrrev_i32_e32 v1, 2, v2
	v_lshlrev_b32_e32 v153, 3, v3
	v_and_b32_e32 v154, 0xffffff8f, v2
	v_lshl_or_b32 v155, v6, 6, v4
	v_lshlrev_b32_e32 v156, 12, v6
	v_lshlrev_b32_e32 v4, 6, v2
	v_lshrrev_b32_e32 v101, 2, v140
	v_sub_u32_e32 v101, 0, v101
	v_lshrrev_b32_e32 v3, 4, v140
	v_xor_b32_e32 v101, v101, v3
	v_and_b32_e32 v101, 3, v101
	v_lshlrev_b32_e32 v3, 4, v101
	v_and_b32_e32 v2, 3, v2
	v_and_b32_e32 v157, 0x3c0, v4
	v_lshl_add_u32 v158, v152, 1, v3
	v_add_u32_e32 v4, v3, v156
	v_lshlrev_b32_e32 v2, 4, v100
	v_mov_b32_e32 v3, v0
	v_add_u32_e32 v149, 0, v7
	v_lshl_add_u64 v[134:135], s[44:45], 0, v[2:3]
	v_add_u32_e32 v159, v4, v157
	v_readlane_b32 s2, v253, 56
	v_readlane_b32 s4, v253, 9
	s_branch .LBB0_412

; template <int EPI, int MF>
; __device__ __forceinline__ void gemm_part(const u16* __restrict__ A, int lda, const u16* __restrict__ Bt, int K, int ntn, GemmEpi ep, char* smem,
;                                           int mbase, int mrows) {
;     ...
;   for (int q = xcd; q * nbx < total; q += (MF == 2) ? 1 : 8) {
;     const int L = q * nbx + li;
;     if (L >= total) continue;
;     const int g = L / (8 * ntn), rr = L % (8 * ntn);
;     const int rows = min(8, ntm - 8 * g);
;     const int tm = 8 * g + rr % rows, tn = rr / rows;
;     const int row0 = mbase + tm * BM, col0 = tn * 128;
;     f32x4 acc[MF][4];
; #pragma unroll
;     for (int m = 0; m < MF; ++m)
; #pragma unroll
;       for (int n = 0; n < 4; ++n) acc[m][n] = (f32x4){0.f, 0.f, 0.f, 0.f};
;     const u16* gA = A + (size_t)(row0 + (tid >> 2)) * lda + (tid & 3) * 8;
;     const u16* gB = Bt + (size_t)(col0 + (tid >> 2)) * K + (tid & 3) * 8;
;     ...
;     GEMM_ISSUE(0);
;     GEMM_ISSUE(1);
.LBB0_412:
	s_add_i32 s2, s2, s63
	s_cmpk_gt_u32 s2, 0x20ff
	s_cbranch_scc1 .LBB0_411
	s_and_b32 s3, s2, 0xffff
	s_mul_i32 s3, s3, 0xf83f
	s_lshr_b32 s3, s3, 24
	s_mul_i32 s5, s3, 0x108
	s_sub_i32 s2, s2, s5
	s_lshl_b32 s3, s3, 3
	s_and_b32 s5, s2, 7
	s_or_b32 s3, s3, s5
	s_and_b32 s3, s3, 0x7ff
	s_lshl_b32 s8, s3, 8
	v_add_u32_e32 v2, s8, v1
	s_lshl_b32 s2, s2, 4
	v_ashrrev_i32_e32 v3, 31, v2
	s_and_b32 s5, s2, 0x1f80
	v_lshlrev_b64 v[2:3], 11, v[2:3]
	v_readfirstlane_b32 s2, v149
	v_add_u32_e32 v10, 0x1000, v149
	v_lshl_add_u64 v[4:5], v[130:131], 0, v[2:3]
	v_lshlrev_b32_e32 v255, 1, v4
	v_bfi_b32 v255, s100, v255, v4
	v_lshrrev_b32_e32 v4, 5, v4
	v_bfi_b32 v4, 64, v4, v255
	s_mov_b32 m0, s2
	s_mov_b64 s[10:11], 0x20000
	v_readfirstlane_b32 s2, v10
	global_load_lds_dwordx4 v[4:5], off
	v_lshl_add_u64 v[8:9], v[4:5], 0, s[10:11]
	s_mov_b32 m0, s2
	s_mov_b64 s[2:3], 0x40000
	v_add_u32_e32 v10, 0x2000, v149
	v_add_u32_e32 v6, s5, v1
	global_load_lds_dwordx4 v[8:9], off
	v_lshl_add_u64 v[8:9], v[4:5], 0, s[2:3]
	v_readfirstlane_b32 s2, v10
	v_ashrrev_i32_e32 v7, 31, v6
	s_mov_b32 m0, s2
	s_mov_b64 s[2:3], 0x60000
	v_add_u32_e32 v10, 0x3000, v149
	v_lshlrev_b64 v[6:7], 11, v[6:7]
	global_load_lds_dwordx4 v[8:9], off
	v_lshl_add_u64 v[8:9], v[4:5], 0, s[2:3]
	v_readfirstlane_b32 s2, v10
	s_mov_b32 m0, s2
	v_lshl_add_u64 v[136:137], v[132:133], 0, v[6:7]
	v_lshlrev_b32_e32 v255, 1, v136
	v_bfi_b32 v255, s100, v255, v136
	v_lshrrev_b32_e32 v136, 5, v136
	v_bfi_b32 v136, 64, v136, v255
	v_add_u32_e32 v6, 0x4000, v149
	global_load_lds_dwordx4 v[8:9], off
	v_readfirstlane_b32 s2, v6
	v_add_u32_e32 v8, 0x5000, v149
	s_mov_b32 m0, s2
	v_readfirstlane_b32 s2, v8
	v_add_u32_e32 v8, 0x6000, v149
	global_load_lds_dwordx4 v[136:137], off
	v_lshl_add_u64 v[6:7], v[136:137], 0, s[10:11]
	s_mov_b32 m0, s2
	v_readfirstlane_b32 s2, v8
	v_add_u32_e32 v8, 0x7000, v149
	global_load_lds_dwordx4 v[6:7], off
	v_lshl_add_u64 v[6:7], v[4:5], 0, 64
	v_lshl_add_u64 v[6:7], v[6:7], 0, 64
	s_mov_b32 m0, s2
	s_mov_b64 s[10:11], 0x20040
	v_readfirstlane_b32 s2, v8
	global_load_lds_dwordx4 v[6:7], off
	v_lshl_add_u64 v[6:7], v[4:5], 0, s[10:11]
	v_lshl_add_u64 v[6:7], v[6:7], 0, 64
	s_mov_b32 m0, s2
	s_mov_b64 s[2:3], 0x40040
	v_add_u32_e32 v8, 0x8000, v149
	global_load_lds_dwordx4 v[6:7], off
	v_lshl_add_u64 v[6:7], v[4:5], 0, s[2:3]
	v_lshl_add_u64 v[6:7], v[6:7], 0, 64
	v_readfirstlane_b32 s2, v8
	s_mov_b32 m0, s2
	s_mov_b64 s[2:3], 0x60040
	global_load_lds_dwordx4 v[6:7], off
	v_add_u32_e32 v6, 0x9000, v149
	v_lshl_add_u64 v[4:5], v[4:5], 0, s[2:3]
	v_lshl_add_u64 v[4:5], v[4:5], 0, 64
	v_readfirstlane_b32 s2, v6
	v_add_u32_e32 v6, 0xa000, v149
	s_mov_b32 m0, s2
	v_readfirstlane_b32 s2, v6
	v_add_u32_e32 v6, 0xb000, v149
	global_load_lds_dwordx4 v[4:5], off
	v_lshl_add_u64 v[4:5], v[136:137], 0, 64
	v_lshl_add_u64 v[4:5], v[4:5], 0, 64
	s_mov_b32 m0, s2
	v_readfirstlane_b32 s2, v6
	global_load_lds_dwordx4 v[4:5], off
	v_lshl_add_u64 v[4:5], v[136:137], 0, s[10:11]
	v_lshl_add_u64 v[4:5], v[4:5], 0, 64
	s_mov_b32 m0, s2
	v_lshl_add_u64 v[138:139], v[134:135], 0, v[2:3]
	v_lshlrev_b32_e32 v255, 1, v138
	v_bfi_b32 v255, s100, v255, v138
	v_lshrrev_b32_e32 v138, 5, v138
	v_bfi_b32 v138, 64, v138, v255
	v_lshl_add_u64 v[138:139], v[138:139], 0, 64
	v_lshl_add_u64 v[138:139], v[138:139], 0, 64
	global_load_lds_dwordx4 v[4:5], off
	v_lshl_add_u64 v[136:137], v[136:137], 0, 64
	v_lshl_add_u64 v[136:137], v[136:137], 0, 64
	v_mov_b32_e32 v2, 0
	s_mov_b64 s[2:3], 0
	s_mov_b32 s9, 2
	v_mov_b32_e32 v3, v2
	v_mov_b32_e32 v4, v2
	v_mov_b32_e32 v5, v2
	v_mov_b32_e32 v6, v2
	v_mov_b32_e32 v7, v2
	v_mov_b32_e32 v8, v2
	v_mov_b32_e32 v9, v2
	v_mov_b32_e32 v10, v2
	v_mov_b32_e32 v11, v2
	v_mov_b32_e32 v12, v2
	v_mov_b32_e32 v13, v2
	v_mov_b32_e32 v14, v2
	v_mov_b32_e32 v15, v2
	v_mov_b32_e32 v16, v2
	v_mov_b32_e32 v17, v2
	v_mov_b32_e32 v18, v2
	v_mov_b32_e32 v19, v2
	v_mov_b32_e32 v20, v2
	v_mov_b32_e32 v21, v2
	v_mov_b32_e32 v22, v2
	v_mov_b32_e32 v23, v2
	v_mov_b32_e32 v24, v2
	v_mov_b32_e32 v25, v2
	v_mov_b32_e32 v26, v2
	v_mov_b32_e32 v27, v2
	v_mov_b32_e32 v28, v2
	v_mov_b32_e32 v29, v2
	v_mov_b32_e32 v30, v2
	v_mov_b32_e32 v31, v2
	v_mov_b32_e32 v32, v2
	v_mov_b32_e32 v33, v2
	v_mov_b32_e32 v34, v2
	v_mov_b32_e32 v35, v2
	v_mov_b32_e32 v36, v2
	v_mov_b32_e32 v37, v2
	v_mov_b32_e32 v38, v2
	v_mov_b32_e32 v39, v2
	v_mov_b32_e32 v40, v2
	v_mov_b32_e32 v41, v2
	v_mov_b32_e32 v42, v2
	v_mov_b32_e32 v43, v2
	v_mov_b32_e32 v44, v2
	v_mov_b32_e32 v45, v2
	v_mov_b32_e32 v46, v2
	v_mov_b32_e32 v47, v2
	v_mov_b32_e32 v48, v2
	v_mov_b32_e32 v49, v2
	v_mov_b32_e32 v50, v2
	v_mov_b32_e32 v51, v2
	v_mov_b32_e32 v52, v2
	v_mov_b32_e32 v53, v2
	v_mov_b32_e32 v54, v2
	v_mov_b32_e32 v55, v2
	v_mov_b32_e32 v56, v2
	v_mov_b32_e32 v57, v2
	v_mov_b32_e32 v58, v2
	v_mov_b32_e32 v59, v2
	v_mov_b32_e32 v60, v2
	v_mov_b32_e32 v61, v2
	v_mov_b32_e32 v62, v2
	v_mov_b32_e32 v63, v2
	v_mov_b32_e32 v64, v2
	v_mov_b32_e32 v65, v2
	v_mov_b32_e32 v66, v2
	v_mov_b32_e32 v67, v2
	v_mov_b32_e32 v68, v2
	v_mov_b32_e32 v69, v2
	v_mov_b32_e32 v70, v2
	v_mov_b32_e32 v71, v2
	v_mov_b32_e32 v72, v2
	v_mov_b32_e32 v73, v2
	v_mov_b32_e32 v74, v2
	v_mov_b32_e32 v75, v2
	v_mov_b32_e32 v76, v2
	v_mov_b32_e32 v77, v2
	v_mov_b32_e32 v78, v2
	v_mov_b32_e32 v79, v2
	v_mov_b32_e32 v80, v2
	v_mov_b32_e32 v81, v2
	v_mov_b32_e32 v82, v2
	v_mov_b32_e32 v83, v2
	v_mov_b32_e32 v84, v2
	v_mov_b32_e32 v85, v2
	v_mov_b32_e32 v86, v2
	v_mov_b32_e32 v87, v2
	s_waitcnt vmcnt(0)
	v_mov_b32_e32 v88, v2
	v_mov_b32_e32 v89, v2
	v_mov_b32_e32 v90, v2
	v_mov_b32_e32 v91, v2
	v_mov_b32_e32 v92, v2
	v_mov_b32_e32 v93, v2
	v_mov_b32_e32 v94, v2
	v_mov_b32_e32 v95, v2
	v_mov_b32_e32 v96, v2
	v_mov_b32_e32 v97, v2
	v_mov_b32_e32 v98, v2
	v_mov_b32_e32 v99, v2
	v_mov_b32_e32 v100, v2
	v_mov_b32_e32 v101, v2
	v_mov_b32_e32 v102, v2
	v_mov_b32_e32 v103, v2
	v_mov_b32_e32 v104, v2
	v_mov_b32_e32 v105, v2
	v_mov_b32_e32 v106, v2
	v_mov_b32_e32 v107, v2
	v_mov_b32_e32 v108, v2
	v_mov_b32_e32 v109, v2
	v_mov_b32_e32 v110, v2
	v_mov_b32_e32 v111, v2
	v_mov_b32_e32 v112, v2
	v_mov_b32_e32 v113, v2
	v_mov_b32_e32 v114, v2
	v_mov_b32_e32 v115, v2
	v_mov_b32_e32 v116, v2
	v_mov_b32_e32 v117, v2
	v_mov_b32_e32 v118, v2
	v_mov_b32_e32 v119, v2
	v_mov_b32_e32 v120, v2
	v_mov_b32_e32 v121, v2
	v_mov_b32_e32 v122, v2
	v_mov_b32_e32 v123, v2
	v_mov_b32_e32 v124, v2
	v_mov_b32_e32 v125, v2
	v_mov_b32_e32 v126, v2
	v_mov_b32_e32 v127, v2
	v_mov_b32_e32 v128, v2
	v_mov_b32_e32 v129, v2
; #define MFMA(a, b, c) __builtin_amdgcn_mfma_f32_16x16x32_bf16((a), (b), (c), 0, 0, 0)
; template <int EPI, int MF>
; __device__ __forceinline__ void gemm_part(const u16* __restrict__ A, int lda, const u16* __restrict__ Bt, int K, int ntn, GemmEpi ep, char* smem,
;                                           int mbase, int mrows) {
;     ...
;     for (int kt = 0; kt < nk; ++kt) {
;       if (kt + 1 < nk) {
;         if (MF == 8) asm volatile("s_waitcnt vmcnt(6)" ::: "memory");
;         else asm volatile("s_waitcnt vmcnt(3)" ::: "memory");
;       } else asm volatile("s_waitcnt vmcnt(0)" ::: "memory");
;       asm volatile("s_waitcnt lgkmcnt(0)" ::: "memory");
;       __builtin_amdgcn_s_barrier();
;       const u16* a_ = sbase + (kt % 3) * STG;
;       const u16* b_ = a_ + BM * 32;
;       bf16x8 bfr[4], afc[2], afn[2];
;       const u16* ap_ = a_ + (wr * (16 * MF) + fr) * 32 + fq * 8;
; #pragma unroll
;       for (int n = 0; n < 4; ++n) bfr[n] = rd_std(b_ + (wc * 64 + n * 16 + fr) * 32 + fq * 8);
;       afc[0] = rd_std(ap_); afc[1] = rd_std(ap_ + 16 * 32);
;       __builtin_amdgcn_sched_barrier(0);
;       if (kt + 2 < nk) GEMM_ISSUE(kt + 2);
;       __builtin_amdgcn_sched_barrier(0);
; #pragma unroll
;       for (int mh = 0; mh < MF / 2; ++mh) {
;         if (mh + 1 < MF / 2) {
;           afn[0] = rd_std(ap_ + ((mh + 1) * 2) * 16 * 32);
;           afn[1] = rd_std(ap_ + ((mh + 1) * 2 + 1) * 16 * 32);
;         }
;         __builtin_amdgcn_sched_barrier(0);
; #pragma unroll
;         for (int m = 0; m < 2; ++m)
; #pragma unroll
;           for (int n = 0; n < 4; ++n) acc[mh * 2 + m][n] = MFMA(bfr[n], afc[m], acc[mh * 2 + m][n]);
;         __builtin_amdgcn_sched_barrier(0);
;         afc[0] = afn[0]; afc[1] = afn[1];
;       }
.LBB0_414:
	s_mul_i32 s10, s9, 0xab
	s_add_i32 s11, s10, 0xfeaa
	s_bfe_u32 s11, s11, 0x70009
	s_mul_i32 s11, s11, 3
	s_sub_i32 s11, s9, s11
	s_add_i32 s11, s11, 0xfffe
	s_and_b32 s11, s11, 0xff
	s_mulk_i32 s11, 0x6000
	s_add_i32 s11, s11, 0
	v_lshl_add_u32 v146, v153, 1, s11
	s_waitcnt vmcnt(6)
	v_add_u32_e32 v147, s11, v159
	s_waitcnt lgkmcnt(0)
	s_barrier
	ds_read_b128 v[160:163], v147 offset:16384
	ds_read_b128 v[164:167], v147 offset:17408
	ds_read_b128 v[168:171], v147 offset:18432
	ds_read_b128 v[172:175], v147 offset:19456
	v_add_u32_e32 v148, s11, v158
	ds_read_b128 v[176:179], v148
	ds_read_b128 v[180:183], v148 offset:1024
	s_bfe_u32 s10, s10, 0x70009
	s_mul_i32 s10, s10, 3
	s_sub_i32 s10, s9, s10
	s_and_b32 s10, s10, 0xff
	s_mulk_i32 s10, 0x6000
	v_add_u32_e32 v184, s10, v149
	v_lshl_add_u64 v[146:147], s[2:3], 1, v[138:139]
	v_readfirstlane_b32 s10, v184
	v_add_u32_e32 v185, 0x1000, v184
	v_lshl_add_u64 v[150:151], v[146:147], 0, s[74:75]
	s_mov_b32 m0, s10
	v_readfirstlane_b32 s10, v185
	v_add_u32_e32 v185, 0x2000, v184
	global_load_lds_dwordx4 v[150:151], off
	v_lshl_add_u64 v[150:151], v[146:147], 0, s[92:93]
	s_mov_b32 m0, s10
	v_readfirstlane_b32 s10, v185
	global_load_lds_dwordx4 v[150:151], off
	v_lshl_add_u64 v[150:151], v[146:147], 0, s[88:89]
	s_mov_b32 m0, s10
	v_lshl_add_u64 v[146:147], v[146:147], 0, s[6:7]
	global_load_lds_dwordx4 v[150:151], off
	v_add_u32_e32 v150, 0x3000, v184
	v_add_u32_e32 v185, 0x4000, v184
	v_readfirstlane_b32 s10, v150
	s_mov_b32 m0, s10
	v_readfirstlane_b32 s10, v185
	global_load_lds_dwordx4 v[146:147], off
	v_lshl_add_u64 v[146:147], s[2:3], 1, v[136:137]
	v_lshl_add_u64 v[150:151], v[146:147], 0, s[74:75]
	s_mov_b32 m0, s10
	v_lshl_add_u64 v[146:147], v[146:147], 0, s[92:93]
	global_load_lds_dwordx4 v[150:151], off
	v_add_u32_e32 v150, 0x5000, v184
	s_nop 0
	v_readfirstlane_b32 s10, v150
	s_mov_b32 m0, s10
	s_nop 0
	global_load_lds_dwordx4 v[146:147], off
	ds_read_b128 v[184:187], v148 offset:3072
	ds_read_b128 v[188:191], v148 offset:2048
	s_waitcnt lgkmcnt(2)
	v_mfma_f32_16x16x32_bf16 v[126:129], v[160:163], v[176:179], v[126:129]
	v_mfma_f32_16x16x32_bf16 v[122:125], v[164:167], v[176:179], v[122:125]
	v_mfma_f32_16x16x32_bf16 v[118:121], v[168:171], v[176:179], v[118:121]
	v_mfma_f32_16x16x32_bf16 v[114:117], v[172:175], v[176:179], v[114:117]
	v_mfma_f32_16x16x32_bf16 v[110:113], v[160:163], v[180:183], v[110:113]
	v_mfma_f32_16x16x32_bf16 v[106:109], v[164:167], v[180:183], v[106:109]
	v_mfma_f32_16x16x32_bf16 v[102:105], v[168:171], v[180:183], v[102:105]
	v_mfma_f32_16x16x32_bf16 v[98:101], v[172:175], v[180:183], v[98:101]
	ds_read_b128 v[176:179], v148 offset:5120
	ds_read_b128 v[180:183], v148 offset:4096
	s_waitcnt lgkmcnt(2)
	v_mfma_f32_16x16x32_bf16 v[94:97], v[160:163], v[188:191], v[94:97]
	v_mfma_f32_16x16x32_bf16 v[90:93], v[164:167], v[188:191], v[90:93]
	v_mfma_f32_16x16x32_bf16 v[86:89], v[168:171], v[188:191], v[86:89]
	v_mfma_f32_16x16x32_bf16 v[82:85], v[172:175], v[188:191], v[82:85]
	v_mfma_f32_16x16x32_bf16 v[78:81], v[160:163], v[184:187], v[78:81]
	v_mfma_f32_16x16x32_bf16 v[74:77], v[164:167], v[184:187], v[74:77]
	v_mfma_f32_16x16x32_bf16 v[70:73], v[168:171], v[184:187], v[70:73]
	v_mfma_f32_16x16x32_bf16 v[66:69], v[172:175], v[184:187], v[66:69]
	ds_read_b128 v[184:187], v148 offset:7168
	ds_read_b128 v[188:191], v148 offset:6144
	s_waitcnt lgkmcnt(2)
	v_mfma_f32_16x16x32_bf16 v[62:65], v[160:163], v[180:183], v[62:65]
	v_mfma_f32_16x16x32_bf16 v[58:61], v[164:167], v[180:183], v[58:61]
	v_mfma_f32_16x16x32_bf16 v[54:57], v[168:171], v[180:183], v[54:57]
	v_mfma_f32_16x16x32_bf16 v[50:53], v[172:175], v[180:183], v[50:53]
	v_mfma_f32_16x16x32_bf16 v[46:49], v[160:163], v[176:179], v[46:49]
	v_mfma_f32_16x16x32_bf16 v[42:45], v[164:167], v[176:179], v[42:45]
	v_mfma_f32_16x16x32_bf16 v[38:41], v[168:171], v[176:179], v[38:41]
	v_mfma_f32_16x16x32_bf16 v[34:37], v[172:175], v[176:179], v[34:37]
	s_waitcnt lgkmcnt(0)
	v_mfma_f32_16x16x32_bf16 v[30:33], v[160:163], v[188:191], v[30:33]
	v_mfma_f32_16x16x32_bf16 v[26:29], v[164:167], v[188:191], v[26:29]
	v_mfma_f32_16x16x32_bf16 v[22:25], v[168:171], v[188:191], v[22:25]
	v_mfma_f32_16x16x32_bf16 v[18:21], v[172:175], v[188:191], v[18:21]
	v_mfma_f32_16x16x32_bf16 v[14:17], v[160:163], v[184:187], v[14:17]
	v_mfma_f32_16x16x32_bf16 v[10:13], v[164:167], v[184:187], v[10:13]
	v_mfma_f32_16x16x32_bf16 v[6:9], v[168:171], v[184:187], v[6:9]
	v_mfma_f32_16x16x32_bf16 v[2:5], v[172:175], v[184:187], v[2:5]
	s_add_u32 s2, s2, 64
	s_addc_u32 s3, s3, 0
	s_add_i32 s9, s9, 1
	s_cmpk_eq_i32 s2, 0x780
	s_cbranch_scc0 .LBB0_414
	s_waitcnt vmcnt(6)
	s_waitcnt lgkmcnt(0)
	s_barrier
; #define MFMA(a, b, c) __builtin_amdgcn_mfma_f32_16x16x32_bf16((a), (b), (c), 0, 0, 0)
; template <int EPI, int MF>
; __device__ __forceinline__ void gemm_part(const u16* __restrict__ A, int lda, const u16* __restrict__ Bt, int K, int ntn, GemmEpi ep, char* smem,
;                                           int mbase, int mrows) {
;     ...
;     for (int kt = 0; kt < nk; ++kt) {
;       if (kt + 1 < nk) {
;         if (MF == 8) asm volatile("s_waitcnt vmcnt(6)" ::: "memory");
;         else asm volatile("s_waitcnt vmcnt(3)" ::: "memory");
;       } else asm volatile("s_waitcnt vmcnt(0)" ::: "memory");
;       asm volatile("s_waitcnt lgkmcnt(0)" ::: "memory");
;       __builtin_amdgcn_s_barrier();
;       const u16* a_ = sbase + (kt % 3) * STG;
;       const u16* b_ = a_ + BM * 32;
;       bf16x8 bfr[4], afc[2], afn[2];
;       const u16* ap_ = a_ + (wr * (16 * MF) + fr) * 32 + fq * 8;
; #pragma unroll
;       for (int n = 0; n < 4; ++n) bfr[n] = rd_std(b_ + (wc * 64 + n * 16 + fr) * 32 + fq * 8);
;       afc[0] = rd_std(ap_); afc[1] = rd_std(ap_ + 16 * 32);
;       __builtin_amdgcn_sched_barrier(0);
;       if (kt + 2 < nk) GEMM_ISSUE(kt + 2);
;       __builtin_amdgcn_sched_barrier(0);
; #pragma unroll
;       for (int mh = 0; mh < MF / 2; ++mh) {
;         if (mh + 1 < MF / 2) {
;           afn[0] = rd_std(ap_ + ((mh + 1) * 2) * 16 * 32);
;           afn[1] = rd_std(ap_ + ((mh + 1) * 2 + 1) * 16 * 32);
;         }
;         __builtin_amdgcn_sched_barrier(0);
; #pragma unroll
;         for (int m = 0; m < 2; ++m)
; #pragma unroll
;           for (int n = 0; n < 4; ++n) acc[mh * 2 + m][n] = MFMA(bfr[n], afc[m], acc[mh * 2 + m][n]);
;         __builtin_amdgcn_sched_barrier(0);
;         afc[0] = afn[0]; afc[1] = afn[1];
;       }
;     }
;     ...
;     __syncthreads();
; #pragma unroll
;     for (int m = 0; m < MF; ++m) {
;       if (EPI == EPI_SWIGLU || (m & 1) == 0) __builtin_amdgcn_sched_barrier(0);
;       const int row = row0 + wr * (16 * MF) + m * 16 + fr;
;       const int cb = col0 + wc * 64 + 4 * fq;
;       float rstd = 1.f;
;       if (EPI != EPI_RESID) { if (ep.rss_in) rstd = rsqrtf(ep.rss_in[row] * (1.f / DM) + 1e-6f); }
	ds_read_b128 v[136:139], v159 offset:16384
	ds_read_b128 v[160:163], v159 offset:17408
	ds_read_b128 v[164:167], v159 offset:18432
	ds_read_b128 v[168:171], v159 offset:19456
	ds_read_b128 v[172:175], v158
	ds_read_b128 v[176:179], v158 offset:1024
	ds_read_b128 v[180:183], v158 offset:3072
	ds_read_b128 v[184:187], v158 offset:2048
	s_waitcnt lgkmcnt(0)
	v_mfma_f32_16x16x32_bf16 v[126:129], v[136:139], v[172:175], v[126:129]
	v_mfma_f32_16x16x32_bf16 v[122:125], v[160:163], v[172:175], v[122:125]
	v_mfma_f32_16x16x32_bf16 v[118:121], v[164:167], v[172:175], v[118:121]
	v_mfma_f32_16x16x32_bf16 v[114:117], v[168:171], v[172:175], v[114:117]
	v_mfma_f32_16x16x32_bf16 v[110:113], v[136:139], v[176:179], v[110:113]
	v_mfma_f32_16x16x32_bf16 v[106:109], v[160:163], v[176:179], v[106:109]
	v_mfma_f32_16x16x32_bf16 v[102:105], v[164:167], v[176:179], v[102:105]
	v_mfma_f32_16x16x32_bf16 v[98:101], v[168:171], v[176:179], v[98:101]
	ds_read_b128 v[172:175], v158 offset:5120
	ds_read_b128 v[176:179], v158 offset:4096
	v_mfma_f32_16x16x32_bf16 v[94:97], v[136:139], v[184:187], v[94:97]
	v_mfma_f32_16x16x32_bf16 v[90:93], v[160:163], v[184:187], v[90:93]
	v_mfma_f32_16x16x32_bf16 v[86:89], v[164:167], v[184:187], v[86:89]
	v_mfma_f32_16x16x32_bf16 v[82:85], v[168:171], v[184:187], v[82:85]
	v_mfma_f32_16x16x32_bf16 v[78:81], v[136:139], v[180:183], v[78:81]
	v_mfma_f32_16x16x32_bf16 v[74:77], v[160:163], v[180:183], v[74:77]
	v_mfma_f32_16x16x32_bf16 v[70:73], v[164:167], v[180:183], v[70:73]
	v_mfma_f32_16x16x32_bf16 v[66:69], v[168:171], v[180:183], v[66:69]
	ds_read_b128 v[180:183], v158 offset:7168
	ds_read_b128 v[184:187], v158 offset:6144
	s_waitcnt lgkmcnt(0)
	v_mfma_f32_16x16x32_bf16 v[62:65], v[136:139], v[176:179], v[62:65]
	v_mfma_f32_16x16x32_bf16 v[58:61], v[160:163], v[176:179], v[58:61]
	v_mfma_f32_16x16x32_bf16 v[54:57], v[164:167], v[176:179], v[54:57]
	v_mfma_f32_16x16x32_bf16 v[50:53], v[168:171], v[176:179], v[50:53]
	v_mfma_f32_16x16x32_bf16 v[46:49], v[136:139], v[172:175], v[46:49]
	v_mfma_f32_16x16x32_bf16 v[42:45], v[160:163], v[172:175], v[42:45]
	v_mfma_f32_16x16x32_bf16 v[38:41], v[164:167], v[172:175], v[38:41]
	v_mfma_f32_16x16x32_bf16 v[34:37], v[168:171], v[172:175], v[34:37]
	v_mfma_f32_16x16x32_bf16 v[30:33], v[136:139], v[184:187], v[30:33]
	v_mfma_f32_16x16x32_bf16 v[26:29], v[160:163], v[184:187], v[26:29]
	v_mfma_f32_16x16x32_bf16 v[22:25], v[164:167], v[184:187], v[22:25]
	v_mfma_f32_16x16x32_bf16 v[18:21], v[168:171], v[184:187], v[18:21]
	v_mfma_f32_16x16x32_bf16 v[14:17], v[136:139], v[180:183], v[14:17]
	v_mfma_f32_16x16x32_bf16 v[10:13], v[160:163], v[180:183], v[10:13]
	v_mfma_f32_16x16x32_bf16 v[6:9], v[164:167], v[180:183], v[6:9]
	v_mfma_f32_16x16x32_bf16 v[2:5], v[168:171], v[180:183], v[2:5]
	s_waitcnt vmcnt(0)
	s_waitcnt lgkmcnt(0)
	s_barrier
	ds_read_b128 v[136:139], v159 offset:40960
	ds_read_b128 v[160:163], v159 offset:41984
	ds_read_b128 v[164:167], v159 offset:43008
	ds_read_b128 v[168:171], v159 offset:44032
	ds_read_b128 v[172:175], v158 offset:24576
	ds_read_b128 v[176:179], v158 offset:25600
	ds_read_b128 v[180:183], v158 offset:27648
	ds_read_b128 v[184:187], v158 offset:26624
	s_waitcnt lgkmcnt(0)
	v_mfma_f32_16x16x32_bf16 v[126:129], v[136:139], v[172:175], v[126:129]
	v_mfma_f32_16x16x32_bf16 v[122:125], v[160:163], v[172:175], v[122:125]
	v_mfma_f32_16x16x32_bf16 v[118:121], v[164:167], v[172:175], v[118:121]
	v_mfma_f32_16x16x32_bf16 v[114:117], v[168:171], v[172:175], v[114:117]
	v_mfma_f32_16x16x32_bf16 v[110:113], v[136:139], v[176:179], v[110:113]
	v_mfma_f32_16x16x32_bf16 v[106:109], v[160:163], v[176:179], v[106:109]
	v_mfma_f32_16x16x32_bf16 v[102:105], v[164:167], v[176:179], v[102:105]
	v_mfma_f32_16x16x32_bf16 v[98:101], v[168:171], v[176:179], v[98:101]
	ds_read_b128 v[172:175], v158 offset:29696
	ds_read_b128 v[176:179], v158 offset:28672
	v_mfma_f32_16x16x32_bf16 v[94:97], v[136:139], v[184:187], v[94:97]
	v_mfma_f32_16x16x32_bf16 v[90:93], v[160:163], v[184:187], v[90:93]
	v_mfma_f32_16x16x32_bf16 v[86:89], v[164:167], v[184:187], v[86:89]
	v_mfma_f32_16x16x32_bf16 v[82:85], v[168:171], v[184:187], v[82:85]
	v_mfma_f32_16x16x32_bf16 v[78:81], v[136:139], v[180:183], v[78:81]
	v_mfma_f32_16x16x32_bf16 v[74:77], v[160:163], v[180:183], v[74:77]
	v_mfma_f32_16x16x32_bf16 v[70:73], v[164:167], v[180:183], v[70:73]
	v_mfma_f32_16x16x32_bf16 v[66:69], v[168:171], v[180:183], v[66:69]
	ds_read_b128 v[180:183], v158 offset:31744
	ds_read_b128 v[184:187], v158 offset:30720
	s_waitcnt lgkmcnt(0)
	v_mfma_f32_16x16x32_bf16 v[62:65], v[136:139], v[176:179], v[62:65]
	v_mfma_f32_16x16x32_bf16 v[58:61], v[160:163], v[176:179], v[58:61]
	v_mfma_f32_16x16x32_bf16 v[54:57], v[164:167], v[176:179], v[54:57]
	v_mfma_f32_16x16x32_bf16 v[50:53], v[168:171], v[176:179], v[50:53]
	v_mfma_f32_16x16x32_bf16 v[46:49], v[136:139], v[172:175], v[46:49]
	v_mfma_f32_16x16x32_bf16 v[42:45], v[160:163], v[172:175], v[42:45]
	v_mfma_f32_16x16x32_bf16 v[38:41], v[164:167], v[172:175], v[38:41]
	v_mfma_f32_16x16x32_bf16 v[34:37], v[168:171], v[172:175], v[34:37]
	v_mfma_f32_16x16x32_bf16 v[30:33], v[136:139], v[184:187], v[30:33]
	v_mfma_f32_16x16x32_bf16 v[26:29], v[160:163], v[184:187], v[26:29]
	v_mfma_f32_16x16x32_bf16 v[22:25], v[164:167], v[184:187], v[22:25]
	v_mfma_f32_16x16x32_bf16 v[18:21], v[168:171], v[184:187], v[18:21]
	v_mfma_f32_16x16x32_bf16 v[14:17], v[136:139], v[180:183], v[14:17]
	v_mfma_f32_16x16x32_bf16 v[10:13], v[160:163], v[180:183], v[10:13]
	v_mfma_f32_16x16x32_bf16 v[6:9], v[164:167], v[180:183], v[6:9]
	v_mfma_f32_16x16x32_bf16 v[2:5], v[168:171], v[180:183], v[2:5]
	v_add_u32_e32 v138, s8, v154
	s_waitcnt vmcnt(0)
	s_barrier
	v_readlane_b32 s2, v253, 30
	v_ashrrev_i32_e32 v139, 31, v138
	v_readlane_b32 s3, v253, 31
	s_and_b64 vcc, exec, s[2:3]
	v_lshl_add_u64 v[146:147], v[138:139], 2, s[66:67]
	s_cbranch_vccz .LBB0_417
	global_load_dword v136, v[146:147], off
	s_waitcnt vmcnt(0)
	v_fmamk_f32 v136, v136, 0x3a800000, v142
	v_mul_f32_e32 v137, 0x4b800000, v136
	v_cmp_gt_f32_e32 vcc, s69, v136
	s_nop 1
	v_cndmask_b32_e32 v136, v136, v137, vcc
	v_rsq_f32_e32 v136, v136
	s_nop 0
	v_mul_f32_e32 v137, 0x45800000, v136
	v_cndmask_b32_e32 v148, v136, v137, vcc
	s_branch .LBB0_418

; template <int EPI, int MF>
; __device__ __forceinline__ void gemm_part(const u16* __restrict__ A, int lda, const u16* __restrict__ Bt, int K, int ntn, GemmEpi ep, char* smem,
;                                           int mbase, int mrows) {
;     ...
;   for (int q = xcd; q * nbx < total; q += (MF == 2) ? 1 : 8) {
;     const int L = q * nbx + li;
;     if (L >= total) continue;
;     const int g = L / (8 * ntn), rr = L % (8 * ntn);
;     const int rows = min(8, ntm - 8 * g);
;     const int tm = 8 * g + rr % rows, tn = rr / rows;
;     const int row0 = mbase + tm * BM, col0 = tn * 128;
;     f32x4 acc[MF][4];
; #pragma unroll
;     for (int m = 0; m < MF; ++m)
; #pragma unroll
;       for (int n = 0; n < 4; ++n) acc[m][n] = (f32x4){0.f, 0.f, 0.f, 0.f};
;     const u16* gA = A + (size_t)(row0 + (tid >> 2)) * lda + (tid & 3) * 8;
;     const u16* gB = Bt + (size_t)(col0 + (tid >> 2)) * K + (tid & 3) * 8;
;     ...
;     GEMM_ISSUE(0);
;     GEMM_ISSUE(1);
.LBB0_506:
	s_add_i32 s2, s2, s64
	s_cmpk_gt_i32 s2, 0x107
	s_cbranch_scc1 .LBB0_505
	s_mul_hi_i32 s3, s2, 0x3e0f83e1
	s_lshr_b32 s5, s3, 31
	s_ashr_i32 s3, s3, 6
	s_add_i32 s3, s3, s5
	s_mul_i32 s5, s3, 0x108
	s_sub_i32 s2, s2, s5
	s_sext_i32_i16 s5, s2
	s_bfe_u32 s5, s5, 0x3001c
	s_add_i32 s5, s2, s5
	s_sext_i32_i16 s9, s5
	s_and_b32 s5, s5, 0xfff8
	s_sub_i32 s2, s2, s5
	s_sext_i32_i16 s2, s2
	s_lshl_b32 s3, s3, 9
	s_lshl_b32 s2, s2, 6
	s_add_i32 s8, s3, s2
	s_lshl_b32 s2, s9, 4
	s_and_b32 s5, s2, 0xffffff80
	s_add_i32 s8, s8, 0x10000
	v_add_u32_e32 v6, s5, v1
	v_add_u32_e32 v2, s8, v1
	v_ashrrev_i32_e32 v7, 31, v6
	v_ashrrev_i32_e32 v3, 31, v2
	v_lshlrev_b64 v[6:7], 11, v[6:7]
	v_lshlrev_b64 v[2:3], 11, v[2:3]
	v_lshl_add_u64 v[40:41], v[36:37], 0, v[6:7]
	v_lshlrev_b32_e32 v255, 1, v40
	v_bfi_b32 v255, s100, v255, v40
	v_lshrrev_b32_e32 v40, 5, v40
	v_bfi_b32 v40, 64, v40, v255
	v_readfirstlane_b32 s2, v47
	v_add_u32_e32 v6, 0x1000, v47
	v_lshl_add_u64 v[4:5], v[34:35], 0, v[2:3]
	v_lshlrev_b32_e32 v255, 1, v4
	v_bfi_b32 v255, s100, v255, v4
	v_lshrrev_b32_e32 v4, 5, v4
	v_bfi_b32 v4, 64, v4, v255
	s_mov_b32 m0, s2
	v_readfirstlane_b32 s2, v6
	global_load_lds_dwordx4 v[4:5], off
	s_mov_b32 m0, s2
	s_mov_b64 s[2:3], 0x20000
	v_add_u32_e32 v8, 0x2000, v47
	v_lshl_add_u64 v[6:7], v[40:41], 0, s[2:3]
	v_readfirstlane_b32 s2, v8
	global_load_lds_dwordx4 v[40:41], off
	s_mov_b32 m0, s2
	v_lshl_add_u64 v[4:5], v[4:5], 0, 64
	v_lshl_add_u64 v[4:5], v[4:5], 0, 64
	global_load_lds_dwordx4 v[6:7], off
	v_add_u32_e32 v6, 0x3000, v47
	v_lshl_add_u64 v[42:43], v[38:39], 0, v[2:3]
	v_lshlrev_b32_e32 v255, 1, v42
	v_bfi_b32 v255, s100, v255, v42
	v_lshrrev_b32_e32 v42, 5, v42
	v_bfi_b32 v42, 64, v42, v255
	v_lshl_add_u64 v[42:43], v[42:43], 0, 64
	v_lshl_add_u64 v[42:43], v[42:43], 0, 64
	v_readfirstlane_b32 s2, v6
	v_add_u32_e32 v6, 0x4000, v47
	s_mov_b32 m0, s2
	v_readfirstlane_b32 s2, v6
	global_load_lds_dwordx4 v[4:5], off
	v_lshl_add_u64 v[4:5], v[40:41], 0, 64
	v_lshl_add_u64 v[4:5], v[4:5], 0, 64
	s_mov_b32 m0, s2
	s_mov_b64 s[2:3], 0x20080
	v_add_u32_e32 v6, 0x5000, v47
	global_load_lds_dwordx4 v[4:5], off
	v_lshl_add_u64 v[4:5], v[40:41], 0, s[2:3]
	v_readfirstlane_b32 s2, v6
	s_mov_b32 m0, s2
	v_mov_b32_e32 v2, 0
	global_load_lds_dwordx4 v[4:5], off
	v_lshl_add_u64 v[40:41], v[40:41], 0, 64
	v_lshl_add_u64 v[40:41], v[40:41], 0, 64
	s_mov_b64 s[2:3], 0
	s_mov_b32 s9, 3
	v_mov_b32_e32 v3, v2
	v_mov_b32_e32 v4, v2
	v_mov_b32_e32 v5, v2
	v_mov_b32_e32 v6, v2
	v_mov_b32_e32 v7, v2
	v_mov_b32_e32 v8, v2
	v_mov_b32_e32 v9, v2
	v_mov_b32_e32 v10, v2
	v_mov_b32_e32 v11, v2
	v_mov_b32_e32 v12, v2
	v_mov_b32_e32 v13, v2
	v_mov_b32_e32 v14, v2
	v_mov_b32_e32 v15, v2
	v_mov_b32_e32 v16, v2
	v_mov_b32_e32 v17, v2
	v_mov_b32_e32 v18, v2
	v_mov_b32_e32 v19, v2
	v_mov_b32_e32 v20, v2
	v_mov_b32_e32 v21, v2
	v_mov_b32_e32 v22, v2
	v_mov_b32_e32 v23, v2
	v_mov_b32_e32 v24, v2
	v_mov_b32_e32 v25, v2
	v_mov_b32_e32 v26, v2
	v_mov_b32_e32 v27, v2
	v_mov_b32_e32 v28, v2
	v_mov_b32_e32 v29, v2
	v_mov_b32_e32 v30, v2
	v_mov_b32_e32 v31, v2
	v_mov_b32_e32 v32, v2
	v_mov_b32_e32 v33, v2
; #define MFMA(a, b, c) __builtin_amdgcn_mfma_f32_16x16x32_bf16((a), (b), (c), 0, 0, 0)
; template <int EPI, int MF>
; __device__ __forceinline__ void gemm_part(const u16* __restrict__ A, int lda, const u16* __restrict__ Bt, int K, int ntn, GemmEpi ep, char* smem,
;                                           int mbase, int mrows) {
;     ...
;     GEMM_ISSUE(0);
;     GEMM_ISSUE(1);
;     for (int kt = 0; kt < nk; ++kt) {
;       if (kt + 1 < nk) {
;         if (MF == 8) asm volatile("s_waitcnt vmcnt(6)" ::: "memory");
;         else asm volatile("s_waitcnt vmcnt(3)" ::: "memory");
;       } else asm volatile("s_waitcnt vmcnt(0)" ::: "memory");
;       asm volatile("s_waitcnt lgkmcnt(0)" ::: "memory");
;       __builtin_amdgcn_s_barrier();
;       const u16* a_ = sbase + (kt % 3) * STG;
;       const u16* b_ = a_ + BM * 32;
;       bf16x8 bfr[4], afc[2], afn[2];
;       const u16* ap_ = a_ + (wr * (16 * MF) + fr) * 32 + fq * 8;
; #pragma unroll
;       for (int n = 0; n < 4; ++n) bfr[n] = rd_std(b_ + (wc * 64 + n * 16 + fr) * 32 + fq * 8);
;       afc[0] = rd_std(ap_); afc[1] = rd_std(ap_ + 16 * 32);
;       __builtin_amdgcn_sched_barrier(0);
;       if (kt + 2 < nk) GEMM_ISSUE(kt + 2);
;       __builtin_amdgcn_sched_barrier(0);
; #pragma unroll
;       for (int mh = 0; mh < MF / 2; ++mh) {
;         if (mh + 1 < MF / 2) {
;           afn[0] = rd_std(ap_ + ((mh + 1) * 2) * 16 * 32);
;           afn[1] = rd_std(ap_ + ((mh + 1) * 2 + 1) * 16 * 32);
;         }
;         __builtin_amdgcn_sched_barrier(0);
; #pragma unroll
;         for (int m = 0; m < 2; ++m)
; #pragma unroll
;           for (int n = 0; n < 4; ++n) acc[mh * 2 + m][n] = MFMA(bfr[n], afc[m], acc[mh * 2 + m][n]);
;         __builtin_amdgcn_sched_barrier(0);
;         afc[0] = afn[0]; afc[1] = afn[1];
;       }
;     }
;     ...
;     __syncthreads();
; #pragma unroll
;     for (int m = 0; m < MF; ++m) {
;       if (EPI == EPI_SWIGLU || (m & 1) == 0) __builtin_amdgcn_sched_barrier(0);
;       const int row = row0 + wr * (16 * MF) + m * 16 + fr;
;       const int cb = col0 + wc * 64 + 4 * fq;
;       float rstd = 1.f;
;       if (EPI != EPI_RESID) { if (ep.rss_in) rstd = rsqrtf(ep.rss_in[row] * (1.f / DM) + 1e-6f); }
.LBB0_508:
	s_add_i32 s10, s9, 0xfffd
	s_and_b32 s11, s10, 0xff
	s_mulk_i32 s11, 0xab
	s_bfe_u32 s11, s11, 0x70009
	s_mul_i32 s11, s11, 3
	s_sub_i32 s11, s10, s11
	s_and_b32 s11, s11, 0xff
	s_mulk_i32 s11, 0x3000
	s_add_i32 s11, s11, 0
	v_add_u32_e32 v45, s11, v56
	s_waitcnt vmcnt(3)
	v_add3_u32 v45, v45, v54, v51
	s_waitcnt lgkmcnt(0)
	s_barrier
	v_add_u32_e32 v44, s11, v50
	ds_read_b128 v[60:63], v45 offset:4096
	ds_read_b128 v[64:67], v45 offset:5120
	ds_read_b128 v[68:71], v45 offset:6144
	ds_read_b128 v[72:75], v45 offset:7168
	v_add3_u32 v44, v44, v51, v56
	ds_read_b128 v[76:79], v44
	ds_read_b128 v[80:83], v44 offset:1024
	s_mul_i32 s11, s9, 0xab
	s_add_i32 s12, s11, 0xff55
	s_bfe_u32 s12, s12, 0x70009
	s_mul_i32 s12, s12, 3
	s_not_b32 s12, s12
	s_add_i32 s12, s12, s9
	s_and_b32 s12, s12, 0xff
	s_mulk_i32 s12, 0x3000
	v_add_u32_e32 v46, s12, v47
	v_lshl_add_u64 v[44:45], s[2:3], 1, v[42:43]
	v_readfirstlane_b32 s12, v46
	v_lshl_add_u64 v[48:49], v[44:45], 0, s[74:75]
	s_mov_b32 m0, s12
	v_add_u32_e32 v59, 0x1000, v46
	global_load_lds_dwordx4 v[48:49], off
	v_lshl_add_u64 v[48:49], s[2:3], 1, v[40:41]
	v_readfirstlane_b32 s12, v59
	v_add_u32_e32 v46, 0x2000, v46
	v_lshl_add_u64 v[84:85], v[48:49], 0, s[74:75]
	s_mov_b32 m0, s12
	v_readfirstlane_b32 s12, v46
	global_load_lds_dwordx4 v[84:85], off
	v_lshl_add_u64 v[84:85], v[48:49], 0, s[92:93]
	s_mov_b32 m0, s12
	s_nop 0
	global_load_lds_dwordx4 v[84:85], off
	s_waitcnt lgkmcnt(0)
	v_mfma_f32_16x16x32_bf16 v[30:33], v[60:63], v[76:79], v[30:33]
	v_mfma_f32_16x16x32_bf16 v[26:29], v[64:67], v[76:79], v[26:29]
	v_mfma_f32_16x16x32_bf16 v[22:25], v[68:71], v[76:79], v[22:25]
	v_mfma_f32_16x16x32_bf16 v[18:21], v[72:75], v[76:79], v[18:21]
	v_mfma_f32_16x16x32_bf16 v[14:17], v[60:63], v[80:83], v[14:17]
	v_mfma_f32_16x16x32_bf16 v[10:13], v[64:67], v[80:83], v[10:13]
	v_mfma_f32_16x16x32_bf16 v[6:9], v[68:71], v[80:83], v[6:9]
	v_mfma_f32_16x16x32_bf16 v[2:5], v[72:75], v[80:83], v[2:5]
	s_or_b32 s10, s10, 1
	s_and_b32 s12, s10, 0xff
	s_mulk_i32 s12, 0xab
	s_bfe_u32 s12, s12, 0x70009
	s_mul_i32 s12, s12, 3
	s_sub_i32 s10, s10, s12
	s_and_b32 s10, s10, 0xff
	s_mulk_i32 s10, 0x3000
	s_add_i32 s10, s10, 0
	v_add_u32_e32 v59, s10, v56
	s_waitcnt vmcnt(3)
	v_add3_u32 v59, v59, v54, v51
	s_waitcnt lgkmcnt(0)
	s_barrier
	v_add_u32_e32 v46, s10, v50
	ds_read_b128 v[60:63], v59 offset:4096
	ds_read_b128 v[64:67], v59 offset:5120
	ds_read_b128 v[68:71], v59 offset:6144
	ds_read_b128 v[72:75], v59 offset:7168
	v_add3_u32 v46, v46, v51, v56
	ds_read_b128 v[76:79], v46
	ds_read_b128 v[80:83], v46 offset:1024
	s_bfe_u32 s10, s11, 0x70009
	s_mul_i32 s10, s10, 3
	s_sub_i32 s10, s9, s10
	s_and_b32 s10, s10, 0xff
	s_mulk_i32 s10, 0x3000
	v_add_u32_e32 v46, s10, v47
	v_add_u32_e32 v59, 0x1000, v46
	v_readfirstlane_b32 s10, v46
	v_lshl_add_u64 v[44:45], v[44:45], 0, s[52:53]
	v_lshl_add_u64 v[44:45], v[44:45], 0, 64
	s_mov_b32 m0, s10
	v_readfirstlane_b32 s10, v59
	v_add_u32_e32 v46, 0x2000, v46
	global_load_lds_dwordx4 v[44:45], off
	v_lshl_add_u64 v[44:45], v[48:49], 0, s[52:53]
	v_lshl_add_u64 v[44:45], v[44:45], 0, 64
	s_mov_b32 m0, s10
	v_readfirstlane_b32 s10, v46
	global_load_lds_dwordx4 v[44:45], off
	v_lshl_add_u64 v[44:45], v[48:49], 0, s[54:55]
	v_lshl_add_u64 v[44:45], v[44:45], 0, 64
	s_mov_b32 m0, s10
	s_nop 0
	global_load_lds_dwordx4 v[44:45], off
	s_waitcnt lgkmcnt(0)
	v_mfma_f32_16x16x32_bf16 v[30:33], v[60:63], v[76:79], v[30:33]
	v_mfma_f32_16x16x32_bf16 v[26:29], v[64:67], v[76:79], v[26:29]
	v_mfma_f32_16x16x32_bf16 v[22:25], v[68:71], v[76:79], v[22:25]
	v_mfma_f32_16x16x32_bf16 v[18:21], v[72:75], v[76:79], v[18:21]
	v_mfma_f32_16x16x32_bf16 v[14:17], v[60:63], v[80:83], v[14:17]
	v_mfma_f32_16x16x32_bf16 v[10:13], v[64:67], v[80:83], v[10:13]
	v_mfma_f32_16x16x32_bf16 v[6:9], v[68:71], v[80:83], v[6:9]
	v_mfma_f32_16x16x32_bf16 v[2:5], v[72:75], v[80:83], v[2:5]
	s_add_u32 s2, s2, 0x80
	s_addc_u32 s3, s3, 0
	s_add_i32 s9, s9, 2
	s_cmpk_eq_i32 s2, 0x780
	s_cbranch_scc0 .LBB0_508
	s_waitcnt vmcnt(3)
	s_waitcnt lgkmcnt(0)
	s_barrier
	ds_read_b128 v[40:43], v57 offset:4096
	ds_read_b128 v[60:63], v57 offset:5120
	ds_read_b128 v[64:67], v57 offset:6144
	ds_read_b128 v[68:71], v57 offset:7168
	ds_read_b128 v[72:75], v55
	ds_read_b128 v[76:79], v55 offset:1024
	s_waitcnt lgkmcnt(0)
	v_mfma_f32_16x16x32_bf16 v[30:33], v[40:43], v[72:75], v[30:33]
	v_mfma_f32_16x16x32_bf16 v[26:29], v[60:63], v[72:75], v[26:29]
	v_mfma_f32_16x16x32_bf16 v[22:25], v[64:67], v[72:75], v[22:25]
	v_mfma_f32_16x16x32_bf16 v[18:21], v[68:71], v[72:75], v[18:21]
	v_mfma_f32_16x16x32_bf16 v[14:17], v[40:43], v[76:79], v[14:17]
	v_mfma_f32_16x16x32_bf16 v[10:13], v[60:63], v[76:79], v[10:13]
	v_mfma_f32_16x16x32_bf16 v[6:9], v[64:67], v[76:79], v[6:9]
	v_mfma_f32_16x16x32_bf16 v[2:5], v[68:71], v[76:79], v[2:5]
	s_waitcnt vmcnt(0)
	s_waitcnt lgkmcnt(0)
	s_barrier
	ds_read_b128 v[40:43], v58 offset:16384
	ds_read_b128 v[60:63], v58 offset:17408
	ds_read_b128 v[64:67], v58 offset:18432
	ds_read_b128 v[68:71], v58 offset:19456
	ds_read_b128 v[72:75], v55 offset:12288
	ds_read_b128 v[76:79], v55 offset:13312
	s_waitcnt lgkmcnt(0)
	v_mfma_f32_16x16x32_bf16 v[30:33], v[40:43], v[72:75], v[30:33]
	v_mfma_f32_16x16x32_bf16 v[26:29], v[60:63], v[72:75], v[26:29]
	v_mfma_f32_16x16x32_bf16 v[22:25], v[64:67], v[72:75], v[22:25]
	v_mfma_f32_16x16x32_bf16 v[18:21], v[68:71], v[72:75], v[18:21]
	v_mfma_f32_16x16x32_bf16 v[14:17], v[40:43], v[76:79], v[14:17]
	v_mfma_f32_16x16x32_bf16 v[10:13], v[60:63], v[76:79], v[10:13]
	v_mfma_f32_16x16x32_bf16 v[6:9], v[64:67], v[76:79], v[6:9]
	v_mfma_f32_16x16x32_bf16 v[2:5], v[68:71], v[76:79], v[2:5]
	v_add_u32_e32 v42, s8, v52
	s_waitcnt vmcnt(0)
	s_barrier
	v_readlane_b32 s2, v253, 30
	v_ashrrev_i32_e32 v43, 31, v42
	v_readlane_b32 s3, v253, 31
	s_and_b64 vcc, exec, s[2:3]
	v_lshl_add_u64 v[44:45], v[42:43], 2, s[66:67]
	s_cbranch_vccz .LBB0_511
	global_load_dword v40, v[44:45], off
	s_waitcnt vmcnt(0)
	v_fmamk_f32 v40, v40, 0x3a800000, v142
	v_mul_f32_e32 v41, 0x4b800000, v40
	v_cmp_gt_f32_e32 vcc, s69, v40
	s_nop 1
	v_cndmask_b32_e32 v40, v40, v41, vcc
	v_rsq_f32_e32 v40, v40
	s_nop 0
	v_mul_f32_e32 v41, 0x45800000, v40
	v_cndmask_b32_e32 v46, v40, v41, vcc
	s_branch .LBB0_512

; __device__ __forceinline__ int opaque_tid() { int t = threadIdx.x; asm volatile("" : "+v"(t)); return t; }
; template <int EPI, int MF>
; __device__ __forceinline__ void gemm_part(const u16* __restrict__ A, int lda, const u16* __restrict__ Bt, int K, int ntn, GemmEpi ep, char* smem,
;                                           int mbase, int mrows) {
;   const int tid = opaque_tid(), lane = tid & 63, wid = tid >> 6, wr = wid >> 1, wc = wid & 1, fr = lane & 15, fq = lane >> 4;
;   constexpr int BM = 32 * MF;
;   constexpr int STG = BM * 32 + 4096;
;   constexpr int NA = MF / 2;
;   u16* const sbase = (u16*)smem;
;   const int ntm = mrows / BM;
;   const int total = ntm * ntn;
;   const int nk = K / 32;
;   const int nbx = (MF == 2) ? (int)gridDim.x : (int)(gridDim.x >> 3);
;   const int xcd = (MF == 2) ? 0 : (int)(blockIdx.x & 7), li = (MF == 2) ? (int)blockIdx.x : (int)(blockIdx.x >> 3);
;   for (int q = xcd; q * nbx < total; q += (MF == 2) ? 1 : 8) {
;     const int L = q * nbx + li;
;     if (L >= total) continue;
;     const int g = L / (8 * ntn), rr = L % (8 * ntn);
;     const int rows = min(8, ntm - 8 * g);
;     const int tm = 8 * g + rr % rows, tn = rr / rows;
;     const int row0 = mbase + tm * BM, col0 = tn * 128;
;     f32x4 acc[MF][4];
; #pragma unroll
;     for (int m = 0; m < MF; ++m)
; #pragma unroll
;       for (int n = 0; n < 4; ++n) acc[m][n] = (f32x4){0.f, 0.f, 0.f, 0.f};
;     const u16* gA = A + (size_t)(row0 + (tid >> 2)) * lda + (tid & 3) * 8;
;     const u16* gB = Bt + (size_t)(col0 + (tid >> 2)) * K + (tid & 3) * 8;
.LBB0_1122:
	s_or_b64 exec, exec, s[2:3]
	v_readlane_b32 s2, v252, 7
	v_readlane_b32 s3, v252, 8
	v_mov_b32_e32 v2, v140
	s_and_b64 vcc, exec, s[2:3]
	s_barrier
	s_cbranch_vccnz .LBB0_1177
	v_lshlrev_b32_e32 v7, 4, v2
	v_lshrrev_b32_e32 v100, 4, v140
	v_sub_u32_e32 v100, 0, v100
	v_xor_b32_e32 v100, v100, v140
	v_and_b32_e32 v100, 3, v100
	v_lshlrev_b32_e32 v4, 4, v100
	v_mov_b32_e32 v5, v0
	v_bfe_u32 v3, v2, 4, 2
	v_lshl_add_u64 v[130:131], s[44:45], 0, v[4:5]
	v_lshl_add_u64 v[132:133], s[42:43], 0, v[4:5]
	v_lshlrev_b32_e32 v4, 5, v2
	v_bfe_u32 v6, v2, 6, 1
	v_and_b32_e32 v149, 0xfffff1e0, v4
	v_lshlrev_b32_e32 v4, 2, v3
	v_lshl_or_b32 v152, v6, 6, v4
	v_lshlrev_b32_e32 v153, 12, v6
	v_lshlrev_b32_e32 v4, 6, v2
	v_lshrrev_b32_e32 v101, 2, v140
	v_sub_u32_e32 v101, 0, v101
	v_lshrrev_b32_e32 v156, 4, v140
	v_xor_b32_e32 v101, v101, v156
	v_and_b32_e32 v101, 3, v101
	v_lshlrev_b32_e32 v156, 4, v101
	v_ashrrev_i32_e32 v1, 2, v2
	v_lshlrev_b32_e32 v150, 3, v3
	v_and_b32_e32 v151, 0xffffff8f, v2
	v_cmp_eq_u32_e32 vcc, 0, v3
	v_and_b32_e32 v154, 0x3c0, v4
	v_lshlrev_b32_e32 v155, 1, v149
	v_add_u32_e32 v3, v156, v153
	v_and_b32_e32 v2, 3, v2
	v_readlane_b32 s2, v254, 2
	v_add_u32_e32 v148, 0, v7
	v_add_u32_e32 v157, v156, v155
	v_lshlrev_b32_e32 v134, 4, v100
	v_mov_b32_e32 v135, v0
	v_add_u32_e32 v158, s2, v1
	v_or_b32_e32 v159, v153, v154
	v_add_u32_e32 v160, v3, v154
	v_readlane_b32 s4, v254, 1
	v_readlane_b32 s5, v254, 0
	v_readlane_b32 s2, v253, 56
	v_readlane_b32 s8, v253, 9
	s_branch .LBB0_1126

; template <int EPI, int MF>
; __device__ __forceinline__ void gemm_part(const u16* __restrict__ A, int lda, const u16* __restrict__ Bt, int K, int ntn, GemmEpi ep, char* smem,
;                                           int mbase, int mrows) {
;     ...
;   for (int q = xcd; q * nbx < total; q += (MF == 2) ? 1 : 8) {
;     const int L = q * nbx + li;
;     if (L >= total) continue;
;     const int g = L / (8 * ntn), rr = L % (8 * ntn);
;     const int rows = min(8, ntm - 8 * g);
;     const int tm = 8 * g + rr % rows, tn = rr / rows;
;     const int row0 = mbase + tm * BM, col0 = tn * 128;
;     f32x4 acc[MF][4];
; #pragma unroll
;     for (int m = 0; m < MF; ++m)
; #pragma unroll
;       for (int n = 0; n < 4; ++n) acc[m][n] = (f32x4){0.f, 0.f, 0.f, 0.f};
;     const u16* gA = A + (size_t)(row0 + (tid >> 2)) * lda + (tid & 3) * 8;
;     const u16* gB = Bt + (size_t)(col0 + (tid >> 2)) * K + (tid & 3) * 8;
;     ...
;     GEMM_ISSUE(0);
;     GEMM_ISSUE(1);
.LBB0_1126:
	s_add_i32 s2, s2, s63
	s_cmpk_gt_u32 s2, 0x7ff
	s_cbranch_scc1 .LBB0_1125
	s_lshl_b32 s3, s5, 5
	s_and_b32 s3, s3, 0xf800
	v_add_u32_e32 v2, s3, v158
	s_waitcnt lgkmcnt(0)
	v_ashrrev_i32_e32 v3, 31, v2
	v_lshlrev_b64 v[2:3], 11, v[2:3]
	s_and_b32 s3, s4, 0x380
	v_lshl_add_u64 v[136:137], s[44:45], 0, v[2:3]
	v_add_u32_e32 v2, s3, v1
	s_lshr_b32 s3, s2, 3
	s_and_b32 s3, s3, 0xf8
	s_and_b32 s9, s2, 7
	v_ashrrev_i32_e32 v3, 31, v2
	s_or_b32 s3, s3, s9
	v_lshlrev_b64 v[2:3], 11, v[2:3]
	s_lshl_b32 s9, s2, 4
	s_lshl_b32 s2, s3, 8
	v_lshl_add_u64 v[138:139], s[42:43], 0, v[2:3]
	v_lshlrev_b32_e32 v255, 1, v138
	v_bfi_b32 v255, s100, v255, v138
	v_lshrrev_b32_e32 v138, 5, v138
	v_bfi_b32 v138, 64, v138, v255
	v_lshl_add_u64 v[138:139], v[138:139], 0, 64
	v_lshl_add_u64 v[138:139], v[138:139], 0, 64
	v_add_u32_e32 v2, s2, v1
	v_ashrrev_i32_e32 v3, 31, v2
	v_lshlrev_b64 v[2:3], 11, v[2:3]
	v_readfirstlane_b32 s3, v148
	v_add_u32_e32 v8, 0x1000, v148
	v_lshl_add_u64 v[2:3], v[130:131], 0, v[2:3]
	s_mov_b32 m0, s3
	s_mov_b64 s[10:11], 0x20000
	v_readfirstlane_b32 s3, v8
	v_add_u32_e32 v8, 0x2000, v148
	global_load_lds_dwordx4 v[2:3], off
	v_lshl_add_u64 v[6:7], v[2:3], 0, s[10:11]
	s_mov_b32 m0, s3
	s_mov_b64 s[12:13], 0x40000
	v_readfirstlane_b32 s3, v8
	v_add_u32_e32 v8, 0x3000, v148
	s_and_b32 s9, s9, 0x380
	global_load_lds_dwordx4 v[6:7], off
	v_lshl_add_u64 v[6:7], v[2:3], 0, s[12:13]
	s_mov_b32 m0, s3
	s_mov_b64 s[12:13], 0x60000
	v_readfirstlane_b32 s3, v8
	v_add_u32_e32 v4, s9, v1
	global_load_lds_dwordx4 v[6:7], off
	v_lshl_add_u64 v[6:7], v[2:3], 0, s[12:13]
	s_mov_b32 m0, s3
	v_ashrrev_i32_e32 v5, 31, v4
	global_load_lds_dwordx4 v[6:7], off
	v_add_u32_e32 v6, 0x4000, v148
	v_lshlrev_b64 v[4:5], 11, v[4:5]
	v_readfirstlane_b32 s3, v6
	v_add_u32_e32 v8, 0x5000, v148
	v_lshl_add_u64 v[4:5], v[132:133], 0, v[4:5]
	v_lshlrev_b32_e32 v255, 1, v4
	v_bfi_b32 v255, s100, v255, v4
	v_lshrrev_b32_e32 v4, 5, v4
	v_bfi_b32 v4, 64, v4, v255
	s_mov_b32 m0, s3
	v_readfirstlane_b32 s3, v8
	v_add_u32_e32 v8, 0x6000, v148
	global_load_lds_dwordx4 v[4:5], off
	v_lshl_add_u64 v[6:7], v[4:5], 0, s[10:11]
	s_mov_b32 m0, s3
	v_readfirstlane_b32 s3, v8
	v_add_u32_e32 v8, 0x7000, v148
	global_load_lds_dwordx4 v[6:7], off
	v_lshl_add_u64 v[6:7], v[2:3], 0, 64
	s_mov_b32 m0, s3
	s_mov_b64 s[10:11], 0x20040
	v_readfirstlane_b32 s3, v8
	v_add_u32_e32 v8, 0x8000, v148
	global_load_lds_dwordx4 v[6:7], off
	v_lshl_add_u64 v[6:7], v[2:3], 0, s[10:11]
	s_mov_b32 m0, s3
	s_mov_b64 s[12:13], 0x40040
	v_readfirstlane_b32 s3, v8
	global_load_lds_dwordx4 v[6:7], off
	v_lshl_add_u64 v[6:7], v[2:3], 0, s[12:13]
	s_mov_b32 m0, s3
	s_mov_b64 s[12:13], 0x60040
	global_load_lds_dwordx4 v[6:7], off
	v_add_u32_e32 v6, 0x9000, v148
	v_lshl_add_u64 v[2:3], v[2:3], 0, s[12:13]
	v_readfirstlane_b32 s3, v6
	v_add_u32_e32 v6, 0xa000, v148
	s_mov_b32 m0, s3
	v_readfirstlane_b32 s3, v6
	global_load_lds_dwordx4 v[2:3], off
	v_lshl_add_u64 v[2:3], v[4:5], 0, 64
	v_lshl_add_u64 v[2:3], v[2:3], 0, 64
	s_mov_b32 m0, s3
	s_mov_b32 s12, 0
	global_load_lds_dwordx4 v[2:3], off
	v_lshl_add_u64 v[2:3], v[4:5], 0, s[10:11]
	v_lshl_add_u64 v[2:3], v[2:3], 0, 64
	v_add_u32_e32 v4, 0xb000, v148
	s_mov_b32 s10, 1
	v_readfirstlane_b32 s3, v4
	s_mov_b32 m0, s3
	s_mov_b32 s3, 0
	global_load_lds_dwordx4 v[2:3], off
	v_mov_b32_e32 v2, 0
	s_mov_b32 s11, 2
	v_mov_b32_e32 v3, v2
	v_mov_b32_e32 v4, v2
	v_mov_b32_e32 v5, v2
	v_mov_b32_e32 v6, v2
	v_mov_b32_e32 v7, v2
	v_mov_b32_e32 v8, v2
	v_mov_b32_e32 v9, v2
	v_mov_b32_e32 v10, v2
	v_mov_b32_e32 v11, v2
	v_mov_b32_e32 v12, v2
	v_mov_b32_e32 v13, v2
	v_mov_b32_e32 v14, v2
	v_mov_b32_e32 v15, v2
	v_mov_b32_e32 v16, v2
	v_mov_b32_e32 v17, v2
	v_mov_b32_e32 v18, v2
	v_mov_b32_e32 v19, v2
	v_mov_b32_e32 v20, v2
	v_mov_b32_e32 v21, v2
	v_mov_b32_e32 v22, v2
	v_mov_b32_e32 v23, v2
	v_mov_b32_e32 v24, v2
	v_mov_b32_e32 v25, v2
	v_mov_b32_e32 v26, v2
	v_mov_b32_e32 v27, v2
	v_mov_b32_e32 v28, v2
	v_mov_b32_e32 v29, v2
	v_mov_b32_e32 v30, v2
	v_mov_b32_e32 v31, v2
	v_mov_b32_e32 v32, v2
	v_mov_b32_e32 v33, v2
	v_mov_b32_e32 v34, v2
	v_mov_b32_e32 v35, v2
	v_mov_b32_e32 v36, v2
	v_mov_b32_e32 v37, v2
	v_mov_b32_e32 v38, v2
	v_mov_b32_e32 v39, v2
	v_mov_b32_e32 v40, v2
	v_mov_b32_e32 v41, v2
	v_mov_b32_e32 v42, v2
	v_mov_b32_e32 v43, v2
	v_mov_b32_e32 v44, v2
	v_mov_b32_e32 v45, v2
	v_mov_b32_e32 v46, v2
	v_mov_b32_e32 v47, v2
	v_mov_b32_e32 v48, v2
	v_mov_b32_e32 v49, v2
	v_mov_b32_e32 v50, v2
	v_mov_b32_e32 v51, v2
	v_mov_b32_e32 v52, v2
	v_mov_b32_e32 v53, v2
	v_mov_b32_e32 v54, v2
	v_mov_b32_e32 v55, v2
	v_mov_b32_e32 v56, v2
	v_mov_b32_e32 v57, v2
	v_mov_b32_e32 v58, v2
	v_mov_b32_e32 v59, v2
	v_mov_b32_e32 v60, v2
	v_mov_b32_e32 v61, v2
	v_mov_b32_e32 v62, v2
	v_mov_b32_e32 v63, v2
	v_mov_b32_e32 v64, v2
	v_mov_b32_e32 v65, v2
	v_mov_b32_e32 v66, v2
	v_mov_b32_e32 v67, v2
	v_mov_b32_e32 v68, v2
	v_mov_b32_e32 v69, v2
	v_mov_b32_e32 v70, v2
	v_mov_b32_e32 v71, v2
	v_mov_b32_e32 v72, v2
	v_mov_b32_e32 v73, v2
	v_mov_b32_e32 v74, v2
	v_mov_b32_e32 v75, v2
	v_mov_b32_e32 v76, v2
	v_mov_b32_e32 v77, v2
	v_mov_b32_e32 v78, v2
	v_mov_b32_e32 v79, v2
	v_mov_b32_e32 v80, v2
	v_mov_b32_e32 v81, v2
	v_mov_b32_e32 v82, v2
	v_mov_b32_e32 v83, v2
	v_mov_b32_e32 v84, v2
	v_mov_b32_e32 v85, v2
	v_mov_b32_e32 v86, v2
	v_mov_b32_e32 v87, v2
	s_waitcnt vmcnt(0)
	v_mov_b32_e32 v88, v2
	v_mov_b32_e32 v89, v2
	v_mov_b32_e32 v90, v2
	v_mov_b32_e32 v91, v2
	v_mov_b32_e32 v92, v2
	v_mov_b32_e32 v93, v2
	v_mov_b32_e32 v94, v2
	v_mov_b32_e32 v95, v2
	v_mov_b32_e32 v96, v2
	v_mov_b32_e32 v97, v2
	v_mov_b32_e32 v98, v2
	v_mov_b32_e32 v99, v2
	v_mov_b32_e32 v100, v2
	v_mov_b32_e32 v101, v2
	v_mov_b32_e32 v102, v2
	v_mov_b32_e32 v103, v2
	v_mov_b32_e32 v104, v2
	v_mov_b32_e32 v105, v2
	v_mov_b32_e32 v106, v2
	v_mov_b32_e32 v107, v2
	v_mov_b32_e32 v108, v2
	v_mov_b32_e32 v109, v2
	v_mov_b32_e32 v110, v2
	v_mov_b32_e32 v111, v2
	v_mov_b32_e32 v112, v2
	v_mov_b32_e32 v113, v2
	v_mov_b32_e32 v114, v2
	v_mov_b32_e32 v115, v2
	v_mov_b32_e32 v116, v2
	v_mov_b32_e32 v117, v2
	v_mov_b32_e32 v118, v2
	v_mov_b32_e32 v119, v2
	v_mov_b32_e32 v120, v2
	v_mov_b32_e32 v121, v2
	v_mov_b32_e32 v122, v2
	v_mov_b32_e32 v123, v2
	v_mov_b32_e32 v124, v2
	v_mov_b32_e32 v125, v2
	v_mov_b32_e32 v126, v2
	v_mov_b32_e32 v127, v2
	v_mov_b32_e32 v128, v2
	v_mov_b32_e32 v129, v2
; #define MFMA(a, b, c) __builtin_amdgcn_mfma_f32_16x16x32_bf16((a), (b), (c), 0, 0, 0)
; template <int EPI, int MF>
; __device__ __forceinline__ void gemm_part(const u16* __restrict__ A, int lda, const u16* __restrict__ Bt, int K, int ntn, GemmEpi ep, char* smem,
;                                           int mbase, int mrows) {
;     ...
;     for (int kt = 0; kt < nk; ++kt) {
;       if (kt + 1 < nk) {
;         if (MF == 8) asm volatile("s_waitcnt vmcnt(6)" ::: "memory");
;         else asm volatile("s_waitcnt vmcnt(3)" ::: "memory");
;       } else asm volatile("s_waitcnt vmcnt(0)" ::: "memory");
;       asm volatile("s_waitcnt lgkmcnt(0)" ::: "memory");
;       __builtin_amdgcn_s_barrier();
;       const u16* a_ = sbase + (kt % 3) * STG;
;       const u16* b_ = a_ + BM * 32;
;       bf16x8 bfr[4], afc[2], afn[2];
;       const u16* ap_ = a_ + (wr * (16 * MF) + fr) * 32 + fq * 8;
; #pragma unroll
;       for (int n = 0; n < 4; ++n) bfr[n] = rd_std(b_ + (wc * 64 + n * 16 + fr) * 32 + fq * 8);
;       afc[0] = rd_std(ap_); afc[1] = rd_std(ap_ + 16 * 32);
;       __builtin_amdgcn_sched_barrier(0);
;       if (kt + 2 < nk) GEMM_ISSUE(kt + 2);
;       __builtin_amdgcn_sched_barrier(0);
; #pragma unroll
;       for (int mh = 0; mh < MF / 2; ++mh) {
;         if (mh + 1 < MF / 2) {
;           afn[0] = rd_std(ap_ + ((mh + 1) * 2) * 16 * 32);
;           afn[1] = rd_std(ap_ + ((mh + 1) * 2 + 1) * 16 * 32);
;         }
;         __builtin_amdgcn_sched_barrier(0);
; #pragma unroll
;         for (int m = 0; m < 2; ++m)
; #pragma unroll
;           for (int n = 0; n < 4; ++n) acc[mh * 2 + m][n] = MFMA(bfr[n], afc[m], acc[mh * 2 + m][n]);
;         __builtin_amdgcn_sched_barrier(0);
;         afc[0] = afn[0]; afc[1] = afn[1];
;       }
;     }
.LBB0_1128:
	s_mul_hi_u32 s13, s12, 0xaaaaaaab
	s_lshr_b32 s13, s13, 1
	s_mul_i32 s13, s13, 0x12000
	v_add_u32_e32 v146, s3, v156
	v_subrev_u32_e32 v147, s13, v159
	s_waitcnt vmcnt(6)
	v_subrev_u32_e32 v161, s13, v155
	v_add_u32_e32 v147, v146, v147
	s_waitcnt lgkmcnt(0)
	s_barrier
	v_add_u32_e32 v161, v146, v161
	ds_read_b128 v[162:165], v147 offset:16384
	ds_read_b128 v[166:169], v147 offset:17408
	ds_read_b128 v[170:173], v147 offset:18432
	ds_read_b128 v[174:177], v147 offset:19456
	ds_read_b128 v[178:181], v161
	ds_read_b128 v[182:185], v161 offset:1024
	s_mul_hi_u32 s13, s11, 0xaaaaaaab
	s_add_i32 s12, s12, 1
	s_lshr_b32 s13, s13, 1
	s_mul_i32 s13, s13, 0x12000
	s_sub_i32 s13, s3, s13
	s_add_i32 s14, s13, 0xc000
	v_add_u32_e32 v188, s14, v148
	v_lshl_add_u64 v[146:147], v[136:137], 0, v[134:135]
	v_readfirstlane_b32 s14, v188
	s_mov_b32 m0, s14
	s_add_i32 s14, s13, 0xd000
	v_add_u32_e32 v188, s14, v148
	v_lshl_add_u64 v[186:187], v[146:147], 0, s[74:75]
	v_readfirstlane_b32 s14, v188
	global_load_lds_dwordx4 v[186:187], off
	s_mov_b32 m0, s14
	s_add_i32 s14, s13, 0xe000
	v_add_u32_e32 v188, s14, v148
	v_lshl_add_u64 v[186:187], v[146:147], 0, s[92:93]
	v_readfirstlane_b32 s14, v188
	global_load_lds_dwordx4 v[186:187], off
	v_lshl_add_u64 v[186:187], v[146:147], 0, s[88:89]
	s_mov_b32 m0, s14
	s_add_i32 s14, s13, 0xf000
	global_load_lds_dwordx4 v[186:187], off
	v_add_u32_e32 v186, s14, v148
	v_lshl_add_u64 v[146:147], v[146:147], 0, s[6:7]
	v_readfirstlane_b32 s14, v186
	s_mov_b32 m0, s14
	s_add_i32 s14, s13, 0x10000
	v_add_u32_e32 v188, s14, v148
	global_load_lds_dwordx4 v[146:147], off
	v_lshl_add_u64 v[146:147], v[138:139], 0, v[134:135]
	v_readfirstlane_b32 s14, v188
	v_lshl_add_u64 v[186:187], v[146:147], 0, s[74:75]
	s_mov_b32 m0, s14
	s_add_i32 s13, s13, 0x11000
	global_load_lds_dwordx4 v[186:187], off
	v_add_u32_e32 v186, s13, v148
	v_lshl_add_u64 v[146:147], v[146:147], 0, s[92:93]
	v_readfirstlane_b32 s13, v186
	s_mov_b32 m0, s13
	s_nop 0
	global_load_lds_dwordx4 v[146:147], off
	ds_read_b128 v[186:189], v161 offset:3072
	ds_read_b128 v[190:193], v161 offset:2048
	s_waitcnt lgkmcnt(2)
	v_mfma_f32_16x16x32_bf16 v[126:129], v[162:165], v[178:181], v[126:129]
	v_mfma_f32_16x16x32_bf16 v[122:125], v[166:169], v[178:181], v[122:125]
	v_mfma_f32_16x16x32_bf16 v[118:121], v[170:173], v[178:181], v[118:121]
	v_mfma_f32_16x16x32_bf16 v[114:117], v[174:177], v[178:181], v[114:117]
	v_mfma_f32_16x16x32_bf16 v[110:113], v[162:165], v[182:185], v[110:113]
	v_mfma_f32_16x16x32_bf16 v[106:109], v[166:169], v[182:185], v[106:109]
	v_mfma_f32_16x16x32_bf16 v[102:105], v[170:173], v[182:185], v[102:105]
	v_mfma_f32_16x16x32_bf16 v[98:101], v[174:177], v[182:185], v[98:101]
	ds_read_b128 v[178:181], v161 offset:5120
	ds_read_b128 v[182:185], v161 offset:4096
	s_waitcnt lgkmcnt(2)
	v_mfma_f32_16x16x32_bf16 v[94:97], v[162:165], v[190:193], v[94:97]
	v_mfma_f32_16x16x32_bf16 v[90:93], v[166:169], v[190:193], v[90:93]
	v_mfma_f32_16x16x32_bf16 v[86:89], v[170:173], v[190:193], v[86:89]
	v_mfma_f32_16x16x32_bf16 v[82:85], v[174:177], v[190:193], v[82:85]
	v_mfma_f32_16x16x32_bf16 v[78:81], v[162:165], v[186:189], v[78:81]
	v_mfma_f32_16x16x32_bf16 v[74:77], v[166:169], v[186:189], v[74:77]
	v_mfma_f32_16x16x32_bf16 v[70:73], v[170:173], v[186:189], v[70:73]
	v_mfma_f32_16x16x32_bf16 v[66:69], v[174:177], v[186:189], v[66:69]
	ds_read_b128 v[186:189], v161 offset:7168
	ds_read_b128 v[190:193], v161 offset:6144
	s_waitcnt lgkmcnt(2)
	v_mfma_f32_16x16x32_bf16 v[62:65], v[162:165], v[182:185], v[62:65]
	v_mfma_f32_16x16x32_bf16 v[58:61], v[166:169], v[182:185], v[58:61]
	v_mfma_f32_16x16x32_bf16 v[54:57], v[170:173], v[182:185], v[54:57]
	v_mfma_f32_16x16x32_bf16 v[50:53], v[174:177], v[182:185], v[50:53]
	v_mfma_f32_16x16x32_bf16 v[46:49], v[162:165], v[178:181], v[46:49]
	v_mfma_f32_16x16x32_bf16 v[42:45], v[166:169], v[178:181], v[42:45]
	v_mfma_f32_16x16x32_bf16 v[38:41], v[170:173], v[178:181], v[38:41]
	v_mfma_f32_16x16x32_bf16 v[34:37], v[174:177], v[178:181], v[34:37]
	s_waitcnt lgkmcnt(0)
	v_mfma_f32_16x16x32_bf16 v[30:33], v[162:165], v[190:193], v[30:33]
	v_mfma_f32_16x16x32_bf16 v[26:29], v[166:169], v[190:193], v[26:29]
	v_mfma_f32_16x16x32_bf16 v[22:25], v[170:173], v[190:193], v[22:25]
	v_mfma_f32_16x16x32_bf16 v[18:21], v[174:177], v[190:193], v[18:21]
	v_mfma_f32_16x16x32_bf16 v[14:17], v[162:165], v[186:189], v[14:17]
	v_mfma_f32_16x16x32_bf16 v[10:13], v[166:169], v[186:189], v[10:13]
	v_mfma_f32_16x16x32_bf16 v[6:9], v[170:173], v[186:189], v[6:9]
	v_mfma_f32_16x16x32_bf16 v[2:5], v[174:177], v[186:189], v[2:5]
	s_addk_i32 s3, 0x6000
	s_add_i32 s10, s10, 1
	s_add_i32 s11, s11, 1
	v_lshl_add_u64 v[136:137], v[136:137], 0, 64
	s_cmp_eq_u32 s3, 0xb4000
	v_lshl_add_u64 v[138:139], v[138:139], 0, 64
	v_lshl_add_u64 v[138:139], v[138:139], 0, 64
	s_cbranch_scc0 .LBB0_1128
	s_waitcnt vmcnt(6)
	s_waitcnt lgkmcnt(0)
	s_barrier
; #define MFMA(a, b, c) __builtin_amdgcn_mfma_f32_16x16x32_bf16((a), (b), (c), 0, 0, 0)
; template <int EPI, int MF>
; __device__ __forceinline__ void gemm_part(const u16* __restrict__ A, int lda, const u16* __restrict__ Bt, int K, int ntn, GemmEpi ep, char* smem,
;                                           int mbase, int mrows) {
;     ...
;     for (int kt = 0; kt < nk; ++kt) {
;       if (kt + 1 < nk) {
;         if (MF == 8) asm volatile("s_waitcnt vmcnt(6)" ::: "memory");
;         else asm volatile("s_waitcnt vmcnt(3)" ::: "memory");
;       } else asm volatile("s_waitcnt vmcnt(0)" ::: "memory");
;       asm volatile("s_waitcnt lgkmcnt(0)" ::: "memory");
;       __builtin_amdgcn_s_barrier();
;       const u16* a_ = sbase + (kt % 3) * STG;
;       const u16* b_ = a_ + BM * 32;
;       bf16x8 bfr[4], afc[2], afn[2];
;       const u16* ap_ = a_ + (wr * (16 * MF) + fr) * 32 + fq * 8;
; #pragma unroll
;       for (int n = 0; n < 4; ++n) bfr[n] = rd_std(b_ + (wc * 64 + n * 16 + fr) * 32 + fq * 8);
;       afc[0] = rd_std(ap_); afc[1] = rd_std(ap_ + 16 * 32);
;       __builtin_amdgcn_sched_barrier(0);
;       if (kt + 2 < nk) GEMM_ISSUE(kt + 2);
;       __builtin_amdgcn_sched_barrier(0);
; #pragma unroll
;       for (int mh = 0; mh < MF / 2; ++mh) {
;         if (mh + 1 < MF / 2) {
;           afn[0] = rd_std(ap_ + ((mh + 1) * 2) * 16 * 32);
;           afn[1] = rd_std(ap_ + ((mh + 1) * 2 + 1) * 16 * 32);
;         }
;         __builtin_amdgcn_sched_barrier(0);
; #pragma unroll
;         for (int m = 0; m < 2; ++m)
; #pragma unroll
;           for (int n = 0; n < 4; ++n) acc[mh * 2 + m][n] = MFMA(bfr[n], afc[m], acc[mh * 2 + m][n]);
;         __builtin_amdgcn_sched_barrier(0);
;         afc[0] = afn[0]; afc[1] = afn[1];
;       }
;     }
;     ...
;     __syncthreads();
	ds_read_b128 v[136:139], v160 offset:16384
	ds_read_b128 v[162:165], v160 offset:17408
	ds_read_b128 v[166:169], v160 offset:18432
	ds_read_b128 v[170:173], v160 offset:19456
	ds_read_b128 v[174:177], v157
	ds_read_b128 v[178:181], v157 offset:1024
	s_mul_hi_u32 s10, s10, 0xaaaaaaab
	s_lshr_b32 s10, s10, 1
	s_mul_i32 s10, s10, 0x12000
	s_sub_i32 s3, s3, s10
	s_add_i32 s3, s3, 0
	s_addk_i32 s3, 0x6000
	ds_read_b128 v[182:185], v157 offset:3072
	ds_read_b128 v[186:189], v157 offset:2048
	s_waitcnt lgkmcnt(0)
	v_mfma_f32_16x16x32_bf16 v[126:129], v[136:139], v[174:177], v[126:129]
	v_mfma_f32_16x16x32_bf16 v[122:125], v[162:165], v[174:177], v[122:125]
	v_mfma_f32_16x16x32_bf16 v[118:121], v[166:169], v[174:177], v[118:121]
	v_mfma_f32_16x16x32_bf16 v[114:117], v[170:173], v[174:177], v[114:117]
	v_mfma_f32_16x16x32_bf16 v[110:113], v[136:139], v[178:181], v[110:113]
	v_mfma_f32_16x16x32_bf16 v[106:109], v[162:165], v[178:181], v[106:109]
	v_mfma_f32_16x16x32_bf16 v[102:105], v[166:169], v[178:181], v[102:105]
	v_mfma_f32_16x16x32_bf16 v[98:101], v[170:173], v[178:181], v[98:101]
	ds_read_b128 v[174:177], v157 offset:5120
	ds_read_b128 v[178:181], v157 offset:4096
	v_mfma_f32_16x16x32_bf16 v[94:97], v[136:139], v[186:189], v[94:97]
	v_mfma_f32_16x16x32_bf16 v[90:93], v[162:165], v[186:189], v[90:93]
	v_mfma_f32_16x16x32_bf16 v[86:89], v[166:169], v[186:189], v[86:89]
	v_mfma_f32_16x16x32_bf16 v[82:85], v[170:173], v[186:189], v[82:85]
	v_mfma_f32_16x16x32_bf16 v[78:81], v[136:139], v[182:185], v[78:81]
	v_mfma_f32_16x16x32_bf16 v[74:77], v[162:165], v[182:185], v[74:77]
	v_mfma_f32_16x16x32_bf16 v[70:73], v[166:169], v[182:185], v[70:73]
	v_mfma_f32_16x16x32_bf16 v[66:69], v[170:173], v[182:185], v[66:69]
	ds_read_b128 v[182:185], v157 offset:7168
	ds_read_b128 v[186:189], v157 offset:6144
	s_waitcnt lgkmcnt(0)
	v_mfma_f32_16x16x32_bf16 v[62:65], v[136:139], v[178:181], v[62:65]
	v_mfma_f32_16x16x32_bf16 v[58:61], v[162:165], v[178:181], v[58:61]
	v_mfma_f32_16x16x32_bf16 v[54:57], v[166:169], v[178:181], v[54:57]
	v_mfma_f32_16x16x32_bf16 v[50:53], v[170:173], v[178:181], v[50:53]
	v_mfma_f32_16x16x32_bf16 v[46:49], v[136:139], v[174:177], v[46:49]
	v_mfma_f32_16x16x32_bf16 v[42:45], v[162:165], v[174:177], v[42:45]
	v_mfma_f32_16x16x32_bf16 v[38:41], v[166:169], v[174:177], v[38:41]
	v_mfma_f32_16x16x32_bf16 v[34:37], v[170:173], v[174:177], v[34:37]
	v_mfma_f32_16x16x32_bf16 v[30:33], v[136:139], v[186:189], v[30:33]
	v_mfma_f32_16x16x32_bf16 v[26:29], v[162:165], v[186:189], v[26:29]
	v_mfma_f32_16x16x32_bf16 v[22:25], v[166:169], v[186:189], v[22:25]
	v_mfma_f32_16x16x32_bf16 v[18:21], v[170:173], v[186:189], v[18:21]
	v_mfma_f32_16x16x32_bf16 v[14:17], v[136:139], v[182:185], v[14:17]
	v_mfma_f32_16x16x32_bf16 v[10:13], v[162:165], v[182:185], v[10:13]
	v_mfma_f32_16x16x32_bf16 v[6:9], v[166:169], v[182:185], v[6:9]
	v_mfma_f32_16x16x32_bf16 v[2:5], v[170:173], v[182:185], v[2:5]
	v_add_u32_e32 v146, s3, v156
	s_waitcnt vmcnt(0)
	v_add3_u32 v147, v146, v153, v154
	s_waitcnt lgkmcnt(0)
	s_barrier
	ds_read_b128 v[136:139], v147 offset:16384
	ds_read_b128 v[162:165], v147 offset:17408
	ds_read_b128 v[166:169], v147 offset:18432
	ds_read_b128 v[170:173], v147 offset:19456
	v_lshl_add_u32 v146, v149, 1, v146
	ds_read_b128 v[174:177], v146
	ds_read_b128 v[178:181], v146 offset:1024
	ds_read_b128 v[182:185], v146 offset:3072
	ds_read_b128 v[186:189], v146 offset:2048
	s_waitcnt lgkmcnt(0)
	v_mfma_f32_16x16x32_bf16 v[126:129], v[136:139], v[174:177], v[126:129]
	v_mfma_f32_16x16x32_bf16 v[122:125], v[162:165], v[174:177], v[122:125]
	v_mfma_f32_16x16x32_bf16 v[118:121], v[166:169], v[174:177], v[118:121]
	v_mfma_f32_16x16x32_bf16 v[114:117], v[170:173], v[174:177], v[114:117]
	v_mfma_f32_16x16x32_bf16 v[110:113], v[136:139], v[178:181], v[110:113]
	v_mfma_f32_16x16x32_bf16 v[106:109], v[162:165], v[178:181], v[106:109]
	v_mfma_f32_16x16x32_bf16 v[102:105], v[166:169], v[178:181], v[102:105]
	v_mfma_f32_16x16x32_bf16 v[98:101], v[170:173], v[178:181], v[98:101]
	ds_read_b128 v[174:177], v146 offset:5120
	ds_read_b128 v[178:181], v146 offset:4096
	v_mfma_f32_16x16x32_bf16 v[94:97], v[136:139], v[186:189], v[94:97]
	v_mfma_f32_16x16x32_bf16 v[90:93], v[162:165], v[186:189], v[90:93]
	v_mfma_f32_16x16x32_bf16 v[86:89], v[166:169], v[186:189], v[86:89]
	v_mfma_f32_16x16x32_bf16 v[82:85], v[170:173], v[186:189], v[82:85]
	v_mfma_f32_16x16x32_bf16 v[78:81], v[136:139], v[182:185], v[78:81]
	v_mfma_f32_16x16x32_bf16 v[74:77], v[162:165], v[182:185], v[74:77]
	v_mfma_f32_16x16x32_bf16 v[70:73], v[166:169], v[182:185], v[70:73]
	v_mfma_f32_16x16x32_bf16 v[66:69], v[170:173], v[182:185], v[66:69]
	ds_read_b128 v[182:185], v146 offset:7168
	ds_read_b128 v[186:189], v146 offset:6144
	s_waitcnt lgkmcnt(0)
	v_mfma_f32_16x16x32_bf16 v[62:65], v[136:139], v[178:181], v[62:65]
	v_mfma_f32_16x16x32_bf16 v[58:61], v[162:165], v[178:181], v[58:61]
	v_mfma_f32_16x16x32_bf16 v[54:57], v[166:169], v[178:181], v[54:57]
	v_mfma_f32_16x16x32_bf16 v[50:53], v[170:173], v[178:181], v[50:53]
	v_mfma_f32_16x16x32_bf16 v[46:49], v[136:139], v[174:177], v[46:49]
	v_mfma_f32_16x16x32_bf16 v[42:45], v[162:165], v[174:177], v[42:45]
	v_mfma_f32_16x16x32_bf16 v[38:41], v[166:169], v[174:177], v[38:41]
	v_mfma_f32_16x16x32_bf16 v[34:37], v[170:173], v[174:177], v[34:37]
	v_mfma_f32_16x16x32_bf16 v[30:33], v[136:139], v[186:189], v[30:33]
	v_mfma_f32_16x16x32_bf16 v[26:29], v[162:165], v[186:189], v[26:29]
	v_mfma_f32_16x16x32_bf16 v[22:25], v[166:169], v[186:189], v[22:25]
	v_mfma_f32_16x16x32_bf16 v[18:21], v[170:173], v[186:189], v[18:21]
	v_mfma_f32_16x16x32_bf16 v[14:17], v[136:139], v[182:185], v[14:17]
	v_mfma_f32_16x16x32_bf16 v[10:13], v[162:165], v[182:185], v[10:13]
	v_mfma_f32_16x16x32_bf16 v[6:9], v[166:169], v[182:185], v[6:9]
	v_mfma_f32_16x16x32_bf16 v[2:5], v[170:173], v[182:185], v[2:5]
	v_add_u32_e32 v136, s2, v151
	s_waitcnt vmcnt(0)
	s_barrier
; template <int EPI, int MF>
; __device__ __forceinline__ void gemm_part(const u16* __restrict__ A, int lda, const u16* __restrict__ Bt, int K, int ntn, GemmEpi ep, char* smem,
;                                           int mbase, int mrows) {
;     ...
;       } else if (EPI == EPI_RESID) {
;         const float* rp = (row < MP) ? ep.res0 + (size_t)row * DM : ep.res1 + (size_t)(row - MP) * DM;
;         float ssq = 0.f;
; #pragma unroll
;         for (int n = 0; n < 4; ++n) {
;           const int col = cb + n * 16;
;           const float4 r = *(const float4*)(rp + col);
;           float4 v;
;           v.x = r.x + ep.scale * acc[m][n][0]; v.y = r.y + ep.scale * acc[m][n][1];
;           v.z = r.z + ep.scale * acc[m][n][2]; v.w = r.w + ep.scale * acc[m][n][3];
;           *(float4*)(ep.outf + (size_t)row * DM + col) = v;
;           if (ep.xcopy) {
;             bf16x4 o;
;             o[0] = (short)f2bf(v.x); o[1] = (short)f2bf(v.y); o[2] = (short)f2bf(v.z); o[3] = (short)f2bf(v.w);
;             *(bf16x4*)(ep.xcopy + (size_t)row * DM + col) = o;
;           }
;           ssq += v.x * v.x + v.y * v.y + v.z * v.z + v.w * v.w;
;         }
;         if (ep.rss_out) {
;           ssq += __shfl_xor(ssq, 16);
;           ssq += __shfl_xor(ssq, 32);
;           if (fq == 0) atomicAdd(ep.rss_out + row, ssq);
;         }
	s_mov_b32 s2, 0xffff
	v_cmp_lt_i32_e64 s[12:13], s2, v136
	s_and_saveexec_b64 s[2:3], s[12:13]
	s_xor_b64 s[2:3], exec, s[2:3]
	v_add_u32_e32 v138, 0xffff0000, v136
	v_mov_b32_e32 v139, v0
	v_lshlrev_b64 v[138:139], 12, v[138:139]
	v_lshl_add_u64 v[146:147], s[72:73], 0, v[138:139]
	v_mov_b32_e32 v137, v0
	s_andn2_saveexec_b64 s[2:3], s[2:3]
	v_ashrrev_i32_e32 v137, 31, v136
	v_lshlrev_b64 v[138:139], 12, v[136:137]
	v_lshl_add_u64 v[146:147], s[26:27], 0, v[138:139]
	s_or_b64 exec, exec, s[2:3]
	v_lshlrev_b64 v[138:139], 12, v[136:137]
	v_or_b32_e32 v161, s9, v152
	v_lshl_add_u64 v[162:163], s[26:27], 0, v[138:139]
	v_lshlrev_b64 v[138:139], 11, v[136:137]
	v_lshl_add_u64 v[166:167], s[28:29], 0, v[138:139]
	v_lshlrev_b32_e32 v138, 2, v161
	v_mov_b32_e32 v139, v0
	v_lshl_add_u64 v[146:147], v[146:147], 0, v[138:139]
	v_lshl_add_u64 v[168:169], v[162:163], 0, v[138:139]
	global_load_dwordx4 v[162:165], v[146:147], off
	global_load_dwordx4 v[172:175], v[146:147], off offset:64
	global_load_dwordx4 v[176:179], v[146:147], off offset:128
	global_load_dwordx4 v[180:183], v[146:147], off offset:192
	s_waitcnt vmcnt(0)
	v_pk_add_f32 v[162:163], v[126:127], v[162:163]
	v_pk_add_f32 v[164:165], v[128:129], v[164:165]
	v_lshlrev_b32_e32 v126, 1, v161
	v_mov_b32_e32 v127, v0
	v_cvt_pk_bf16_f32 v129, v164, v165
	v_cvt_pk_bf16_f32 v128, v162, v163
	v_lshl_add_u64 v[166:167], v[166:167], 0, v[126:127]
	global_store_dwordx4 v[168:169], v[162:165], off
	v_lshlrev_b32_e32 v184, 1, v166
	v_bfi_b32 v184, s100, v184, v166
	v_lshrrev_b32_e32 v185, 5, v166
	v_bfi_b32 v184, 64, v185, v184
	v_mov_b32_e32 v185, v167
	global_store_dwordx2 v[184:185], v[128:129], off
	v_pk_mul_f32 v[128:129], v[162:163], v[162:163]
	v_pk_mul_f32 v[170:171], v[164:165], v[164:165]
	s_nop 0
	s_nop 0
	v_pk_add_f32 v[122:123], v[122:123], v[172:173]
	v_pk_add_f32 v[124:125], v[124:125], v[174:175]
	v_cvt_pk_bf16_f32 v162, v122, v123
	v_cvt_pk_bf16_f32 v163, v124, v125
	global_store_dwordx4 v[168:169], v[122:125], off offset:64
	v_lshlrev_b32_e32 v184, 1, v166
	v_bfi_b32 v184, s100, v184, v166
	v_lshrrev_b32_e32 v185, 5, v166
	v_bfi_b32 v184, 64, v185, v184
	v_mov_b32_e32 v185, v167
	global_store_dwordx2 v[184:185], v[162:163], off offset:32
	v_pk_mul_f32 v[162:163], v[122:123], v[122:123]
	v_pk_mul_f32 v[164:165], v[124:125], v[124:125]
	s_nop 0
	s_nop 0
	v_pk_add_f32 v[118:119], v[118:119], v[176:177]
	v_pk_add_f32 v[120:121], v[120:121], v[178:179]
	v_cvt_pk_bf16_f32 v122, v118, v119
	v_cvt_pk_bf16_f32 v123, v120, v121
	global_store_dwordx4 v[168:169], v[118:121], off offset:128
	v_lshlrev_b32_e32 v184, 1, v166
	v_bfi_b32 v184, s100, v184, v166
	v_lshrrev_b32_e32 v185, 5, v166
	v_bfi_b32 v184, 64, v185, v184
	v_mov_b32_e32 v185, v167
	global_store_dwordx2 v[184:185], v[122:123], off offset:128
	v_pk_mul_f32 v[122:123], v[118:119], v[118:119]
	v_pk_mul_f32 v[124:125], v[120:121], v[120:121]
	s_nop 0
	s_nop 0
	v_pk_add_f32 v[114:115], v[114:115], v[180:181]
	v_pk_add_f32 v[116:117], v[116:117], v[182:183]
	v_cvt_pk_bf16_f32 v118, v114, v115
	v_cvt_pk_bf16_f32 v119, v116, v117
	global_store_dwordx4 v[168:169], v[114:117], off offset:192
	v_lshlrev_b32_e32 v184, 1, v166
	v_bfi_b32 v184, s100, v184, v166
	v_lshrrev_b32_e32 v185, 5, v166
	v_bfi_b32 v184, 64, v185, v184
	v_mov_b32_e32 v185, v167
	global_store_dwordx2 v[184:185], v[118:119], off offset:160
	v_add_f32_e32 v118, v128, v129
	v_add_f32_e32 v119, v162, v163
	v_pk_mul_f32 v[114:115], v[114:115], v[114:115]
	v_add_f32_e32 v118, v170, v118
	v_add_f32_e32 v119, v164, v119
	v_pk_mul_f32 v[116:117], v[116:117], v[116:117]
	v_add_f32_e32 v118, v171, v118
	v_add_f32_e32 v119, v165, v119
	v_add_f32_e32 v114, v114, v115
	v_add_f32_e32 v118, v118, v119
	v_add_f32_e32 v119, v122, v123
	v_add_f32_e32 v114, v116, v114
	v_and_b32_e32 v116, 64, v141
	v_add_f32_e32 v119, v124, v119
	v_xor_b32_e32 v115, 16, v141
	v_add_u32_e32 v116, 64, v116
	v_add_f32_e32 v119, v125, v119
	v_cmp_lt_i32_e64 s[12:13], v115, v116
	v_add_f32_e32 v118, v118, v119
	v_add_f32_e32 v114, v117, v114
	v_cndmask_b32_e64 v115, v141, v115, s[12:13]
	v_add_f32_e32 v114, v118, v114
	v_lshlrev_b32_e32 v118, 2, v115
	ds_bpermute_b32 v115, v118, v114
	s_waitcnt lgkmcnt(0)
	v_add_f32_e32 v114, v114, v115
	v_xor_b32_e32 v115, 32, v141
	v_cmp_lt_i32_e64 s[12:13], v115, v116
	s_nop 1
	v_cndmask_b32_e64 v115, v141, v115, s[12:13]
	v_lshlrev_b32_e32 v119, 2, v115
	ds_bpermute_b32 v115, v119, v114
	s_and_saveexec_b64 s[2:3], vcc
	s_cbranch_execz .LBB0_1135
	v_readlane_b32 s10, v252, 9
	v_readlane_b32 s11, v252, 10
	s_waitcnt lgkmcnt(0)
	v_add_f32_e32 v114, v114, v115
	v_lshl_add_u64 v[116:117], v[136:137], 2, s[10:11]
	global_atomic_add_f32 v[116:117], v114, off

; template <int EPI, int MF>
; __device__ __forceinline__ void gemm_part(const u16* __restrict__ A, int lda, const u16* __restrict__ Bt, int K, int ntn, GemmEpi ep, char* smem,
;                                           int mbase, int mrows) {
;     ...
;   for (int q = xcd; q * nbx < total; q += (MF == 2) ? 1 : 8) {
;     const int L = q * nbx + li;
;     if (L >= total) continue;
;     const int g = L / (8 * ntn), rr = L % (8 * ntn);
;     const int rows = min(8, ntm - 8 * g);
;     const int tm = 8 * g + rr % rows, tn = rr / rows;
;     const int row0 = mbase + tm * BM, col0 = tn * 128;
;     f32x4 acc[MF][4];
; #pragma unroll
;     for (int m = 0; m < MF; ++m)
; #pragma unroll
;       for (int n = 0; n < 4; ++n) acc[m][n] = (f32x4){0.f, 0.f, 0.f, 0.f};
;     const u16* gA = A + (size_t)(row0 + (tid >> 2)) * lda + (tid & 3) * 8;
;     const u16* gB = Bt + (size_t)(col0 + (tid >> 2)) * K + (tid & 3) * 8;
;     ...
;     GEMM_ISSUE(0);
;     GEMM_ISSUE(1);
;     for (int kt = 0; kt < nk; ++kt) {
;       if (kt + 1 < nk) {
;         if (MF == 8) asm volatile("s_waitcnt vmcnt(6)" ::: "memory");
;         else asm volatile("s_waitcnt vmcnt(3)" ::: "memory");
;       } else asm volatile("s_waitcnt vmcnt(0)" ::: "memory");
;       asm volatile("s_waitcnt lgkmcnt(0)" ::: "memory");
;       __builtin_amdgcn_s_barrier();
;       const u16* a_ = sbase + (kt % 3) * STG;
;       const u16* b_ = a_ + BM * 32;
;       bf16x8 bfr[4], afc[2], afn[2];
;       const u16* ap_ = a_ + (wr * (16 * MF) + fr) * 32 + fq * 8;
; #pragma unroll
;       for (int n = 0; n < 4; ++n) bfr[n] = rd_std(b_ + (wc * 64 + n * 16 + fr) * 32 + fq * 8);
;       afc[0] = rd_std(ap_); afc[1] = rd_std(ap_ + 16 * 32);
;       __builtin_amdgcn_sched_barrier(0);
;       if (kt + 2 < nk) GEMM_ISSUE(kt + 2);
.LBB0_1180:
	s_add_i32 s2, s2, s64
	s_cmp_gt_i32 s2, 63
	s_cbranch_scc1 .LBB0_1179
	s_ashr_i32 s3, s2, 31
	s_lshr_b32 s3, s3, 26
	s_add_i32 s3, s2, s3
	s_and_b32 s5, s3, 0xffc0
	s_sub_i32 s2, s2, s5
	s_bfe_i32 s5, s2, 0x80000
	s_bfe_u32 s5, s5, 0x3000c
	s_add_i32 s5, s2, s5
	s_bfe_i32 s8, s5, 0x80000
	s_and_b32 s5, s5, 0xf8
	s_sub_i32 s2, s2, s5
	s_sext_i32_i8 s2, s2
	s_lshl_b32 s3, s3, 3
	s_and_b32 s3, s3, 0xfffffe00
	s_lshl_b32 s2, s2, 6
	s_sext_i32_i16 s8, s8
	s_add_i32 s2, s3, s2
	s_add_i32 s2, s2, 0x10000
	s_lshl_b32 s3, s8, 4
	s_and_b32 s5, s3, 0xffffff80
	v_add_u32_e32 v2, s2, v1
	s_waitcnt lgkmcnt(0)
	v_ashrrev_i32_e32 v3, 31, v2
	v_add_u32_e32 v6, s5, v1
	v_lshlrev_b64 v[2:3], 11, v[2:3]
	v_ashrrev_i32_e32 v7, 31, v6
	v_readfirstlane_b32 s3, v48
	v_add_u32_e32 v10, 0x1000, v48
	v_lshl_add_u64 v[4:5], v[34:35], 0, v[2:3]
	v_lshlrev_b64 v[6:7], 11, v[6:7]
	s_mov_b32 m0, s3
	v_readfirstlane_b32 s3, v10
	v_add_u32_e32 v12, 0x2000, v48
	v_lshl_add_u64 v[8:9], v[36:37], 0, v[6:7]
	v_lshlrev_b32_e32 v255, 1, v8
	v_bfi_b32 v255, s100, v255, v8
	v_lshrrev_b32_e32 v8, 5, v8
	v_bfi_b32 v8, 64, v8, v255
	global_load_lds_dwordx4 v[4:5], off
	s_mov_b32 m0, s3
	s_mov_b64 s[8:9], 0x20000
	v_readfirstlane_b32 s3, v12
	global_load_lds_dwordx4 v[8:9], off
	v_lshl_add_u64 v[10:11], v[8:9], 0, s[8:9]
	s_mov_b32 m0, s3
	v_lshl_add_u64 v[4:5], v[4:5], 0, 64
	global_load_lds_dwordx4 v[10:11], off
	v_add_u32_e32 v10, 0x3000, v48
	s_mov_b64 s[8:9], 0x20040
	v_readfirstlane_b32 s3, v10
	v_add_u32_e32 v10, 0x4000, v48
	s_mov_b32 m0, s3
	v_readfirstlane_b32 s3, v10
	global_load_lds_dwordx4 v[4:5], off
	v_lshl_add_u64 v[4:5], v[8:9], 0, 64
	v_lshl_add_u64 v[4:5], v[4:5], 0, 64
	s_mov_b32 m0, s3
	v_lshl_add_u64 v[42:43], s[44:45], 0, v[2:3]
	global_load_lds_dwordx4 v[4:5], off
	v_lshl_add_u64 v[4:5], v[8:9], 0, s[8:9]
	v_lshl_add_u64 v[4:5], v[4:5], 0, 64
	v_add_u32_e32 v8, 0x5000, v48
	v_mov_b32_e32 v2, 0
	v_readfirstlane_b32 s3, v8
	s_mov_b32 m0, s3
	s_mov_b32 s8, 3
	global_load_lds_dwordx4 v[4:5], off
	v_lshl_add_u64 v[40:41], s[42:43], 0, v[6:7]
	v_lshlrev_b32_e32 v255, 1, v40
	v_bfi_b32 v255, s100, v255, v40
	v_lshrrev_b32_e32 v40, 5, v40
	v_bfi_b32 v40, 64, v40, v255
	v_lshl_add_u64 v[40:41], v[40:41], 0, 64
	v_lshl_add_u64 v[40:41], v[40:41], 0, 64
	s_mov_b32 s3, 0
	s_mov_b32 s9, 1
	s_mov_b32 s10, 2
	s_mov_b32 s11, 0
	v_mov_b32_e32 v3, v2
	v_mov_b32_e32 v4, v2
	v_mov_b32_e32 v5, v2
	v_mov_b32_e32 v6, v2
	v_mov_b32_e32 v7, v2
	v_mov_b32_e32 v8, v2
	v_mov_b32_e32 v9, v2
	v_mov_b32_e32 v10, v2
	v_mov_b32_e32 v11, v2
	v_mov_b32_e32 v12, v2
	v_mov_b32_e32 v13, v2
	v_mov_b32_e32 v14, v2
	v_mov_b32_e32 v15, v2
	v_mov_b32_e32 v16, v2
	v_mov_b32_e32 v17, v2
	v_mov_b32_e32 v18, v2
	v_mov_b32_e32 v19, v2
	v_mov_b32_e32 v20, v2
	v_mov_b32_e32 v21, v2
	v_mov_b32_e32 v22, v2
	v_mov_b32_e32 v23, v2
	v_mov_b32_e32 v24, v2
	v_mov_b32_e32 v25, v2
	v_mov_b32_e32 v26, v2
	v_mov_b32_e32 v27, v2
	v_mov_b32_e32 v28, v2
	v_mov_b32_e32 v29, v2
	v_mov_b32_e32 v30, v2
	v_mov_b32_e32 v31, v2
	v_mov_b32_e32 v32, v2
	v_mov_b32_e32 v33, v2
	s_waitcnt vmcnt(0)
.LBB0_1182:
	s_mul_hi_u32 s13, s11, 0xaaaaaaab
	s_lshr_b32 s13, s13, 1
	s_mul_i32 s13, s13, 0x9000
	s_mul_hi_u32 s12, s9, 0xaaaaaaab
	v_subrev_u32_e32 v44, s13, v56
	v_add_u32_e32 v98, s3, v54
	s_lshr_b32 s12, s12, 1
	s_waitcnt vmcnt(3)
	v_add_u32_e32 v76, v98, v44
	s_mul_i32 s12, s12, 0x9000
	v_subrev_u32_e32 v80, s13, v57
	s_waitcnt lgkmcnt(0)
	s_barrier
	ds_read_b128 v[44:47], v76 offset:4096
	ds_read_b128 v[68:71], v76 offset:5120
	ds_read_b128 v[72:75], v76 offset:6144
	ds_read_b128 v[76:79], v76 offset:7168
	v_subrev_u32_e32 v67, s12, v56
	v_subrev_u32_e32 v94, s12, v58
	s_mul_hi_u32 s12, s8, 0xaaaaaaab
	v_add_u32_e32 v84, v98, v80
	s_lshr_b32 s12, s12, 1
	ds_read_b128 v[80:83], v84
	ds_read_b128 v[84:87], v84 offset:1024
	s_mul_i32 s12, s12, 0x9000
	v_subrev_u32_e32 v95, s12, v59
	v_subrev_u32_e32 v96, s12, v60
	v_subrev_u32_e32 v97, s12, v61
	s_mul_hi_u32 s12, s10, 0xaaaaaaab
	s_lshr_b32 s12, s12, 1
	s_mul_i32 s12, s12, 0x9000
	v_subrev_u32_e32 v92, s12, v62
	v_subrev_u32_e32 v99, s12, v63
	v_subrev_u32_e32 v100, s12, v64
	s_add_i32 s12, s3, 0
	v_add_u32_e32 v92, s12, v92
	v_lshl_add_u64 v[88:89], v[42:43], 0, v[38:39]
	v_readfirstlane_b32 s13, v92
	v_lshl_add_u64 v[90:91], v[88:89], 0, s[74:75]
	s_mov_b32 m0, s13
	v_add_u32_e32 v99, s12, v99
	global_load_lds_dwordx4 v[90:91], off
	v_lshl_add_u64 v[90:91], v[40:41], 0, v[38:39]
	v_readfirstlane_b32 s13, v99
	v_add_u32_e32 v99, s12, v100
	v_lshl_add_u64 v[92:93], v[90:91], 0, s[74:75]
	s_mov_b32 m0, s13
	v_readfirstlane_b32 s13, v99
	global_load_lds_dwordx4 v[92:93], off
	v_lshl_add_u64 v[92:93], v[90:91], 0, s[92:93]
	s_mov_b32 m0, s13
	s_add_i32 s11, s11, 2
	global_load_lds_dwordx4 v[92:93], off
	s_waitcnt lgkmcnt(0)
	v_mfma_f32_16x16x32_bf16 v[30:33], v[44:47], v[80:83], v[30:33]
	v_mfma_f32_16x16x32_bf16 v[26:29], v[68:71], v[80:83], v[26:29]
	v_mfma_f32_16x16x32_bf16 v[22:25], v[72:75], v[80:83], v[22:25]
	v_mfma_f32_16x16x32_bf16 v[18:21], v[76:79], v[80:83], v[18:21]
	v_mfma_f32_16x16x32_bf16 v[14:17], v[44:47], v[84:87], v[14:17]
	v_mfma_f32_16x16x32_bf16 v[10:13], v[68:71], v[84:87], v[10:13]
	v_mfma_f32_16x16x32_bf16 v[6:9], v[72:75], v[84:87], v[6:9]
	v_mfma_f32_16x16x32_bf16 v[2:5], v[76:79], v[84:87], v[2:5]
	s_waitcnt vmcnt(3)
	v_add_u32_e32 v67, v98, v67
	s_waitcnt lgkmcnt(0)
	s_barrier
; #define MFMA(a, b, c) __builtin_amdgcn_mfma_f32_16x16x32_bf16((a), (b), (c), 0, 0, 0)
; template <int EPI, int MF>
; __device__ __forceinline__ void gemm_part(const u16* __restrict__ A, int lda, const u16* __restrict__ Bt, int K, int ntn, GemmEpi ep, char* smem,
;                                           int mbase, int mrows) {
;     ...
;     for (int kt = 0; kt < nk; ++kt) {
;       if (kt + 1 < nk) {
;         if (MF == 8) asm volatile("s_waitcnt vmcnt(6)" ::: "memory");
;         else asm volatile("s_waitcnt vmcnt(3)" ::: "memory");
;       } else asm volatile("s_waitcnt vmcnt(0)" ::: "memory");
;       asm volatile("s_waitcnt lgkmcnt(0)" ::: "memory");
;       __builtin_amdgcn_s_barrier();
;       const u16* a_ = sbase + (kt % 3) * STG;
;       const u16* b_ = a_ + BM * 32;
;       bf16x8 bfr[4], afc[2], afn[2];
;       const u16* ap_ = a_ + (wr * (16 * MF) + fr) * 32 + fq * 8;
; #pragma unroll
;       for (int n = 0; n < 4; ++n) bfr[n] = rd_std(b_ + (wc * 64 + n * 16 + fr) * 32 + fq * 8);
;       afc[0] = rd_std(ap_); afc[1] = rd_std(ap_ + 16 * 32);
;       __builtin_amdgcn_sched_barrier(0);
;       if (kt + 2 < nk) GEMM_ISSUE(kt + 2);
;       __builtin_amdgcn_sched_barrier(0);
; #pragma unroll
;       for (int mh = 0; mh < MF / 2; ++mh) {
;         if (mh + 1 < MF / 2) {
;           afn[0] = rd_std(ap_ + ((mh + 1) * 2) * 16 * 32);
;           afn[1] = rd_std(ap_ + ((mh + 1) * 2 + 1) * 16 * 32);
;         }
;         __builtin_amdgcn_sched_barrier(0);
; #pragma unroll
;         for (int m = 0; m < 2; ++m)
; #pragma unroll
;           for (int n = 0; n < 4; ++n) acc[mh * 2 + m][n] = MFMA(bfr[n], afc[m], acc[mh * 2 + m][n]);
;         __builtin_amdgcn_sched_barrier(0);
;         afc[0] = afn[0]; afc[1] = afn[1];
;       }
;     }
;     ...
;     __syncthreads();
	ds_read_b128 v[44:47], v67 offset:16384
	ds_read_b128 v[68:71], v67 offset:17408
	ds_read_b128 v[72:75], v67 offset:18432
	ds_read_b128 v[76:79], v67 offset:19456
	v_add_u32_e32 v67, v98, v94
	ds_read_b128 v[80:83], v67
	ds_read_b128 v[84:87], v67 offset:1024
	v_add_u32_e32 v67, s12, v97
	v_lshl_add_u64 v[88:89], v[88:89], 0, s[52:53]
	v_readfirstlane_b32 s13, v67
	v_add_u32_e32 v67, s12, v96
	s_mov_b32 m0, s13
	v_readfirstlane_b32 s13, v67
	v_add_u32_e32 v67, s12, v95
	global_load_lds_dwordx4 v[88:89], off
	v_lshl_add_u64 v[88:89], v[90:91], 0, s[52:53]
	v_lshl_add_u64 v[88:89], v[88:89], 0, 64
	s_mov_b32 m0, s13
	v_readfirstlane_b32 s12, v67
	global_load_lds_dwordx4 v[88:89], off
	v_lshl_add_u64 v[88:89], v[90:91], 0, s[54:55]
	v_lshl_add_u64 v[88:89], v[88:89], 0, 64
	s_mov_b32 m0, s12
	s_nop 0
	global_load_lds_dwordx4 v[88:89], off
	s_waitcnt lgkmcnt(0)
	v_mfma_f32_16x16x32_bf16 v[30:33], v[44:47], v[80:83], v[30:33]
	v_mfma_f32_16x16x32_bf16 v[26:29], v[68:71], v[80:83], v[26:29]
	v_mfma_f32_16x16x32_bf16 v[22:25], v[72:75], v[80:83], v[22:25]
	v_mfma_f32_16x16x32_bf16 v[18:21], v[76:79], v[80:83], v[18:21]
	v_mfma_f32_16x16x32_bf16 v[14:17], v[44:47], v[84:87], v[14:17]
	v_mfma_f32_16x16x32_bf16 v[10:13], v[68:71], v[84:87], v[10:13]
	v_mfma_f32_16x16x32_bf16 v[6:9], v[72:75], v[84:87], v[6:9]
	v_mfma_f32_16x16x32_bf16 v[2:5], v[76:79], v[84:87], v[2:5]
	s_addk_i32 s3, 0x6000
	s_add_i32 s9, s9, 2
	s_add_i32 s8, s8, 2
	s_add_i32 s10, s10, 2
	v_lshl_add_u64 v[40:41], v[40:41], 0, s[74:75]
	v_lshl_add_u64 v[40:41], v[40:41], 0, s[74:75]
	s_cmp_eq_u32 s3, 0x5a000
	v_lshl_add_u64 v[42:43], v[42:43], 0, s[74:75]
	s_cbranch_scc0 .LBB0_1182
	s_waitcnt vmcnt(3)
	s_waitcnt lgkmcnt(0)
	s_barrier
	ds_read_b128 v[40:43], v65 offset:4096
	ds_read_b128 v[44:47], v65 offset:5120
	ds_read_b128 v[68:71], v65 offset:6144
	ds_read_b128 v[72:75], v65 offset:7168
	ds_read_b128 v[76:79], v55
	ds_read_b128 v[80:83], v55 offset:1024
	s_mul_hi_u32 s8, s9, 0xaaaaaaab
	s_lshr_b32 s8, s8, 1
	s_mul_i32 s8, s8, 0x9000
	s_sub_i32 s3, s3, s8
	s_add_i32 s3, s3, 0
	s_addk_i32 s3, 0x3000
	s_waitcnt lgkmcnt(0)
	v_mfma_f32_16x16x32_bf16 v[30:33], v[40:43], v[76:79], v[30:33]
	v_mfma_f32_16x16x32_bf16 v[26:29], v[44:47], v[76:79], v[26:29]
	v_mfma_f32_16x16x32_bf16 v[22:25], v[68:71], v[76:79], v[22:25]
	v_mfma_f32_16x16x32_bf16 v[18:21], v[72:75], v[76:79], v[18:21]
	v_mfma_f32_16x16x32_bf16 v[14:17], v[40:43], v[80:83], v[14:17]
	v_mfma_f32_16x16x32_bf16 v[10:13], v[44:47], v[80:83], v[10:13]
	v_mfma_f32_16x16x32_bf16 v[6:9], v[68:71], v[80:83], v[6:9]
	v_mfma_f32_16x16x32_bf16 v[2:5], v[72:75], v[80:83], v[2:5]
	v_add_u32_e32 v40, s3, v66
	s_waitcnt vmcnt(0)
	v_add3_u32 v72, v40, v53, v50
	s_waitcnt lgkmcnt(0)
	s_barrier
	v_add_u32_e32 v67, s3, v49
	ds_read_b128 v[40:43], v72 offset:4096
	ds_read_b128 v[44:47], v72 offset:5120
	ds_read_b128 v[68:71], v72 offset:6144
	ds_read_b128 v[72:75], v72 offset:7168
	v_add3_u32 v67, v67, v50, v66
	ds_read_b128 v[76:79], v67
	ds_read_b128 v[80:83], v67 offset:1024
	s_waitcnt lgkmcnt(0)
	v_mfma_f32_16x16x32_bf16 v[30:33], v[40:43], v[76:79], v[30:33]
	v_mfma_f32_16x16x32_bf16 v[26:29], v[44:47], v[76:79], v[26:29]
	v_mfma_f32_16x16x32_bf16 v[22:25], v[68:71], v[76:79], v[22:25]
	v_mfma_f32_16x16x32_bf16 v[18:21], v[72:75], v[76:79], v[18:21]
	v_mfma_f32_16x16x32_bf16 v[14:17], v[40:43], v[80:83], v[14:17]
	v_mfma_f32_16x16x32_bf16 v[10:13], v[44:47], v[80:83], v[10:13]
	v_mfma_f32_16x16x32_bf16 v[6:9], v[68:71], v[80:83], v[6:9]
	v_mfma_f32_16x16x32_bf16 v[2:5], v[72:75], v[80:83], v[2:5]
	v_add_u32_e32 v44, s2, v51
	s_waitcnt vmcnt(0)
	s_barrier
; template <int EPI, int MF>
; __device__ __forceinline__ void gemm_part(const u16* __restrict__ A, int lda, const u16* __restrict__ Bt, int K, int ntn, GemmEpi ep, char* smem,
;                                           int mbase, int mrows) {
;     ...
;       } else if (EPI == EPI_RESID) {
;         const float* rp = (row < MP) ? ep.res0 + (size_t)row * DM : ep.res1 + (size_t)(row - MP) * DM;
;         float ssq = 0.f;
; #pragma unroll
;         for (int n = 0; n < 4; ++n) {
;           const int col = cb + n * 16;
;           const float4 r = *(const float4*)(rp + col);
;           float4 v;
;           v.x = r.x + ep.scale * acc[m][n][0]; v.y = r.y + ep.scale * acc[m][n][1];
;           v.z = r.z + ep.scale * acc[m][n][2]; v.w = r.w + ep.scale * acc[m][n][3];
;           *(float4*)(ep.outf + (size_t)row * DM + col) = v;
;           if (ep.xcopy) {
;             bf16x4 o;
;             o[0] = (short)f2bf(v.x); o[1] = (short)f2bf(v.y); o[2] = (short)f2bf(v.z); o[3] = (short)f2bf(v.w);
;             *(bf16x4*)(ep.xcopy + (size_t)row * DM + col) = o;
;           }
;           ssq += v.x * v.x + v.y * v.y + v.z * v.z + v.w * v.w;
;         }
;         if (ep.rss_out) {
;           ssq += __shfl_xor(ssq, 16);
;           ssq += __shfl_xor(ssq, 32);
;           if (fq == 0) atomicAdd(ep.rss_out + row, ssq);
;         }
	s_mov_b32 s2, 0xffff
	v_cmp_lt_i32_e64 s[12:13], s2, v44
	s_and_saveexec_b64 s[2:3], s[12:13]
	s_xor_b64 s[2:3], exec, s[2:3]
	v_add_u32_e32 v40, 0xffff0000, v44
	v_mov_b32_e32 v41, v0
	v_lshlrev_b64 v[40:41], 12, v[40:41]
	v_lshl_add_u64 v[46:47], s[72:73], 0, v[40:41]
	v_mov_b32_e32 v45, v0
	s_andn2_saveexec_b64 s[2:3], s[2:3]
	v_ashrrev_i32_e32 v45, 31, v44
	v_lshlrev_b64 v[40:41], 12, v[44:45]
	v_lshl_add_u64 v[46:47], s[26:27], 0, v[40:41]
	s_or_b64 exec, exec, s[2:3]
	v_or_b32_e32 v40, s5, v52
	v_ashrrev_i32_e32 v41, 31, v40
	v_lshlrev_b64 v[42:43], 2, v[40:41]
	v_lshl_add_u64 v[46:47], v[46:47], 0, v[42:43]
	global_load_dwordx4 v[68:71], v[46:47], off
	v_lshlrev_b64 v[72:73], 12, v[44:45]
	v_lshlrev_b64 v[74:75], 11, v[44:45]
	v_lshl_add_u64 v[72:73], s[26:27], 0, v[72:73]
	v_lshl_add_u64 v[74:75], s[28:29], 0, v[74:75]
	v_lshl_add_u64 v[76:77], v[40:41], 1, v[74:75]
	v_lshl_add_u64 v[78:79], v[72:73], 0, v[42:43]
	s_waitcnt vmcnt(0)
	v_pk_add_f32 v[30:31], v[30:31], v[68:69]
	v_pk_add_f32 v[32:33], v[32:33], v[70:71]
	v_cvt_pk_bf16_f32 v68, v30, v31
	v_cvt_pk_bf16_f32 v69, v32, v33
	global_store_dwordx4 v[78:79], v[30:33], off
	v_lshlrev_b32_e32 v84, 1, v76
	v_bfi_b32 v84, s100, v84, v76
	v_lshrrev_b32_e32 v85, 5, v76
	v_bfi_b32 v84, 64, v85, v84
	v_mov_b32_e32 v85, v77
	global_store_dwordx2 v[84:85], v[68:69], off
	global_load_dwordx4 v[68:71], v[46:47], off offset:64
	s_waitcnt vmcnt(0)
	v_pk_add_f32 v[26:27], v[26:27], v[68:69]
	v_pk_add_f32 v[28:29], v[28:29], v[70:71]
	v_cvt_pk_bf16_f32 v68, v26, v27
	v_cvt_pk_bf16_f32 v69, v28, v29
	global_store_dwordx4 v[78:79], v[26:29], off offset:64
	v_lshlrev_b32_e32 v84, 1, v76
	v_bfi_b32 v84, s100, v84, v76
	v_lshrrev_b32_e32 v85, 5, v76
	v_bfi_b32 v84, 64, v85, v84
	v_mov_b32_e32 v85, v77
	global_store_dwordx2 v[84:85], v[68:69], off offset:32
	global_load_dwordx4 v[68:71], v[46:47], off offset:128
	s_waitcnt vmcnt(0)
	v_pk_add_f32 v[68:69], v[22:23], v[68:69]
	v_pk_add_f32 v[70:71], v[24:25], v[70:71]
	v_cvt_pk_bf16_f32 v22, v68, v69
	v_cvt_pk_bf16_f32 v23, v70, v71
	global_store_dwordx4 v[78:79], v[68:71], off offset:128
	v_lshlrev_b32_e32 v84, 1, v76
	v_bfi_b32 v84, s100, v84, v76
	v_lshrrev_b32_e32 v85, 5, v76
	v_bfi_b32 v84, 64, v85, v84
	v_mov_b32_e32 v85, v77
	global_store_dwordx2 v[84:85], v[22:23], off offset:128
	global_load_dwordx4 v[72:75], v[46:47], off offset:192
	v_pk_mul_f32 v[24:25], v[30:31], v[30:31]
	v_pk_mul_f32 v[30:31], v[32:33], v[32:33]
	v_add_f32_e32 v24, v24, v25
	v_add_f32_e32 v24, v30, v24
	v_add_f32_e32 v30, v31, v24
	v_pk_mul_f32 v[24:25], v[26:27], v[26:27]
	v_pk_mul_f32 v[26:27], v[28:29], v[28:29]
	v_add_f32_e32 v24, v24, v25
	v_add_f32_e32 v24, v26, v24
	v_add_f32_e32 v24, v27, v24
	v_add_f32_e32 v28, v30, v24
	v_pk_mul_f32 v[24:25], v[68:69], v[68:69]
	v_pk_mul_f32 v[26:27], v[70:71], v[70:71]
	v_add_f32_e32 v24, v24, v25
	v_add_f32_e32 v24, v26, v24
	v_add_f32_e32 v24, v27, v24
	v_add_f32_e32 v28, v28, v24
	v_and_b32_e32 v23, 64, v141
	v_xor_b32_e32 v22, 16, v141
	v_add_u32_e32 v23, 64, v23
	v_cmp_lt_i32_e64 s[12:13], v22, v23
	s_waitcnt vmcnt(0)
	v_pk_add_f32 v[24:25], v[18:19], v[72:73]
	v_pk_add_f32 v[26:27], v[20:21], v[74:75]
	v_pk_mul_f32 v[20:21], v[24:25], v[24:25]
	v_pk_mul_f32 v[18:19], v[26:27], v[26:27]
	v_add_f32_e32 v20, v20, v21
	v_add_f32_e32 v18, v18, v20
	v_cndmask_b32_e64 v22, v141, v22, s[12:13]
	v_add_f32_e32 v18, v19, v18
	v_lshlrev_b32_e32 v22, 2, v22
	v_add_f32_e32 v18, v28, v18
	ds_bpermute_b32 v19, v22, v18
	v_xor_b32_e32 v20, 32, v141
	v_cmp_lt_i32_e64 s[12:13], v20, v23
	v_cvt_pk_bf16_f32 v21, v26, v27
	global_store_dwordx4 v[78:79], v[24:27], off offset:192
	v_cndmask_b32_e64 v20, v141, v20, s[12:13]
	s_waitcnt lgkmcnt(0)
	v_add_f32_e32 v18, v18, v19
	v_lshlrev_b32_e32 v23, 2, v20
	ds_bpermute_b32 v19, v23, v18
	v_cvt_pk_bf16_f32 v20, v24, v25
	v_lshlrev_b32_e32 v84, 1, v76
	v_bfi_b32 v84, s100, v84, v76
	v_lshrrev_b32_e32 v85, 5, v76
	v_bfi_b32 v84, 64, v85, v84
	v_mov_b32_e32 v85, v77
	global_store_dwordx2 v[84:85], v[20:21], off offset:160
	s_and_saveexec_b64 s[2:3], vcc
	s_cbranch_execz .LBB0_1189
	v_readlane_b32 s8, v252, 9
	v_readlane_b32 s9, v252, 10
	s_waitcnt lgkmcnt(0)
	v_add_f32_e32 v18, v18, v19
	v_lshl_add_u64 v[20:21], v[44:45], 2, s[8:9]
	global_atomic_add_f32 v[20:21], v18, off

; template <int EPI, int MF>
; __device__ __forceinline__ void gemm_part(const u16* __restrict__ A, int lda, const u16* __restrict__ Bt, int K, int ntn, GemmEpi ep, char* smem,
;                                           int mbase, int mrows) {
;   const int tid = opaque_tid(), lane = tid & 63, wid = tid >> 6, wr = wid >> 1, wc = wid & 1, fr = lane & 15, fq = lane >> 4;
;   constexpr int BM = 32 * MF;
;   constexpr int STG = BM * 32 + 4096;
;   constexpr int NA = MF / 2;
;   u16* const sbase = (u16*)smem;
;   const int ntm = mrows / BM;
;   const int total = ntm * ntn;
;   const int nk = K / 32;
;   const int nbx = (MF == 2) ? (int)gridDim.x : (int)(gridDim.x >> 3);
;   const int xcd = (MF == 2) ? 0 : (int)(blockIdx.x & 7), li = (MF == 2) ? (int)blockIdx.x : (int)(blockIdx.x >> 3);
;   for (int q = xcd; q * nbx < total; q += (MF == 2) ? 1 : 8) {
;     const int L = q * nbx + li;
;     if (L >= total) continue;
;     const int g = L / (8 * ntn), rr = L % (8 * ntn);
;     const int rows = min(8, ntm - 8 * g);
;     const int tm = 8 * g + rr % rows, tn = rr / rows;
;     const int row0 = mbase + tm * BM, col0 = tn * 128;
;     f32x4 acc[MF][4];
; #pragma unroll
;     for (int m = 0; m < MF; ++m)
; #pragma unroll
;       for (int n = 0; n < 4; ++n) acc[m][n] = (f32x4){0.f, 0.f, 0.f, 0.f};
;     const u16* gA = A + (size_t)(row0 + (tid >> 2)) * lda + (tid & 3) * 8;
;     const u16* gB = Bt + (size_t)(col0 + (tid >> 2)) * K + (tid & 3) * 8;
;     ...
;               u16* st = sbase + (wc * 64 + n * 16 + 4 * fq) * 264 + wr * 128 + m * 16 + fr;
;               st[0] = (u16)o[0]; st[264] = (u16)o[1]; st[528] = (u16)o[2]; st[792] = (u16)o[3];
;             }
;           }
;         }
;       } else {
; #pragma unroll
;         for (int n = 0; n < 4; ++n) {
;           const int col = cb + n * 16;
;           if (col < OPJ) {
;             bf16x4 o;
; #pragma unroll
;             for (int jj = 0; jj < 4; ++jj) o[jj] = (short)f2bf(acc[m][n][jj] * rstd);
;             *(bf16x4*)(ep.outb + (size_t)row * OPJ + col) = o;
;           }
;         }
;       }
;     }
;     if (EPI == EPI_PROJ_EVEN && MF == 8) {
;       if (col0 >= 1024 && col0 < 1536) {
;         __syncthreads();
;         u16* vt = ep.vT + ((size_t)((row0 >> 12) * 512 + (col0 - 1024))) * SEQ + (row0 & 4095);
; #pragma unroll
;         for (int i = 0; i < 16; ++i) {
.LBB0_1196:
	s_and_b64 vcc, exec, s[2:3]
	s_cbranch_vccz .LBB0_1905
	v_readlane_b32 s2, v253, 40
	v_readlane_b32 s3, v253, 41
	v_mov_b32_e32 v2, v140
	s_andn2_b64 vcc, exec, s[2:3]
	s_cbranch_vccnz .LBB0_1454
	v_lshlrev_b32_e32 v10, 4, v2
	v_bfe_u32 v8, v2, 6, 1
	v_lshrrev_b32_e32 v100, 4, v140
	v_sub_u32_e32 v100, 0, v100
	v_xor_b32_e32 v100, v100, v140
	v_and_b32_e32 v100, 3, v100
	v_lshlrev_b32_e32 v4, 4, v100
	v_mov_b32_e32 v5, v0
	v_bfe_u32 v7, v2, 4, 2
	v_lshl_add_u64 v[130:131], s[44:45], 0, v[4:5]
	v_lshl_add_u64 v[132:133], s[36:37], 0, v[4:5]
	v_lshlrev_b32_e32 v4, 5, v2
	v_lshlrev_b32_e32 v5, 6, v8
	s_waitcnt lgkmcnt(0)
	v_and_b32_e32 v3, 15, v2
	v_and_b32_e32 v195, 0xfffff1e0, v4
	v_and_b32_e32 v4, 0x7fffff80, v2
	v_lshl_or_b32 v198, v7, 2, v5
	v_lshl_add_u32 v6, v3, 1, 0
	v_lshlrev_b32_e32 v196, 3, v7
	v_lshlrev_b32_e32 v5, 1, v4
	v_lshlrev_b32_e32 v209, 6, v3
	v_lshrrev_b32_e32 v101, 2, v140
	v_sub_u32_e32 v101, 0, v101
	v_lshrrev_b32_e32 v3, 4, v140
	v_xor_b32_e32 v101, v101, v3
	v_and_b32_e32 v101, 3, v101
	v_lshlrev_b32_e32 v3, 4, v101
	v_mul_u32_u24_e32 v7, 0x210, v198
	v_add3_u32 v211, v6, v5, v7
	v_ashrrev_i32_e32 v6, 5, v2
	s_movk_i32 s2, 0x210
	v_ashrrev_i32_e32 v7, 31, v6
	v_mul_lo_u32 v5, v6, s2
	v_lshlrev_b64 v[134:135], 13, v[6:7]
	v_add_u32_e32 v6, 0x100, v2
	v_ashrrev_i32_e32 v6, 5, v6
	v_ashrrev_i32_e32 v7, 31, v6
	v_lshlrev_b32_e32 v199, 12, v8
	v_mul_lo_u32 v8, v6, s2
	v_lshlrev_b64 v[136:137], 13, v[6:7]
	v_add_u32_e32 v6, 0x200, v2
	v_ashrrev_i32_e32 v6, 5, v6
	v_ashrrev_i32_e32 v7, 31, v6
	v_add_u32_e32 v194, 0, v10
	v_mul_lo_u32 v10, v6, s2
	v_lshlrev_b64 v[138:139], 13, v[6:7]
	v_add_u32_e32 v6, 0x300, v2
	v_ashrrev_i32_e32 v6, 5, v6
	v_ashrrev_i32_e32 v7, 31, v6
	v_mul_lo_u32 v11, v6, s2
	v_lshlrev_b64 v[146:147], 13, v[6:7]
	v_add_u32_e32 v6, 0x400, v2
	v_ashrrev_i32_e32 v6, 5, v6
	v_ashrrev_i32_e32 v7, 31, v6
	v_mul_lo_u32 v12, v6, s2
	v_lshlrev_b64 v[148:149], 13, v[6:7]
	v_add_u32_e32 v6, 0x500, v2
	v_ashrrev_i32_e32 v6, 5, v6
	v_ashrrev_i32_e32 v7, 31, v6
	v_mul_lo_u32 v13, v6, s2
	v_lshlrev_b64 v[150:151], 13, v[6:7]
	v_add_u32_e32 v6, 0x600, v2
	v_ashrrev_i32_e32 v6, 5, v6
	v_ashrrev_i32_e32 v7, 31, v6
	v_mul_lo_u32 v14, v6, s2
	v_lshlrev_b64 v[152:153], 13, v[6:7]
	v_add_u32_e32 v6, 0x700, v2
	v_ashrrev_i32_e32 v6, 5, v6
	v_ashrrev_i32_e32 v7, 31, v6
	v_mul_lo_u32 v15, v6, s2
	v_lshlrev_b64 v[154:155], 13, v[6:7]
	v_add_u32_e32 v6, 0x800, v2
	v_ashrrev_i32_e32 v6, 5, v6
	v_ashrrev_i32_e32 v7, 31, v6
	v_mul_lo_u32 v16, v6, s2
	v_lshlrev_b64 v[156:157], 13, v[6:7]
	v_add_u32_e32 v6, 0x900, v2
	v_ashrrev_i32_e32 v6, 5, v6
	v_ashrrev_i32_e32 v7, 31, v6
	v_mul_lo_u32 v17, v6, s2
	v_lshlrev_b64 v[158:159], 13, v[6:7]
	v_add_u32_e32 v6, 0xa00, v2
	v_ashrrev_i32_e32 v6, 5, v6
	v_ashrrev_i32_e32 v7, 31, v6
	v_mul_lo_u32 v18, v6, s2
	v_lshlrev_b64 v[160:161], 13, v[6:7]
	v_add_u32_e32 v6, 0xb00, v2
	v_ashrrev_i32_e32 v6, 5, v6
	v_ashrrev_i32_e32 v7, 31, v6
	v_mul_lo_u32 v19, v6, s2
	v_lshlrev_b64 v[162:163], 13, v[6:7]
	v_add_u32_e32 v6, 0xc00, v2
	v_ashrrev_i32_e32 v6, 5, v6
	v_ashrrev_i32_e32 v7, 31, v6
	v_mul_lo_u32 v20, v6, s2
	v_lshlrev_b64 v[164:165], 13, v[6:7]
	v_add_u32_e32 v6, 0xd00, v2
	v_ashrrev_i32_e32 v6, 5, v6
	v_ashrrev_i32_e32 v7, 31, v6
	v_mul_lo_u32 v21, v6, s2
	v_lshlrev_b64 v[166:167], 13, v[6:7]
	v_add_u32_e32 v6, 0xe00, v2
	v_ashrrev_i32_e32 v6, 5, v6
	v_ashrrev_i32_e32 v7, 31, v6
	v_mul_lo_u32 v22, v6, s2
	v_lshlrev_b64 v[168:169], 13, v[6:7]
	v_add_u32_e32 v6, 0xf00, v2
	v_lshlrev_b32_e32 v9, 3, v2
	v_ashrrev_i32_e32 v6, 5, v6
	v_ashrrev_i32_e32 v1, 2, v2
	v_and_b32_e32 v197, 0xffffff8f, v2
	v_and_b32_e32 v4, 0xf8, v9
	v_ashrrev_i32_e32 v7, 31, v6
	v_and_b32_e32 v2, 3, v2
	v_lshl_add_u32 v9, v4, 1, 0
	v_lshl_add_u32 v210, v195, 1, v3
	v_mul_lo_u32 v23, v6, s2
	v_lshlrev_b64 v[170:171], 13, v[6:7]
	v_add_u32_e32 v6, v3, v199
	v_lshlrev_b32_e32 v2, 4, v100
	v_mov_b32_e32 v3, v0
	v_lshl_add_u64 v[172:173], s[44:45], 0, v[2:3]
	v_add_u32_e32 v212, v6, v209
	v_lshlrev_b32_e32 v174, 1, v4
	v_add_u32_e32 v213, v9, v5
	v_add_u32_e32 v214, v9, v8
	v_add_u32_e32 v215, v9, v10
	v_add_u32_e32 v216, v9, v11
	v_add_u32_e32 v217, v9, v12
	v_add_u32_e32 v218, v9, v13
	v_add_u32_e32 v219, v9, v14
	v_add_u32_e32 v220, v9, v15
	v_add_u32_e32 v221, v9, v16
	v_add_u32_e32 v222, v9, v17
	v_add_u32_e32 v223, v9, v18
	v_add_u32_e32 v224, v9, v19
	v_add_u32_e32 v225, v9, v20
	v_add_u32_e32 v226, v9, v21
	v_add_u32_e32 v227, v9, v22
	v_add_u32_e32 v228, v9, v23
	v_readlane_b32 s2, v253, 56
	v_readlane_b32 s8, v253, 9
	s_branch .LBB0_1200

; template <int EPI, int MF>
; __device__ __forceinline__ void gemm_part(const u16* __restrict__ A, int lda, const u16* __restrict__ Bt, int K, int ntn, GemmEpi ep, char* smem,
;                                           int mbase, int mrows) {
;     ...
;   for (int q = xcd; q * nbx < total; q += (MF == 2) ? 1 : 8) {
;     const int L = q * nbx + li;
;     if (L >= total) continue;
;     const int g = L / (8 * ntn), rr = L % (8 * ntn);
;     const int rows = min(8, ntm - 8 * g);
;     const int tm = 8 * g + rr % rows, tn = rr / rows;
;     const int row0 = mbase + tm * BM, col0 = tn * 128;
;     f32x4 acc[MF][4];
; #pragma unroll
;     for (int m = 0; m < MF; ++m)
; #pragma unroll
;       for (int n = 0; n < 4; ++n) acc[m][n] = (f32x4){0.f, 0.f, 0.f, 0.f};
;     const u16* gA = A + (size_t)(row0 + (tid >> 2)) * lda + (tid & 3) * 8;
;     const u16* gB = Bt + (size_t)(col0 + (tid >> 2)) * K + (tid & 3) * 8;
;     ...
;     GEMM_ISSUE(0);
;     GEMM_ISSUE(1);
.LBB0_1200:
	s_add_i32 s2, s2, s63
	s_cmpk_gt_u32 s2, 0x1bff
	s_cbranch_scc1 .LBB0_1199
	s_bfe_u32 s3, s2, 0xb0005
	s_mulk_i32 s3, 0x2493
	s_lshr_b32 s3, s3, 16
	s_mul_i32 s4, s3, 0xe0
	s_sub_i32 s2, s2, s4
	s_lshl_b32 s3, s3, 3
	s_and_b32 s4, s2, 7
	s_or_b32 s3, s3, s4
	s_and_b32 s10, s3, 0xffff
	s_lshl_b32 s9, s10, 8
	v_add_u32_e32 v2, s9, v1
	v_ashrrev_i32_e32 v3, 31, v2
	s_bfe_u32 s4, s2, 0xd0003
	v_lshlrev_b64 v[2:3], 11, v[2:3]
	v_readfirstlane_b32 s2, v194
	v_add_u32_e32 v10, 0x1000, v194
	v_lshl_add_u64 v[4:5], v[130:131], 0, v[2:3]
	v_lshlrev_b32_e32 v255, 1, v4
	v_bfi_b32 v255, s100, v255, v4
	v_lshrrev_b32_e32 v4, 5, v4
	v_bfi_b32 v4, 64, v4, v255
	s_mov_b32 m0, s2
	s_mov_b64 s[12:13], 0x20000
	v_readfirstlane_b32 s2, v10
	s_lshl_b32 s11, s4, 7
	global_load_lds_dwordx4 v[4:5], off
	v_lshl_add_u64 v[8:9], v[4:5], 0, s[12:13]
	s_mov_b32 m0, s2
	s_mov_b64 s[2:3], 0x40000
	v_add_u32_e32 v10, 0x2000, v194
	v_add_u32_e32 v6, s11, v1
	global_load_lds_dwordx4 v[8:9], off
	v_lshl_add_u64 v[8:9], v[4:5], 0, s[2:3]
	v_readfirstlane_b32 s2, v10
	v_ashrrev_i32_e32 v7, 31, v6
	s_mov_b32 m0, s2
	s_mov_b64 s[2:3], 0x60000
	v_add_u32_e32 v10, 0x3000, v194
	v_lshlrev_b64 v[6:7], 11, v[6:7]
	global_load_lds_dwordx4 v[8:9], off
	v_lshl_add_u64 v[8:9], v[4:5], 0, s[2:3]
	v_readfirstlane_b32 s2, v10
	s_mov_b32 m0, s2
	v_lshl_add_u64 v[176:177], v[132:133], 0, v[6:7]
	v_lshlrev_b32_e32 v255, 1, v176
	v_bfi_b32 v255, s100, v255, v176
	v_lshrrev_b32_e32 v176, 5, v176
	v_bfi_b32 v176, 64, v176, v255
	v_add_u32_e32 v6, 0x4000, v194
	global_load_lds_dwordx4 v[8:9], off
	v_readfirstlane_b32 s2, v6
	v_add_u32_e32 v8, 0x5000, v194
	s_mov_b32 m0, s2
	v_readfirstlane_b32 s2, v8
	v_add_u32_e32 v8, 0x6000, v194
	global_load_lds_dwordx4 v[176:177], off
	v_lshl_add_u64 v[6:7], v[176:177], 0, s[12:13]
	s_mov_b32 m0, s2
	v_readfirstlane_b32 s2, v8
	v_add_u32_e32 v8, 0x7000, v194
	global_load_lds_dwordx4 v[6:7], off
	v_lshl_add_u64 v[6:7], v[4:5], 0, 64
	v_lshl_add_u64 v[6:7], v[6:7], 0, 64
	s_mov_b32 m0, s2
	s_mov_b64 s[12:13], 0x20040
	v_readfirstlane_b32 s2, v8
	global_load_lds_dwordx4 v[6:7], off
	v_lshl_add_u64 v[6:7], v[4:5], 0, s[12:13]
	v_lshl_add_u64 v[6:7], v[6:7], 0, 64
	s_mov_b32 m0, s2
	s_mov_b64 s[2:3], 0x40040
	v_add_u32_e32 v8, 0x8000, v194
	global_load_lds_dwordx4 v[6:7], off
	v_lshl_add_u64 v[6:7], v[4:5], 0, s[2:3]
	v_lshl_add_u64 v[6:7], v[6:7], 0, 64
	v_readfirstlane_b32 s2, v8
	s_mov_b32 m0, s2
	s_mov_b64 s[2:3], 0x60040
	global_load_lds_dwordx4 v[6:7], off
	v_add_u32_e32 v6, 0x9000, v194
	v_lshl_add_u64 v[4:5], v[4:5], 0, s[2:3]
	v_lshl_add_u64 v[4:5], v[4:5], 0, 64
	v_readfirstlane_b32 s2, v6
	v_add_u32_e32 v6, 0xa000, v194
	s_mov_b32 m0, s2
	v_readfirstlane_b32 s2, v6
	v_add_u32_e32 v6, 0xb000, v194
	global_load_lds_dwordx4 v[4:5], off
	v_lshl_add_u64 v[4:5], v[176:177], 0, 64
	v_lshl_add_u64 v[4:5], v[4:5], 0, 64
	s_mov_b32 m0, s2
	v_readfirstlane_b32 s2, v6
	global_load_lds_dwordx4 v[4:5], off
	v_lshl_add_u64 v[4:5], v[176:177], 0, s[12:13]
	v_lshl_add_u64 v[4:5], v[4:5], 0, 64
	s_mov_b32 m0, s2
	v_lshl_add_u64 v[178:179], v[172:173], 0, v[2:3]
	v_lshlrev_b32_e32 v255, 1, v178
	v_bfi_b32 v255, s100, v255, v178
	v_lshrrev_b32_e32 v178, 5, v178
	v_bfi_b32 v178, 64, v178, v255
	v_lshl_add_u64 v[178:179], v[178:179], 0, 64
	v_lshl_add_u64 v[178:179], v[178:179], 0, 64
	global_load_lds_dwordx4 v[4:5], off
	v_lshl_add_u64 v[176:177], v[176:177], 0, 64
	v_lshl_add_u64 v[176:177], v[176:177], 0, 64
	v_mov_b32_e32 v2, 0
	s_mov_b64 s[2:3], 0
	s_mov_b32 s5, 2
	v_mov_b32_e32 v3, v2
	v_mov_b32_e32 v4, v2
	v_mov_b32_e32 v5, v2
	v_mov_b32_e32 v6, v2
	v_mov_b32_e32 v7, v2
	v_mov_b32_e32 v8, v2
	v_mov_b32_e32 v9, v2
	v_mov_b32_e32 v10, v2
	v_mov_b32_e32 v11, v2
	v_mov_b32_e32 v12, v2
	v_mov_b32_e32 v13, v2
	v_mov_b32_e32 v14, v2
	v_mov_b32_e32 v15, v2
	v_mov_b32_e32 v16, v2
	v_mov_b32_e32 v17, v2
	v_mov_b32_e32 v18, v2
	v_mov_b32_e32 v19, v2
	v_mov_b32_e32 v20, v2
	v_mov_b32_e32 v21, v2
	v_mov_b32_e32 v22, v2
	v_mov_b32_e32 v23, v2
	v_mov_b32_e32 v24, v2
	v_mov_b32_e32 v25, v2
	v_mov_b32_e32 v26, v2
	v_mov_b32_e32 v27, v2
	v_mov_b32_e32 v28, v2
	v_mov_b32_e32 v29, v2
	v_mov_b32_e32 v30, v2
	v_mov_b32_e32 v31, v2
	v_mov_b32_e32 v32, v2
	v_mov_b32_e32 v33, v2
	v_mov_b32_e32 v34, v2
	v_mov_b32_e32 v35, v2
	v_mov_b32_e32 v36, v2
	v_mov_b32_e32 v37, v2
	v_mov_b32_e32 v38, v2
	v_mov_b32_e32 v39, v2
	v_mov_b32_e32 v40, v2
	v_mov_b32_e32 v41, v2
	v_mov_b32_e32 v42, v2
	v_mov_b32_e32 v43, v2
	v_mov_b32_e32 v44, v2
	v_mov_b32_e32 v45, v2
	v_mov_b32_e32 v46, v2
	v_mov_b32_e32 v47, v2
	v_mov_b32_e32 v48, v2
	v_mov_b32_e32 v49, v2
	v_mov_b32_e32 v50, v2
	v_mov_b32_e32 v51, v2
	v_mov_b32_e32 v52, v2
	v_mov_b32_e32 v53, v2
	v_mov_b32_e32 v54, v2
	v_mov_b32_e32 v55, v2
	v_mov_b32_e32 v56, v2
	v_mov_b32_e32 v57, v2
	v_mov_b32_e32 v58, v2
	v_mov_b32_e32 v59, v2
	v_mov_b32_e32 v60, v2
	v_mov_b32_e32 v61, v2
	v_mov_b32_e32 v62, v2
	v_mov_b32_e32 v63, v2
	v_mov_b32_e32 v64, v2
	v_mov_b32_e32 v65, v2
	v_mov_b32_e32 v66, v2
	v_mov_b32_e32 v67, v2
	v_mov_b32_e32 v68, v2
	v_mov_b32_e32 v69, v2
	v_mov_b32_e32 v70, v2
	v_mov_b32_e32 v71, v2
	v_mov_b32_e32 v72, v2
	v_mov_b32_e32 v73, v2
	v_mov_b32_e32 v74, v2
	v_mov_b32_e32 v75, v2
	v_mov_b32_e32 v76, v2
	v_mov_b32_e32 v77, v2
	v_mov_b32_e32 v78, v2
	v_mov_b32_e32 v79, v2
	v_mov_b32_e32 v80, v2
	v_mov_b32_e32 v81, v2
	v_mov_b32_e32 v82, v2
	v_mov_b32_e32 v83, v2
	v_mov_b32_e32 v84, v2
	v_mov_b32_e32 v85, v2
	v_mov_b32_e32 v86, v2
	v_mov_b32_e32 v87, v2
	s_waitcnt vmcnt(0)
	v_mov_b32_e32 v88, v2
	v_mov_b32_e32 v89, v2
	v_mov_b32_e32 v90, v2
	v_mov_b32_e32 v91, v2
	v_mov_b32_e32 v92, v2
	v_mov_b32_e32 v93, v2
	v_mov_b32_e32 v94, v2
	v_mov_b32_e32 v95, v2
	v_mov_b32_e32 v96, v2
	v_mov_b32_e32 v97, v2
	v_mov_b32_e32 v98, v2
	v_mov_b32_e32 v99, v2
	v_mov_b32_e32 v100, v2
	v_mov_b32_e32 v101, v2
	v_mov_b32_e32 v102, v2
	v_mov_b32_e32 v103, v2
	v_mov_b32_e32 v104, v2
	v_mov_b32_e32 v105, v2
	v_mov_b32_e32 v106, v2
	v_mov_b32_e32 v107, v2
	v_mov_b32_e32 v108, v2
	v_mov_b32_e32 v109, v2
	v_mov_b32_e32 v110, v2
	v_mov_b32_e32 v111, v2
	v_mov_b32_e32 v112, v2
	v_mov_b32_e32 v113, v2
	v_mov_b32_e32 v114, v2
	v_mov_b32_e32 v115, v2
	v_mov_b32_e32 v116, v2
	v_mov_b32_e32 v117, v2
	v_mov_b32_e32 v118, v2
	v_mov_b32_e32 v119, v2
	v_mov_b32_e32 v120, v2
	v_mov_b32_e32 v121, v2
	v_mov_b32_e32 v122, v2
	v_mov_b32_e32 v123, v2
	v_mov_b32_e32 v124, v2
	v_mov_b32_e32 v125, v2
	v_mov_b32_e32 v126, v2
	v_mov_b32_e32 v127, v2
	v_mov_b32_e32 v128, v2
	v_mov_b32_e32 v129, v2
; #define MFMA(a, b, c) __builtin_amdgcn_mfma_f32_16x16x32_bf16((a), (b), (c), 0, 0, 0)
; template <int EPI, int MF>
; __device__ __forceinline__ void gemm_part(const u16* __restrict__ A, int lda, const u16* __restrict__ Bt, int K, int ntn, GemmEpi ep, char* smem,
;                                           int mbase, int mrows) {
;     ...
;     for (int kt = 0; kt < nk; ++kt) {
;       if (kt + 1 < nk) {
;         if (MF == 8) asm volatile("s_waitcnt vmcnt(6)" ::: "memory");
;         else asm volatile("s_waitcnt vmcnt(3)" ::: "memory");
;       } else asm volatile("s_waitcnt vmcnt(0)" ::: "memory");
;       asm volatile("s_waitcnt lgkmcnt(0)" ::: "memory");
;       __builtin_amdgcn_s_barrier();
;       const u16* a_ = sbase + (kt % 3) * STG;
;       const u16* b_ = a_ + BM * 32;
;       bf16x8 bfr[4], afc[2], afn[2];
;       const u16* ap_ = a_ + (wr * (16 * MF) + fr) * 32 + fq * 8;
; #pragma unroll
;       for (int n = 0; n < 4; ++n) bfr[n] = rd_std(b_ + (wc * 64 + n * 16 + fr) * 32 + fq * 8);
;       afc[0] = rd_std(ap_); afc[1] = rd_std(ap_ + 16 * 32);
;       __builtin_amdgcn_sched_barrier(0);
;       if (kt + 2 < nk) GEMM_ISSUE(kt + 2);
;       __builtin_amdgcn_sched_barrier(0);
; #pragma unroll
;       for (int mh = 0; mh < MF / 2; ++mh) {
;         if (mh + 1 < MF / 2) {
;           afn[0] = rd_std(ap_ + ((mh + 1) * 2) * 16 * 32);
;           afn[1] = rd_std(ap_ + ((mh + 1) * 2 + 1) * 16 * 32);
;         }
;         __builtin_amdgcn_sched_barrier(0);
; #pragma unroll
;         for (int m = 0; m < 2; ++m)
; #pragma unroll
;           for (int n = 0; n < 4; ++n) acc[mh * 2 + m][n] = MFMA(bfr[n], afc[m], acc[mh * 2 + m][n]);
;         __builtin_amdgcn_sched_barrier(0);
;         afc[0] = afn[0]; afc[1] = afn[1];
;       }
;     }
.LBB0_1202:
	s_mul_i32 s12, s5, 0xab
	s_add_i32 s13, s12, 0xfeaa
	s_bfe_u32 s13, s13, 0x70009
	s_mul_i32 s13, s13, 3
	s_sub_i32 s13, s5, s13
	s_add_i32 s13, s13, 0xfffe
	s_and_b32 s13, s13, 0xff
	s_mulk_i32 s13, 0x6000
	s_add_i32 s13, s13, 0
	v_lshl_add_u32 v175, v196, 1, s13
	s_waitcnt vmcnt(6)
	v_add_u32_e32 v192, s13, v212
	s_waitcnt lgkmcnt(0)
	s_barrier
	ds_read_b128 v[180:183], v192 offset:16384
	ds_read_b128 v[184:187], v192 offset:17408
	ds_read_b128 v[188:191], v192 offset:18432
	ds_read_b128 v[230:233], v192 offset:19456
	v_add_u32_e32 v175, s13, v210
	ds_read_b128 v[234:237], v175
	ds_read_b128 v[238:241], v175 offset:1024
	s_bfe_u32 s12, s12, 0x70009
	s_mul_i32 s12, s12, 3
	s_sub_i32 s12, s5, s12
	s_and_b32 s12, s12, 0xff
	s_mulk_i32 s12, 0x6000
	v_add_u32_e32 v229, s12, v194
	v_lshl_add_u64 v[192:193], s[2:3], 1, v[178:179]
	v_readfirstlane_b32 s12, v229
	v_add_u32_e32 v244, 0x1000, v229
	v_lshl_add_u64 v[242:243], v[192:193], 0, s[74:75]
	s_mov_b32 m0, s12
	v_readfirstlane_b32 s12, v244
	v_add_u32_e32 v244, 0x2000, v229
	global_load_lds_dwordx4 v[242:243], off
	v_lshl_add_u64 v[242:243], v[192:193], 0, s[92:93]
	s_mov_b32 m0, s12
	v_readfirstlane_b32 s12, v244
	global_load_lds_dwordx4 v[242:243], off
	v_lshl_add_u64 v[242:243], v[192:193], 0, s[88:89]
	s_mov_b32 m0, s12
	v_lshl_add_u64 v[192:193], v[192:193], 0, s[6:7]
	global_load_lds_dwordx4 v[242:243], off
	v_add_u32_e32 v242, 0x3000, v229
	v_add_u32_e32 v244, 0x4000, v229
	v_readfirstlane_b32 s12, v242
	s_mov_b32 m0, s12
	v_readfirstlane_b32 s12, v244
	global_load_lds_dwordx4 v[192:193], off
	v_lshl_add_u64 v[192:193], s[2:3], 1, v[176:177]
	v_add_u32_e32 v229, 0x5000, v229
	v_lshl_add_u64 v[242:243], v[192:193], 0, s[74:75]
	s_mov_b32 m0, s12
	v_readfirstlane_b32 s12, v229
	global_load_lds_dwordx4 v[242:243], off
	v_lshl_add_u64 v[192:193], v[192:193], 0, s[92:93]
	s_mov_b32 m0, s12
	s_nop 0
	global_load_lds_dwordx4 v[192:193], off
	ds_read_b128 v[242:245], v175 offset:3072
	ds_read_b128 v[246:249], v175 offset:2048
	s_waitcnt lgkmcnt(2)
	v_mfma_f32_16x16x32_bf16 v[126:129], v[180:183], v[234:237], v[126:129]
	v_mfma_f32_16x16x32_bf16 v[122:125], v[184:187], v[234:237], v[122:125]
	v_mfma_f32_16x16x32_bf16 v[118:121], v[188:191], v[234:237], v[118:121]
	v_mfma_f32_16x16x32_bf16 v[114:117], v[230:233], v[234:237], v[114:117]
	v_mfma_f32_16x16x32_bf16 v[110:113], v[180:183], v[238:241], v[110:113]
	v_mfma_f32_16x16x32_bf16 v[106:109], v[184:187], v[238:241], v[106:109]
	v_mfma_f32_16x16x32_bf16 v[102:105], v[188:191], v[238:241], v[102:105]
	v_mfma_f32_16x16x32_bf16 v[98:101], v[230:233], v[238:241], v[98:101]
	ds_read_b128 v[234:237], v175 offset:5120
	ds_read_b128 v[238:241], v175 offset:4096
	s_waitcnt lgkmcnt(2)
	v_mfma_f32_16x16x32_bf16 v[94:97], v[180:183], v[246:249], v[94:97]
	v_mfma_f32_16x16x32_bf16 v[90:93], v[184:187], v[246:249], v[90:93]
	v_mfma_f32_16x16x32_bf16 v[86:89], v[188:191], v[246:249], v[86:89]
	v_mfma_f32_16x16x32_bf16 v[82:85], v[230:233], v[246:249], v[82:85]
	v_mfma_f32_16x16x32_bf16 v[78:81], v[180:183], v[242:245], v[78:81]
	v_mfma_f32_16x16x32_bf16 v[74:77], v[184:187], v[242:245], v[74:77]
	v_mfma_f32_16x16x32_bf16 v[70:73], v[188:191], v[242:245], v[70:73]
	v_mfma_f32_16x16x32_bf16 v[66:69], v[230:233], v[242:245], v[66:69]
	ds_read_b128 v[242:245], v175 offset:7168
	ds_read_b128 v[246:249], v175 offset:6144
	s_waitcnt lgkmcnt(2)
	v_mfma_f32_16x16x32_bf16 v[62:65], v[180:183], v[238:241], v[62:65]
	v_mfma_f32_16x16x32_bf16 v[58:61], v[184:187], v[238:241], v[58:61]
	v_mfma_f32_16x16x32_bf16 v[54:57], v[188:191], v[238:241], v[54:57]
	v_mfma_f32_16x16x32_bf16 v[50:53], v[230:233], v[238:241], v[50:53]
	v_mfma_f32_16x16x32_bf16 v[46:49], v[180:183], v[234:237], v[46:49]
	v_mfma_f32_16x16x32_bf16 v[42:45], v[184:187], v[234:237], v[42:45]
	v_mfma_f32_16x16x32_bf16 v[38:41], v[188:191], v[234:237], v[38:41]
	v_mfma_f32_16x16x32_bf16 v[34:37], v[230:233], v[234:237], v[34:37]
	s_waitcnt lgkmcnt(0)
	v_mfma_f32_16x16x32_bf16 v[30:33], v[180:183], v[246:249], v[30:33]
	v_mfma_f32_16x16x32_bf16 v[26:29], v[184:187], v[246:249], v[26:29]
	v_mfma_f32_16x16x32_bf16 v[22:25], v[188:191], v[246:249], v[22:25]
	v_mfma_f32_16x16x32_bf16 v[18:21], v[230:233], v[246:249], v[18:21]
	v_mfma_f32_16x16x32_bf16 v[14:17], v[180:183], v[242:245], v[14:17]
	v_mfma_f32_16x16x32_bf16 v[10:13], v[184:187], v[242:245], v[10:13]
	v_mfma_f32_16x16x32_bf16 v[6:9], v[188:191], v[242:245], v[6:9]
	v_mfma_f32_16x16x32_bf16 v[2:5], v[230:233], v[242:245], v[2:5]
	s_add_u32 s2, s2, 64
	s_addc_u32 s3, s3, 0
	s_add_i32 s5, s5, 1
	s_cmpk_eq_i32 s2, 0x780
	s_cbranch_scc0 .LBB0_1202
	s_waitcnt vmcnt(6)
	s_waitcnt lgkmcnt(0)
	s_barrier
; #define MFMA(a, b, c) __builtin_amdgcn_mfma_f32_16x16x32_bf16((a), (b), (c), 0, 0, 0)
; template <int EPI, int MF>
; __device__ __forceinline__ void gemm_part(const u16* __restrict__ A, int lda, const u16* __restrict__ Bt, int K, int ntn, GemmEpi ep, char* smem,
;                                           int mbase, int mrows) {
;     ...
;     for (int kt = 0; kt < nk; ++kt) {
;       if (kt + 1 < nk) {
;         if (MF == 8) asm volatile("s_waitcnt vmcnt(6)" ::: "memory");
;         else asm volatile("s_waitcnt vmcnt(3)" ::: "memory");
;       } else asm volatile("s_waitcnt vmcnt(0)" ::: "memory");
;       asm volatile("s_waitcnt lgkmcnt(0)" ::: "memory");
;       __builtin_amdgcn_s_barrier();
;       const u16* a_ = sbase + (kt % 3) * STG;
;       const u16* b_ = a_ + BM * 32;
;       bf16x8 bfr[4], afc[2], afn[2];
;       const u16* ap_ = a_ + (wr * (16 * MF) + fr) * 32 + fq * 8;
; #pragma unroll
;       for (int n = 0; n < 4; ++n) bfr[n] = rd_std(b_ + (wc * 64 + n * 16 + fr) * 32 + fq * 8);
;       afc[0] = rd_std(ap_); afc[1] = rd_std(ap_ + 16 * 32);
;       __builtin_amdgcn_sched_barrier(0);
;       if (kt + 2 < nk) GEMM_ISSUE(kt + 2);
;       __builtin_amdgcn_sched_barrier(0);
; #pragma unroll
;       for (int mh = 0; mh < MF / 2; ++mh) {
;         if (mh + 1 < MF / 2) {
;           afn[0] = rd_std(ap_ + ((mh + 1) * 2) * 16 * 32);
;           afn[1] = rd_std(ap_ + ((mh + 1) * 2 + 1) * 16 * 32);
;         }
;         __builtin_amdgcn_sched_barrier(0);
; #pragma unroll
;         for (int m = 0; m < 2; ++m)
; #pragma unroll
;           for (int n = 0; n < 4; ++n) acc[mh * 2 + m][n] = MFMA(bfr[n], afc[m], acc[mh * 2 + m][n]);
;         __builtin_amdgcn_sched_barrier(0);
;         afc[0] = afn[0]; afc[1] = afn[1];
;       }
;     }
;     ...
;     __syncthreads();
; #pragma unroll
;     for (int m = 0; m < MF; ++m) {
;       if (EPI == EPI_SWIGLU || (m & 1) == 0) __builtin_amdgcn_sched_barrier(0);
;       const int row = row0 + wr * (16 * MF) + m * 16 + fr;
;       const int cb = col0 + wc * 64 + 4 * fq;
;       float rstd = 1.f;
;       if (EPI != EPI_RESID) { if (ep.rss_in) rstd = rsqrtf(ep.rss_in[row] * (1.f / DM) + 1e-6f); }
	ds_read_b128 v[176:179], v212 offset:16384
	ds_read_b128 v[180:183], v212 offset:17408
	ds_read_b128 v[184:187], v212 offset:18432
	ds_read_b128 v[188:191], v212 offset:19456
	ds_read_b128 v[230:233], v210
	ds_read_b128 v[234:237], v210 offset:1024
	ds_read_b128 v[238:241], v210 offset:3072
	ds_read_b128 v[242:245], v210 offset:2048
	s_waitcnt lgkmcnt(0)
	v_mfma_f32_16x16x32_bf16 v[126:129], v[176:179], v[230:233], v[126:129]
	v_mfma_f32_16x16x32_bf16 v[122:125], v[180:183], v[230:233], v[122:125]
	v_mfma_f32_16x16x32_bf16 v[118:121], v[184:187], v[230:233], v[118:121]
	v_mfma_f32_16x16x32_bf16 v[114:117], v[188:191], v[230:233], v[114:117]
	v_mfma_f32_16x16x32_bf16 v[110:113], v[176:179], v[234:237], v[110:113]
	v_mfma_f32_16x16x32_bf16 v[106:109], v[180:183], v[234:237], v[106:109]
	v_mfma_f32_16x16x32_bf16 v[102:105], v[184:187], v[234:237], v[102:105]
	v_mfma_f32_16x16x32_bf16 v[98:101], v[188:191], v[234:237], v[98:101]
	ds_read_b128 v[230:233], v210 offset:5120
	ds_read_b128 v[234:237], v210 offset:4096
	v_mfma_f32_16x16x32_bf16 v[94:97], v[176:179], v[242:245], v[94:97]
	v_mfma_f32_16x16x32_bf16 v[90:93], v[180:183], v[242:245], v[90:93]
	v_mfma_f32_16x16x32_bf16 v[86:89], v[184:187], v[242:245], v[86:89]
	v_mfma_f32_16x16x32_bf16 v[82:85], v[188:191], v[242:245], v[82:85]
	v_mfma_f32_16x16x32_bf16 v[78:81], v[176:179], v[238:241], v[78:81]
	v_mfma_f32_16x16x32_bf16 v[74:77], v[180:183], v[238:241], v[74:77]
	v_mfma_f32_16x16x32_bf16 v[70:73], v[184:187], v[238:241], v[70:73]
	v_mfma_f32_16x16x32_bf16 v[66:69], v[188:191], v[238:241], v[66:69]
	ds_read_b128 v[238:241], v210 offset:7168
	ds_read_b128 v[242:245], v210 offset:6144
	s_waitcnt lgkmcnt(0)
	v_mfma_f32_16x16x32_bf16 v[62:65], v[176:179], v[234:237], v[62:65]
	v_mfma_f32_16x16x32_bf16 v[58:61], v[180:183], v[234:237], v[58:61]
	v_mfma_f32_16x16x32_bf16 v[54:57], v[184:187], v[234:237], v[54:57]
	v_mfma_f32_16x16x32_bf16 v[50:53], v[188:191], v[234:237], v[50:53]
	v_mfma_f32_16x16x32_bf16 v[46:49], v[176:179], v[230:233], v[46:49]
	v_mfma_f32_16x16x32_bf16 v[42:45], v[180:183], v[230:233], v[42:45]
	v_mfma_f32_16x16x32_bf16 v[38:41], v[184:187], v[230:233], v[38:41]
	v_mfma_f32_16x16x32_bf16 v[34:37], v[188:191], v[230:233], v[34:37]
	v_mfma_f32_16x16x32_bf16 v[30:33], v[176:179], v[242:245], v[30:33]
	v_mfma_f32_16x16x32_bf16 v[26:29], v[180:183], v[242:245], v[26:29]
	v_mfma_f32_16x16x32_bf16 v[22:25], v[184:187], v[242:245], v[22:25]
	v_mfma_f32_16x16x32_bf16 v[18:21], v[188:191], v[242:245], v[18:21]
	v_mfma_f32_16x16x32_bf16 v[14:17], v[176:179], v[238:241], v[14:17]
	v_mfma_f32_16x16x32_bf16 v[10:13], v[180:183], v[238:241], v[10:13]
	v_mfma_f32_16x16x32_bf16 v[6:9], v[184:187], v[238:241], v[6:9]
	v_mfma_f32_16x16x32_bf16 v[2:5], v[188:191], v[238:241], v[2:5]
	s_waitcnt vmcnt(0)
	s_waitcnt lgkmcnt(0)
	s_barrier
	ds_read_b128 v[176:179], v212 offset:40960
	ds_read_b128 v[180:183], v212 offset:41984
	ds_read_b128 v[184:187], v212 offset:43008
	ds_read_b128 v[188:191], v212 offset:44032
	ds_read_b128 v[230:233], v210 offset:24576
	ds_read_b128 v[234:237], v210 offset:25600
	ds_read_b128 v[238:241], v210 offset:27648
	ds_read_b128 v[242:245], v210 offset:26624
	s_waitcnt lgkmcnt(0)
	v_mfma_f32_16x16x32_bf16 v[126:129], v[176:179], v[230:233], v[126:129]
	v_mfma_f32_16x16x32_bf16 v[122:125], v[180:183], v[230:233], v[122:125]
	v_mfma_f32_16x16x32_bf16 v[118:121], v[184:187], v[230:233], v[118:121]
	v_mfma_f32_16x16x32_bf16 v[114:117], v[188:191], v[230:233], v[114:117]
	v_mfma_f32_16x16x32_bf16 v[110:113], v[176:179], v[234:237], v[110:113]
	v_mfma_f32_16x16x32_bf16 v[106:109], v[180:183], v[234:237], v[106:109]
	v_mfma_f32_16x16x32_bf16 v[102:105], v[184:187], v[234:237], v[102:105]
	v_mfma_f32_16x16x32_bf16 v[98:101], v[188:191], v[234:237], v[98:101]
	ds_read_b128 v[230:233], v210 offset:29696
	ds_read_b128 v[234:237], v210 offset:28672
	v_mfma_f32_16x16x32_bf16 v[94:97], v[176:179], v[242:245], v[94:97]
	v_mfma_f32_16x16x32_bf16 v[90:93], v[180:183], v[242:245], v[90:93]
	v_mfma_f32_16x16x32_bf16 v[86:89], v[184:187], v[242:245], v[86:89]
	v_mfma_f32_16x16x32_bf16 v[82:85], v[188:191], v[242:245], v[82:85]
	v_mfma_f32_16x16x32_bf16 v[78:81], v[176:179], v[238:241], v[78:81]
	v_mfma_f32_16x16x32_bf16 v[74:77], v[180:183], v[238:241], v[74:77]
	v_mfma_f32_16x16x32_bf16 v[70:73], v[184:187], v[238:241], v[70:73]
	v_mfma_f32_16x16x32_bf16 v[66:69], v[188:191], v[238:241], v[66:69]
	ds_read_b128 v[238:241], v210 offset:31744
	ds_read_b128 v[242:245], v210 offset:30720
	s_waitcnt lgkmcnt(0)
	v_mfma_f32_16x16x32_bf16 v[62:65], v[176:179], v[234:237], v[62:65]
	v_mfma_f32_16x16x32_bf16 v[58:61], v[180:183], v[234:237], v[58:61]
	v_mfma_f32_16x16x32_bf16 v[54:57], v[184:187], v[234:237], v[54:57]
	v_mfma_f32_16x16x32_bf16 v[50:53], v[188:191], v[234:237], v[50:53]
	v_mfma_f32_16x16x32_bf16 v[46:49], v[176:179], v[230:233], v[46:49]
	v_mfma_f32_16x16x32_bf16 v[42:45], v[180:183], v[230:233], v[42:45]
	v_mfma_f32_16x16x32_bf16 v[38:41], v[184:187], v[230:233], v[38:41]
	v_mfma_f32_16x16x32_bf16 v[34:37], v[188:191], v[230:233], v[34:37]
	v_mfma_f32_16x16x32_bf16 v[30:33], v[176:179], v[242:245], v[30:33]
	v_mfma_f32_16x16x32_bf16 v[26:29], v[180:183], v[242:245], v[26:29]
	v_mfma_f32_16x16x32_bf16 v[22:25], v[184:187], v[242:245], v[22:25]
	v_mfma_f32_16x16x32_bf16 v[18:21], v[188:191], v[242:245], v[18:21]
	v_mfma_f32_16x16x32_bf16 v[14:17], v[176:179], v[238:241], v[14:17]
	v_mfma_f32_16x16x32_bf16 v[10:13], v[180:183], v[238:241], v[10:13]
	v_mfma_f32_16x16x32_bf16 v[6:9], v[184:187], v[238:241], v[6:9]
	v_mfma_f32_16x16x32_bf16 v[2:5], v[188:191], v[238:241], v[2:5]
	v_add_u32_e32 v178, s9, v197
	s_waitcnt vmcnt(0)
	s_barrier
	v_readlane_b32 s2, v253, 30
	v_ashrrev_i32_e32 v179, 31, v178
	v_readlane_b32 s3, v253, 31
	s_and_b64 vcc, exec, s[2:3]
	v_lshl_add_u64 v[180:181], v[178:179], 2, s[66:67]
	s_cbranch_vccz .LBB0_1205
	global_load_dword v175, v[180:181], off
	s_waitcnt vmcnt(0)
	v_fmamk_f32 v175, v175, 0x3a800000, v142
	v_mul_f32_e32 v176, 0x4b800000, v175
	v_cmp_gt_f32_e32 vcc, s69, v175
	s_nop 1
	v_cndmask_b32_e32 v175, v175, v176, vcc
	v_rsq_f32_e32 v175, v175
	s_nop 0
	v_mul_f32_e32 v176, 0x45800000, v175
	v_cndmask_b32_e32 v182, v175, v176, vcc
	s_branch .LBB0_1206

; template <int EPI, int MF>
; __device__ __forceinline__ void gemm_part(const u16* __restrict__ A, int lda, const u16* __restrict__ Bt, int K, int ntn, GemmEpi ep, char* smem,
;                                           int mbase, int mrows) {
;     ...
;   for (int q = xcd; q * nbx < total; q += (MF == 2) ? 1 : 8) {
;     const int L = q * nbx + li;
;     if (L >= total) continue;
;     const int g = L / (8 * ntn), rr = L % (8 * ntn);
;     const int rows = min(8, ntm - 8 * g);
;     const int tm = 8 * g + rr % rows, tn = rr / rows;
;     const int row0 = mbase + tm * BM, col0 = tn * 128;
;     f32x4 acc[MF][4];
; #pragma unroll
;     for (int m = 0; m < MF; ++m)
; #pragma unroll
;       for (int n = 0; n < 4; ++n) acc[m][n] = (f32x4){0.f, 0.f, 0.f, 0.f};
;     const u16* gA = A + (size_t)(row0 + (tid >> 2)) * lda + (tid & 3) * 8;
;     const u16* gB = Bt + (size_t)(col0 + (tid >> 2)) * K + (tid & 3) * 8;
;     ...
;     GEMM_ISSUE(0);
;     GEMM_ISSUE(1);
.LBB0_1456:
	s_add_i32 s2, s2, s64
	s_cmpk_gt_i32 s2, 0xdf
	s_cbranch_scc1 .LBB0_1455
	s_mul_hi_i32 s3, s2, 0x92492493
	s_add_i32 s3, s3, s2
	s_lshr_b32 s4, s3, 31
	s_ashr_i32 s3, s3, 7
	s_add_i32 s3, s3, s4
	s_mul_i32 s4, s3, 0xe0
	s_sub_i32 s2, s2, s4
	s_sext_i32_i16 s4, s2
	s_bfe_u32 s4, s4, 0x3001c
	s_add_i32 s4, s2, s4
	s_sext_i32_i16 s5, s4
	s_and_b32 s4, s4, 0xfff8
	s_sub_i32 s2, s2, s4
	s_sext_i32_i16 s2, s2
	s_lshl_b32 s3, s3, 9
	s_lshl_b32 s2, s2, 6
	s_ashr_i32 s4, s5, 3
	s_add_i32 s9, s3, s2
	s_lshl_b32 s5, s4, 7
	s_add_i32 s9, s9, 0x10000
	v_add_u32_e32 v6, s5, v1
	v_add_u32_e32 v2, s9, v1
	v_ashrrev_i32_e32 v7, 31, v6
	v_ashrrev_i32_e32 v3, 31, v2
	v_lshlrev_b64 v[6:7], 11, v[6:7]
	v_lshlrev_b64 v[2:3], 11, v[2:3]
	v_lshl_add_u64 v[40:41], v[36:37], 0, v[6:7]
	v_lshlrev_b32_e32 v255, 1, v40
	v_bfi_b32 v255, s100, v255, v40
	v_lshrrev_b32_e32 v40, 5, v40
	v_bfi_b32 v40, 64, v40, v255
	v_readfirstlane_b32 s2, v58
	v_add_u32_e32 v6, 0x1000, v58
	v_lshl_add_u64 v[4:5], v[34:35], 0, v[2:3]
	v_lshlrev_b32_e32 v255, 1, v4
	v_bfi_b32 v255, s100, v255, v4
	v_lshrrev_b32_e32 v4, 5, v4
	v_bfi_b32 v4, 64, v4, v255
	s_mov_b32 m0, s2
	v_readfirstlane_b32 s2, v6
	global_load_lds_dwordx4 v[4:5], off
	s_mov_b32 m0, s2
	s_mov_b64 s[2:3], 0x20000
	v_add_u32_e32 v8, 0x2000, v58
	v_lshl_add_u64 v[6:7], v[40:41], 0, s[2:3]
	v_readfirstlane_b32 s2, v8
	global_load_lds_dwordx4 v[40:41], off
	s_mov_b32 m0, s2
	v_lshl_add_u64 v[4:5], v[4:5], 0, 64
	v_lshl_add_u64 v[4:5], v[4:5], 0, 64
	global_load_lds_dwordx4 v[6:7], off
	v_add_u32_e32 v6, 0x3000, v58
	v_lshl_add_u64 v[42:43], v[38:39], 0, v[2:3]
	v_lshlrev_b32_e32 v255, 1, v42
	v_bfi_b32 v255, s100, v255, v42
	v_lshrrev_b32_e32 v42, 5, v42
	v_bfi_b32 v42, 64, v42, v255
	v_lshl_add_u64 v[42:43], v[42:43], 0, 64
	v_lshl_add_u64 v[42:43], v[42:43], 0, 64
	v_readfirstlane_b32 s2, v6
	v_add_u32_e32 v6, 0x4000, v58
	s_mov_b32 m0, s2
	v_readfirstlane_b32 s2, v6
	global_load_lds_dwordx4 v[4:5], off
	v_lshl_add_u64 v[4:5], v[40:41], 0, 64
	v_lshl_add_u64 v[4:5], v[4:5], 0, 64
	s_mov_b32 m0, s2
	s_mov_b64 s[2:3], 0x20080
	v_add_u32_e32 v6, 0x5000, v58
	global_load_lds_dwordx4 v[4:5], off
	v_lshl_add_u64 v[4:5], v[40:41], 0, s[2:3]
	v_readfirstlane_b32 s2, v6
	s_mov_b32 m0, s2
	v_mov_b32_e32 v2, 0
	global_load_lds_dwordx4 v[4:5], off
	v_lshl_add_u64 v[40:41], v[40:41], 0, 64
	v_lshl_add_u64 v[40:41], v[40:41], 0, 64
	s_mov_b32 s10, 3
	s_mov_b64 s[2:3], 0
	v_mov_b32_e32 v3, v2
	v_mov_b32_e32 v4, v2
	v_mov_b32_e32 v5, v2
	v_mov_b32_e32 v6, v2
	v_mov_b32_e32 v7, v2
	v_mov_b32_e32 v8, v2
	v_mov_b32_e32 v9, v2
	v_mov_b32_e32 v10, v2
	v_mov_b32_e32 v11, v2
	v_mov_b32_e32 v12, v2
	v_mov_b32_e32 v13, v2
	v_mov_b32_e32 v14, v2
	v_mov_b32_e32 v15, v2
	v_mov_b32_e32 v16, v2
	v_mov_b32_e32 v17, v2
	v_mov_b32_e32 v18, v2
	v_mov_b32_e32 v19, v2
	v_mov_b32_e32 v20, v2
	v_mov_b32_e32 v21, v2
	v_mov_b32_e32 v22, v2
	v_mov_b32_e32 v23, v2
	v_mov_b32_e32 v24, v2
	v_mov_b32_e32 v25, v2
	v_mov_b32_e32 v26, v2
	v_mov_b32_e32 v27, v2
	v_mov_b32_e32 v28, v2
	v_mov_b32_e32 v29, v2
	v_mov_b32_e32 v30, v2
	v_mov_b32_e32 v31, v2
	v_mov_b32_e32 v32, v2
	v_mov_b32_e32 v33, v2
; #define MFMA(a, b, c) __builtin_amdgcn_mfma_f32_16x16x32_bf16((a), (b), (c), 0, 0, 0)
; template <int EPI, int MF>
; __device__ __forceinline__ void gemm_part(const u16* __restrict__ A, int lda, const u16* __restrict__ Bt, int K, int ntn, GemmEpi ep, char* smem,
;                                           int mbase, int mrows) {
;     ...
;     for (int kt = 0; kt < nk; ++kt) {
;       if (kt + 1 < nk) {
;         if (MF == 8) asm volatile("s_waitcnt vmcnt(6)" ::: "memory");
;         else asm volatile("s_waitcnt vmcnt(3)" ::: "memory");
;       } else asm volatile("s_waitcnt vmcnt(0)" ::: "memory");
;       asm volatile("s_waitcnt lgkmcnt(0)" ::: "memory");
;       __builtin_amdgcn_s_barrier();
;       const u16* a_ = sbase + (kt % 3) * STG;
;       const u16* b_ = a_ + BM * 32;
;       bf16x8 bfr[4], afc[2], afn[2];
;       const u16* ap_ = a_ + (wr * (16 * MF) + fr) * 32 + fq * 8;
; #pragma unroll
;       for (int n = 0; n < 4; ++n) bfr[n] = rd_std(b_ + (wc * 64 + n * 16 + fr) * 32 + fq * 8);
;       afc[0] = rd_std(ap_); afc[1] = rd_std(ap_ + 16 * 32);
;       __builtin_amdgcn_sched_barrier(0);
;       if (kt + 2 < nk) GEMM_ISSUE(kt + 2);
;       __builtin_amdgcn_sched_barrier(0);
; #pragma unroll
;       for (int mh = 0; mh < MF / 2; ++mh) {
;         if (mh + 1 < MF / 2) {
;           afn[0] = rd_std(ap_ + ((mh + 1) * 2) * 16 * 32);
;           afn[1] = rd_std(ap_ + ((mh + 1) * 2 + 1) * 16 * 32);
;         }
;         __builtin_amdgcn_sched_barrier(0);
; #pragma unroll
;         for (int m = 0; m < 2; ++m)
; #pragma unroll
;           for (int n = 0; n < 4; ++n) acc[mh * 2 + m][n] = MFMA(bfr[n], afc[m], acc[mh * 2 + m][n]);
;         __builtin_amdgcn_sched_barrier(0);
;         afc[0] = afn[0]; afc[1] = afn[1];
;       }
;     }
;     ...
;     __syncthreads();
; #pragma unroll
;     for (int m = 0; m < MF; ++m) {
;       if (EPI == EPI_SWIGLU || (m & 1) == 0) __builtin_amdgcn_sched_barrier(0);
;       const int row = row0 + wr * (16 * MF) + m * 16 + fr;
;       const int cb = col0 + wc * 64 + 4 * fq;
;       float rstd = 1.f;
;       if (EPI != EPI_RESID) { if (ep.rss_in) rstd = rsqrtf(ep.rss_in[row] * (1.f / DM) + 1e-6f); }
.LBB0_1458:
	s_add_i32 s11, s10, 0xfffd
	s_and_b32 s12, s11, 0xff
	s_mulk_i32 s12, 0xab
	s_bfe_u32 s12, s12, 0x70009
	s_mul_i32 s12, s12, 3
	s_sub_i32 s12, s11, s12
	s_and_b32 s12, s12, 0xff
	s_mulk_i32 s12, 0x3000
	s_add_i32 s12, s12, 0
	v_add_u32_e32 v44, s12, v65
	s_waitcnt vmcnt(3)
	v_add3_u32 v57, v44, v63, v60
	s_waitcnt lgkmcnt(0)
	s_barrier
	v_add_u32_e32 v56, s12, v59
	ds_read_b128 v[44:47], v57 offset:4096
	ds_read_b128 v[48:51], v57 offset:5120
	ds_read_b128 v[52:55], v57 offset:6144
	ds_read_b128 v[68:71], v57 offset:7168
	v_add3_u32 v56, v56, v60, v65
	ds_read_b128 v[72:75], v56
	ds_read_b128 v[76:79], v56 offset:1024
	s_mul_i32 s12, s10, 0xab
	s_add_i32 s13, s12, 0xff55
	s_bfe_u32 s13, s13, 0x70009
	s_mul_i32 s13, s13, 3
	s_not_b32 s13, s13
	s_add_i32 s13, s13, s10
	s_and_b32 s13, s13, 0xff
	s_mulk_i32 s13, 0x3000
	v_add_u32_e32 v84, s13, v58
	v_lshl_add_u64 v[56:57], s[2:3], 1, v[42:43]
	v_readfirstlane_b32 s13, v84
	v_lshl_add_u64 v[80:81], v[56:57], 0, s[74:75]
	s_mov_b32 m0, s13
	v_add_u32_e32 v85, 0x1000, v84
	global_load_lds_dwordx4 v[80:81], off
	v_lshl_add_u64 v[80:81], s[2:3], 1, v[40:41]
	v_readfirstlane_b32 s13, v85
	v_add_u32_e32 v84, 0x2000, v84
	v_lshl_add_u64 v[82:83], v[80:81], 0, s[74:75]
	s_mov_b32 m0, s13
	v_readfirstlane_b32 s13, v84
	global_load_lds_dwordx4 v[82:83], off
	v_lshl_add_u64 v[82:83], v[80:81], 0, s[92:93]
	s_mov_b32 m0, s13
	s_nop 0
	global_load_lds_dwordx4 v[82:83], off
	s_waitcnt lgkmcnt(0)
	v_mfma_f32_16x16x32_bf16 v[30:33], v[44:47], v[72:75], v[30:33]
	v_mfma_f32_16x16x32_bf16 v[26:29], v[48:51], v[72:75], v[26:29]
	v_mfma_f32_16x16x32_bf16 v[22:25], v[52:55], v[72:75], v[22:25]
	v_mfma_f32_16x16x32_bf16 v[18:21], v[68:71], v[72:75], v[18:21]
	v_mfma_f32_16x16x32_bf16 v[14:17], v[44:47], v[76:79], v[14:17]
	v_mfma_f32_16x16x32_bf16 v[10:13], v[48:51], v[76:79], v[10:13]
	v_mfma_f32_16x16x32_bf16 v[6:9], v[52:55], v[76:79], v[6:9]
	v_mfma_f32_16x16x32_bf16 v[2:5], v[68:71], v[76:79], v[2:5]
	s_or_b32 s11, s11, 1
	s_and_b32 s13, s11, 0xff
	s_mulk_i32 s13, 0xab
	s_bfe_u32 s13, s13, 0x70009
	s_mul_i32 s13, s13, 3
	s_sub_i32 s11, s11, s13
	s_and_b32 s11, s11, 0xff
	s_mulk_i32 s11, 0x3000
	s_add_i32 s11, s11, 0
	v_add_u32_e32 v44, s11, v65
	s_waitcnt vmcnt(3)
	v_add3_u32 v68, v44, v63, v60
	s_waitcnt lgkmcnt(0)
	s_barrier
	v_add_u32_e32 v72, s11, v59
	ds_read_b128 v[44:47], v68 offset:4096
	ds_read_b128 v[48:51], v68 offset:5120
	ds_read_b128 v[52:55], v68 offset:6144
	ds_read_b128 v[68:71], v68 offset:7168
	v_add3_u32 v76, v72, v60, v65
	ds_read_b128 v[72:75], v76
	ds_read_b128 v[76:79], v76 offset:1024
	s_bfe_u32 s11, s12, 0x70009
	s_mul_i32 s11, s11, 3
	s_sub_i32 s11, s10, s11
	s_and_b32 s11, s11, 0xff
	s_mulk_i32 s11, 0x3000
	v_add_u32_e32 v82, s11, v58
	v_add_u32_e32 v83, 0x1000, v82
	v_readfirstlane_b32 s11, v82
	v_lshl_add_u64 v[56:57], v[56:57], 0, s[52:53]
	v_lshl_add_u64 v[56:57], v[56:57], 0, 64
	s_mov_b32 m0, s11
	v_readfirstlane_b32 s11, v83
	global_load_lds_dwordx4 v[56:57], off
	v_lshl_add_u64 v[56:57], v[80:81], 0, s[52:53]
	v_lshl_add_u64 v[56:57], v[56:57], 0, 64
	s_mov_b32 m0, s11
	s_nop 0
	global_load_lds_dwordx4 v[56:57], off
	v_lshl_add_u64 v[56:57], v[80:81], 0, s[54:55]
	v_lshl_add_u64 v[56:57], v[56:57], 0, 64
	v_add_u32_e32 v80, 0x2000, v82
	s_nop 0
	v_readfirstlane_b32 s11, v80
	s_mov_b32 m0, s11
	s_nop 0
	global_load_lds_dwordx4 v[56:57], off
	s_waitcnt lgkmcnt(0)
	v_mfma_f32_16x16x32_bf16 v[30:33], v[44:47], v[72:75], v[30:33]
	v_mfma_f32_16x16x32_bf16 v[26:29], v[48:51], v[72:75], v[26:29]
	v_mfma_f32_16x16x32_bf16 v[22:25], v[52:55], v[72:75], v[22:25]
	v_mfma_f32_16x16x32_bf16 v[18:21], v[68:71], v[72:75], v[18:21]
	v_mfma_f32_16x16x32_bf16 v[14:17], v[44:47], v[76:79], v[14:17]
	v_mfma_f32_16x16x32_bf16 v[10:13], v[48:51], v[76:79], v[10:13]
	v_mfma_f32_16x16x32_bf16 v[6:9], v[52:55], v[76:79], v[6:9]
	v_mfma_f32_16x16x32_bf16 v[2:5], v[68:71], v[76:79], v[2:5]
	s_add_u32 s2, s2, 0x80
	s_addc_u32 s3, s3, 0
	s_add_i32 s10, s10, 2
	s_cmpk_eq_i32 s2, 0x780
	s_cbranch_scc0 .LBB0_1458
	s_waitcnt vmcnt(3)
	s_waitcnt lgkmcnt(0)
	s_barrier
	ds_read_b128 v[40:43], v66 offset:4096
	ds_read_b128 v[44:47], v66 offset:5120
	ds_read_b128 v[48:51], v66 offset:6144
	ds_read_b128 v[52:55], v66 offset:7168
	ds_read_b128 v[68:71], v64
	ds_read_b128 v[72:75], v64 offset:1024
	s_waitcnt lgkmcnt(0)
	v_mfma_f32_16x16x32_bf16 v[30:33], v[40:43], v[68:71], v[30:33]
	v_mfma_f32_16x16x32_bf16 v[26:29], v[44:47], v[68:71], v[26:29]
	v_mfma_f32_16x16x32_bf16 v[22:25], v[48:51], v[68:71], v[22:25]
	v_mfma_f32_16x16x32_bf16 v[18:21], v[52:55], v[68:71], v[18:21]
	v_mfma_f32_16x16x32_bf16 v[14:17], v[40:43], v[72:75], v[14:17]
	v_mfma_f32_16x16x32_bf16 v[10:13], v[44:47], v[72:75], v[10:13]
	v_mfma_f32_16x16x32_bf16 v[6:9], v[48:51], v[72:75], v[6:9]
	v_mfma_f32_16x16x32_bf16 v[2:5], v[52:55], v[72:75], v[2:5]
	s_waitcnt vmcnt(0)
	s_waitcnt lgkmcnt(0)
	s_barrier
	ds_read_b128 v[40:43], v67 offset:16384
	ds_read_b128 v[44:47], v67 offset:17408
	ds_read_b128 v[48:51], v67 offset:18432
	ds_read_b128 v[52:55], v67 offset:19456
	ds_read_b128 v[68:71], v64 offset:12288
	ds_read_b128 v[72:75], v64 offset:13312
	s_waitcnt lgkmcnt(0)
	v_mfma_f32_16x16x32_bf16 v[30:33], v[40:43], v[68:71], v[30:33]
	v_mfma_f32_16x16x32_bf16 v[26:29], v[44:47], v[68:71], v[26:29]
	v_mfma_f32_16x16x32_bf16 v[22:25], v[48:51], v[68:71], v[22:25]
	v_mfma_f32_16x16x32_bf16 v[18:21], v[52:55], v[68:71], v[18:21]
	v_mfma_f32_16x16x32_bf16 v[14:17], v[40:43], v[72:75], v[14:17]
	v_mfma_f32_16x16x32_bf16 v[10:13], v[44:47], v[72:75], v[10:13]
	v_mfma_f32_16x16x32_bf16 v[6:9], v[48:51], v[72:75], v[6:9]
	v_mfma_f32_16x16x32_bf16 v[2:5], v[52:55], v[72:75], v[2:5]
	v_add_u32_e32 v42, s9, v61
	s_waitcnt vmcnt(0)
	s_barrier
	v_readlane_b32 s2, v253, 30
	v_ashrrev_i32_e32 v43, 31, v42
	v_readlane_b32 s3, v253, 31
	s_and_b64 vcc, exec, s[2:3]
	v_lshl_add_u64 v[44:45], v[42:43], 2, s[66:67]
	s_cbranch_vccz .LBB0_1461
	global_load_dword v40, v[44:45], off
	s_waitcnt vmcnt(0)
	v_fmamk_f32 v40, v40, 0x3a800000, v142
	v_mul_f32_e32 v41, 0x4b800000, v40
	v_cmp_gt_f32_e32 vcc, s69, v40
	s_nop 1
	v_cndmask_b32_e32 v40, v40, v41, vcc
	v_rsq_f32_e32 v40, v40
	s_nop 0
	v_mul_f32_e32 v41, 0x45800000, v40
	v_cndmask_b32_e32 v46, v40, v41, vcc
	s_branch .LBB0_1462

; __device__ __forceinline__ int opaque_tid() { int t = threadIdx.x; asm volatile("" : "+v"(t)); return t; }
; template <int EPI, int MF>
; __device__ __forceinline__ void gemm_part(const u16* __restrict__ A, int lda, const u16* __restrict__ Bt, int K, int ntn, GemmEpi ep, char* smem,
;                                           int mbase, int mrows) {
;   const int tid = opaque_tid(), lane = tid & 63, wid = tid >> 6, wr = wid >> 1, wc = wid & 1, fr = lane & 15, fq = lane >> 4;
;   constexpr int BM = 32 * MF;
;   constexpr int STG = BM * 32 + 4096;
;   constexpr int NA = MF / 2;
;   u16* const sbase = (u16*)smem;
;   const int ntm = mrows / BM;
;   const int total = ntm * ntn;
;   const int nk = K / 32;
;   const int nbx = (MF == 2) ? (int)gridDim.x : (int)(gridDim.x >> 3);
;   const int xcd = (MF == 2) ? 0 : (int)(blockIdx.x & 7), li = (MF == 2) ? (int)blockIdx.x : (int)(blockIdx.x >> 3);
;   for (int q = xcd; q * nbx < total; q += (MF == 2) ? 1 : 8) {
;     const int L = q * nbx + li;
;     if (L >= total) continue;
;     const int g = L / (8 * ntn), rr = L % (8 * ntn);
;     const int rows = min(8, ntm - 8 * g);
;     const int tm = 8 * g + rr % rows, tn = rr / rows;
;     const int row0 = mbase + tm * BM, col0 = tn * 128;
;     f32x4 acc[MF][4];
; #pragma unroll
;     for (int m = 0; m < MF; ++m)
; #pragma unroll
;       for (int n = 0; n < 4; ++n) acc[m][n] = (f32x4){0.f, 0.f, 0.f, 0.f};
;     const u16* gA = A + (size_t)(row0 + (tid >> 2)) * lda + (tid & 3) * 8;
;     const u16* gB = Bt + (size_t)(col0 + (tid >> 2)) * K + (tid & 3) * 8;
.LBB0_1832:
	s_or_b64 exec, exec, s[2:3]
	v_readlane_b32 s2, v252, 7
	v_readlane_b32 s3, v252, 8
	v_mov_b32_e32 v2, v140
	s_and_b64 vcc, exec, s[2:3]
	s_barrier
	s_cbranch_vccnz .LBB0_1887
	v_lshlrev_b32_e32 v7, 4, v2
	v_lshrrev_b32_e32 v100, 4, v140
	v_sub_u32_e32 v100, 0, v100
	v_xor_b32_e32 v100, v100, v140
	v_and_b32_e32 v100, 3, v100
	v_lshlrev_b32_e32 v4, 4, v100
	v_mov_b32_e32 v5, v0
	v_bfe_u32 v3, v2, 4, 2
	v_lshl_add_u64 v[130:131], s[44:45], 0, v[4:5]
	v_lshl_add_u64 v[132:133], s[38:39], 0, v[4:5]
	v_lshlrev_b32_e32 v4, 5, v2
	v_bfe_u32 v6, v2, 6, 1
	v_and_b32_e32 v149, 0xfffff1e0, v4
	v_lshlrev_b32_e32 v4, 2, v3
	v_lshl_or_b32 v152, v6, 6, v4
	v_lshlrev_b32_e32 v153, 12, v6
	v_lshlrev_b32_e32 v4, 6, v2
	v_lshrrev_b32_e32 v101, 2, v140
	v_sub_u32_e32 v101, 0, v101
	v_lshrrev_b32_e32 v156, 4, v140
	v_xor_b32_e32 v101, v101, v156
	v_and_b32_e32 v101, 3, v101
	v_lshlrev_b32_e32 v156, 4, v101
	v_ashrrev_i32_e32 v1, 2, v2
	v_lshlrev_b32_e32 v150, 3, v3
	v_and_b32_e32 v151, 0xffffff8f, v2
	v_cmp_eq_u32_e32 vcc, 0, v3
	v_and_b32_e32 v154, 0x3c0, v4
	v_lshlrev_b32_e32 v155, 1, v149
	v_add_u32_e32 v3, v156, v153
	v_and_b32_e32 v2, 3, v2
	v_readlane_b32 s2, v254, 2
	v_add_u32_e32 v148, 0, v7
	v_add_u32_e32 v157, v156, v155
	v_lshlrev_b32_e32 v134, 4, v100
	v_mov_b32_e32 v135, v0
	v_add_u32_e32 v158, s2, v1
	v_or_b32_e32 v159, v153, v154
	v_add_u32_e32 v160, v3, v154
	v_readlane_b32 s4, v254, 1
	v_readlane_b32 s5, v254, 0
	v_readlane_b32 s2, v253, 56
	v_readlane_b32 s8, v253, 9
	s_branch .LBB0_1836

; template <int EPI, int MF>
; __device__ __forceinline__ void gemm_part(const u16* __restrict__ A, int lda, const u16* __restrict__ Bt, int K, int ntn, GemmEpi ep, char* smem,
;                                           int mbase, int mrows) {
;     ...
;   for (int q = xcd; q * nbx < total; q += (MF == 2) ? 1 : 8) {
;     const int L = q * nbx + li;
;     if (L >= total) continue;
;     const int g = L / (8 * ntn), rr = L % (8 * ntn);
;     const int rows = min(8, ntm - 8 * g);
;     const int tm = 8 * g + rr % rows, tn = rr / rows;
;     const int row0 = mbase + tm * BM, col0 = tn * 128;
;     f32x4 acc[MF][4];
; #pragma unroll
;     for (int m = 0; m < MF; ++m)
; #pragma unroll
;       for (int n = 0; n < 4; ++n) acc[m][n] = (f32x4){0.f, 0.f, 0.f, 0.f};
;     const u16* gA = A + (size_t)(row0 + (tid >> 2)) * lda + (tid & 3) * 8;
;     const u16* gB = Bt + (size_t)(col0 + (tid >> 2)) * K + (tid & 3) * 8;
;     ...
;     GEMM_ISSUE(0);
;     GEMM_ISSUE(1);
.LBB0_1836:
	s_add_i32 s2, s2, s63
	s_cmpk_gt_u32 s2, 0x7ff
	s_cbranch_scc1 .LBB0_1835
	s_lshl_b32 s3, s5, 5
	s_and_b32 s3, s3, 0xf800
	v_add_u32_e32 v2, s3, v158
	s_waitcnt lgkmcnt(0)
	v_ashrrev_i32_e32 v3, 31, v2
	v_lshlrev_b64 v[2:3], 11, v[2:3]
	s_and_b32 s3, s4, 0x380
	v_lshl_add_u64 v[136:137], s[44:45], 0, v[2:3]
	v_add_u32_e32 v2, s3, v1
	s_lshr_b32 s3, s2, 3
	s_and_b32 s3, s3, 0xf8
	s_and_b32 s9, s2, 7
	v_ashrrev_i32_e32 v3, 31, v2
	s_or_b32 s3, s3, s9
	v_lshlrev_b64 v[2:3], 11, v[2:3]
	s_lshl_b32 s9, s2, 4
	s_lshl_b32 s2, s3, 8
	v_lshl_add_u64 v[138:139], s[38:39], 0, v[2:3]
	v_lshlrev_b32_e32 v255, 1, v138
	v_bfi_b32 v255, s100, v255, v138
	v_lshrrev_b32_e32 v138, 5, v138
	v_bfi_b32 v138, 64, v138, v255
	v_lshl_add_u64 v[138:139], v[138:139], 0, 64
	v_lshl_add_u64 v[138:139], v[138:139], 0, 64
	v_add_u32_e32 v2, s2, v1
	v_ashrrev_i32_e32 v3, 31, v2
	v_lshlrev_b64 v[2:3], 11, v[2:3]
	v_readfirstlane_b32 s3, v148
	v_add_u32_e32 v8, 0x1000, v148
	v_lshl_add_u64 v[2:3], v[130:131], 0, v[2:3]
	s_mov_b32 m0, s3
	s_mov_b64 s[10:11], 0x20000
	v_readfirstlane_b32 s3, v8
	v_add_u32_e32 v8, 0x2000, v148
	global_load_lds_dwordx4 v[2:3], off
	v_lshl_add_u64 v[6:7], v[2:3], 0, s[10:11]
	s_mov_b32 m0, s3
	s_mov_b64 s[12:13], 0x40000
	v_readfirstlane_b32 s3, v8
	v_add_u32_e32 v8, 0x3000, v148
	s_and_b32 s9, s9, 0x380
	global_load_lds_dwordx4 v[6:7], off
	v_lshl_add_u64 v[6:7], v[2:3], 0, s[12:13]
	s_mov_b32 m0, s3
	s_mov_b64 s[12:13], 0x60000
	v_readfirstlane_b32 s3, v8
	v_add_u32_e32 v4, s9, v1
	global_load_lds_dwordx4 v[6:7], off
	v_lshl_add_u64 v[6:7], v[2:3], 0, s[12:13]
	s_mov_b32 m0, s3
	v_ashrrev_i32_e32 v5, 31, v4
	global_load_lds_dwordx4 v[6:7], off
	v_add_u32_e32 v6, 0x4000, v148
	v_lshlrev_b64 v[4:5], 11, v[4:5]
	v_readfirstlane_b32 s3, v6
	v_add_u32_e32 v8, 0x5000, v148
	v_lshl_add_u64 v[4:5], v[132:133], 0, v[4:5]
	v_lshlrev_b32_e32 v255, 1, v4
	v_bfi_b32 v255, s100, v255, v4
	v_lshrrev_b32_e32 v4, 5, v4
	v_bfi_b32 v4, 64, v4, v255
	s_mov_b32 m0, s3
	v_readfirstlane_b32 s3, v8
	v_add_u32_e32 v8, 0x6000, v148
	global_load_lds_dwordx4 v[4:5], off
	v_lshl_add_u64 v[6:7], v[4:5], 0, s[10:11]
	s_mov_b32 m0, s3
	v_readfirstlane_b32 s3, v8
	v_add_u32_e32 v8, 0x7000, v148
	global_load_lds_dwordx4 v[6:7], off
	v_lshl_add_u64 v[6:7], v[2:3], 0, 64
	s_mov_b32 m0, s3
	s_mov_b64 s[10:11], 0x20040
	v_readfirstlane_b32 s3, v8
	v_add_u32_e32 v8, 0x8000, v148
	global_load_lds_dwordx4 v[6:7], off
	v_lshl_add_u64 v[6:7], v[2:3], 0, s[10:11]
	s_mov_b32 m0, s3
	s_mov_b64 s[12:13], 0x40040
	v_readfirstlane_b32 s3, v8
	global_load_lds_dwordx4 v[6:7], off
	v_lshl_add_u64 v[6:7], v[2:3], 0, s[12:13]
	s_mov_b32 m0, s3
	s_mov_b64 s[12:13], 0x60040
	global_load_lds_dwordx4 v[6:7], off
	v_add_u32_e32 v6, 0x9000, v148
	v_lshl_add_u64 v[2:3], v[2:3], 0, s[12:13]
	v_readfirstlane_b32 s3, v6
	v_add_u32_e32 v6, 0xa000, v148
	s_mov_b32 m0, s3
	v_readfirstlane_b32 s3, v6
	global_load_lds_dwordx4 v[2:3], off
	v_lshl_add_u64 v[2:3], v[4:5], 0, 64
	v_lshl_add_u64 v[2:3], v[2:3], 0, 64
	s_mov_b32 m0, s3
	s_mov_b32 s12, 0
	global_load_lds_dwordx4 v[2:3], off
	v_lshl_add_u64 v[2:3], v[4:5], 0, s[10:11]
	v_lshl_add_u64 v[2:3], v[2:3], 0, 64
	v_add_u32_e32 v4, 0xb000, v148
	s_mov_b32 s10, 1
	v_readfirstlane_b32 s3, v4
	s_mov_b32 m0, s3
	s_mov_b32 s3, 0
	global_load_lds_dwordx4 v[2:3], off
	v_mov_b32_e32 v2, 0
	s_mov_b32 s11, 2
	v_mov_b32_e32 v3, v2
	v_mov_b32_e32 v4, v2
	v_mov_b32_e32 v5, v2
	v_mov_b32_e32 v6, v2
	v_mov_b32_e32 v7, v2
	v_mov_b32_e32 v8, v2
	v_mov_b32_e32 v9, v2
	v_mov_b32_e32 v10, v2
	v_mov_b32_e32 v11, v2
	v_mov_b32_e32 v12, v2
	v_mov_b32_e32 v13, v2
	v_mov_b32_e32 v14, v2
	v_mov_b32_e32 v15, v2
	v_mov_b32_e32 v16, v2
	v_mov_b32_e32 v17, v2
	v_mov_b32_e32 v18, v2
	v_mov_b32_e32 v19, v2
	v_mov_b32_e32 v20, v2
	v_mov_b32_e32 v21, v2
	v_mov_b32_e32 v22, v2
	v_mov_b32_e32 v23, v2
	v_mov_b32_e32 v24, v2
	v_mov_b32_e32 v25, v2
	v_mov_b32_e32 v26, v2
	v_mov_b32_e32 v27, v2
	v_mov_b32_e32 v28, v2
	v_mov_b32_e32 v29, v2
	v_mov_b32_e32 v30, v2
	v_mov_b32_e32 v31, v2
	v_mov_b32_e32 v32, v2
	v_mov_b32_e32 v33, v2
	v_mov_b32_e32 v34, v2
	v_mov_b32_e32 v35, v2
	v_mov_b32_e32 v36, v2
	v_mov_b32_e32 v37, v2
	v_mov_b32_e32 v38, v2
	v_mov_b32_e32 v39, v2
	v_mov_b32_e32 v40, v2
	v_mov_b32_e32 v41, v2
	v_mov_b32_e32 v42, v2
	v_mov_b32_e32 v43, v2
	v_mov_b32_e32 v44, v2
	v_mov_b32_e32 v45, v2
	v_mov_b32_e32 v46, v2
	v_mov_b32_e32 v47, v2
	v_mov_b32_e32 v48, v2
	v_mov_b32_e32 v49, v2
	v_mov_b32_e32 v50, v2
	v_mov_b32_e32 v51, v2
	v_mov_b32_e32 v52, v2
	v_mov_b32_e32 v53, v2
	v_mov_b32_e32 v54, v2
	v_mov_b32_e32 v55, v2
	v_mov_b32_e32 v56, v2
	v_mov_b32_e32 v57, v2
	v_mov_b32_e32 v58, v2
	v_mov_b32_e32 v59, v2
	v_mov_b32_e32 v60, v2
	v_mov_b32_e32 v61, v2
	v_mov_b32_e32 v62, v2
	v_mov_b32_e32 v63, v2
	v_mov_b32_e32 v64, v2
	v_mov_b32_e32 v65, v2
	v_mov_b32_e32 v66, v2
	v_mov_b32_e32 v67, v2
	v_mov_b32_e32 v68, v2
	v_mov_b32_e32 v69, v2
	v_mov_b32_e32 v70, v2
	v_mov_b32_e32 v71, v2
	v_mov_b32_e32 v72, v2
	v_mov_b32_e32 v73, v2
	v_mov_b32_e32 v74, v2
	v_mov_b32_e32 v75, v2
	v_mov_b32_e32 v76, v2
	v_mov_b32_e32 v77, v2
	v_mov_b32_e32 v78, v2
	v_mov_b32_e32 v79, v2
	v_mov_b32_e32 v80, v2
	v_mov_b32_e32 v81, v2
	v_mov_b32_e32 v82, v2
	v_mov_b32_e32 v83, v2
	v_mov_b32_e32 v84, v2
	v_mov_b32_e32 v85, v2
	v_mov_b32_e32 v86, v2
	v_mov_b32_e32 v87, v2
	s_waitcnt vmcnt(0)
	v_mov_b32_e32 v88, v2
	v_mov_b32_e32 v89, v2
	v_mov_b32_e32 v90, v2
	v_mov_b32_e32 v91, v2
	v_mov_b32_e32 v92, v2
	v_mov_b32_e32 v93, v2
	v_mov_b32_e32 v94, v2
	v_mov_b32_e32 v95, v2
	v_mov_b32_e32 v96, v2
	v_mov_b32_e32 v97, v2
	v_mov_b32_e32 v98, v2
	v_mov_b32_e32 v99, v2
	v_mov_b32_e32 v100, v2
	v_mov_b32_e32 v101, v2
	v_mov_b32_e32 v102, v2
	v_mov_b32_e32 v103, v2
	v_mov_b32_e32 v104, v2
	v_mov_b32_e32 v105, v2
	v_mov_b32_e32 v106, v2
	v_mov_b32_e32 v107, v2
	v_mov_b32_e32 v108, v2
	v_mov_b32_e32 v109, v2
	v_mov_b32_e32 v110, v2
	v_mov_b32_e32 v111, v2
	v_mov_b32_e32 v112, v2
	v_mov_b32_e32 v113, v2
	v_mov_b32_e32 v114, v2
	v_mov_b32_e32 v115, v2
	v_mov_b32_e32 v116, v2
	v_mov_b32_e32 v117, v2
	v_mov_b32_e32 v118, v2
	v_mov_b32_e32 v119, v2
	v_mov_b32_e32 v120, v2
	v_mov_b32_e32 v121, v2
	v_mov_b32_e32 v122, v2
	v_mov_b32_e32 v123, v2
	v_mov_b32_e32 v124, v2
	v_mov_b32_e32 v125, v2
	v_mov_b32_e32 v126, v2
	v_mov_b32_e32 v127, v2
	v_mov_b32_e32 v128, v2
	v_mov_b32_e32 v129, v2

; template <int EPI, int MF>
; __device__ __forceinline__ void gemm_part(const u16* __restrict__ A, int lda, const u16* __restrict__ Bt, int K, int ntn, GemmEpi ep, char* smem,
;                                           int mbase, int mrows) {
;     ...
;   for (int q = xcd; q * nbx < total; q += (MF == 2) ? 1 : 8) {
;     const int L = q * nbx + li;
;     if (L >= total) continue;
;     const int g = L / (8 * ntn), rr = L % (8 * ntn);
;     const int rows = min(8, ntm - 8 * g);
;     const int tm = 8 * g + rr % rows, tn = rr / rows;
;     const int row0 = mbase + tm * BM, col0 = tn * 128;
;     f32x4 acc[MF][4];
; #pragma unroll
;     for (int m = 0; m < MF; ++m)
; #pragma unroll
;       for (int n = 0; n < 4; ++n) acc[m][n] = (f32x4){0.f, 0.f, 0.f, 0.f};
;     const u16* gA = A + (size_t)(row0 + (tid >> 2)) * lda + (tid & 3) * 8;
;     const u16* gB = Bt + (size_t)(col0 + (tid >> 2)) * K + (tid & 3) * 8;
;     ...
;     GEMM_ISSUE(0);
;     GEMM_ISSUE(1);
.LBB0_1890:
	s_add_i32 s2, s2, s64
	s_cmp_gt_i32 s2, 63
	s_cbranch_scc1 .LBB0_1889
	s_ashr_i32 s3, s2, 31
	s_lshr_b32 s3, s3, 26
	s_add_i32 s3, s2, s3
	s_and_b32 s5, s3, 0xffc0
	s_sub_i32 s2, s2, s5
	s_bfe_i32 s5, s2, 0x80000
	s_bfe_u32 s5, s5, 0x3000c
	s_add_i32 s5, s2, s5
	s_bfe_i32 s8, s5, 0x80000
	s_and_b32 s5, s5, 0xf8
	s_sub_i32 s2, s2, s5
	s_sext_i32_i8 s2, s2
	s_lshl_b32 s3, s3, 3
	s_and_b32 s3, s3, 0xfffffe00
	s_lshl_b32 s2, s2, 6
	s_sext_i32_i16 s8, s8
	s_add_i32 s2, s3, s2
	s_add_i32 s2, s2, 0x10000
	s_lshl_b32 s3, s8, 4
	s_and_b32 s5, s3, 0xffffff80
	v_add_u32_e32 v2, s2, v1
	s_waitcnt lgkmcnt(0)
	v_ashrrev_i32_e32 v3, 31, v2
	v_add_u32_e32 v6, s5, v1
	v_lshlrev_b64 v[2:3], 11, v[2:3]
	v_ashrrev_i32_e32 v7, 31, v6
	v_readfirstlane_b32 s3, v48
	v_add_u32_e32 v10, 0x1000, v48
	v_lshl_add_u64 v[4:5], v[34:35], 0, v[2:3]
	v_lshlrev_b64 v[6:7], 11, v[6:7]
	s_mov_b32 m0, s3
	v_readfirstlane_b32 s3, v10
	v_add_u32_e32 v12, 0x2000, v48
	v_lshl_add_u64 v[8:9], v[36:37], 0, v[6:7]
	v_lshlrev_b32_e32 v255, 1, v8
	v_bfi_b32 v255, s100, v255, v8
	v_lshrrev_b32_e32 v8, 5, v8
	v_bfi_b32 v8, 64, v8, v255
	global_load_lds_dwordx4 v[4:5], off
	s_mov_b32 m0, s3
	s_mov_b64 s[8:9], 0x20000
	v_readfirstlane_b32 s3, v12
	global_load_lds_dwordx4 v[8:9], off
	v_lshl_add_u64 v[10:11], v[8:9], 0, s[8:9]
	s_mov_b32 m0, s3
	v_lshl_add_u64 v[4:5], v[4:5], 0, 64
	global_load_lds_dwordx4 v[10:11], off
	v_add_u32_e32 v10, 0x3000, v48
	s_mov_b64 s[8:9], 0x20040
	v_readfirstlane_b32 s3, v10
	v_add_u32_e32 v10, 0x4000, v48
	s_mov_b32 m0, s3
	v_readfirstlane_b32 s3, v10
	global_load_lds_dwordx4 v[4:5], off
	v_lshl_add_u64 v[4:5], v[8:9], 0, 64
	v_lshl_add_u64 v[4:5], v[4:5], 0, 64
	s_mov_b32 m0, s3
	v_lshl_add_u64 v[42:43], s[44:45], 0, v[2:3]
	global_load_lds_dwordx4 v[4:5], off
	v_lshl_add_u64 v[4:5], v[8:9], 0, s[8:9]
	v_lshl_add_u64 v[4:5], v[4:5], 0, 64
	v_add_u32_e32 v8, 0x5000, v48
	v_mov_b32_e32 v2, 0
	v_readfirstlane_b32 s3, v8
	s_mov_b32 m0, s3
	s_mov_b32 s8, 3
	global_load_lds_dwordx4 v[4:5], off
	v_lshl_add_u64 v[40:41], s[38:39], 0, v[6:7]
	v_lshlrev_b32_e32 v255, 1, v40
	v_bfi_b32 v255, s100, v255, v40
	v_lshrrev_b32_e32 v40, 5, v40
	v_bfi_b32 v40, 64, v40, v255
	v_lshl_add_u64 v[40:41], v[40:41], 0, 64
	v_lshl_add_u64 v[40:41], v[40:41], 0, 64
	s_mov_b32 s3, 0
	s_mov_b32 s9, 1
	s_mov_b32 s10, 2
	s_mov_b32 s11, 0
	v_mov_b32_e32 v3, v2
	v_mov_b32_e32 v4, v2
	v_mov_b32_e32 v5, v2
	v_mov_b32_e32 v6, v2
	v_mov_b32_e32 v7, v2
	v_mov_b32_e32 v8, v2
	v_mov_b32_e32 v9, v2
	v_mov_b32_e32 v10, v2
	v_mov_b32_e32 v11, v2
	v_mov_b32_e32 v12, v2
	v_mov_b32_e32 v13, v2
	v_mov_b32_e32 v14, v2
	v_mov_b32_e32 v15, v2
	v_mov_b32_e32 v16, v2
	v_mov_b32_e32 v17, v2
	v_mov_b32_e32 v18, v2
	v_mov_b32_e32 v19, v2
	v_mov_b32_e32 v20, v2
	v_mov_b32_e32 v21, v2
	v_mov_b32_e32 v22, v2
	v_mov_b32_e32 v23, v2
	v_mov_b32_e32 v24, v2
	v_mov_b32_e32 v25, v2
	v_mov_b32_e32 v26, v2
	v_mov_b32_e32 v27, v2
	v_mov_b32_e32 v28, v2
	v_mov_b32_e32 v29, v2
	v_mov_b32_e32 v30, v2
	v_mov_b32_e32 v31, v2
	v_mov_b32_e32 v32, v2
	v_mov_b32_e32 v33, v2
	s_waitcnt vmcnt(0)

; __device__ __forceinline__ int opaque_tid() { int t = threadIdx.x; asm volatile("" : "+v"(t)); return t; }
; template <int EPI, int MF>
; __device__ __forceinline__ void gemm_part(const u16* __restrict__ A, int lda, const u16* __restrict__ Bt, int K, int ntn, GemmEpi ep, char* smem,
;                                           int mbase, int mrows) {
;   const int tid = opaque_tid(), lane = tid & 63, wid = tid >> 6, wr = wid >> 1, wc = wid & 1, fr = lane & 15, fq = lane >> 4;
;   constexpr int BM = 32 * MF;
;   constexpr int STG = BM * 32 + 4096;
;   constexpr int NA = MF / 2;
;   u16* const sbase = (u16*)smem;
;   const int ntm = mrows / BM;
;   const int total = ntm * ntn;
;   const int nk = K / 32;
;   const int nbx = (MF == 2) ? (int)gridDim.x : (int)(gridDim.x >> 3);
;   const int xcd = (MF == 2) ? 0 : (int)(blockIdx.x & 7), li = (MF == 2) ? (int)blockIdx.x : (int)(blockIdx.x >> 3);
;   for (int q = xcd; q * nbx < total; q += (MF == 2) ? 1 : 8) {
;     const int L = q * nbx + li;
;     if (L >= total) continue;
;     const int g = L / (8 * ntn), rr = L % (8 * ntn);
;     const int rows = min(8, ntm - 8 * g);
;     const int tm = 8 * g + rr % rows, tn = rr / rows;
;     const int row0 = mbase + tm * BM, col0 = tn * 128;
;     f32x4 acc[MF][4];
; #pragma unroll
;     for (int m = 0; m < MF; ++m)
; #pragma unroll
;       for (int n = 0; n < 4; ++n) acc[m][n] = (f32x4){0.f, 0.f, 0.f, 0.f};
;     const u16* gA = A + (size_t)(row0 + (tid >> 2)) * lda + (tid & 3) * 8;
;     const u16* gB = Bt + (size_t)(col0 + (tid >> 2)) * K + (tid & 3) * 8;
.LBB0_1942:
	s_or_b64 exec, exec, s[2:3]
	v_readlane_b32 s2, v252, 3
	v_readlane_b32 s3, v252, 4
	s_barrier
	s_load_dwordx2 s[10:11], s[2:3], 0xe8
	v_readlane_b32 s2, v252, 5
	v_readlane_b32 s3, v252, 6
	v_mov_b32_e32 v2, v140
	s_and_b64 vcc, exec, s[2:3]
	s_cbranch_vccnz .LBB0_1949
	v_lshlrev_b32_e32 v7, 4, v2
	v_lshrrev_b32_e32 v100, 4, v140
	v_sub_u32_e32 v100, 0, v100
	v_xor_b32_e32 v100, v100, v140
	v_and_b32_e32 v100, 3, v100
	v_lshlrev_b32_e32 v4, 4, v100
	v_mov_b32_e32 v5, v0
	v_bfe_u32 v6, v2, 6, 1
	v_lshl_add_u64 v[130:131], s[28:29], 0, v[4:5]
	s_waitcnt lgkmcnt(0)
	v_lshl_add_u64 v[132:133], s[10:11], 0, v[4:5]
	v_lshlrev_b32_e32 v4, 5, v2
	v_bfe_u32 v3, v2, 4, 2
	v_and_b32_e32 v151, 0xfffff1e0, v4
	v_lshlrev_b32_e32 v4, 6, v6
	v_lshlrev_b32_e32 v134, 3, v3
	v_lshl_add_u64 v[4:5], s[46:47], 0, v[4:5]
	v_mov_b32_e32 v135, v0
	v_ashrrev_i32_e32 v1, 2, v2
	v_and_b32_e32 v152, 0xffffff8f, v2
	v_lshl_add_u64 v[136:137], v[4:5], 0, v[134:135]
	v_and_b32_e32 v8, 1, v140
	v_mul_u32_u24_e32 v8, 0x15c0, v8
	v_bfe_u32 v9, v140, 6, 1
	v_lshlrev_b32_e32 v9, 6, v9
	v_sub_u32_e32 v8, v9, v8
	v_ashrrev_i32_e32 v9, 31, v8
	v_lshl_add_u64 v[136:137], v[136:137], 0, v[8:9]
	v_lshlrev_b32_e32 v135, 12, v6
	v_lshlrev_b32_e32 v4, 6, v2
	v_lshrrev_b32_e32 v101, 2, v140
	v_sub_u32_e32 v101, 0, v101
	v_lshrrev_b32_e32 v3, 4, v140
	v_xor_b32_e32 v101, v101, v3
	v_and_b32_e32 v101, 3, v101
	v_lshlrev_b32_e32 v3, 4, v101
	v_and_b32_e32 v2, 3, v2
	v_readlane_b32 s2, v253, 0
	v_and_b32_e32 v153, 0x3c0, v4
	v_lshl_add_u32 v154, v151, 1, v3
	v_add_u32_e32 v4, v3, v135
	v_lshlrev_b32_e32 v2, 4, v100
	v_mov_b32_e32 v3, v0
	v_readlane_b32 s3, v253, 1
	v_add_u32_e32 v150, 0, v7
	v_add_u32_e32 v155, v4, v153
	v_lshl_add_u64 v[138:139], s[2:3], 0, v[2:3]
	v_readlane_b32 s2, v253, 56
	v_readlane_b32 s4, v253, 9
	s_branch .LBB0_1945

; #define MFMA(a, b, c) __builtin_amdgcn_mfma_f32_16x16x32_bf16((a), (b), (c), 0, 0, 0)
; template <int EPI, int MF>
; __device__ __forceinline__ void gemm_part(const u16* __restrict__ A, int lda, const u16* __restrict__ Bt, int K, int ntn, GemmEpi ep, char* smem,
;                                           int mbase, int mrows) {
;     ...
;     for (int kt = 0; kt < nk; ++kt) {
;       if (kt + 1 < nk) {
;         if (MF == 8) asm volatile("s_waitcnt vmcnt(6)" ::: "memory");
;         else asm volatile("s_waitcnt vmcnt(3)" ::: "memory");
;       } else asm volatile("s_waitcnt vmcnt(0)" ::: "memory");
;       asm volatile("s_waitcnt lgkmcnt(0)" ::: "memory");
;       __builtin_amdgcn_s_barrier();
;       const u16* a_ = sbase + (kt % 3) * STG;
;       const u16* b_ = a_ + BM * 32;
;       bf16x8 bfr[4], afc[2], afn[2];
;       const u16* ap_ = a_ + (wr * (16 * MF) + fr) * 32 + fq * 8;
; #pragma unroll
;       for (int n = 0; n < 4; ++n) bfr[n] = rd_std(b_ + (wc * 64 + n * 16 + fr) * 32 + fq * 8);
;       afc[0] = rd_std(ap_); afc[1] = rd_std(ap_ + 16 * 32);
;       __builtin_amdgcn_sched_barrier(0);
;       if (kt + 2 < nk) GEMM_ISSUE(kt + 2);
;       __builtin_amdgcn_sched_barrier(0);
; #pragma unroll
;       for (int mh = 0; mh < MF / 2; ++mh) {
;         if (mh + 1 < MF / 2) {
;           afn[0] = rd_std(ap_ + ((mh + 1) * 2) * 16 * 32);
;           afn[1] = rd_std(ap_ + ((mh + 1) * 2 + 1) * 16 * 32);
;         }
;         __builtin_amdgcn_sched_barrier(0);
; #pragma unroll
;         for (int m = 0; m < 2; ++m)
; #pragma unroll
;           for (int n = 0; n < 4; ++n) acc[mh * 2 + m][n] = MFMA(bfr[n], afc[m], acc[mh * 2 + m][n]);
;         __builtin_amdgcn_sched_barrier(0);
;         afc[0] = afn[0]; afc[1] = afn[1];
;       }
;     }
.LBB0_1947:
	s_mul_i32 s12, s9, 0xab
	s_add_i32 s13, s12, 0xfeaa
	s_bfe_u32 s13, s13, 0x70009
	s_mul_i32 s13, s13, 3
	s_sub_i32 s13, s9, s13
	s_add_i32 s13, s13, 0xfffe
	s_and_b32 s13, s13, 0xff
	s_mulk_i32 s13, 0x6000
	s_add_i32 s13, s13, 0
	v_lshl_add_u32 v172, v134, 1, s13
	s_waitcnt vmcnt(6)
	v_add_u32_e32 v168, s13, v155
	s_waitcnt lgkmcnt(0)
	s_barrier
	ds_read_b128 v[156:159], v168 offset:16384
	ds_read_b128 v[160:163], v168 offset:17408
	ds_read_b128 v[164:167], v168 offset:18432
	ds_read_b128 v[168:171], v168 offset:19456
	v_add_u32_e32 v188, s13, v154
	ds_read_b128 v[172:175], v188
	ds_read_b128 v[176:179], v188 offset:1024
	s_bfe_u32 s12, s12, 0x70009
	s_mul_i32 s12, s12, 3
	s_sub_i32 s12, s9, s12
	s_and_b32 s12, s12, 0xff
	s_mulk_i32 s12, 0x6000
	v_add_u32_e32 v184, s12, v150
	v_lshl_add_u64 v[180:181], s[2:3], 1, v[148:149]
	v_readfirstlane_b32 s12, v184
	v_lshl_add_u64 v[182:183], v[180:181], 0, s[30:31]
	s_mov_b32 m0, s12
	s_mov_b64 s[12:13], 0x162e0080
	v_add_u32_e32 v185, 0x1000, v184
	global_load_lds_dwordx4 v[182:183], off
	v_lshl_add_u64 v[182:183], v[180:181], 0, s[12:13]
	v_readfirstlane_b32 s12, v185
	s_mov_b32 m0, s12
	s_mov_b64 s[12:13], 0x16300080
	v_add_u32_e32 v185, 0x2000, v184
	global_load_lds_dwordx4 v[182:183], off
	v_lshl_add_u64 v[182:183], v[180:181], 0, s[12:13]
	v_readfirstlane_b32 s12, v185
	s_mov_b32 m0, s12
	s_mov_b64 s[12:13], 0x16320080
	global_load_lds_dwordx4 v[182:183], off
	v_add_u32_e32 v182, 0x3000, v184
	v_lshl_add_u64 v[180:181], v[180:181], 0, s[12:13]
	v_readfirstlane_b32 s12, v182
	s_mov_b32 m0, s12
	v_add_u32_e32 v185, 0x4000, v184
	global_load_lds_dwordx4 v[180:181], off
	v_lshl_add_u64 v[180:181], s[2:3], 1, v[146:147]
	v_readfirstlane_b32 s12, v185
	v_lshl_add_u64 v[182:183], v[180:181], 0, s[74:75]
	s_mov_b32 m0, s12
	v_lshl_add_u64 v[180:181], v[180:181], 0, s[92:93]
	global_load_lds_dwordx4 v[182:183], off
	v_add_u32_e32 v182, 0x5000, v184
	s_nop 0
	v_readfirstlane_b32 s12, v182
	s_mov_b32 m0, s12
	s_nop 0
	global_load_lds_dwordx4 v[180:181], off
	ds_read_b128 v[180:183], v188 offset:2048
	ds_read_b128 v[184:187], v188 offset:3072
	s_waitcnt lgkmcnt(2)
	v_mfma_f32_16x16x32_bf16 v[126:129], v[156:159], v[172:175], v[126:129]
	v_mfma_f32_16x16x32_bf16 v[122:125], v[160:163], v[172:175], v[122:125]
	v_mfma_f32_16x16x32_bf16 v[118:121], v[164:167], v[172:175], v[118:121]
	v_mfma_f32_16x16x32_bf16 v[114:117], v[168:171], v[172:175], v[114:117]
	v_mfma_f32_16x16x32_bf16 v[110:113], v[156:159], v[176:179], v[110:113]
	v_mfma_f32_16x16x32_bf16 v[106:109], v[160:163], v[176:179], v[106:109]
	v_mfma_f32_16x16x32_bf16 v[102:105], v[164:167], v[176:179], v[102:105]
	v_mfma_f32_16x16x32_bf16 v[98:101], v[168:171], v[176:179], v[98:101]
	ds_read_b128 v[172:175], v188 offset:4096
	ds_read_b128 v[176:179], v188 offset:5120
	s_waitcnt lgkmcnt(2)
	v_mfma_f32_16x16x32_bf16 v[94:97], v[156:159], v[180:183], v[94:97]
	v_mfma_f32_16x16x32_bf16 v[90:93], v[160:163], v[180:183], v[90:93]
	v_mfma_f32_16x16x32_bf16 v[86:89], v[164:167], v[180:183], v[86:89]
	v_mfma_f32_16x16x32_bf16 v[82:85], v[168:171], v[180:183], v[82:85]
	v_mfma_f32_16x16x32_bf16 v[78:81], v[156:159], v[184:187], v[78:81]
	v_mfma_f32_16x16x32_bf16 v[74:77], v[160:163], v[184:187], v[74:77]
	v_mfma_f32_16x16x32_bf16 v[70:73], v[164:167], v[184:187], v[70:73]
	v_mfma_f32_16x16x32_bf16 v[66:69], v[168:171], v[184:187], v[66:69]
	ds_read_b128 v[180:183], v188 offset:6144
	ds_read_b128 v[184:187], v188 offset:7168
	s_waitcnt lgkmcnt(2)
	v_mfma_f32_16x16x32_bf16 v[62:65], v[156:159], v[172:175], v[62:65]
	v_mfma_f32_16x16x32_bf16 v[58:61], v[160:163], v[172:175], v[58:61]
	v_mfma_f32_16x16x32_bf16 v[54:57], v[164:167], v[172:175], v[54:57]
	v_mfma_f32_16x16x32_bf16 v[50:53], v[168:171], v[172:175], v[50:53]
	v_mfma_f32_16x16x32_bf16 v[46:49], v[156:159], v[176:179], v[46:49]
	v_mfma_f32_16x16x32_bf16 v[42:45], v[160:163], v[176:179], v[42:45]
	v_mfma_f32_16x16x32_bf16 v[38:41], v[164:167], v[176:179], v[38:41]
	v_mfma_f32_16x16x32_bf16 v[34:37], v[168:171], v[176:179], v[34:37]
	s_waitcnt lgkmcnt(0)
	v_mfma_f32_16x16x32_bf16 v[30:33], v[156:159], v[180:183], v[30:33]
	v_mfma_f32_16x16x32_bf16 v[26:29], v[160:163], v[180:183], v[26:29]
	v_mfma_f32_16x16x32_bf16 v[22:25], v[164:167], v[180:183], v[22:25]
	v_mfma_f32_16x16x32_bf16 v[18:21], v[168:171], v[180:183], v[18:21]
	v_mfma_f32_16x16x32_bf16 v[14:17], v[156:159], v[184:187], v[14:17]
	v_mfma_f32_16x16x32_bf16 v[10:13], v[160:163], v[184:187], v[10:13]
	v_mfma_f32_16x16x32_bf16 v[6:9], v[164:167], v[184:187], v[6:9]
	v_mfma_f32_16x16x32_bf16 v[2:5], v[168:171], v[184:187], v[2:5]
	s_add_u32 s2, s2, 64
	s_addc_u32 s3, s3, 0
	s_add_i32 s9, s9, 1
	s_cmpk_eq_i32 s2, 0x780
	s_cbranch_scc0 .LBB0_1947
	s_waitcnt vmcnt(6)
	s_waitcnt lgkmcnt(0)
	s_barrier
; #define MFMA(a, b, c) __builtin_amdgcn_mfma_f32_16x16x32_bf16((a), (b), (c), 0, 0, 0)
; template <int EPI, int MF>
; __device__ __forceinline__ void gemm_part(const u16* __restrict__ A, int lda, const u16* __restrict__ Bt, int K, int ntn, GemmEpi ep, char* smem,
;                                           int mbase, int mrows) {
;     ...
;     for (int kt = 0; kt < nk; ++kt) {
;       if (kt + 1 < nk) {
;         if (MF == 8) asm volatile("s_waitcnt vmcnt(6)" ::: "memory");
;         else asm volatile("s_waitcnt vmcnt(3)" ::: "memory");
;       } else asm volatile("s_waitcnt vmcnt(0)" ::: "memory");
;       asm volatile("s_waitcnt lgkmcnt(0)" ::: "memory");
;       __builtin_amdgcn_s_barrier();
;       const u16* a_ = sbase + (kt % 3) * STG;
;       const u16* b_ = a_ + BM * 32;
;       bf16x8 bfr[4], afc[2], afn[2];
;       const u16* ap_ = a_ + (wr * (16 * MF) + fr) * 32 + fq * 8;
; #pragma unroll
;       for (int n = 0; n < 4; ++n) bfr[n] = rd_std(b_ + (wc * 64 + n * 16 + fr) * 32 + fq * 8);
;       afc[0] = rd_std(ap_); afc[1] = rd_std(ap_ + 16 * 32);
;       __builtin_amdgcn_sched_barrier(0);
;       if (kt + 2 < nk) GEMM_ISSUE(kt + 2);
;       __builtin_amdgcn_sched_barrier(0);
; #pragma unroll
;       for (int mh = 0; mh < MF / 2; ++mh) {
;         if (mh + 1 < MF / 2) {
;           afn[0] = rd_std(ap_ + ((mh + 1) * 2) * 16 * 32);
;           afn[1] = rd_std(ap_ + ((mh + 1) * 2 + 1) * 16 * 32);
;         }
;         __builtin_amdgcn_sched_barrier(0);
; #pragma unroll
;         for (int m = 0; m < 2; ++m)
; #pragma unroll
;           for (int n = 0; n < 4; ++n) acc[mh * 2 + m][n] = MFMA(bfr[n], afc[m], acc[mh * 2 + m][n]);
;         __builtin_amdgcn_sched_barrier(0);
;         afc[0] = afn[0]; afc[1] = afn[1];
;       }
;     }
;     ...
;     __syncthreads();
	ds_read_b128 v[146:149], v155 offset:16384
	ds_read_b128 v[156:159], v155 offset:17408
	ds_read_b128 v[160:163], v155 offset:18432
	ds_read_b128 v[164:167], v155 offset:19456
	ds_read_b128 v[168:171], v154
	ds_read_b128 v[172:175], v154 offset:1024
	ds_read_b128 v[176:179], v154 offset:2048
	ds_read_b128 v[180:183], v154 offset:3072
	s_waitcnt lgkmcnt(0)
	v_mfma_f32_16x16x32_bf16 v[126:129], v[146:149], v[168:171], v[126:129]
	v_mfma_f32_16x16x32_bf16 v[122:125], v[156:159], v[168:171], v[122:125]
	v_mfma_f32_16x16x32_bf16 v[184:187], v[160:163], v[168:171], v[118:121]
	v_mfma_f32_16x16x32_bf16 v[114:117], v[164:167], v[168:171], v[114:117]
	v_mfma_f32_16x16x32_bf16 v[110:113], v[146:149], v[172:175], v[110:113]
	v_mfma_f32_16x16x32_bf16 v[106:109], v[156:159], v[172:175], v[106:109]
	v_mfma_f32_16x16x32_bf16 v[168:171], v[160:163], v[172:175], v[102:105]
	v_mfma_f32_16x16x32_bf16 v[98:101], v[164:167], v[172:175], v[98:101]
	s_nop 1
	ds_read_b128 v[102:105], v154 offset:4096
	ds_read_b128 v[118:121], v154 offset:5120
	v_mfma_f32_16x16x32_bf16 v[94:97], v[146:149], v[176:179], v[94:97]
	v_mfma_f32_16x16x32_bf16 v[90:93], v[156:159], v[176:179], v[90:93]
	v_mfma_f32_16x16x32_bf16 v[172:175], v[160:163], v[176:179], v[86:89]
	v_mfma_f32_16x16x32_bf16 v[82:85], v[164:167], v[176:179], v[82:85]
	v_mfma_f32_16x16x32_bf16 v[78:81], v[146:149], v[180:183], v[78:81]
	v_mfma_f32_16x16x32_bf16 v[74:77], v[156:159], v[180:183], v[74:77]
	v_mfma_f32_16x16x32_bf16 v[176:179], v[160:163], v[180:183], v[70:73]
	v_mfma_f32_16x16x32_bf16 v[66:69], v[164:167], v[180:183], v[66:69]
	s_nop 1
	ds_read_b128 v[70:73], v154 offset:6144
	ds_read_b128 v[86:89], v154 offset:7168
	s_waitcnt lgkmcnt(0)
	v_mfma_f32_16x16x32_bf16 v[62:65], v[146:149], v[102:105], v[62:65]
	v_mfma_f32_16x16x32_bf16 v[58:61], v[156:159], v[102:105], v[58:61]
	v_mfma_f32_16x16x32_bf16 v[180:183], v[160:163], v[102:105], v[54:57]
	v_mfma_f32_16x16x32_bf16 v[50:53], v[164:167], v[102:105], v[50:53]
	v_mfma_f32_16x16x32_bf16 v[46:49], v[146:149], v[118:121], v[46:49]
	v_mfma_f32_16x16x32_bf16 v[42:45], v[156:159], v[118:121], v[42:45]
	v_mfma_f32_16x16x32_bf16 v[188:191], v[160:163], v[118:121], v[38:41]
	v_mfma_f32_16x16x32_bf16 v[34:37], v[164:167], v[118:121], v[34:37]
	v_mfma_f32_16x16x32_bf16 v[30:33], v[146:149], v[70:73], v[30:33]
	v_mfma_f32_16x16x32_bf16 v[26:29], v[156:159], v[70:73], v[26:29]
	v_mfma_f32_16x16x32_bf16 v[192:195], v[160:163], v[70:73], v[22:25]
	v_mfma_f32_16x16x32_bf16 v[18:21], v[164:167], v[70:73], v[18:21]
	v_mfma_f32_16x16x32_bf16 v[14:17], v[146:149], v[86:89], v[14:17]
	v_mfma_f32_16x16x32_bf16 v[10:13], v[156:159], v[86:89], v[10:13]
	v_mfma_f32_16x16x32_bf16 v[146:149], v[160:163], v[86:89], v[6:9]
	v_mfma_f32_16x16x32_bf16 v[2:5], v[164:167], v[86:89], v[2:5]
	s_waitcnt vmcnt(0)
	s_waitcnt lgkmcnt(0)
	s_barrier
	s_nop 0
	ds_read_b128 v[6:9], v155 offset:40960
	ds_read_b128 v[156:159], v155 offset:41984
	ds_read_b128 v[160:163], v155 offset:43008
	ds_read_b128 v[164:167], v155 offset:44032
	ds_read_b128 v[22:25], v154 offset:24576
	ds_read_b128 v[38:41], v154 offset:25600
	ds_read_b128 v[54:57], v154 offset:26624
	ds_read_b128 v[196:199], v154 offset:27648
	s_waitcnt lgkmcnt(0)
	v_mfma_f32_16x16x32_bf16 v[210:213], v[6:9], v[22:25], v[126:129]
	v_mfma_f32_16x16x32_bf16 v[118:121], v[156:159], v[22:25], v[122:125]
	v_mfma_f32_16x16x32_bf16 v[184:187], v[160:163], v[22:25], v[184:187]
	v_mfma_f32_16x16x32_bf16 v[114:117], v[164:167], v[22:25], v[114:117]
	v_mfma_f32_16x16x32_bf16 v[110:113], v[6:9], v[38:41], v[110:113]
	v_mfma_f32_16x16x32_bf16 v[102:105], v[156:159], v[38:41], v[106:109]
	v_mfma_f32_16x16x32_bf16 v[106:109], v[160:163], v[38:41], v[168:171]
	v_mfma_f32_16x16x32_bf16 v[98:101], v[164:167], v[38:41], v[98:101]
	ds_read_b128 v[22:25], v154 offset:28672
	ds_read_b128 v[122:125], v154 offset:29696
	v_mfma_f32_16x16x32_bf16 v[94:97], v[6:9], v[54:57], v[94:97]
	v_mfma_f32_16x16x32_bf16 v[86:89], v[156:159], v[54:57], v[90:93]
	v_mfma_f32_16x16x32_bf16 v[90:93], v[160:163], v[54:57], v[172:175]
	v_mfma_f32_16x16x32_bf16 v[82:85], v[164:167], v[54:57], v[82:85]
	v_mfma_f32_16x16x32_bf16 v[78:81], v[6:9], v[196:199], v[78:81]
	v_mfma_f32_16x16x32_bf16 v[70:73], v[156:159], v[196:199], v[74:77]
	v_mfma_f32_16x16x32_bf16 v[74:77], v[160:163], v[196:199], v[176:179]
	v_mfma_f32_16x16x32_bf16 v[66:69], v[164:167], v[196:199], v[66:69]
	ds_read_b128 v[126:129], v154 offset:30720
	ds_read_b128 v[168:171], v154 offset:31744
	s_waitcnt lgkmcnt(0)
	v_mfma_f32_16x16x32_bf16 v[62:65], v[6:9], v[22:25], v[62:65]
	v_mfma_f32_16x16x32_bf16 v[54:57], v[156:159], v[22:25], v[58:61]
	v_mfma_f32_16x16x32_bf16 v[58:61], v[160:163], v[22:25], v[180:183]
	v_mfma_f32_16x16x32_bf16 v[50:53], v[164:167], v[22:25], v[50:53]
	v_mfma_f32_16x16x32_bf16 v[46:49], v[6:9], v[122:125], v[46:49]
	v_mfma_f32_16x16x32_bf16 v[38:41], v[156:159], v[122:125], v[42:45]
	v_mfma_f32_16x16x32_bf16 v[42:45], v[160:163], v[122:125], v[188:191]
	v_mfma_f32_16x16x32_bf16 v[34:37], v[164:167], v[122:125], v[34:37]
	v_mfma_f32_16x16x32_bf16 v[30:33], v[6:9], v[126:129], v[30:33]
	v_mfma_f32_16x16x32_bf16 v[22:25], v[156:159], v[126:129], v[26:29]
	v_mfma_f32_16x16x32_bf16 v[26:29], v[160:163], v[126:129], v[192:195]
	v_mfma_f32_16x16x32_bf16 v[18:21], v[164:167], v[126:129], v[18:21]
	v_mfma_f32_16x16x32_bf16 v[14:17], v[6:9], v[168:171], v[14:17]
	v_mfma_f32_16x16x32_bf16 v[6:9], v[156:159], v[168:171], v[10:13]
	v_mfma_f32_16x16x32_bf16 v[10:13], v[160:163], v[168:171], v[146:149]
	v_mfma_f32_16x16x32_bf16 v[2:5], v[164:167], v[168:171], v[2:5]
	s_lshl_b32 s90, s5, 8
	s_waitcnt vmcnt(0)
	s_barrier
; __device__ __forceinline__ float siluf_(float x) { return x * __builtin_amdgcn_rcpf(1.f + __expf(-x)); }
; template <int EPI, int MF>
; __device__ __forceinline__ void gemm_part(const u16* __restrict__ A, int lda, const u16* __restrict__ Bt, int K, int ntn, GemmEpi ep, char* smem,
;                                           int mbase, int mrows) {
;     ...
;     for (int m = 0; m < MF; ++m) {
;       if (EPI == EPI_SWIGLU || (m & 1) == 0) __builtin_amdgcn_sched_barrier(0);
;       const int row = row0 + wr * (16 * MF) + m * 16 + fr;
;       const int cb = col0 + wc * 64 + 4 * fq;
;       float rstd = 1.f;
;       if (EPI != EPI_RESID) { if (ep.rss_in) rstd = rsqrtf(ep.rss_in[row] * (1.f / DM) + 1e-6f); }
;       if (EPI == EPI_SWIGLU) {
; #pragma unroll
;         for (int n = 0; n < 2; ++n) {
;           bf16x4 o;
; #pragma unroll
;           for (int jj = 0; jj < 4; ++jj) o[jj] = (short)f2bf(siluf_(acc[m][n][jj] * rstd) * (acc[m][n + 2][jj] * rstd));
;           *(bf16x4*)(ep.outb + (size_t)row * FF + (col0 >> 1) + wc * 32 + n * 16 + 4 * fq) = o;
;         }
	v_add_u32_e32 v124, s8, v152
	v_lshl_add_u64 v[122:123], v[136:137], 0, s[90:91]
	v_readlane_b32 s2, v252, 9
	v_ashrrev_i32_e32 v125, 31, v124
	v_readlane_b32 s3, v252, 10
	s_nop 1
	v_lshl_add_u64 v[126:127], v[124:125], 2, s[2:3]
	global_load_dword v125, v[126:127], off
	s_waitcnt vmcnt(0)
	v_fmamk_f32 v125, v125, 0x3a800000, v142
	v_cmp_gt_f32_e32 vcc, s69, v125
	v_mul_f32_e32 v128, 0x4b800000, v125
	s_nop 0
	v_cndmask_b32_e32 v125, v125, v128, vcc
	v_rsq_f32_e32 v125, v125
	s_nop 0
	v_mul_f32_e32 v128, 0x45800000, v125
	v_cndmask_b32_e32 v146, v125, v128, vcc
	v_pk_mul_f32 v[148:149], v[210:211], v[146:147] op_sel_hi:[1,0]
	v_pk_mul_f32 v[118:119], v[118:119], v[146:147] op_sel_hi:[1,0]
	v_mul_f32_e32 v125, 0xbfb8aa3b, v148
	v_exp_f32_e32 v125, v125
	v_mad_i64_i32 v[128:129], s[2:3], v124, s33, v[122:123]
	v_pk_mul_f32 v[114:115], v[114:115], v[146:147] op_sel_hi:[1,0]
	v_add_f32_e32 v125, 1.0, v125
	v_rcp_f32_e32 v156, v125
	v_mul_f32_e32 v125, 0xbfb8aa3b, v149
	v_exp_f32_e32 v125, v125
	v_pk_mul_f32 v[116:117], v[116:117], v[146:147] op_sel_hi:[1,0]
	v_add_f32_e32 v125, 1.0, v125
	v_rcp_f32_e32 v157, v125
	s_nop 0
	v_pk_mul_f32 v[148:149], v[148:149], v[156:157]
	v_pk_mul_f32 v[156:157], v[184:185], v[146:147] op_sel_hi:[1,0]
	s_nop 0
	v_pk_mul_f32 v[148:149], v[156:157], v[148:149]
	v_pk_mul_f32 v[156:157], v[212:213], v[146:147] op_sel_hi:[1,0]
	v_cvt_pk_bf16_f32 v148, v148, v149
	v_mul_f32_e32 v125, 0xbfb8aa3b, v156
	v_exp_f32_e32 v125, v125
	s_nop 0
	v_add_f32_e32 v125, 1.0, v125
	v_rcp_f32_e32 v158, v125
	v_mul_f32_e32 v125, 0xbfb8aa3b, v157
	v_exp_f32_e32 v125, v125
	s_nop 0
	v_add_f32_e32 v125, 1.0, v125
	v_rcp_f32_e32 v159, v125
	v_mul_f32_e32 v125, 0xbfb8aa3b, v118
	v_exp_f32_e32 v125, v125
	v_pk_mul_f32 v[156:157], v[156:157], v[158:159]
	v_pk_mul_f32 v[158:159], v[186:187], v[146:147] op_sel_hi:[1,0]
	v_add_f32_e32 v125, 1.0, v125
	v_pk_mul_f32 v[156:157], v[158:159], v[156:157]
	s_nop 0
	v_cvt_pk_bf16_f32 v149, v156, v157
	global_store_dwordx2 v[128:129], v[148:149], off
	v_rcp_f32_e32 v148, v125
	v_mul_f32_e32 v125, 0xbfb8aa3b, v119
	v_exp_f32_e32 v125, v125
	s_nop 0
	v_add_f32_e32 v125, 1.0, v125
	v_rcp_f32_e32 v149, v125
	s_nop 0
	v_pk_mul_f32 v[118:119], v[118:119], v[148:149]
	s_nop 0
	v_pk_mul_f32 v[114:115], v[114:115], v[118:119]
	v_pk_mul_f32 v[118:119], v[120:121], v[146:147] op_sel_hi:[1,0]
	v_cvt_pk_bf16_f32 v114, v114, v115
	v_mul_f32_e32 v115, 0xbfb8aa3b, v118
	v_exp_f32_e32 v115, v115
	s_nop 0
	v_add_f32_e32 v115, 1.0, v115
	v_rcp_f32_e32 v120, v115
	v_mul_f32_e32 v115, 0xbfb8aa3b, v119
	v_exp_f32_e32 v115, v115
	s_nop 0
	v_add_f32_e32 v115, 1.0, v115
	v_rcp_f32_e32 v121, v115
	s_nop 0
	v_pk_mul_f32 v[118:119], v[118:119], v[120:121]
	s_nop 0
	v_pk_mul_f32 v[116:117], v[116:117], v[118:119]
	s_nop 0
	v_cvt_pk_bf16_f32 v115, v116, v117
	global_store_dwordx2 v[128:129], v[114:115], off offset:32
	global_load_dword v115, v[126:127], off offset:64
	v_or_b32_e32 v114, 16, v124
	s_waitcnt vmcnt(0)
	v_fmamk_f32 v115, v115, 0x3a800000, v142
	v_cmp_gt_f32_e32 vcc, s69, v115
	v_mul_f32_e32 v116, 0x4b800000, v115
	s_nop 0
	v_cndmask_b32_e32 v115, v115, v116, vcc
	v_rsq_f32_e32 v115, v115
	s_nop 0
	v_mul_f32_e32 v116, 0x45800000, v115
	v_cndmask_b32_e32 v116, v115, v116, vcc
	v_pk_mul_f32 v[110:111], v[110:111], v[116:117] op_sel_hi:[1,0]
	v_mad_i64_i32 v[114:115], s[2:3], v114, s33, v[122:123]
	v_mul_f32_e32 v117, 0xbfb8aa3b, v110
	v_exp_f32_e32 v117, v117
	s_nop 0
	v_add_f32_e32 v117, 1.0, v117
	v_rcp_f32_e32 v118, v117
	v_mul_f32_e32 v117, 0xbfb8aa3b, v111
	v_exp_f32_e32 v117, v117
	s_nop 0
	v_add_f32_e32 v117, 1.0, v117
	v_rcp_f32_e32 v119, v117
	v_pk_mul_f32 v[106:107], v[106:107], v[116:117] op_sel_hi:[1,0]
	v_pk_mul_f32 v[108:109], v[108:109], v[116:117] op_sel_hi:[1,0]
	v_pk_mul_f32 v[102:103], v[102:103], v[116:117] op_sel_hi:[1,0]
	v_pk_mul_f32 v[110:111], v[110:111], v[118:119]
	v_pk_mul_f32 v[98:99], v[98:99], v[116:117] op_sel_hi:[1,0]
	v_pk_mul_f32 v[106:107], v[106:107], v[110:111]
	v_pk_mul_f32 v[110:111], v[112:113], v[116:117] op_sel_hi:[1,0]
	v_cvt_pk_bf16_f32 v106, v106, v107
	v_mul_f32_e32 v107, 0xbfb8aa3b, v110
	v_exp_f32_e32 v107, v107
	v_pk_mul_f32 v[100:101], v[100:101], v[116:117] op_sel_hi:[1,0]
	v_add_f32_e32 v107, 1.0, v107
	v_rcp_f32_e32 v112, v107
	v_mul_f32_e32 v107, 0xbfb8aa3b, v111
	v_exp_f32_e32 v107, v107
	s_nop 0
	v_add_f32_e32 v107, 1.0, v107
	v_rcp_f32_e32 v113, v107
	s_nop 0
	v_pk_mul_f32 v[110:111], v[110:111], v[112:113]
	s_nop 0
	v_pk_mul_f32 v[108:109], v[108:109], v[110:111]
	s_nop 0
	v_cvt_pk_bf16_f32 v107, v108, v109
	global_store_dwordx2 v[114:115], v[106:107], off
	v_mul_f32_e32 v106, 0xbfb8aa3b, v102
	v_mul_f32_e32 v107, 0xbfb8aa3b, v103
	v_exp_f32_e32 v106, v106
	v_exp_f32_e32 v107, v107
	v_add_f32_e32 v106, 1.0, v106
	v_add_f32_e32 v107, 1.0, v107
	v_rcp_f32_e32 v106, v106
	v_rcp_f32_e32 v107, v107
	s_nop 0
	v_pk_mul_f32 v[102:103], v[102:103], v[106:107]
	s_nop 0
	v_pk_mul_f32 v[98:99], v[98:99], v[102:103]
	v_pk_mul_f32 v[102:103], v[104:105], v[116:117] op_sel_hi:[1,0]
	v_cvt_pk_bf16_f32 v98, v98, v99
	v_mul_f32_e32 v99, 0xbfb8aa3b, v102
	v_exp_f32_e32 v99, v99
	s_nop 0
	v_add_f32_e32 v99, 1.0, v99
	v_rcp_f32_e32 v104, v99
	v_mul_f32_e32 v99, 0xbfb8aa3b, v103
	v_exp_f32_e32 v99, v99
	s_nop 0
	v_add_f32_e32 v99, 1.0, v99
	v_rcp_f32_e32 v105, v99
	s_nop 0
	v_pk_mul_f32 v[102:103], v[102:103], v[104:105]
	s_nop 0
	v_pk_mul_f32 v[100:101], v[100:101], v[102:103]
	s_nop 0
	v_cvt_pk_bf16_f32 v99, v100, v101
	global_store_dwordx2 v[114:115], v[98:99], off offset:32
	global_load_dword v99, v[126:127], off offset:128
	v_or_b32_e32 v98, 32, v124
	s_waitcnt vmcnt(0)
; __device__ __forceinline__ float siluf_(float x) { return x * __builtin_amdgcn_rcpf(1.f + __expf(-x)); }
; template <int EPI, int MF>
; __device__ __forceinline__ void gemm_part(const u16* __restrict__ A, int lda, const u16* __restrict__ Bt, int K, int ntn, GemmEpi ep, char* smem,
;                                           int mbase, int mrows) {
;     ...
;     for (int m = 0; m < MF; ++m) {
;       if (EPI == EPI_SWIGLU || (m & 1) == 0) __builtin_amdgcn_sched_barrier(0);
;       const int row = row0 + wr * (16 * MF) + m * 16 + fr;
;       const int cb = col0 + wc * 64 + 4 * fq;
;       float rstd = 1.f;
;       if (EPI != EPI_RESID) { if (ep.rss_in) rstd = rsqrtf(ep.rss_in[row] * (1.f / DM) + 1e-6f); }
;       if (EPI == EPI_SWIGLU) {
; #pragma unroll
;         for (int n = 0; n < 2; ++n) {
;           bf16x4 o;
; #pragma unroll
;           for (int jj = 0; jj < 4; ++jj) o[jj] = (short)f2bf(siluf_(acc[m][n][jj] * rstd) * (acc[m][n + 2][jj] * rstd));
;           *(bf16x4*)(ep.outb + (size_t)row * FF + (col0 >> 1) + wc * 32 + n * 16 + 4 * fq) = o;
;         }
	v_fmamk_f32 v99, v99, 0x3a800000, v142
	v_cmp_gt_f32_e32 vcc, s69, v99
	v_mul_f32_e32 v100, 0x4b800000, v99
	s_nop 0
	v_cndmask_b32_e32 v99, v99, v100, vcc
	v_rsq_f32_e32 v99, v99
	s_nop 0
	v_mul_f32_e32 v100, 0x45800000, v99
	v_cndmask_b32_e32 v100, v99, v100, vcc
	v_pk_mul_f32 v[94:95], v[94:95], v[100:101] op_sel_hi:[1,0]
	v_mad_i64_i32 v[98:99], s[2:3], v98, s33, v[122:123]
	v_mul_f32_e32 v101, 0xbfb8aa3b, v94
	v_exp_f32_e32 v101, v101
	s_nop 0
	v_add_f32_e32 v101, 1.0, v101
	v_rcp_f32_e32 v102, v101
	v_mul_f32_e32 v101, 0xbfb8aa3b, v95
	v_exp_f32_e32 v101, v101
	s_nop 0
	v_add_f32_e32 v101, 1.0, v101
	v_rcp_f32_e32 v103, v101
	v_pk_mul_f32 v[90:91], v[90:91], v[100:101] op_sel_hi:[1,0]
	v_pk_mul_f32 v[92:93], v[92:93], v[100:101] op_sel_hi:[1,0]
	v_pk_mul_f32 v[86:87], v[86:87], v[100:101] op_sel_hi:[1,0]
	v_pk_mul_f32 v[94:95], v[94:95], v[102:103]
	v_pk_mul_f32 v[82:83], v[82:83], v[100:101] op_sel_hi:[1,0]
	v_pk_mul_f32 v[90:91], v[90:91], v[94:95]
	v_pk_mul_f32 v[94:95], v[96:97], v[100:101] op_sel_hi:[1,0]
	v_cvt_pk_bf16_f32 v90, v90, v91
	v_mul_f32_e32 v91, 0xbfb8aa3b, v94
	v_exp_f32_e32 v91, v91
	v_pk_mul_f32 v[84:85], v[84:85], v[100:101] op_sel_hi:[1,0]
	v_add_f32_e32 v91, 1.0, v91
	v_rcp_f32_e32 v96, v91
	v_mul_f32_e32 v91, 0xbfb8aa3b, v95
	v_exp_f32_e32 v91, v91
	s_nop 0
	v_add_f32_e32 v91, 1.0, v91
	v_rcp_f32_e32 v97, v91
	s_nop 0
	v_pk_mul_f32 v[94:95], v[94:95], v[96:97]
	s_nop 0
	v_pk_mul_f32 v[92:93], v[92:93], v[94:95]
	s_nop 0
	v_cvt_pk_bf16_f32 v91, v92, v93
	global_store_dwordx2 v[98:99], v[90:91], off
	v_mul_f32_e32 v90, 0xbfb8aa3b, v86
	v_mul_f32_e32 v91, 0xbfb8aa3b, v87
	v_exp_f32_e32 v90, v90
	v_exp_f32_e32 v91, v91
	v_add_f32_e32 v90, 1.0, v90
	v_add_f32_e32 v91, 1.0, v91
	v_rcp_f32_e32 v90, v90
	v_rcp_f32_e32 v91, v91
	s_nop 0
	v_pk_mul_f32 v[86:87], v[86:87], v[90:91]
	s_nop 0
	v_pk_mul_f32 v[82:83], v[82:83], v[86:87]
	v_pk_mul_f32 v[86:87], v[88:89], v[100:101] op_sel_hi:[1,0]
	v_cvt_pk_bf16_f32 v82, v82, v83
	v_mul_f32_e32 v83, 0xbfb8aa3b, v86
	v_exp_f32_e32 v83, v83
	s_nop 0
	v_add_f32_e32 v83, 1.0, v83
	v_rcp_f32_e32 v88, v83
	v_mul_f32_e32 v83, 0xbfb8aa3b, v87
	v_exp_f32_e32 v83, v83
	s_nop 0
	v_add_f32_e32 v83, 1.0, v83
	v_rcp_f32_e32 v89, v83
	s_nop 0
	v_pk_mul_f32 v[86:87], v[86:87], v[88:89]
	s_nop 0
	v_pk_mul_f32 v[84:85], v[84:85], v[86:87]
	s_nop 0
	v_cvt_pk_bf16_f32 v83, v84, v85
	global_store_dwordx2 v[98:99], v[82:83], off offset:32
	global_load_dword v83, v[126:127], off offset:192
	v_or_b32_e32 v82, 48, v124
	s_waitcnt vmcnt(0)
	v_fmamk_f32 v83, v83, 0x3a800000, v142
	v_cmp_gt_f32_e32 vcc, s69, v83
	v_mul_f32_e32 v84, 0x4b800000, v83
	s_nop 0
	v_cndmask_b32_e32 v83, v83, v84, vcc
	v_rsq_f32_e32 v83, v83
	s_nop 0
	v_mul_f32_e32 v84, 0x45800000, v83
	v_cndmask_b32_e32 v84, v83, v84, vcc
	v_pk_mul_f32 v[78:79], v[78:79], v[84:85] op_sel_hi:[1,0]
	v_mad_i64_i32 v[82:83], s[2:3], v82, s33, v[122:123]
	v_mul_f32_e32 v85, 0xbfb8aa3b, v78
	v_exp_f32_e32 v85, v85
	s_nop 0
	v_add_f32_e32 v85, 1.0, v85
	v_rcp_f32_e32 v86, v85
	v_mul_f32_e32 v85, 0xbfb8aa3b, v79
	v_exp_f32_e32 v85, v85
	s_nop 0
	v_add_f32_e32 v85, 1.0, v85
	v_rcp_f32_e32 v87, v85
	v_pk_mul_f32 v[74:75], v[74:75], v[84:85] op_sel_hi:[1,0]
	v_pk_mul_f32 v[76:77], v[76:77], v[84:85] op_sel_hi:[1,0]
	v_pk_mul_f32 v[70:71], v[70:71], v[84:85] op_sel_hi:[1,0]
	v_pk_mul_f32 v[78:79], v[78:79], v[86:87]
	v_pk_mul_f32 v[66:67], v[66:67], v[84:85] op_sel_hi:[1,0]
	v_pk_mul_f32 v[74:75], v[74:75], v[78:79]
	v_pk_mul_f32 v[78:79], v[80:81], v[84:85] op_sel_hi:[1,0]
	v_cvt_pk_bf16_f32 v74, v74, v75
	v_mul_f32_e32 v75, 0xbfb8aa3b, v78
	v_exp_f32_e32 v75, v75
	v_pk_mul_f32 v[68:69], v[68:69], v[84:85] op_sel_hi:[1,0]
	v_add_f32_e32 v75, 1.0, v75
	v_rcp_f32_e32 v80, v75
	v_mul_f32_e32 v75, 0xbfb8aa3b, v79
	v_exp_f32_e32 v75, v75
	s_nop 0
	v_add_f32_e32 v75, 1.0, v75
	v_rcp_f32_e32 v81, v75
	s_nop 0
	v_pk_mul_f32 v[78:79], v[78:79], v[80:81]
	s_nop 0
	v_pk_mul_f32 v[76:77], v[76:77], v[78:79]
	s_nop 0
	v_cvt_pk_bf16_f32 v75, v76, v77
	global_store_dwordx2 v[82:83], v[74:75], off
	v_mul_f32_e32 v74, 0xbfb8aa3b, v70
	v_mul_f32_e32 v75, 0xbfb8aa3b, v71
	v_exp_f32_e32 v74, v74
	v_exp_f32_e32 v75, v75
	v_add_f32_e32 v74, 1.0, v74
	v_add_f32_e32 v75, 1.0, v75
	v_rcp_f32_e32 v74, v74
	v_rcp_f32_e32 v75, v75
	s_nop 0
	v_pk_mul_f32 v[70:71], v[70:71], v[74:75]
	s_nop 0
	v_pk_mul_f32 v[66:67], v[66:67], v[70:71]
	v_pk_mul_f32 v[70:71], v[72:73], v[84:85] op_sel_hi:[1,0]
	v_cvt_pk_bf16_f32 v66, v66, v67
	v_mul_f32_e32 v67, 0xbfb8aa3b, v70
	v_exp_f32_e32 v67, v67
	s_nop 0
	v_add_f32_e32 v67, 1.0, v67
	v_rcp_f32_e32 v72, v67
	v_mul_f32_e32 v67, 0xbfb8aa3b, v71
	v_exp_f32_e32 v67, v67
	s_nop 0
	v_add_f32_e32 v67, 1.0, v67
	v_rcp_f32_e32 v73, v67
	s_nop 0
	v_pk_mul_f32 v[70:71], v[70:71], v[72:73]
	s_nop 0
	v_pk_mul_f32 v[68:69], v[68:69], v[70:71]
	s_nop 0
	v_cvt_pk_bf16_f32 v67, v68, v69
	global_store_dwordx2 v[82:83], v[66:67], off offset:32
	global_load_dword v67, v[126:127], off offset:256
	v_or_b32_e32 v66, 64, v124
	s_waitcnt vmcnt(0)
; __device__ __forceinline__ float siluf_(float x) { return x * __builtin_amdgcn_rcpf(1.f + __expf(-x)); }
; template <int EPI, int MF>
; __device__ __forceinline__ void gemm_part(const u16* __restrict__ A, int lda, const u16* __restrict__ Bt, int K, int ntn, GemmEpi ep, char* smem,
;                                           int mbase, int mrows) {
;     ...
;     for (int m = 0; m < MF; ++m) {
;       if (EPI == EPI_SWIGLU || (m & 1) == 0) __builtin_amdgcn_sched_barrier(0);
;       const int row = row0 + wr * (16 * MF) + m * 16 + fr;
;       const int cb = col0 + wc * 64 + 4 * fq;
;       float rstd = 1.f;
;       if (EPI != EPI_RESID) { if (ep.rss_in) rstd = rsqrtf(ep.rss_in[row] * (1.f / DM) + 1e-6f); }
;       if (EPI == EPI_SWIGLU) {
; #pragma unroll
;         for (int n = 0; n < 2; ++n) {
;           bf16x4 o;
; #pragma unroll
;           for (int jj = 0; jj < 4; ++jj) o[jj] = (short)f2bf(siluf_(acc[m][n][jj] * rstd) * (acc[m][n + 2][jj] * rstd));
;           *(bf16x4*)(ep.outb + (size_t)row * FF + (col0 >> 1) + wc * 32 + n * 16 + 4 * fq) = o;
;         }
	v_fmamk_f32 v67, v67, 0x3a800000, v142
	v_cmp_gt_f32_e32 vcc, s69, v67
	v_mul_f32_e32 v68, 0x4b800000, v67
	s_nop 0
	v_cndmask_b32_e32 v67, v67, v68, vcc
	v_rsq_f32_e32 v67, v67
	s_nop 0
	v_mul_f32_e32 v68, 0x45800000, v67
	v_cndmask_b32_e32 v68, v67, v68, vcc
	v_pk_mul_f32 v[62:63], v[62:63], v[68:69] op_sel_hi:[1,0]
	v_mad_i64_i32 v[66:67], s[2:3], v66, s33, v[122:123]
	v_mul_f32_e32 v69, 0xbfb8aa3b, v62
	v_exp_f32_e32 v69, v69
	s_nop 0
	v_add_f32_e32 v69, 1.0, v69
	v_rcp_f32_e32 v70, v69
	v_mul_f32_e32 v69, 0xbfb8aa3b, v63
	v_exp_f32_e32 v69, v69
	s_nop 0
	v_add_f32_e32 v69, 1.0, v69
	v_rcp_f32_e32 v71, v69
	v_pk_mul_f32 v[58:59], v[58:59], v[68:69] op_sel_hi:[1,0]
	v_pk_mul_f32 v[60:61], v[60:61], v[68:69] op_sel_hi:[1,0]
	v_pk_mul_f32 v[54:55], v[54:55], v[68:69] op_sel_hi:[1,0]
	v_pk_mul_f32 v[62:63], v[62:63], v[70:71]
	v_pk_mul_f32 v[50:51], v[50:51], v[68:69] op_sel_hi:[1,0]
	v_pk_mul_f32 v[58:59], v[58:59], v[62:63]
	v_pk_mul_f32 v[62:63], v[64:65], v[68:69] op_sel_hi:[1,0]
	v_cvt_pk_bf16_f32 v58, v58, v59
	v_mul_f32_e32 v59, 0xbfb8aa3b, v62
	v_exp_f32_e32 v59, v59
	v_pk_mul_f32 v[52:53], v[52:53], v[68:69] op_sel_hi:[1,0]
	v_add_f32_e32 v59, 1.0, v59
	v_rcp_f32_e32 v64, v59
	v_mul_f32_e32 v59, 0xbfb8aa3b, v63
	v_exp_f32_e32 v59, v59
	s_nop 0
	v_add_f32_e32 v59, 1.0, v59
	v_rcp_f32_e32 v65, v59
	s_nop 0
	v_pk_mul_f32 v[62:63], v[62:63], v[64:65]
	s_nop 0
	v_pk_mul_f32 v[60:61], v[60:61], v[62:63]
	s_nop 0
	v_cvt_pk_bf16_f32 v59, v60, v61
	global_store_dwordx2 v[66:67], v[58:59], off
	v_mul_f32_e32 v58, 0xbfb8aa3b, v54
	v_mul_f32_e32 v59, 0xbfb8aa3b, v55
	v_exp_f32_e32 v58, v58
	v_exp_f32_e32 v59, v59
	v_add_f32_e32 v58, 1.0, v58
	v_add_f32_e32 v59, 1.0, v59
	v_rcp_f32_e32 v58, v58
	v_rcp_f32_e32 v59, v59
	s_nop 0
	v_pk_mul_f32 v[54:55], v[54:55], v[58:59]
	s_nop 0
	v_pk_mul_f32 v[50:51], v[50:51], v[54:55]
	v_pk_mul_f32 v[54:55], v[56:57], v[68:69] op_sel_hi:[1,0]
	v_cvt_pk_bf16_f32 v50, v50, v51
	v_mul_f32_e32 v51, 0xbfb8aa3b, v54
	v_exp_f32_e32 v51, v51
	s_nop 0
	v_add_f32_e32 v51, 1.0, v51
	v_rcp_f32_e32 v56, v51
	v_mul_f32_e32 v51, 0xbfb8aa3b, v55
	v_exp_f32_e32 v51, v51
	s_nop 0
	v_add_f32_e32 v51, 1.0, v51
	v_rcp_f32_e32 v57, v51
	s_nop 0
	v_pk_mul_f32 v[54:55], v[54:55], v[56:57]
	s_nop 0
	v_pk_mul_f32 v[52:53], v[52:53], v[54:55]
	s_nop 0
	v_cvt_pk_bf16_f32 v51, v52, v53
	global_store_dwordx2 v[66:67], v[50:51], off offset:32
	global_load_dword v51, v[126:127], off offset:320
	v_or_b32_e32 v50, 0x50, v124
	s_waitcnt vmcnt(0)
	v_fmamk_f32 v51, v51, 0x3a800000, v142
	v_cmp_gt_f32_e32 vcc, s69, v51
	v_mul_f32_e32 v52, 0x4b800000, v51
	s_nop 0
	v_cndmask_b32_e32 v51, v51, v52, vcc
	v_rsq_f32_e32 v51, v51
	s_nop 0
	v_mul_f32_e32 v52, 0x45800000, v51
	v_cndmask_b32_e32 v52, v51, v52, vcc
	v_pk_mul_f32 v[46:47], v[46:47], v[52:53] op_sel_hi:[1,0]
	v_mad_i64_i32 v[50:51], s[2:3], v50, s33, v[122:123]
	v_mul_f32_e32 v53, 0xbfb8aa3b, v46
	v_exp_f32_e32 v53, v53
	s_nop 0
	v_add_f32_e32 v53, 1.0, v53
	v_rcp_f32_e32 v54, v53
	v_mul_f32_e32 v53, 0xbfb8aa3b, v47
	v_exp_f32_e32 v53, v53
	s_nop 0
	v_add_f32_e32 v53, 1.0, v53
	v_rcp_f32_e32 v55, v53
	v_pk_mul_f32 v[42:43], v[42:43], v[52:53] op_sel_hi:[1,0]
	v_pk_mul_f32 v[44:45], v[44:45], v[52:53] op_sel_hi:[1,0]
	v_pk_mul_f32 v[38:39], v[38:39], v[52:53] op_sel_hi:[1,0]
	v_pk_mul_f32 v[46:47], v[46:47], v[54:55]
	v_pk_mul_f32 v[34:35], v[34:35], v[52:53] op_sel_hi:[1,0]
	v_pk_mul_f32 v[42:43], v[42:43], v[46:47]
	v_pk_mul_f32 v[46:47], v[48:49], v[52:53] op_sel_hi:[1,0]
	v_cvt_pk_bf16_f32 v42, v42, v43
	v_mul_f32_e32 v43, 0xbfb8aa3b, v46
	v_exp_f32_e32 v43, v43
	v_pk_mul_f32 v[36:37], v[36:37], v[52:53] op_sel_hi:[1,0]
	v_add_f32_e32 v43, 1.0, v43
	v_rcp_f32_e32 v48, v43
	v_mul_f32_e32 v43, 0xbfb8aa3b, v47
	v_exp_f32_e32 v43, v43
	s_nop 0
	v_add_f32_e32 v43, 1.0, v43
	v_rcp_f32_e32 v49, v43
	s_nop 0
	v_pk_mul_f32 v[46:47], v[46:47], v[48:49]
	s_nop 0
	v_pk_mul_f32 v[44:45], v[44:45], v[46:47]
	s_nop 0
	v_cvt_pk_bf16_f32 v43, v44, v45
	global_store_dwordx2 v[50:51], v[42:43], off
	v_mul_f32_e32 v42, 0xbfb8aa3b, v38
	v_mul_f32_e32 v43, 0xbfb8aa3b, v39
	v_exp_f32_e32 v42, v42
	v_exp_f32_e32 v43, v43
	v_add_f32_e32 v42, 1.0, v42
	v_add_f32_e32 v43, 1.0, v43
	v_rcp_f32_e32 v42, v42
	v_rcp_f32_e32 v43, v43
	s_nop 0
	v_pk_mul_f32 v[38:39], v[38:39], v[42:43]
	s_nop 0
	v_pk_mul_f32 v[34:35], v[34:35], v[38:39]
	v_pk_mul_f32 v[38:39], v[40:41], v[52:53] op_sel_hi:[1,0]
	v_cvt_pk_bf16_f32 v34, v34, v35
	v_mul_f32_e32 v35, 0xbfb8aa3b, v38
	v_exp_f32_e32 v35, v35
	s_nop 0
	v_add_f32_e32 v35, 1.0, v35
	v_rcp_f32_e32 v40, v35
	v_mul_f32_e32 v35, 0xbfb8aa3b, v39
	v_exp_f32_e32 v35, v35
	s_nop 0
	v_add_f32_e32 v35, 1.0, v35
	v_rcp_f32_e32 v41, v35
	s_nop 0
	v_pk_mul_f32 v[38:39], v[38:39], v[40:41]
	s_nop 0
	v_pk_mul_f32 v[36:37], v[36:37], v[38:39]
	s_nop 0
	v_cvt_pk_bf16_f32 v35, v36, v37
	global_store_dwordx2 v[50:51], v[34:35], off offset:32
	global_load_dword v35, v[126:127], off offset:384
	v_or_b32_e32 v34, 0x60, v124
	s_waitcnt vmcnt(0)
; __device__ __forceinline__ float siluf_(float x) { return x * __builtin_amdgcn_rcpf(1.f + __expf(-x)); }
; template <int EPI, int MF>
; __device__ __forceinline__ void gemm_part(const u16* __restrict__ A, int lda, const u16* __restrict__ Bt, int K, int ntn, GemmEpi ep, char* smem,
;                                           int mbase, int mrows) {
;     ...
;     for (int m = 0; m < MF; ++m) {
;       if (EPI == EPI_SWIGLU || (m & 1) == 0) __builtin_amdgcn_sched_barrier(0);
;       const int row = row0 + wr * (16 * MF) + m * 16 + fr;
;       const int cb = col0 + wc * 64 + 4 * fq;
;       float rstd = 1.f;
;       if (EPI != EPI_RESID) { if (ep.rss_in) rstd = rsqrtf(ep.rss_in[row] * (1.f / DM) + 1e-6f); }
;       if (EPI == EPI_SWIGLU) {
; #pragma unroll
;         for (int n = 0; n < 2; ++n) {
;           bf16x4 o;
; #pragma unroll
;           for (int jj = 0; jj < 4; ++jj) o[jj] = (short)f2bf(siluf_(acc[m][n][jj] * rstd) * (acc[m][n + 2][jj] * rstd));
;           *(bf16x4*)(ep.outb + (size_t)row * FF + (col0 >> 1) + wc * 32 + n * 16 + 4 * fq) = o;
;         }
	v_fmamk_f32 v35, v35, 0x3a800000, v142
	v_cmp_gt_f32_e32 vcc, s69, v35
	v_mul_f32_e32 v36, 0x4b800000, v35
	s_nop 0
	v_cndmask_b32_e32 v35, v35, v36, vcc
	v_rsq_f32_e32 v35, v35
	s_nop 0
	v_mul_f32_e32 v36, 0x45800000, v35
	v_cndmask_b32_e32 v36, v35, v36, vcc
	v_pk_mul_f32 v[30:31], v[30:31], v[36:37] op_sel_hi:[1,0]
	v_mad_i64_i32 v[34:35], s[2:3], v34, s33, v[122:123]
	v_mul_f32_e32 v37, 0xbfb8aa3b, v30
	v_exp_f32_e32 v37, v37
	s_nop 0
	v_add_f32_e32 v37, 1.0, v37
	v_rcp_f32_e32 v38, v37
	v_mul_f32_e32 v37, 0xbfb8aa3b, v31
	v_exp_f32_e32 v37, v37
	s_nop 0
	v_add_f32_e32 v37, 1.0, v37
	v_rcp_f32_e32 v39, v37
	v_pk_mul_f32 v[26:27], v[26:27], v[36:37] op_sel_hi:[1,0]
	v_pk_mul_f32 v[28:29], v[28:29], v[36:37] op_sel_hi:[1,0]
	v_pk_mul_f32 v[22:23], v[22:23], v[36:37] op_sel_hi:[1,0]
	v_pk_mul_f32 v[30:31], v[30:31], v[38:39]
	v_pk_mul_f32 v[18:19], v[18:19], v[36:37] op_sel_hi:[1,0]
	v_pk_mul_f32 v[26:27], v[26:27], v[30:31]
	v_pk_mul_f32 v[30:31], v[32:33], v[36:37] op_sel_hi:[1,0]
	v_cvt_pk_bf16_f32 v26, v26, v27
	v_mul_f32_e32 v27, 0xbfb8aa3b, v30
	v_exp_f32_e32 v27, v27
	v_pk_mul_f32 v[20:21], v[20:21], v[36:37] op_sel_hi:[1,0]
	v_add_f32_e32 v27, 1.0, v27
	v_rcp_f32_e32 v32, v27
	v_mul_f32_e32 v27, 0xbfb8aa3b, v31
	v_exp_f32_e32 v27, v27
	s_nop 0
	v_add_f32_e32 v27, 1.0, v27
	v_rcp_f32_e32 v33, v27
	s_nop 0
	v_pk_mul_f32 v[30:31], v[30:31], v[32:33]
	s_nop 0
	v_pk_mul_f32 v[28:29], v[28:29], v[30:31]
	s_nop 0
	v_cvt_pk_bf16_f32 v27, v28, v29
	global_store_dwordx2 v[34:35], v[26:27], off
	v_mul_f32_e32 v26, 0xbfb8aa3b, v22
	v_mul_f32_e32 v27, 0xbfb8aa3b, v23
	v_exp_f32_e32 v26, v26
	v_exp_f32_e32 v27, v27
	v_add_f32_e32 v26, 1.0, v26
	v_add_f32_e32 v27, 1.0, v27
	v_rcp_f32_e32 v26, v26
	v_rcp_f32_e32 v27, v27
	s_nop 0
	v_pk_mul_f32 v[22:23], v[22:23], v[26:27]
	s_nop 0
	v_pk_mul_f32 v[18:19], v[18:19], v[22:23]
	v_pk_mul_f32 v[22:23], v[24:25], v[36:37] op_sel_hi:[1,0]
	v_cvt_pk_bf16_f32 v18, v18, v19
	v_mul_f32_e32 v19, 0xbfb8aa3b, v22
	v_exp_f32_e32 v19, v19
	s_nop 0
	v_add_f32_e32 v19, 1.0, v19
	v_rcp_f32_e32 v24, v19
	v_mul_f32_e32 v19, 0xbfb8aa3b, v23
	v_exp_f32_e32 v19, v19
	s_nop 0
	v_add_f32_e32 v19, 1.0, v19
	v_rcp_f32_e32 v25, v19
	s_nop 0
	v_pk_mul_f32 v[22:23], v[22:23], v[24:25]
	s_nop 0
	v_pk_mul_f32 v[20:21], v[20:21], v[22:23]
	s_nop 0
	v_cvt_pk_bf16_f32 v19, v20, v21
	global_store_dwordx2 v[34:35], v[18:19], off offset:32
	global_load_dword v19, v[126:127], off offset:448
	v_or_b32_e32 v18, 0x70, v124
	s_waitcnt vmcnt(0)
	v_fmamk_f32 v19, v19, 0x3a800000, v142
	v_cmp_gt_f32_e32 vcc, s69, v19
	v_mul_f32_e32 v20, 0x4b800000, v19
	s_nop 0
	v_cndmask_b32_e32 v19, v19, v20, vcc
	v_rsq_f32_e32 v19, v19
	s_nop 0
	v_mul_f32_e32 v20, 0x45800000, v19
	v_cndmask_b32_e32 v20, v19, v20, vcc
	v_pk_mul_f32 v[14:15], v[14:15], v[20:21] op_sel_hi:[1,0]
	v_mad_i64_i32 v[18:19], s[2:3], v18, s33, v[122:123]
	v_mul_f32_e32 v21, 0xbfb8aa3b, v14
	v_exp_f32_e32 v21, v21
	s_nop 0
	v_add_f32_e32 v21, 1.0, v21
	v_rcp_f32_e32 v22, v21
	v_mul_f32_e32 v21, 0xbfb8aa3b, v15
	v_exp_f32_e32 v21, v21
	s_nop 0
	v_add_f32_e32 v21, 1.0, v21
	v_rcp_f32_e32 v23, v21
	v_pk_mul_f32 v[10:11], v[10:11], v[20:21] op_sel_hi:[1,0]
	v_pk_mul_f32 v[12:13], v[12:13], v[20:21] op_sel_hi:[1,0]
	v_pk_mul_f32 v[6:7], v[6:7], v[20:21] op_sel_hi:[1,0]
	v_pk_mul_f32 v[14:15], v[14:15], v[22:23]
	v_pk_mul_f32 v[2:3], v[2:3], v[20:21] op_sel_hi:[1,0]
	v_pk_mul_f32 v[10:11], v[10:11], v[14:15]
	v_pk_mul_f32 v[14:15], v[16:17], v[20:21] op_sel_hi:[1,0]
	v_cvt_pk_bf16_f32 v10, v10, v11
	v_mul_f32_e32 v11, 0xbfb8aa3b, v14
	v_exp_f32_e32 v11, v11
	v_pk_mul_f32 v[4:5], v[4:5], v[20:21] op_sel_hi:[1,0]
	v_add_f32_e32 v11, 1.0, v11
	v_rcp_f32_e32 v16, v11
	v_mul_f32_e32 v11, 0xbfb8aa3b, v15
	v_exp_f32_e32 v11, v11
	s_nop 0
	v_add_f32_e32 v11, 1.0, v11
	v_rcp_f32_e32 v17, v11
	s_nop 0
	v_pk_mul_f32 v[14:15], v[14:15], v[16:17]
	s_nop 0
	v_pk_mul_f32 v[12:13], v[12:13], v[14:15]
	s_nop 0
	v_cvt_pk_bf16_f32 v11, v12, v13
	global_store_dwordx2 v[18:19], v[10:11], off
	v_mul_f32_e32 v10, 0xbfb8aa3b, v6
	v_mul_f32_e32 v11, 0xbfb8aa3b, v7
	v_exp_f32_e32 v10, v10
	v_exp_f32_e32 v11, v11
	v_add_f32_e32 v10, 1.0, v10
	v_add_f32_e32 v11, 1.0, v11
	v_rcp_f32_e32 v10, v10
	v_rcp_f32_e32 v11, v11
	s_nop 0
	v_pk_mul_f32 v[6:7], v[6:7], v[10:11]
	s_nop 0
	v_pk_mul_f32 v[2:3], v[2:3], v[6:7]
	v_pk_mul_f32 v[6:7], v[8:9], v[20:21] op_sel_hi:[1,0]
	v_cvt_pk_bf16_f32 v2, v2, v3
	v_mul_f32_e32 v3, 0xbfb8aa3b, v6
	v_exp_f32_e32 v3, v3
	s_nop 0
	v_add_f32_e32 v3, 1.0, v3
	v_rcp_f32_e32 v8, v3
	v_mul_f32_e32 v3, 0xbfb8aa3b, v7
	v_exp_f32_e32 v3, v3
	s_nop 0
	v_add_f32_e32 v3, 1.0, v3
	v_rcp_f32_e32 v9, v3
	s_nop 0
	v_pk_mul_f32 v[6:7], v[6:7], v[8:9]
	s_nop 0
	v_pk_mul_f32 v[4:5], v[4:5], v[6:7]
	s_nop 0
	v_cvt_pk_bf16_f32 v3, v4, v5
	global_store_dwordx2 v[18:19], v[2:3], off offset:32
	s_branch .LBB0_1944

; __device__ __forceinline__ int opaque_tid() { int t = threadIdx.x; asm volatile("" : "+v"(t)); return t; }
; template <int EPI, int MF>
; __device__ __forceinline__ void gemm_part(const u16* __restrict__ A, int lda, const u16* __restrict__ Bt, int K, int ntn, GemmEpi ep, char* smem,
;                                           int mbase, int mrows) {
;   const int tid = opaque_tid(), lane = tid & 63, wid = tid >> 6, wr = wid >> 1, wc = wid & 1, fr = lane & 15, fq = lane >> 4;
;   constexpr int BM = 32 * MF;
;   constexpr int STG = BM * 32 + 4096;
;   constexpr int NA = MF / 2;
;   u16* const sbase = (u16*)smem;
;   const int ntm = mrows / BM;
;   const int total = ntm * ntn;
;   const int nk = K / 32;
;   const int nbx = (MF == 2) ? (int)gridDim.x : (int)(gridDim.x >> 3);
;   const int xcd = (MF == 2) ? 0 : (int)(blockIdx.x & 7), li = (MF == 2) ? (int)blockIdx.x : (int)(blockIdx.x >> 3);
;   for (int q = xcd; q * nbx < total; q += (MF == 2) ? 1 : 8) {
;     const int L = q * nbx + li;
;     if (L >= total) continue;
;     const int g = L / (8 * ntn), rr = L % (8 * ntn);
;     const int rows = min(8, ntm - 8 * g);
;     const int tm = 8 * g + rr % rows, tn = rr / rows;
;     const int row0 = mbase + tm * BM, col0 = tn * 128;
;     f32x4 acc[MF][4];
; #pragma unroll
;     for (int m = 0; m < MF; ++m)
; #pragma unroll
;       for (int n = 0; n < 4; ++n) acc[m][n] = (f32x4){0.f, 0.f, 0.f, 0.f};
;     const u16* gA = A + (size_t)(row0 + (tid >> 2)) * lda + (tid & 3) * 8;
;     const u16* gB = Bt + (size_t)(col0 + (tid >> 2)) * K + (tid & 3) * 8;
.LBB0_1992:
	s_or_b64 exec, exec, s[2:3]
	v_readlane_b32 s2, v254, 63
	v_readlane_b32 s3, v252, 0
	s_and_b64 s[2:3], s[2:3], exec
	v_readlane_b32 s2, v252, 3
	v_readlane_b32 s3, v252, 4
	s_barrier
	s_load_dwordx2 s[16:17], s[2:3], 0x108
	v_readlane_b32 s2, v252, 7
	v_readlane_b32 s3, v252, 8
	s_cselect_b32 s15, s45, 0
	s_cselect_b32 s14, s44, 0
	v_mov_b32_e32 v2, v140
	s_and_b64 vcc, exec, s[2:3]
	s_cbranch_vccnz .LBB0_2126
	v_lshlrev_b32_e32 v7, 4, v2
	v_bfe_u32 v3, v2, 4, 2
	v_lshrrev_b32_e32 v100, 4, v140
	v_sub_u32_e32 v100, 0, v100
	v_xor_b32_e32 v100, v100, v140
	v_and_b32_e32 v100, 3, v100
	v_lshlrev_b32_e32 v4, 4, v100
	v_mov_b32_e32 v5, v0
	v_bfe_u32 v6, v2, 6, 1
	v_lshl_add_u64 v[130:131], s[46:47], 0, v[4:5]
	s_waitcnt lgkmcnt(0)
	v_lshl_add_u64 v[132:133], s[16:17], 0, v[4:5]
	v_lshlrev_b32_e32 v4, 2, v3
	s_cmp_lg_u64 s[14:15], 0
	v_lshlrev_b32_e32 v155, 3, v3
	v_lshl_or_b32 v157, v6, 6, v4
	s_cselect_b64 s[2:3], -1, 0
	v_cmp_eq_u32_e64 s[8:9], 0, v3
	v_lshlrev_b32_e32 v158, 12, v6
	v_lshlrev_b32_e32 v4, 6, v2
	s_add_i32 s4, 0, 0x10000
	v_lshrrev_b32_e32 v101, 2, v140
	v_sub_u32_e32 v101, 0, v101
	v_lshrrev_b32_e32 v3, 4, v140
	v_xor_b32_e32 v101, v101, v3
	v_and_b32_e32 v101, 3, v101
	v_lshlrev_b32_e32 v3, 4, v101
	v_ashrrev_i32_e32 v1, 2, v2
	v_and_b32_e32 v156, 0xffffff8f, v2
	v_and_b32_e32 v159, 0x3c0, v4
	v_and_b32_e32 v160, 0xffffe3c0, v4
	v_add3_u32 v4, s4, v3, v158
	v_add_u32_e32 v161, 0, v3
	v_and_b32_e32 v2, 3, v2
	v_readlane_b32 s4, v254, 2
	v_add_u32_e32 v154, 0, v7
	v_add_u32_e32 v162, v161, v160
	v_lshlrev_b32_e32 v134, 4, v100
	v_mov_b32_e32 v135, v0
	v_add_u32_e32 v163, s4, v1
	v_or_b32_e32 v164, v158, v159
	v_add_u32_e32 v165, v4, v159
	v_readlane_b32 s18, v254, 1
	v_readlane_b32 s19, v254, 0
	v_readlane_b32 s4, v253, 56
	v_readlane_b32 s20, v253, 9
	s_branch .LBB0_1996

; #define MFMA(a, b, c) __builtin_amdgcn_mfma_f32_16x16x32_bf16((a), (b), (c), 0, 0, 0)
; template <int EPI, int MF>
; __device__ __forceinline__ void gemm_part(const u16* __restrict__ A, int lda, const u16* __restrict__ Bt, int K, int ntn, GemmEpi ep, char* smem,
;                                           int mbase, int mrows) {
;     ...
;     GEMM_ISSUE(0);
;     GEMM_ISSUE(1);
;     for (int kt = 0; kt < nk; ++kt) {
;       if (kt + 1 < nk) {
;         if (MF == 8) asm volatile("s_waitcnt vmcnt(6)" ::: "memory");
;         else asm volatile("s_waitcnt vmcnt(3)" ::: "memory");
;       } else asm volatile("s_waitcnt vmcnt(0)" ::: "memory");
;       asm volatile("s_waitcnt lgkmcnt(0)" ::: "memory");
;       __builtin_amdgcn_s_barrier();
;       const u16* a_ = sbase + (kt % 3) * STG;
;       const u16* b_ = a_ + BM * 32;
;       bf16x8 bfr[4], afc[2], afn[2];
;       const u16* ap_ = a_ + (wr * (16 * MF) + fr) * 32 + fq * 8;
; #pragma unroll
;       for (int n = 0; n < 4; ++n) bfr[n] = rd_std(b_ + (wc * 64 + n * 16 + fr) * 32 + fq * 8);
;       afc[0] = rd_std(ap_); afc[1] = rd_std(ap_ + 16 * 32);
;       __builtin_amdgcn_sched_barrier(0);
;       if (kt + 2 < nk) GEMM_ISSUE(kt + 2);
;       __builtin_amdgcn_sched_barrier(0);
; #pragma unroll
;       for (int mh = 0; mh < MF / 2; ++mh) {
;         if (mh + 1 < MF / 2) {
;           afn[0] = rd_std(ap_ + ((mh + 1) * 2) * 16 * 32);
;           afn[1] = rd_std(ap_ + ((mh + 1) * 2 + 1) * 16 * 32);
;         }
;         __builtin_amdgcn_sched_barrier(0);
; #pragma unroll
;         for (int m = 0; m < 2; ++m)
; #pragma unroll
;           for (int n = 0; n < 4; ++n) acc[mh * 2 + m][n] = MFMA(bfr[n], afc[m], acc[mh * 2 + m][n]);
;         __builtin_amdgcn_sched_barrier(0);
;         afc[0] = afn[0]; afc[1] = afn[1];
;       }
.LBB0_1998:
	s_mul_hi_u32 s21, s13, 0xaaaaaaab
	s_lshr_b32 s21, s21, 1
	s_mul_i32 s21, s21, 0x12000
	v_add_u32_e32 v146, s5, v161
	v_subrev_u32_e32 v147, s21, v164
	s_waitcnt vmcnt(6)
	v_subrev_u32_e32 v148, s21, v160
	v_add_u32_e32 v170, v146, v147
	s_waitcnt lgkmcnt(0)
	s_barrier
	v_add_u32_e32 v190, v146, v148
	ds_read_b128 v[146:149], v170 offset:16384
	ds_read_b128 v[150:153], v170 offset:17408
	ds_read_b128 v[166:169], v170 offset:18432
	ds_read_b128 v[170:173], v170 offset:19456
	ds_read_b128 v[174:177], v190
	ds_read_b128 v[178:181], v190 offset:1024
	s_mul_hi_u32 s21, s12, 0xaaaaaaab
	s_add_i32 s13, s13, 1
	s_lshr_b32 s21, s21, 1
	s_mul_i32 s21, s21, 0x12000
	s_sub_i32 s21, s5, s21
	s_add_i32 s22, s21, 0xc000
	v_add_u32_e32 v186, s22, v154
	v_lshl_add_u64 v[182:183], v[136:137], 0, v[134:135]
	v_readfirstlane_b32 s22, v186
	s_mov_b32 m0, s22
	s_add_i32 s22, s21, 0xd000
	v_add_u32_e32 v186, s22, v154
	v_lshl_add_u64 v[184:185], v[182:183], 0, s[74:75]
	v_readfirstlane_b32 s22, v186
	global_load_lds_dwordx4 v[184:185], off
	s_mov_b32 m0, s22
	s_add_i32 s22, s21, 0xe000
	v_add_u32_e32 v186, s22, v154
	v_lshl_add_u64 v[184:185], v[182:183], 0, s[56:57]
	v_readfirstlane_b32 s22, v186
	global_load_lds_dwordx4 v[184:185], off
	v_lshl_add_u64 v[184:185], v[182:183], 0, s[58:59]
	s_mov_b32 m0, s22
	s_add_i32 s22, s21, 0xf000
	global_load_lds_dwordx4 v[184:185], off
	v_add_u32_e32 v184, s22, v154
	v_lshl_add_u64 v[182:183], v[182:183], 0, s[86:87]
	v_readfirstlane_b32 s22, v184
	s_mov_b32 m0, s22
	s_add_i32 s22, s21, 0x10000
	v_add_u32_e32 v186, s22, v154
	global_load_lds_dwordx4 v[182:183], off
	v_lshl_add_u64 v[182:183], v[138:139], 0, v[134:135]
	v_readfirstlane_b32 s22, v186
	v_lshl_add_u64 v[184:185], v[182:183], 0, s[74:75]
	s_mov_b32 m0, s22
	s_add_i32 s21, s21, 0x11000
	global_load_lds_dwordx4 v[184:185], off
	v_add_u32_e32 v184, s21, v154
	v_lshl_add_u64 v[182:183], v[182:183], 0, s[56:57]
	v_readfirstlane_b32 s21, v184
	s_mov_b32 m0, s21
	s_nop 0
	global_load_lds_dwordx4 v[182:183], off
	ds_read_b128 v[182:185], v190 offset:3072
	ds_read_b128 v[186:189], v190 offset:2048
	s_waitcnt lgkmcnt(2)
	v_mfma_f32_16x16x32_bf16 v[126:129], v[146:149], v[174:177], v[126:129]
	v_mfma_f32_16x16x32_bf16 v[122:125], v[150:153], v[174:177], v[122:125]
	v_mfma_f32_16x16x32_bf16 v[118:121], v[166:169], v[174:177], v[118:121]
	v_mfma_f32_16x16x32_bf16 v[114:117], v[170:173], v[174:177], v[114:117]
	v_mfma_f32_16x16x32_bf16 v[110:113], v[146:149], v[178:181], v[110:113]
	v_mfma_f32_16x16x32_bf16 v[106:109], v[150:153], v[178:181], v[106:109]
	v_mfma_f32_16x16x32_bf16 v[102:105], v[166:169], v[178:181], v[102:105]
	v_mfma_f32_16x16x32_bf16 v[98:101], v[170:173], v[178:181], v[98:101]
	ds_read_b128 v[174:177], v190 offset:5120
	ds_read_b128 v[178:181], v190 offset:4096
	s_waitcnt lgkmcnt(2)
	v_mfma_f32_16x16x32_bf16 v[94:97], v[146:149], v[186:189], v[94:97]
	v_mfma_f32_16x16x32_bf16 v[90:93], v[150:153], v[186:189], v[90:93]
	v_mfma_f32_16x16x32_bf16 v[86:89], v[166:169], v[186:189], v[86:89]
	v_mfma_f32_16x16x32_bf16 v[82:85], v[170:173], v[186:189], v[82:85]
	v_mfma_f32_16x16x32_bf16 v[78:81], v[146:149], v[182:185], v[78:81]
	v_mfma_f32_16x16x32_bf16 v[74:77], v[150:153], v[182:185], v[74:77]
	v_mfma_f32_16x16x32_bf16 v[70:73], v[166:169], v[182:185], v[70:73]
	v_mfma_f32_16x16x32_bf16 v[66:69], v[170:173], v[182:185], v[66:69]
	ds_read_b128 v[182:185], v190 offset:7168
	ds_read_b128 v[186:189], v190 offset:6144
	s_waitcnt lgkmcnt(2)
	v_mfma_f32_16x16x32_bf16 v[62:65], v[146:149], v[178:181], v[62:65]
	v_mfma_f32_16x16x32_bf16 v[58:61], v[150:153], v[178:181], v[58:61]
	v_mfma_f32_16x16x32_bf16 v[54:57], v[166:169], v[178:181], v[54:57]
	v_mfma_f32_16x16x32_bf16 v[50:53], v[170:173], v[178:181], v[50:53]
	v_mfma_f32_16x16x32_bf16 v[46:49], v[146:149], v[174:177], v[46:49]
	v_mfma_f32_16x16x32_bf16 v[42:45], v[150:153], v[174:177], v[42:45]
	v_mfma_f32_16x16x32_bf16 v[38:41], v[166:169], v[174:177], v[38:41]
	v_mfma_f32_16x16x32_bf16 v[34:37], v[170:173], v[174:177], v[34:37]
	s_waitcnt lgkmcnt(0)
	v_mfma_f32_16x16x32_bf16 v[30:33], v[146:149], v[186:189], v[30:33]
	v_mfma_f32_16x16x32_bf16 v[26:29], v[150:153], v[186:189], v[26:29]
	v_mfma_f32_16x16x32_bf16 v[22:25], v[166:169], v[186:189], v[22:25]
	v_mfma_f32_16x16x32_bf16 v[18:21], v[170:173], v[186:189], v[18:21]
	v_mfma_f32_16x16x32_bf16 v[14:17], v[146:149], v[182:185], v[14:17]
	v_mfma_f32_16x16x32_bf16 v[10:13], v[150:153], v[182:185], v[10:13]
	v_mfma_f32_16x16x32_bf16 v[6:9], v[166:169], v[182:185], v[6:9]
	v_mfma_f32_16x16x32_bf16 v[2:5], v[170:173], v[182:185], v[2:5]
	s_addk_i32 s5, 0x6000
	s_add_i32 s11, s11, 1
	s_add_i32 s12, s12, 1
	v_lshl_add_u64 v[136:137], v[136:137], 0, 64
	v_lshl_add_u64 v[136:137], v[136:137], 0, 64
	s_cmp_eq_u32 s5, 0x204000
	v_lshl_add_u64 v[138:139], v[138:139], 0, 64
	v_lshl_add_u64 v[138:139], v[138:139], 0, 64
	s_cbranch_scc0 .LBB0_1998
	s_waitcnt vmcnt(6)
	s_waitcnt lgkmcnt(0)
	s_barrier
; #define MFMA(a, b, c) __builtin_amdgcn_mfma_f32_16x16x32_bf16((a), (b), (c), 0, 0, 0)
; template <int EPI, int MF>
; __device__ __forceinline__ void gemm_part(const u16* __restrict__ A, int lda, const u16* __restrict__ Bt, int K, int ntn, GemmEpi ep, char* smem,
;                                           int mbase, int mrows) {
;     ...
; #pragma unroll
;       for (int n = 0; n < 4; ++n) bfr[n] = rd_std(b_ + (wc * 64 + n * 16 + fr) * 32 + fq * 8);
;       afc[0] = rd_std(ap_); afc[1] = rd_std(ap_ + 16 * 32);
;       __builtin_amdgcn_sched_barrier(0);
;       if (kt + 2 < nk) GEMM_ISSUE(kt + 2);
;       __builtin_amdgcn_sched_barrier(0);
; #pragma unroll
;       for (int mh = 0; mh < MF / 2; ++mh) {
;         if (mh + 1 < MF / 2) {
;           afn[0] = rd_std(ap_ + ((mh + 1) * 2) * 16 * 32);
;           afn[1] = rd_std(ap_ + ((mh + 1) * 2 + 1) * 16 * 32);
;         }
;         __builtin_amdgcn_sched_barrier(0);
; #pragma unroll
;         for (int m = 0; m < 2; ++m)
; #pragma unroll
;           for (int n = 0; n < 4; ++n) acc[mh * 2 + m][n] = MFMA(bfr[n], afc[m], acc[mh * 2 + m][n]);
;         __builtin_amdgcn_sched_barrier(0);
;         afc[0] = afn[0]; afc[1] = afn[1];
;       }
	ds_read_b128 v[136:139], v165
	ds_read_b128 v[146:149], v165 offset:1024
	ds_read_b128 v[150:153], v165 offset:2048
	ds_read_b128 v[166:169], v165 offset:3072
	ds_read_b128 v[170:173], v162 offset:49152
	ds_read_b128 v[174:177], v162 offset:50176
	s_mul_hi_u32 s11, s11, 0xaaaaaaab
	s_lshr_b32 s11, s11, 1
	s_mul_i32 s11, s11, 0x12000
	s_sub_i32 s5, s5, s11
	s_add_i32 s5, s5, 0
	s_addk_i32 s5, 0x6000
	ds_read_b128 v[178:181], v162 offset:52224
	ds_read_b128 v[182:185], v162 offset:51200
	s_waitcnt lgkmcnt(0)
	v_mfma_f32_16x16x32_bf16 v[126:129], v[136:139], v[170:173], v[126:129]
	v_mfma_f32_16x16x32_bf16 v[122:125], v[146:149], v[170:173], v[122:125]
	v_mfma_f32_16x16x32_bf16 v[118:121], v[150:153], v[170:173], v[118:121]
	v_mfma_f32_16x16x32_bf16 v[114:117], v[166:169], v[170:173], v[114:117]
	v_mfma_f32_16x16x32_bf16 v[110:113], v[136:139], v[174:177], v[110:113]
	v_mfma_f32_16x16x32_bf16 v[106:109], v[146:149], v[174:177], v[106:109]
	v_mfma_f32_16x16x32_bf16 v[102:105], v[150:153], v[174:177], v[102:105]
	v_mfma_f32_16x16x32_bf16 v[98:101], v[166:169], v[174:177], v[98:101]
	ds_read_b128 v[170:173], v162 offset:54272
	ds_read_b128 v[174:177], v162 offset:53248
	v_mfma_f32_16x16x32_bf16 v[94:97], v[136:139], v[182:185], v[94:97]
	v_mfma_f32_16x16x32_bf16 v[90:93], v[146:149], v[182:185], v[90:93]
	v_mfma_f32_16x16x32_bf16 v[86:89], v[150:153], v[182:185], v[86:89]
	v_mfma_f32_16x16x32_bf16 v[82:85], v[166:169], v[182:185], v[82:85]
	v_mfma_f32_16x16x32_bf16 v[78:81], v[136:139], v[178:181], v[78:81]
	v_mfma_f32_16x16x32_bf16 v[74:77], v[146:149], v[178:181], v[74:77]
	v_mfma_f32_16x16x32_bf16 v[70:73], v[150:153], v[178:181], v[70:73]
	v_mfma_f32_16x16x32_bf16 v[66:69], v[166:169], v[178:181], v[66:69]
	ds_read_b128 v[178:181], v162 offset:56320
	ds_read_b128 v[182:185], v162 offset:55296
	s_waitcnt lgkmcnt(0)
	v_mfma_f32_16x16x32_bf16 v[62:65], v[136:139], v[174:177], v[62:65]
	v_mfma_f32_16x16x32_bf16 v[58:61], v[146:149], v[174:177], v[58:61]
	v_mfma_f32_16x16x32_bf16 v[54:57], v[150:153], v[174:177], v[54:57]
	v_mfma_f32_16x16x32_bf16 v[50:53], v[166:169], v[174:177], v[50:53]
	v_mfma_f32_16x16x32_bf16 v[46:49], v[136:139], v[170:173], v[46:49]
	v_mfma_f32_16x16x32_bf16 v[42:45], v[146:149], v[170:173], v[42:45]
	v_mfma_f32_16x16x32_bf16 v[38:41], v[150:153], v[170:173], v[38:41]
	v_mfma_f32_16x16x32_bf16 v[34:37], v[166:169], v[170:173], v[34:37]
	v_mfma_f32_16x16x32_bf16 v[30:33], v[136:139], v[182:185], v[30:33]
	v_mfma_f32_16x16x32_bf16 v[26:29], v[146:149], v[182:185], v[26:29]
	v_mfma_f32_16x16x32_bf16 v[22:25], v[150:153], v[182:185], v[22:25]
	v_mfma_f32_16x16x32_bf16 v[18:21], v[166:169], v[182:185], v[18:21]
	v_mfma_f32_16x16x32_bf16 v[14:17], v[136:139], v[178:181], v[14:17]
	v_mfma_f32_16x16x32_bf16 v[10:13], v[146:149], v[178:181], v[10:13]
	v_mfma_f32_16x16x32_bf16 v[6:9], v[150:153], v[178:181], v[6:9]
	v_mfma_f32_16x16x32_bf16 v[2:5], v[166:169], v[178:181], v[2:5]
	v_add_u32_e32 v136, s5, v161
	s_waitcnt vmcnt(0)
	v_add3_u32 v166, v136, v158, v159
	s_waitcnt lgkmcnt(0)
	s_barrier
; #define MFMA(a, b, c) __builtin_amdgcn_mfma_f32_16x16x32_bf16((a), (b), (c), 0, 0, 0)
; template <int EPI, int MF>
; __device__ __forceinline__ void gemm_part(const u16* __restrict__ A, int lda, const u16* __restrict__ Bt, int K, int ntn, GemmEpi ep, char* smem,
;                                           int mbase, int mrows) {
;     ...
; #pragma unroll
;       for (int n = 0; n < 4; ++n) bfr[n] = rd_std(b_ + (wc * 64 + n * 16 + fr) * 32 + fq * 8);
;       afc[0] = rd_std(ap_); afc[1] = rd_std(ap_ + 16 * 32);
;       __builtin_amdgcn_sched_barrier(0);
;       if (kt + 2 < nk) GEMM_ISSUE(kt + 2);
;       __builtin_amdgcn_sched_barrier(0);
; #pragma unroll
;       for (int mh = 0; mh < MF / 2; ++mh) {
;         if (mh + 1 < MF / 2) {
;           afn[0] = rd_std(ap_ + ((mh + 1) * 2) * 16 * 32);
;           afn[1] = rd_std(ap_ + ((mh + 1) * 2 + 1) * 16 * 32);
;         }
;         __builtin_amdgcn_sched_barrier(0);
; #pragma unroll
;         for (int m = 0; m < 2; ++m)
; #pragma unroll
;           for (int n = 0; n < 4; ++n) acc[mh * 2 + m][n] = MFMA(bfr[n], afc[m], acc[mh * 2 + m][n]);
;         __builtin_amdgcn_sched_barrier(0);
;         afc[0] = afn[0]; afc[1] = afn[1];
;       }
;     ...
;       } else if (EPI == EPI_RESID) {
;         const float* rp = (row < MP) ? ep.res0 + (size_t)row * DM : ep.res1 + (size_t)(row - MP) * DM;
;         float ssq = 0.f;
; #pragma unroll
;         for (int n = 0; n < 4; ++n) {
;           const int col = cb + n * 16;
;           const float4 r = *(const float4*)(rp + col);
;           float4 v;
;           v.x = r.x + ep.scale * acc[m][n][0]; v.y = r.y + ep.scale * acc[m][n][1];
;           v.z = r.z + ep.scale * acc[m][n][2]; v.w = r.w + ep.scale * acc[m][n][3];
;           *(float4*)(ep.outf + (size_t)row * DM + col) = v;
;           if (ep.xcopy) {
;             bf16x4 o;
;             o[0] = (short)f2bf(v.x); o[1] = (short)f2bf(v.y); o[2] = (short)f2bf(v.z); o[3] = (short)f2bf(v.w);
;             *(bf16x4*)(ep.xcopy + (size_t)row * DM + col) = o;
	ds_read_b128 v[136:139], v166 offset:16384
	ds_read_b128 v[146:149], v166 offset:17408
	ds_read_b128 v[150:153], v166 offset:18432
	ds_read_b128 v[166:169], v166 offset:19456
	ds_read_b128 v[170:173], v162
	ds_read_b128 v[174:177], v162 offset:1024
	ds_read_b128 v[178:181], v162 offset:3072
	ds_read_b128 v[182:185], v162 offset:2048
	s_waitcnt lgkmcnt(0)
	v_mfma_f32_16x16x32_bf16 v[126:129], v[136:139], v[170:173], v[126:129]
	v_mfma_f32_16x16x32_bf16 v[122:125], v[146:149], v[170:173], v[122:125]
	v_mfma_f32_16x16x32_bf16 v[118:121], v[150:153], v[170:173], v[118:121]
	v_mfma_f32_16x16x32_bf16 v[114:117], v[166:169], v[170:173], v[114:117]
	v_mfma_f32_16x16x32_bf16 v[110:113], v[136:139], v[174:177], v[110:113]
	v_mfma_f32_16x16x32_bf16 v[106:109], v[146:149], v[174:177], v[106:109]
	v_mfma_f32_16x16x32_bf16 v[102:105], v[150:153], v[174:177], v[102:105]
	v_mfma_f32_16x16x32_bf16 v[98:101], v[166:169], v[174:177], v[98:101]
	ds_read_b128 v[170:173], v162 offset:5120
	ds_read_b128 v[174:177], v162 offset:4096
	v_mfma_f32_16x16x32_bf16 v[94:97], v[136:139], v[182:185], v[94:97]
	v_mfma_f32_16x16x32_bf16 v[90:93], v[146:149], v[182:185], v[90:93]
	v_mfma_f32_16x16x32_bf16 v[86:89], v[150:153], v[182:185], v[86:89]
	v_mfma_f32_16x16x32_bf16 v[82:85], v[166:169], v[182:185], v[82:85]
	v_mfma_f32_16x16x32_bf16 v[78:81], v[136:139], v[178:181], v[78:81]
	v_mfma_f32_16x16x32_bf16 v[74:77], v[146:149], v[178:181], v[74:77]
	v_mfma_f32_16x16x32_bf16 v[70:73], v[150:153], v[178:181], v[70:73]
	v_mfma_f32_16x16x32_bf16 v[66:69], v[166:169], v[178:181], v[66:69]
	ds_read_b128 v[178:181], v162 offset:7168
	ds_read_b128 v[182:185], v162 offset:6144
	s_waitcnt lgkmcnt(0)
	v_mfma_f32_16x16x32_bf16 v[62:65], v[136:139], v[174:177], v[62:65]
	v_mfma_f32_16x16x32_bf16 v[58:61], v[146:149], v[174:177], v[58:61]
	v_mfma_f32_16x16x32_bf16 v[54:57], v[150:153], v[174:177], v[54:57]
	v_mfma_f32_16x16x32_bf16 v[50:53], v[166:169], v[174:177], v[50:53]
	v_mfma_f32_16x16x32_bf16 v[46:49], v[136:139], v[170:173], v[46:49]
	v_mfma_f32_16x16x32_bf16 v[42:45], v[146:149], v[170:173], v[42:45]
	v_mfma_f32_16x16x32_bf16 v[38:41], v[150:153], v[170:173], v[38:41]
	v_mfma_f32_16x16x32_bf16 v[34:37], v[166:169], v[170:173], v[34:37]
	v_mfma_f32_16x16x32_bf16 v[30:33], v[136:139], v[182:185], v[30:33]
	v_mfma_f32_16x16x32_bf16 v[26:29], v[146:149], v[182:185], v[26:29]
	v_mfma_f32_16x16x32_bf16 v[22:25], v[150:153], v[182:185], v[22:25]
	v_mfma_f32_16x16x32_bf16 v[18:21], v[166:169], v[182:185], v[18:21]
	v_mfma_f32_16x16x32_bf16 v[14:17], v[136:139], v[178:181], v[14:17]
	v_mfma_f32_16x16x32_bf16 v[10:13], v[146:149], v[178:181], v[10:13]
	v_mfma_f32_16x16x32_bf16 v[6:9], v[150:153], v[178:181], v[6:9]
	v_mfma_f32_16x16x32_bf16 v[2:5], v[166:169], v[178:181], v[2:5]
	v_add_u32_e32 v138, s4, v156
	s_waitcnt vmcnt(0)
	s_barrier
	s_mov_b32 s4, 0xffff
	v_cmp_lt_i32_e32 vcc, s4, v138
	s_and_saveexec_b64 s[4:5], vcc
	s_xor_b64 s[4:5], exec, s[4:5]
	v_add_u32_e32 v136, 0xffff0000, v138
	v_mov_b32_e32 v137, v0
	v_lshlrev_b64 v[136:137], 12, v[136:137]
	v_lshl_add_u64 v[136:137], s[72:73], 0, v[136:137]
	v_mov_b32_e32 v139, v0
	s_andn2_saveexec_b64 s[4:5], s[4:5]
	v_ashrrev_i32_e32 v139, 31, v138
	v_lshlrev_b64 v[136:137], 12, v[138:139]
	v_lshl_add_u64 v[136:137], s[26:27], 0, v[136:137]
	s_or_b64 exec, exec, s[4:5]
	v_lshlrev_b64 v[146:147], 12, v[138:139]
	v_or_b32_e32 v170, s10, v157
	v_lshl_add_u64 v[150:151], s[26:27], 0, v[146:147]
	v_lshlrev_b64 v[146:147], 11, v[138:139]
	v_lshl_add_u64 v[148:149], s[14:15], 0, v[146:147]
	v_lshlrev_b32_e32 v146, 2, v170
	v_mov_b32_e32 v147, v0
	v_lshl_add_u64 v[152:153], v[136:137], 0, v[146:147]
	global_load_dwordx4 v[166:169], v[152:153], off
	global_load_dwordx4 v[172:175], v[152:153], off offset:64
	global_load_dwordx4 v[176:179], v[152:153], off offset:128
	global_load_dwordx4 v[180:183], v[152:153], off offset:192
	v_cndmask_b32_e64 v136, 0, 1, s[2:3]
	v_lshl_add_u64 v[150:151], v[150:151], 0, v[146:147]
	v_cmp_ne_u32_e64 s[10:11], 1, v136
	s_andn2_b64 vcc, exec, s[2:3]
	v_lshlrev_b32_e32 v136, 1, v170
	s_waitcnt vmcnt(0)
	v_pk_fma_f32 v[126:127], v[126:127], 0.5, v[166:167] op_sel_hi:[1,0,1]
	v_pk_fma_f32 v[128:129], v[128:129], 0.5, v[168:169] op_sel_hi:[1,0,1]
	global_store_dwordx4 v[150:151], v[126:129], off
	s_cbranch_vccnz .LBB0_2005
	v_mov_b32_e32 v137, v0
	v_cvt_pk_bf16_f32 v166, v126, v127
	v_cvt_pk_bf16_f32 v167, v128, v129
	v_lshl_add_u64 v[168:169], v[148:149], 0, v[136:137]
	v_lshlrev_b32_e32 v184, 1, v168
	v_bfi_b32 v184, s100, v184, v168
	v_lshrrev_b32_e32 v185, 5, v168
	v_bfi_b32 v184, 64, v185, v184
	v_mov_b32_e32 v185, v169
	global_store_dwordx2 v[184:185], v[166:167], off
